# re-measure of the same file (v16: counted LDS waits in attention + placement pad before P12)
# baseline (speedup 1.0000x reference)
; #define PG8_STAGE(bufoff, gbase, voff) do { _Pragma("unroll") for (int _i = 0; _i < 2; ++_i) \
;         __builtin_amdgcn_global_load_lds((const unsigned*)((const char*)(gbase) + (voff)[_i]), (PG8_LAS unsigned*)(lds + (bufoff) + ldsw + _i * 8192), 16, 0, 0); } while (0)
; #define PG8_LDA(dst, b, h) do { _Pragma("unroll") for (int m = 0; m < 4; ++m) _Pragma("unroll") for (int k = 0; k < 2; ++k) dst[m][k] = *(const PG8_LAS bf16x8*)(lds + PG8_SA(b, h) + aoff + m * 2048 + k * 1024); } while (0)
; #define PG8_LDB(dst, b, h) do { _Pragma("unroll") for (int n = 0; n < 2; ++n) _Pragma("unroll") for (int k = 0; k < 2; ++k) dst[n][k] = *(const PG8_LAS bf16x8*)(lds + PG8_SB(b, h) + boff + n * 2048 + k * 1024); } while (0)
; #define PG8_WAIT_V(n) asm volatile("s_waitcnt vmcnt(" #n ")" ::: "memory")
; template <class Epi, class Sched, bool ALIGN_EPI = false, bool SP2 = false>
; __device__ __forceinline__ void gemm_phase(PG8_LAS unsigned char* lds, const Gemm g, const Sched& S, const Epi& E) {
;     ...
;             const char* a1 = cA + (size_t)(t + 1) * kstep;
;             const char* a2 = last ? nA : cA + (size_t)(t + 2) * kstep; const char* b2 = last ? nB : cB + (size_t)(t + 2) * kstep;
;             const char* a3 = a2 + kstep; const char* b3 = b2 + kstep;
;             if (last && has_next) S.a_ready(nxt);
;             if constexpr (SP2) {
;             PG8_LDB(B0, 0, 0); PG8_LDB(B1, 0, 1); PG8_SCHED; PG8_LDA(At, 0, 0); PG8_STAGE(PG8_SA(1, 1), a1 + hstep, voffA);
;             PG8_WAIT_V(8); PG8_WAIT_L(0); PG8_BAR; PG8_MMA(0, 0, At, B0); PG8_MMA(0, 1, At, B1); PG8_BAR; PG8_SCHED;
;             PG8_LDA(At, 0, 1); PG8_STAGE(PG8_SB(0, 0), b2, voffB); PG8_STAGE(PG8_SB(0, 1), b2 + hstep, voffB); PG8_STAGE(PG8_SA(0, 0), a2, voffA);
;             PG8_WAIT_V(8); PG8_WAIT_L(0); PG8_BAR; PG8_MMA(1, 0, At, B0); PG8_MMA(1, 1, At, B1); PG8_BAR; PG8_SCHED;
;             PG8_LDB(B0, 1, 0); PG8_LDB(B1, 1, 1); PG8_SCHED; PG8_LDA(At, 1, 0); PG8_STAGE(PG8_SA(0, 1), a2 + hstep, voffA);
;             PG8_WAIT_V(8); PG8_WAIT_L(0); PG8_BAR; PG8_MMA(0, 0, At, B0); PG8_MMA(0, 1, At, B1); PG8_BAR; PG8_SCHED;
;             PG8_LDA(At, 1, 1); PG8_STAGE(PG8_SB(1, 0), b3, voffB); PG8_STAGE(PG8_SB(1, 1), b3 + hstep, voffB); PG8_STAGE(PG8_SA(1, 0), a3, voffA);
;             PG8_WAIT_V(8); PG8_WAIT_L(0); PG8_BAR; PG8_MMA(1, 0, At, B0); PG8_MMA(1, 1, At, B1); PG8_BAR; PG8_SCHED;
.LBB0_275:
	s_ashr_i32 s15, s14, 31
	s_lshl_b64 s[0:1], s[14:15], 20
	s_add_u32 s64, s54, s0
	s_addc_u32 s65, s55, s1
	s_and_b64 s[0:1], s[20:21], exec
	s_cselect_b32 s0, s65, s75
	s_cselect_b32 s1, s64, s74
	s_ashr_i32 s13, s12, 31
	s_lshl_b64 s[28:29], s[12:13], 20
	s_add_u32 s68, s36, s28
	s_addc_u32 s69, s37, s29
	s_and_b64 s[28:29], s[20:21], exec
	s_cselect_b32 s3, s69, s85
	s_cselect_b32 s4, s68, s84
	s_add_u32 s74, s74, 0x80080
	s_addc_u32 s75, s75, 0
	s_add_u32 s13, s84, 0x100
	s_addc_u32 s15, s85, 0
	s_mov_b32 s28, -2
	ds_read_b128 v[150:153], v158
	ds_read_b128 v[162:165], v158 offset:1024
	ds_read_b128 v[166:169], v158 offset:2048
	ds_read_b128 v[170:173], v158 offset:3072
	ds_read_b128 v[174:177], v159
	ds_read_b128 v[178:181], v159 offset:1024
	ds_read_b128 v[182:185], v159 offset:2048
	ds_read_b128 v[190:193], v159 offset:3072
	s_add_u32 s29, s74, 0xfff80080
	s_addc_u32 s57, s75, -1
	s_cmp_eq_u32 s28, 28
	s_cselect_b32 s89, s0, s57
	s_cselect_b32 s88, s1, s29
	s_cselect_b32 s85, s3, s15
	s_cselect_b32 s84, s4, s13
	v_lshl_add_u64 v[154:155], s[74:75], 0, v[142:143]
	s_add_i32 m0, s30, 0xc000
	ds_read_b128 v[194:197], v160
	ds_read_b128 v[198:201], v160 offset:1024
	ds_read_b128 v[202:205], v160 offset:2048
	ds_read_b128 v[206:209], v160 offset:3072
	ds_read_b128 v[210:213], v160 offset:4096
	ds_read_b128 v[214:217], v160 offset:5120
	ds_read_b128 v[218:221], v160 offset:6144
	ds_read_b128 v[222:225], v160 offset:7168
	global_load_lds_dwordx4 v[154:155], off
	v_lshl_add_u64 v[154:155], s[74:75], 0, v[144:145]
	s_add_i32 m0, s30, 0xe000
	s_nop 0
	global_load_lds_dwordx4 v[154:155], off
	s_waitcnt vmcnt(8)
	s_waitcnt lgkmcnt(0)
	s_barrier
	s_waitcnt lgkmcnt(0)
	v_mfma_f32_16x16x32_bf16 v[124:127], v[150:153], v[194:197], 0
	v_mfma_f32_16x16x32_bf16 v[116:119], v[166:169], v[194:197], 0
	v_mfma_f32_16x16x32_bf16 v[108:111], v[150:153], v[202:205], 0
	v_mfma_f32_16x16x32_bf16 v[100:103], v[166:169], v[202:205], 0
	v_mfma_f32_16x16x32_bf16 v[92:95], v[150:153], v[210:213], 0
	v_mfma_f32_16x16x32_bf16 v[84:87], v[166:169], v[210:213], 0
	v_mfma_f32_16x16x32_bf16 v[76:79], v[150:153], v[218:221], 0
	v_mfma_f32_16x16x32_bf16 v[68:71], v[166:169], v[218:221], 0
	v_mfma_f32_16x16x32_bf16 v[124:127], v[162:165], v[198:201], v[124:127]
	v_mfma_f32_16x16x32_bf16 v[116:119], v[170:173], v[198:201], v[116:119]
	v_mfma_f32_16x16x32_bf16 v[108:111], v[162:165], v[206:209], v[108:111]
	v_mfma_f32_16x16x32_bf16 v[100:103], v[170:173], v[206:209], v[100:103]
	v_mfma_f32_16x16x32_bf16 v[92:95], v[162:165], v[214:217], v[92:95]
	v_mfma_f32_16x16x32_bf16 v[84:87], v[170:173], v[214:217], v[84:87]
	v_mfma_f32_16x16x32_bf16 v[76:79], v[162:165], v[222:225], v[76:79]
	v_mfma_f32_16x16x32_bf16 v[68:71], v[170:173], v[222:225], v[68:71]
	v_mfma_f32_16x16x32_bf16 v[120:123], v[174:177], v[194:197], 0
	v_mfma_f32_16x16x32_bf16 v[112:115], v[182:185], v[194:197], 0
	v_mfma_f32_16x16x32_bf16 v[104:107], v[174:177], v[202:205], 0
	v_mfma_f32_16x16x32_bf16 v[96:99], v[182:185], v[202:205], 0
	v_mfma_f32_16x16x32_bf16 v[88:91], v[174:177], v[210:213], 0
	v_mfma_f32_16x16x32_bf16 v[80:83], v[182:185], v[210:213], 0
	v_mfma_f32_16x16x32_bf16 v[72:75], v[174:177], v[218:221], 0
	v_mfma_f32_16x16x32_bf16 v[64:67], v[182:185], v[218:221], 0
	v_mfma_f32_16x16x32_bf16 v[120:123], v[178:181], v[198:201], v[120:123]
	v_mfma_f32_16x16x32_bf16 v[112:115], v[190:193], v[198:201], v[112:115]
	v_mfma_f32_16x16x32_bf16 v[104:107], v[178:181], v[206:209], v[104:107]
	v_mfma_f32_16x16x32_bf16 v[96:99], v[190:193], v[206:209], v[96:99]
	v_mfma_f32_16x16x32_bf16 v[88:91], v[178:181], v[214:217], v[88:91]
	v_mfma_f32_16x16x32_bf16 v[80:83], v[190:193], v[214:217], v[80:83]
	v_mfma_f32_16x16x32_bf16 v[72:75], v[178:181], v[222:225], v[72:75]
	v_mfma_f32_16x16x32_bf16 v[64:67], v[190:193], v[222:225], v[64:67]
	s_barrier
	s_add_i32 s29, s94, s23
	v_lshl_add_u64 v[154:155], s[84:85], 0, v[130:131]
	s_mov_b32 m0, s29
	ds_read_b128 v[194:197], v160 offset:16384
	ds_read_b128 v[198:201], v160 offset:17408
	ds_read_b128 v[202:205], v160 offset:18432
	ds_read_b128 v[206:209], v160 offset:19456
	ds_read_b128 v[210:213], v160 offset:20480
	ds_read_b128 v[214:217], v160 offset:21504
	ds_read_b128 v[218:221], v160 offset:22528
	ds_read_b128 v[222:225], v160 offset:23552
	global_load_lds_dwordx4 v[154:155], off
	s_add_i32 m0, s29, 0x2000
	s_add_u32 s96, s84, 0x80000
	v_lshl_add_u64 v[186:187], s[84:85], 0, v[134:135]
	s_addc_u32 s97, s85, 0
	s_add_i32 s29, s95, s23
	global_load_lds_dwordx4 v[186:187], off
	v_lshl_add_u64 v[226:227], s[96:97], 0, v[130:131]
	s_mov_b32 m0, s29
	v_lshl_add_u64 v[228:229], s[88:89], 0, v[132:133]
	global_load_lds_dwordx4 v[226:227], off
	v_lshl_add_u64 v[226:227], s[96:97], 0, v[134:135]
	s_add_i32 m0, s29, 0x2000
	s_nop 0
	global_load_lds_dwordx4 v[226:227], off
	v_lshl_add_u64 v[226:227], s[88:89], 0, v[128:129]
	s_mov_b32 m0, s30
	s_nop 0
	global_load_lds_dwordx4 v[226:227], off
	s_mov_b32 m0, s31
	s_nop 0
	global_load_lds_dwordx4 v[228:229], off
	s_waitcnt vmcnt(8)
	s_waitcnt lgkmcnt(0)
	s_barrier
; #define PG8_STAGE(bufoff, gbase, voff) do { _Pragma("unroll") for (int _i = 0; _i < 2; ++_i) \
;         __builtin_amdgcn_global_load_lds((const unsigned*)((const char*)(gbase) + (voff)[_i]), (PG8_LAS unsigned*)(lds + (bufoff) + ldsw + _i * 8192), 16, 0, 0); } while (0)
; #define PG8_LDA(dst, b, h) do { _Pragma("unroll") for (int m = 0; m < 4; ++m) _Pragma("unroll") for (int k = 0; k < 2; ++k) dst[m][k] = *(const PG8_LAS bf16x8*)(lds + PG8_SA(b, h) + aoff + m * 2048 + k * 1024); } while (0)
; #define PG8_LDB(dst, b, h) do { _Pragma("unroll") for (int n = 0; n < 2; ++n) _Pragma("unroll") for (int k = 0; k < 2; ++k) dst[n][k] = *(const PG8_LAS bf16x8*)(lds + PG8_SB(b, h) + boff + n * 2048 + k * 1024); } while (0)
; #define PG8_MMA(ai, bj, At, Bt) do { __builtin_amdgcn_s_setprio(1); _Pragma("unroll") for (int m = 0; m < 4; ++m) _Pragma("unroll") for (int n = 0; n < 2; ++n) _Pragma("unroll") for (int k = 0; k < 2; ++k) \
;         acc[ai][bj][m][n] = __builtin_amdgcn_mfma_f32_16x16x32_bf16(Bt[n][k], At[m][k], acc[ai][bj][m][n], 0, 0, 0); __builtin_amdgcn_s_setprio(0); } while (0)
; #define PG8_WAIT_V(n) asm volatile("s_waitcnt vmcnt(" #n ")" ::: "memory")
; #define PG8_WAIT_L(n) asm volatile("s_waitcnt lgkmcnt(" #n ")" ::: "memory")
; #define PG8_BAR __builtin_amdgcn_s_barrier()
; #define PG8_SCHED __builtin_amdgcn_sched_barrier(0)
; template <class Epi, class Sched, bool ALIGN_EPI = false, bool SP2 = false>
; __device__ __forceinline__ void gemm_phase(PG8_LAS unsigned char* lds, const Gemm g, const Sched& S, const Epi& E) {
;     ...
;             PG8_WAIT_V(8); PG8_WAIT_L(0); PG8_BAR; PG8_MMA(1, 0, At, B0); PG8_MMA(1, 1, At, B1); PG8_BAR; PG8_SCHED;
;             PG8_LDB(B0, 1, 0); PG8_LDB(B1, 1, 1); PG8_SCHED; PG8_LDA(At, 1, 0); PG8_STAGE(PG8_SA(0, 1), a2 + hstep, voffA);
;             PG8_WAIT_V(8); PG8_WAIT_L(0); PG8_BAR; PG8_MMA(0, 0, At, B0); PG8_MMA(0, 1, At, B1); PG8_BAR; PG8_SCHED;
	s_waitcnt lgkmcnt(0)
	v_mfma_f32_16x16x32_bf16 v[60:63], v[150:153], v[194:197], 0
	v_mfma_f32_16x16x32_bf16 v[52:55], v[166:169], v[194:197], 0
	v_mfma_f32_16x16x32_bf16 v[44:47], v[150:153], v[202:205], 0
	v_mfma_f32_16x16x32_bf16 v[36:39], v[166:169], v[202:205], 0
	v_mfma_f32_16x16x32_bf16 v[28:31], v[150:153], v[210:213], 0
	v_mfma_f32_16x16x32_bf16 v[20:23], v[166:169], v[210:213], 0
	v_mfma_f32_16x16x32_bf16 v[12:15], v[150:153], v[218:221], 0
	v_mfma_f32_16x16x32_bf16 v[4:7], v[166:169], v[218:221], 0
	v_mfma_f32_16x16x32_bf16 v[60:63], v[162:165], v[198:201], v[60:63]
	v_mfma_f32_16x16x32_bf16 v[52:55], v[170:173], v[198:201], v[52:55]
	v_mfma_f32_16x16x32_bf16 v[44:47], v[162:165], v[206:209], v[44:47]
	v_mfma_f32_16x16x32_bf16 v[36:39], v[170:173], v[206:209], v[36:39]
	v_mfma_f32_16x16x32_bf16 v[28:31], v[162:165], v[214:217], v[28:31]
	v_mfma_f32_16x16x32_bf16 v[20:23], v[170:173], v[214:217], v[20:23]
	v_mfma_f32_16x16x32_bf16 v[12:15], v[162:165], v[222:225], v[12:15]
	v_mfma_f32_16x16x32_bf16 v[4:7], v[170:173], v[222:225], v[4:7]
	v_mfma_f32_16x16x32_bf16 v[56:59], v[174:177], v[194:197], 0
	v_mfma_f32_16x16x32_bf16 v[48:51], v[182:185], v[194:197], 0
	v_mfma_f32_16x16x32_bf16 v[40:43], v[174:177], v[202:205], 0
	v_mfma_f32_16x16x32_bf16 v[32:35], v[182:185], v[202:205], 0
	v_mfma_f32_16x16x32_bf16 v[24:27], v[174:177], v[210:213], 0
	v_mfma_f32_16x16x32_bf16 v[16:19], v[182:185], v[210:213], 0
	v_mfma_f32_16x16x32_bf16 v[8:11], v[174:177], v[218:221], 0
	v_mfma_f32_16x16x32_bf16 v[0:3], v[182:185], v[218:221], 0
	v_mfma_f32_16x16x32_bf16 v[56:59], v[178:181], v[198:201], v[56:59]
	v_mfma_f32_16x16x32_bf16 v[48:51], v[190:193], v[198:201], v[48:51]
	v_mfma_f32_16x16x32_bf16 v[40:43], v[178:181], v[206:209], v[40:43]
	v_mfma_f32_16x16x32_bf16 v[32:35], v[190:193], v[206:209], v[32:35]
	v_mfma_f32_16x16x32_bf16 v[24:27], v[178:181], v[214:217], v[24:27]
	v_mfma_f32_16x16x32_bf16 v[16:19], v[190:193], v[214:217], v[16:19]
	v_mfma_f32_16x16x32_bf16 v[8:11], v[178:181], v[222:225], v[8:11]
	v_mfma_f32_16x16x32_bf16 v[0:3], v[190:193], v[222:225], v[0:3]
	s_barrier
	s_add_i32 s29, 0, 0x18000
	v_add_u32_e32 v136, s29, v156
	s_add_i32 s57, 0, 0x1c000
	ds_read_b128 v[150:153], v136
	ds_read_b128 v[162:165], v136 offset:1024
	ds_read_b128 v[166:169], v136 offset:2048
	ds_read_b128 v[170:173], v136 offset:3072
	v_add_u32_e32 v136, s57, v156
	ds_read_b128 v[174:177], v136
	ds_read_b128 v[178:181], v136 offset:1024
	ds_read_b128 v[182:185], v136 offset:2048
	ds_read_b128 v[190:193], v136 offset:3072
	s_add_u32 s88, s88, 0x80000
	s_addc_u32 s89, s89, 0
	s_mov_b32 m0, s33
	v_lshl_add_u64 v[230:231], s[88:89], 0, v[128:129]
	ds_read_b128 v[194:197], v160 offset:32768
	ds_read_b128 v[198:201], v160 offset:33792
	ds_read_b128 v[202:205], v160 offset:34816
	ds_read_b128 v[206:209], v160 offset:35840
	ds_read_b128 v[210:213], v160 offset:36864
	ds_read_b128 v[214:217], v160 offset:37888
	ds_read_b128 v[218:221], v160 offset:38912
	ds_read_b128 v[222:225], v160 offset:39936
	global_load_lds_dwordx4 v[230:231], off
	v_lshl_add_u64 v[230:231], s[88:89], 0, v[132:133]
	s_mov_b32 m0, s71
	s_nop 0
	global_load_lds_dwordx4 v[230:231], off
	s_waitcnt vmcnt(8)
	s_waitcnt lgkmcnt(0)
	s_barrier
	s_waitcnt lgkmcnt(0)
	v_mfma_f32_16x16x32_bf16 v[124:127], v[150:153], v[194:197], v[124:127]
	v_mfma_f32_16x16x32_bf16 v[116:119], v[166:169], v[194:197], v[116:119]
	v_mfma_f32_16x16x32_bf16 v[108:111], v[150:153], v[202:205], v[108:111]
	v_mfma_f32_16x16x32_bf16 v[100:103], v[166:169], v[202:205], v[100:103]
	v_mfma_f32_16x16x32_bf16 v[92:95], v[150:153], v[210:213], v[92:95]
	v_mfma_f32_16x16x32_bf16 v[84:87], v[166:169], v[210:213], v[84:87]
	v_mfma_f32_16x16x32_bf16 v[76:79], v[150:153], v[218:221], v[76:79]
	v_mfma_f32_16x16x32_bf16 v[68:71], v[166:169], v[218:221], v[68:71]
	v_mfma_f32_16x16x32_bf16 v[124:127], v[162:165], v[198:201], v[124:127]
	v_mfma_f32_16x16x32_bf16 v[116:119], v[170:173], v[198:201], v[116:119]
	v_mfma_f32_16x16x32_bf16 v[108:111], v[162:165], v[206:209], v[108:111]
	v_mfma_f32_16x16x32_bf16 v[100:103], v[170:173], v[206:209], v[100:103]
	v_mfma_f32_16x16x32_bf16 v[92:95], v[162:165], v[214:217], v[92:95]
	v_mfma_f32_16x16x32_bf16 v[84:87], v[170:173], v[214:217], v[84:87]
	v_mfma_f32_16x16x32_bf16 v[76:79], v[162:165], v[222:225], v[76:79]
	v_mfma_f32_16x16x32_bf16 v[68:71], v[170:173], v[222:225], v[68:71]
	v_mfma_f32_16x16x32_bf16 v[120:123], v[174:177], v[194:197], v[120:123]
	v_mfma_f32_16x16x32_bf16 v[112:115], v[182:185], v[194:197], v[112:115]
	v_mfma_f32_16x16x32_bf16 v[104:107], v[174:177], v[202:205], v[104:107]
	v_mfma_f32_16x16x32_bf16 v[96:99], v[182:185], v[202:205], v[96:99]
	v_mfma_f32_16x16x32_bf16 v[88:91], v[174:177], v[210:213], v[88:91]
	v_mfma_f32_16x16x32_bf16 v[80:83], v[182:185], v[210:213], v[80:83]
	v_mfma_f32_16x16x32_bf16 v[72:75], v[174:177], v[218:221], v[72:75]
	v_mfma_f32_16x16x32_bf16 v[64:67], v[182:185], v[218:221], v[64:67]
	v_mfma_f32_16x16x32_bf16 v[120:123], v[178:181], v[198:201], v[120:123]
	v_mfma_f32_16x16x32_bf16 v[112:115], v[190:193], v[198:201], v[112:115]
	v_mfma_f32_16x16x32_bf16 v[104:107], v[178:181], v[206:209], v[104:107]
	v_mfma_f32_16x16x32_bf16 v[96:99], v[190:193], v[206:209], v[96:99]
	v_mfma_f32_16x16x32_bf16 v[88:91], v[178:181], v[214:217], v[88:91]
	v_mfma_f32_16x16x32_bf16 v[80:83], v[190:193], v[214:217], v[80:83]
	v_mfma_f32_16x16x32_bf16 v[72:75], v[178:181], v[222:225], v[72:75]
	v_mfma_f32_16x16x32_bf16 v[64:67], v[190:193], v[222:225], v[64:67]
	s_barrier
; #define PG8_STAGE(bufoff, gbase, voff) do { _Pragma("unroll") for (int _i = 0; _i < 2; ++_i) \
;         __builtin_amdgcn_global_load_lds((const unsigned*)((const char*)(gbase) + (voff)[_i]), (PG8_LAS unsigned*)(lds + (bufoff) + ldsw + _i * 8192), 16, 0, 0); } while (0)
; #define PG8_LDA(dst, b, h) do { _Pragma("unroll") for (int m = 0; m < 4; ++m) _Pragma("unroll") for (int k = 0; k < 2; ++k) dst[m][k] = *(const PG8_LAS bf16x8*)(lds + PG8_SA(b, h) + aoff + m * 2048 + k * 1024); } while (0)
; #define PG8_LDB(dst, b, h) do { _Pragma("unroll") for (int n = 0; n < 2; ++n) _Pragma("unroll") for (int k = 0; k < 2; ++k) dst[n][k] = *(const PG8_LAS bf16x8*)(lds + PG8_SB(b, h) + boff + n * 2048 + k * 1024); } while (0)
; #define PG8_WAIT_V(n) asm volatile("s_waitcnt vmcnt(" #n ")" ::: "memory")
; #define PG8_WAIT_L(n) asm volatile("s_waitcnt lgkmcnt(" #n ")" ::: "memory")
; #define PG8_BAR __builtin_amdgcn_s_barrier()
; #define PG8_SCHED __builtin_amdgcn_sched_barrier(0)
; template <class Epi, class Sched, bool ALIGN_EPI = false, bool SP2 = false>
; __device__ __forceinline__ void gemm_phase(PG8_LAS unsigned char* lds, const Gemm g, const Sched& S, const Epi& E) {
;     ...
;         for (int t = seg * tseg; t < (seg + 1) * tseg; t += 2) {
;             const bool last = (t == nt - 2);
;             const char* a1 = cA + (size_t)(t + 1) * kstep;
;             const char* a2 = last ? nA : cA + (size_t)(t + 2) * kstep; const char* b2 = last ? nB : cB + (size_t)(t + 2) * kstep;
;             const char* a3 = a2 + kstep; const char* b3 = b2 + kstep;
;             if (last && has_next) S.a_ready(nxt);
;             if constexpr (SP2) {
;             PG8_LDB(B0, 0, 0); PG8_LDB(B1, 0, 1); PG8_SCHED; PG8_LDA(At, 0, 0); PG8_STAGE(PG8_SA(1, 1), a1 + hstep, voffA);
;             PG8_WAIT_V(8); PG8_WAIT_L(0); PG8_BAR; PG8_MMA(0, 0, At, B0); PG8_MMA(0, 1, At, B1); PG8_BAR; PG8_SCHED;
;             PG8_LDA(At, 0, 1); PG8_STAGE(PG8_SB(0, 0), b2, voffB); PG8_STAGE(PG8_SB(0, 1), b2 + hstep, voffB); PG8_STAGE(PG8_SA(0, 0), a2, voffA);
;     ...
;             PG8_LDA(At, 1, 1); PG8_STAGE(PG8_SB(1, 0), b3, voffB); PG8_STAGE(PG8_SB(1, 1), b3 + hstep, voffB); PG8_STAGE(PG8_SA(1, 0), a3, voffA);
;             PG8_WAIT_V(8); PG8_WAIT_L(0); PG8_BAR; PG8_MMA(1, 0, At, B0); PG8_MMA(1, 1, At, B1); PG8_BAR; PG8_SCHED;
	s_add_i32 s29, s29, s23
	v_lshl_add_u64 v[154:155], v[154:155], 0, s[8:9]
	s_mov_b32 m0, s29
	ds_read_b128 v[194:197], v160 offset:49152
	ds_read_b128 v[198:201], v160 offset:50176
	ds_read_b128 v[202:205], v160 offset:51200
	ds_read_b128 v[206:209], v160 offset:52224
	ds_read_b128 v[210:213], v160 offset:53248
	ds_read_b128 v[214:217], v160 offset:54272
	ds_read_b128 v[218:221], v160 offset:55296
	ds_read_b128 v[222:225], v160 offset:56320
	global_load_lds_dwordx4 v[154:155], off
	s_add_i32 m0, s29, 0x2000
	s_add_u32 s84, s84, 0x80080
	v_lshl_add_u64 v[154:155], v[186:187], 0, s[8:9]
	s_addc_u32 s85, s85, 0
	s_add_i32 s29, s57, s23
	global_load_lds_dwordx4 v[154:155], off
	v_lshl_add_u64 v[154:155], s[84:85], 0, v[130:131]
	s_mov_b32 m0, s29
	s_nop 0
	global_load_lds_dwordx4 v[154:155], off
	v_lshl_add_u64 v[154:155], s[84:85], 0, v[134:135]
	s_add_i32 m0, s29, 0x2000
	s_nop 0
	global_load_lds_dwordx4 v[154:155], off
	v_lshl_add_u64 v[154:155], v[226:227], 0, s[8:9]
	s_mov_b32 m0, s92
	s_nop 0
	global_load_lds_dwordx4 v[154:155], off
	v_lshl_add_u64 v[154:155], v[228:229], 0, s[8:9]
	s_mov_b32 m0, s93
	s_nop 0
	global_load_lds_dwordx4 v[154:155], off
	s_waitcnt vmcnt(8)
	s_waitcnt lgkmcnt(0)
	s_barrier
	s_waitcnt lgkmcnt(0)
	v_mfma_f32_16x16x32_bf16 v[60:63], v[150:153], v[194:197], v[60:63]
	v_mfma_f32_16x16x32_bf16 v[52:55], v[166:169], v[194:197], v[52:55]
	v_mfma_f32_16x16x32_bf16 v[44:47], v[150:153], v[202:205], v[44:47]
	v_mfma_f32_16x16x32_bf16 v[36:39], v[166:169], v[202:205], v[36:39]
	v_mfma_f32_16x16x32_bf16 v[28:31], v[150:153], v[210:213], v[28:31]
	v_mfma_f32_16x16x32_bf16 v[20:23], v[166:169], v[210:213], v[20:23]
	v_mfma_f32_16x16x32_bf16 v[12:15], v[150:153], v[218:221], v[12:15]
	v_mfma_f32_16x16x32_bf16 v[4:7], v[166:169], v[218:221], v[4:7]
	v_mfma_f32_16x16x32_bf16 v[60:63], v[162:165], v[198:201], v[60:63]
	v_mfma_f32_16x16x32_bf16 v[52:55], v[170:173], v[198:201], v[52:55]
	v_mfma_f32_16x16x32_bf16 v[44:47], v[162:165], v[206:209], v[44:47]
	v_mfma_f32_16x16x32_bf16 v[36:39], v[170:173], v[206:209], v[36:39]
	v_mfma_f32_16x16x32_bf16 v[28:31], v[162:165], v[214:217], v[28:31]
	v_mfma_f32_16x16x32_bf16 v[20:23], v[170:173], v[214:217], v[20:23]
	v_mfma_f32_16x16x32_bf16 v[12:15], v[162:165], v[222:225], v[12:15]
	v_mfma_f32_16x16x32_bf16 v[4:7], v[170:173], v[222:225], v[4:7]
	v_mfma_f32_16x16x32_bf16 v[56:59], v[174:177], v[194:197], v[56:59]
	v_mfma_f32_16x16x32_bf16 v[48:51], v[182:185], v[194:197], v[48:51]
	v_mfma_f32_16x16x32_bf16 v[40:43], v[174:177], v[202:205], v[40:43]
	v_mfma_f32_16x16x32_bf16 v[32:35], v[182:185], v[202:205], v[32:35]
	v_mfma_f32_16x16x32_bf16 v[24:27], v[174:177], v[210:213], v[24:27]
	v_mfma_f32_16x16x32_bf16 v[16:19], v[182:185], v[210:213], v[16:19]
	v_mfma_f32_16x16x32_bf16 v[8:11], v[174:177], v[218:221], v[8:11]
	v_mfma_f32_16x16x32_bf16 v[0:3], v[182:185], v[218:221], v[0:3]
	v_mfma_f32_16x16x32_bf16 v[56:59], v[178:181], v[198:201], v[56:59]
	v_mfma_f32_16x16x32_bf16 v[48:51], v[190:193], v[198:201], v[48:51]
	v_mfma_f32_16x16x32_bf16 v[40:43], v[178:181], v[206:209], v[40:43]
	v_mfma_f32_16x16x32_bf16 v[32:35], v[190:193], v[206:209], v[32:35]
	v_mfma_f32_16x16x32_bf16 v[24:27], v[178:181], v[214:217], v[24:27]
	v_mfma_f32_16x16x32_bf16 v[16:19], v[190:193], v[214:217], v[16:19]
	v_mfma_f32_16x16x32_bf16 v[8:11], v[178:181], v[222:225], v[8:11]
	v_mfma_f32_16x16x32_bf16 v[0:3], v[190:193], v[222:225], v[0:3]
	s_barrier
	s_add_i32 s28, s28, 2
	s_add_u32 s74, s74, 0x100
	s_addc_u32 s75, s75, 0
	s_add_u32 s13, s13, 0x100
	s_addc_u32 s15, s15, 0
	s_cmp_gt_u32 s28, 29
.LBB0_276:
	ds_read_b128 v[150:153], v158
	ds_read_b128 v[162:165], v158 offset:1024
	ds_read_b128 v[166:169], v158 offset:2048
	ds_read_b128 v[170:173], v158 offset:3072
	ds_read_b128 v[174:177], v159
	ds_read_b128 v[178:181], v159 offset:1024
	ds_read_b128 v[182:185], v159 offset:2048
	ds_read_b128 v[190:193], v159 offset:3072
	s_add_u32 s29, s74, 0xfff80080
	s_addc_u32 s57, s75, -1
	s_cmp_eq_u32 s28, 28
	s_cselect_b32 s89, s0, s57
	s_cselect_b32 s88, s1, s29
	s_cselect_b32 s85, s3, s15
	s_cselect_b32 s84, s4, s13
	v_lshl_add_u64 v[154:155], s[74:75], 0, v[142:143]
	s_add_i32 m0, s30, 0xc000
	ds_read_b128 v[194:197], v160
	ds_read_b128 v[198:201], v160 offset:1024
	ds_read_b128 v[202:205], v160 offset:2048
	ds_read_b128 v[206:209], v160 offset:3072
	ds_read_b128 v[210:213], v160 offset:4096
	ds_read_b128 v[214:217], v160 offset:5120
	ds_read_b128 v[218:221], v160 offset:6144
	ds_read_b128 v[222:225], v160 offset:7168
	global_load_lds_dwordx4 v[154:155], off
	v_lshl_add_u64 v[154:155], s[74:75], 0, v[144:145]
	s_add_i32 m0, s30, 0xe000
	s_nop 0
	global_load_lds_dwordx4 v[154:155], off
	s_waitcnt vmcnt(8)
	s_waitcnt lgkmcnt(0)
	s_barrier
; #define PG8_STAGE(bufoff, gbase, voff) do { _Pragma("unroll") for (int _i = 0; _i < 2; ++_i) \
;         __builtin_amdgcn_global_load_lds((const unsigned*)((const char*)(gbase) + (voff)[_i]), (PG8_LAS unsigned*)(lds + (bufoff) + ldsw + _i * 8192), 16, 0, 0); } while (0)
; #define PG8_LDA(dst, b, h) do { _Pragma("unroll") for (int m = 0; m < 4; ++m) _Pragma("unroll") for (int k = 0; k < 2; ++k) dst[m][k] = *(const PG8_LAS bf16x8*)(lds + PG8_SA(b, h) + aoff + m * 2048 + k * 1024); } while (0)
; #define PG8_MMA(ai, bj, At, Bt) do { __builtin_amdgcn_s_setprio(1); _Pragma("unroll") for (int m = 0; m < 4; ++m) _Pragma("unroll") for (int n = 0; n < 2; ++n) _Pragma("unroll") for (int k = 0; k < 2; ++k) \
;         acc[ai][bj][m][n] = __builtin_amdgcn_mfma_f32_16x16x32_bf16(Bt[n][k], At[m][k], acc[ai][bj][m][n], 0, 0, 0); __builtin_amdgcn_s_setprio(0); } while (0)
; #define PG8_WAIT_V(n) asm volatile("s_waitcnt vmcnt(" #n ")" ::: "memory")
; #define PG8_WAIT_L(n) asm volatile("s_waitcnt lgkmcnt(" #n ")" ::: "memory")
; #define PG8_BAR __builtin_amdgcn_s_barrier()
; #define PG8_SCHED __builtin_amdgcn_sched_barrier(0)
; template <class Epi, class Sched, bool ALIGN_EPI = false, bool SP2 = false>
; __device__ __forceinline__ void gemm_phase(PG8_LAS unsigned char* lds, const Gemm g, const Sched& S, const Epi& E) {
;     ...
;             PG8_WAIT_V(8); PG8_WAIT_L(0); PG8_BAR; PG8_MMA(0, 0, At, B0); PG8_MMA(0, 1, At, B1); PG8_BAR; PG8_SCHED;
;             PG8_LDA(At, 0, 1); PG8_STAGE(PG8_SB(0, 0), b2, voffB); PG8_STAGE(PG8_SB(0, 1), b2 + hstep, voffB); PG8_STAGE(PG8_SA(0, 0), a2, voffA);
;             PG8_WAIT_V(8); PG8_WAIT_L(0); PG8_BAR; PG8_MMA(1, 0, At, B0); PG8_MMA(1, 1, At, B1); PG8_BAR; PG8_SCHED;
	s_waitcnt lgkmcnt(0)
	v_mfma_f32_16x16x32_bf16 v[124:127], v[150:153], v[194:197], v[124:127]
	v_mfma_f32_16x16x32_bf16 v[116:119], v[166:169], v[194:197], v[116:119]
	v_mfma_f32_16x16x32_bf16 v[108:111], v[150:153], v[202:205], v[108:111]
	v_mfma_f32_16x16x32_bf16 v[100:103], v[166:169], v[202:205], v[100:103]
	v_mfma_f32_16x16x32_bf16 v[92:95], v[150:153], v[210:213], v[92:95]
	v_mfma_f32_16x16x32_bf16 v[84:87], v[166:169], v[210:213], v[84:87]
	v_mfma_f32_16x16x32_bf16 v[76:79], v[150:153], v[218:221], v[76:79]
	v_mfma_f32_16x16x32_bf16 v[68:71], v[166:169], v[218:221], v[68:71]
	v_mfma_f32_16x16x32_bf16 v[124:127], v[162:165], v[198:201], v[124:127]
	v_mfma_f32_16x16x32_bf16 v[116:119], v[170:173], v[198:201], v[116:119]
	v_mfma_f32_16x16x32_bf16 v[108:111], v[162:165], v[206:209], v[108:111]
	v_mfma_f32_16x16x32_bf16 v[100:103], v[170:173], v[206:209], v[100:103]
	v_mfma_f32_16x16x32_bf16 v[92:95], v[162:165], v[214:217], v[92:95]
	v_mfma_f32_16x16x32_bf16 v[84:87], v[170:173], v[214:217], v[84:87]
	v_mfma_f32_16x16x32_bf16 v[76:79], v[162:165], v[222:225], v[76:79]
	v_mfma_f32_16x16x32_bf16 v[68:71], v[170:173], v[222:225], v[68:71]
	v_mfma_f32_16x16x32_bf16 v[120:123], v[174:177], v[194:197], v[120:123]
	v_mfma_f32_16x16x32_bf16 v[112:115], v[182:185], v[194:197], v[112:115]
	v_mfma_f32_16x16x32_bf16 v[104:107], v[174:177], v[202:205], v[104:107]
	v_mfma_f32_16x16x32_bf16 v[96:99], v[182:185], v[202:205], v[96:99]
	v_mfma_f32_16x16x32_bf16 v[88:91], v[174:177], v[210:213], v[88:91]
	v_mfma_f32_16x16x32_bf16 v[80:83], v[182:185], v[210:213], v[80:83]
	v_mfma_f32_16x16x32_bf16 v[72:75], v[174:177], v[218:221], v[72:75]
	v_mfma_f32_16x16x32_bf16 v[64:67], v[182:185], v[218:221], v[64:67]
	v_mfma_f32_16x16x32_bf16 v[120:123], v[178:181], v[198:201], v[120:123]
	v_mfma_f32_16x16x32_bf16 v[112:115], v[190:193], v[198:201], v[112:115]
	v_mfma_f32_16x16x32_bf16 v[104:107], v[178:181], v[206:209], v[104:107]
	v_mfma_f32_16x16x32_bf16 v[96:99], v[190:193], v[206:209], v[96:99]
	v_mfma_f32_16x16x32_bf16 v[88:91], v[178:181], v[214:217], v[88:91]
	v_mfma_f32_16x16x32_bf16 v[80:83], v[190:193], v[214:217], v[80:83]
	v_mfma_f32_16x16x32_bf16 v[72:75], v[178:181], v[222:225], v[72:75]
	v_mfma_f32_16x16x32_bf16 v[64:67], v[190:193], v[222:225], v[64:67]
	s_barrier
	s_add_i32 s29, s94, s23
	v_lshl_add_u64 v[154:155], s[84:85], 0, v[130:131]
	s_mov_b32 m0, s29
	ds_read_b128 v[194:197], v160 offset:16384
	ds_read_b128 v[198:201], v160 offset:17408
	ds_read_b128 v[202:205], v160 offset:18432
	ds_read_b128 v[206:209], v160 offset:19456
	ds_read_b128 v[210:213], v160 offset:20480
	ds_read_b128 v[214:217], v160 offset:21504
	ds_read_b128 v[218:221], v160 offset:22528
	ds_read_b128 v[222:225], v160 offset:23552
	global_load_lds_dwordx4 v[154:155], off
	s_add_i32 m0, s29, 0x2000
	s_add_u32 s96, s84, 0x80000
	v_lshl_add_u64 v[186:187], s[84:85], 0, v[134:135]
	s_addc_u32 s97, s85, 0
	s_add_i32 s29, s95, s23
	global_load_lds_dwordx4 v[186:187], off
	v_lshl_add_u64 v[226:227], s[96:97], 0, v[130:131]
	s_mov_b32 m0, s29
	v_lshl_add_u64 v[228:229], s[88:89], 0, v[132:133]
	global_load_lds_dwordx4 v[226:227], off
	v_lshl_add_u64 v[226:227], s[96:97], 0, v[134:135]
	s_add_i32 m0, s29, 0x2000
	s_nop 0
	global_load_lds_dwordx4 v[226:227], off
	v_lshl_add_u64 v[226:227], s[88:89], 0, v[128:129]
	s_mov_b32 m0, s30
	s_nop 0
	global_load_lds_dwordx4 v[226:227], off
	s_mov_b32 m0, s31
	s_nop 0
	global_load_lds_dwordx4 v[228:229], off
	s_waitcnt vmcnt(8)
	s_waitcnt lgkmcnt(0)
	s_barrier
	s_waitcnt lgkmcnt(0)
	v_mfma_f32_16x16x32_bf16 v[60:63], v[150:153], v[194:197], v[60:63]
	v_mfma_f32_16x16x32_bf16 v[52:55], v[166:169], v[194:197], v[52:55]
	v_mfma_f32_16x16x32_bf16 v[44:47], v[150:153], v[202:205], v[44:47]
	v_mfma_f32_16x16x32_bf16 v[36:39], v[166:169], v[202:205], v[36:39]
	v_mfma_f32_16x16x32_bf16 v[28:31], v[150:153], v[210:213], v[28:31]
	v_mfma_f32_16x16x32_bf16 v[20:23], v[166:169], v[210:213], v[20:23]
	v_mfma_f32_16x16x32_bf16 v[12:15], v[150:153], v[218:221], v[12:15]
	v_mfma_f32_16x16x32_bf16 v[4:7], v[166:169], v[218:221], v[4:7]
	v_mfma_f32_16x16x32_bf16 v[60:63], v[162:165], v[198:201], v[60:63]
	v_mfma_f32_16x16x32_bf16 v[52:55], v[170:173], v[198:201], v[52:55]
	v_mfma_f32_16x16x32_bf16 v[44:47], v[162:165], v[206:209], v[44:47]
	v_mfma_f32_16x16x32_bf16 v[36:39], v[170:173], v[206:209], v[36:39]
	v_mfma_f32_16x16x32_bf16 v[28:31], v[162:165], v[214:217], v[28:31]
	v_mfma_f32_16x16x32_bf16 v[20:23], v[170:173], v[214:217], v[20:23]
	v_mfma_f32_16x16x32_bf16 v[12:15], v[162:165], v[222:225], v[12:15]
	v_mfma_f32_16x16x32_bf16 v[4:7], v[170:173], v[222:225], v[4:7]
	v_mfma_f32_16x16x32_bf16 v[56:59], v[174:177], v[194:197], v[56:59]
	v_mfma_f32_16x16x32_bf16 v[48:51], v[182:185], v[194:197], v[48:51]
	v_mfma_f32_16x16x32_bf16 v[40:43], v[174:177], v[202:205], v[40:43]
	v_mfma_f32_16x16x32_bf16 v[32:35], v[182:185], v[202:205], v[32:35]
	v_mfma_f32_16x16x32_bf16 v[24:27], v[174:177], v[210:213], v[24:27]
	v_mfma_f32_16x16x32_bf16 v[16:19], v[182:185], v[210:213], v[16:19]
	v_mfma_f32_16x16x32_bf16 v[8:11], v[174:177], v[218:221], v[8:11]
	v_mfma_f32_16x16x32_bf16 v[0:3], v[182:185], v[218:221], v[0:3]
	v_mfma_f32_16x16x32_bf16 v[56:59], v[178:181], v[198:201], v[56:59]
	v_mfma_f32_16x16x32_bf16 v[48:51], v[190:193], v[198:201], v[48:51]
	v_mfma_f32_16x16x32_bf16 v[40:43], v[178:181], v[206:209], v[40:43]
	v_mfma_f32_16x16x32_bf16 v[32:35], v[190:193], v[206:209], v[32:35]
	v_mfma_f32_16x16x32_bf16 v[24:27], v[178:181], v[214:217], v[24:27]
	v_mfma_f32_16x16x32_bf16 v[16:19], v[190:193], v[214:217], v[16:19]
	v_mfma_f32_16x16x32_bf16 v[8:11], v[178:181], v[222:225], v[8:11]
	v_mfma_f32_16x16x32_bf16 v[0:3], v[190:193], v[222:225], v[0:3]
	s_barrier
; #define PG8_STAGE(bufoff, gbase, voff) do { _Pragma("unroll") for (int _i = 0; _i < 2; ++_i) \
;         __builtin_amdgcn_global_load_lds((const unsigned*)((const char*)(gbase) + (voff)[_i]), (PG8_LAS unsigned*)(lds + (bufoff) + ldsw + _i * 8192), 16, 0, 0); } while (0)
; #define PG8_LDA(dst, b, h) do { _Pragma("unroll") for (int m = 0; m < 4; ++m) _Pragma("unroll") for (int k = 0; k < 2; ++k) dst[m][k] = *(const PG8_LAS bf16x8*)(lds + PG8_SA(b, h) + aoff + m * 2048 + k * 1024); } while (0)
; #define PG8_LDB(dst, b, h) do { _Pragma("unroll") for (int n = 0; n < 2; ++n) _Pragma("unroll") for (int k = 0; k < 2; ++k) dst[n][k] = *(const PG8_LAS bf16x8*)(lds + PG8_SB(b, h) + boff + n * 2048 + k * 1024); } while (0)
; #define PG8_MMA(ai, bj, At, Bt) do { __builtin_amdgcn_s_setprio(1); _Pragma("unroll") for (int m = 0; m < 4; ++m) _Pragma("unroll") for (int n = 0; n < 2; ++n) _Pragma("unroll") for (int k = 0; k < 2; ++k) \
;         acc[ai][bj][m][n] = __builtin_amdgcn_mfma_f32_16x16x32_bf16(Bt[n][k], At[m][k], acc[ai][bj][m][n], 0, 0, 0); __builtin_amdgcn_s_setprio(0); } while (0)
; #define PG8_WAIT_V(n) asm volatile("s_waitcnt vmcnt(" #n ")" ::: "memory")
; #define PG8_WAIT_L(n) asm volatile("s_waitcnt lgkmcnt(" #n ")" ::: "memory")
; #define PG8_BAR __builtin_amdgcn_s_barrier()
; #define PG8_SCHED __builtin_amdgcn_sched_barrier(0)
; template <class Epi, class Sched, bool ALIGN_EPI = false, bool SP2 = false>
; __device__ __forceinline__ void gemm_phase(PG8_LAS unsigned char* lds, const Gemm g, const Sched& S, const Epi& E) {
;     ...
;             PG8_LDB(B0, 1, 0); PG8_LDB(B1, 1, 1); PG8_SCHED; PG8_LDA(At, 1, 0); PG8_STAGE(PG8_SA(0, 1), a2 + hstep, voffA);
;             PG8_WAIT_V(8); PG8_WAIT_L(0); PG8_BAR; PG8_MMA(0, 0, At, B0); PG8_MMA(0, 1, At, B1); PG8_BAR; PG8_SCHED;
	s_add_i32 s29, 0, 0x18000
	v_add_u32_e32 v136, s29, v156
	s_add_i32 s57, 0, 0x1c000
	ds_read_b128 v[150:153], v136
	ds_read_b128 v[162:165], v136 offset:1024
	ds_read_b128 v[166:169], v136 offset:2048
	ds_read_b128 v[170:173], v136 offset:3072
	v_add_u32_e32 v136, s57, v156
	ds_read_b128 v[174:177], v136
	ds_read_b128 v[178:181], v136 offset:1024
	ds_read_b128 v[182:185], v136 offset:2048
	ds_read_b128 v[190:193], v136 offset:3072
	s_add_u32 s88, s88, 0x80000
	s_addc_u32 s89, s89, 0
	s_mov_b32 m0, s33
	v_lshl_add_u64 v[230:231], s[88:89], 0, v[128:129]
	ds_read_b128 v[194:197], v160 offset:32768
	ds_read_b128 v[198:201], v160 offset:33792
	ds_read_b128 v[202:205], v160 offset:34816
	ds_read_b128 v[206:209], v160 offset:35840
	ds_read_b128 v[210:213], v160 offset:36864
	ds_read_b128 v[214:217], v160 offset:37888
	ds_read_b128 v[218:221], v160 offset:38912
	ds_read_b128 v[222:225], v160 offset:39936
	global_load_lds_dwordx4 v[230:231], off
	v_lshl_add_u64 v[230:231], s[88:89], 0, v[132:133]
	s_mov_b32 m0, s71
	s_nop 0
	global_load_lds_dwordx4 v[230:231], off
	s_waitcnt vmcnt(8)
	s_waitcnt lgkmcnt(0)
	s_barrier
	s_waitcnt lgkmcnt(0)
	v_mfma_f32_16x16x32_bf16 v[124:127], v[150:153], v[194:197], v[124:127]
	v_mfma_f32_16x16x32_bf16 v[116:119], v[166:169], v[194:197], v[116:119]
	v_mfma_f32_16x16x32_bf16 v[108:111], v[150:153], v[202:205], v[108:111]
	v_mfma_f32_16x16x32_bf16 v[100:103], v[166:169], v[202:205], v[100:103]
	v_mfma_f32_16x16x32_bf16 v[92:95], v[150:153], v[210:213], v[92:95]
	v_mfma_f32_16x16x32_bf16 v[84:87], v[166:169], v[210:213], v[84:87]
	v_mfma_f32_16x16x32_bf16 v[76:79], v[150:153], v[218:221], v[76:79]
	v_mfma_f32_16x16x32_bf16 v[68:71], v[166:169], v[218:221], v[68:71]
	v_mfma_f32_16x16x32_bf16 v[124:127], v[162:165], v[198:201], v[124:127]
	v_mfma_f32_16x16x32_bf16 v[116:119], v[170:173], v[198:201], v[116:119]
	v_mfma_f32_16x16x32_bf16 v[108:111], v[162:165], v[206:209], v[108:111]
	v_mfma_f32_16x16x32_bf16 v[100:103], v[170:173], v[206:209], v[100:103]
	v_mfma_f32_16x16x32_bf16 v[92:95], v[162:165], v[214:217], v[92:95]
	v_mfma_f32_16x16x32_bf16 v[84:87], v[170:173], v[214:217], v[84:87]
	v_mfma_f32_16x16x32_bf16 v[76:79], v[162:165], v[222:225], v[76:79]
	v_mfma_f32_16x16x32_bf16 v[68:71], v[170:173], v[222:225], v[68:71]
	v_mfma_f32_16x16x32_bf16 v[120:123], v[174:177], v[194:197], v[120:123]
	v_mfma_f32_16x16x32_bf16 v[112:115], v[182:185], v[194:197], v[112:115]
	v_mfma_f32_16x16x32_bf16 v[104:107], v[174:177], v[202:205], v[104:107]
	v_mfma_f32_16x16x32_bf16 v[96:99], v[182:185], v[202:205], v[96:99]
	v_mfma_f32_16x16x32_bf16 v[88:91], v[174:177], v[210:213], v[88:91]
	v_mfma_f32_16x16x32_bf16 v[80:83], v[182:185], v[210:213], v[80:83]
	v_mfma_f32_16x16x32_bf16 v[72:75], v[174:177], v[218:221], v[72:75]
	v_mfma_f32_16x16x32_bf16 v[64:67], v[182:185], v[218:221], v[64:67]
	v_mfma_f32_16x16x32_bf16 v[120:123], v[178:181], v[198:201], v[120:123]
	v_mfma_f32_16x16x32_bf16 v[112:115], v[190:193], v[198:201], v[112:115]
	v_mfma_f32_16x16x32_bf16 v[104:107], v[178:181], v[206:209], v[104:107]
	v_mfma_f32_16x16x32_bf16 v[96:99], v[190:193], v[206:209], v[96:99]
	v_mfma_f32_16x16x32_bf16 v[88:91], v[178:181], v[214:217], v[88:91]
	v_mfma_f32_16x16x32_bf16 v[80:83], v[190:193], v[214:217], v[80:83]
	v_mfma_f32_16x16x32_bf16 v[72:75], v[178:181], v[222:225], v[72:75]
	v_mfma_f32_16x16x32_bf16 v[64:67], v[190:193], v[222:225], v[64:67]
	s_barrier
; #define PG8_STAGE(bufoff, gbase, voff) do { _Pragma("unroll") for (int _i = 0; _i < 2; ++_i) \
;         __builtin_amdgcn_global_load_lds((const unsigned*)((const char*)(gbase) + (voff)[_i]), (PG8_LAS unsigned*)(lds + (bufoff) + ldsw + _i * 8192), 16, 0, 0); } while (0)
; #define PG8_LDA(dst, b, h) do { _Pragma("unroll") for (int m = 0; m < 4; ++m) _Pragma("unroll") for (int k = 0; k < 2; ++k) dst[m][k] = *(const PG8_LAS bf16x8*)(lds + PG8_SA(b, h) + aoff + m * 2048 + k * 1024); } while (0)
; #define PG8_MMA(ai, bj, At, Bt) do { __builtin_amdgcn_s_setprio(1); _Pragma("unroll") for (int m = 0; m < 4; ++m) _Pragma("unroll") for (int n = 0; n < 2; ++n) _Pragma("unroll") for (int k = 0; k < 2; ++k) \
;         acc[ai][bj][m][n] = __builtin_amdgcn_mfma_f32_16x16x32_bf16(Bt[n][k], At[m][k], acc[ai][bj][m][n], 0, 0, 0); __builtin_amdgcn_s_setprio(0); } while (0)
; #define PG8_WAIT_V(n) asm volatile("s_waitcnt vmcnt(" #n ")" ::: "memory")
; #define PG8_WAIT_L(n) asm volatile("s_waitcnt lgkmcnt(" #n ")" ::: "memory")
; #define PG8_BAR __builtin_amdgcn_s_barrier()
; #define PG8_SCHED __builtin_amdgcn_sched_barrier(0)
; template <class Epi, class Sched, bool ALIGN_EPI = false, bool SP2 = false>
; __device__ __forceinline__ void gemm_phase(PG8_LAS unsigned char* lds, const Gemm g, const Sched& S, const Epi& E) {
;     ...
;             PG8_LDA(At, 1, 1); PG8_STAGE(PG8_SB(1, 0), b3, voffB); PG8_STAGE(PG8_SB(1, 1), b3 + hstep, voffB); PG8_STAGE(PG8_SA(1, 0), a3, voffA);
;             PG8_WAIT_V(8); PG8_WAIT_L(0); PG8_BAR; PG8_MMA(1, 0, At, B0); PG8_MMA(1, 1, At, B1); PG8_BAR; PG8_SCHED;
;     ...
;         if constexpr (ALIGN_EPI) { if (wr == 0) PG8_BAR; }
	s_add_i32 s29, s29, s23
	v_lshl_add_u64 v[154:155], v[154:155], 0, s[8:9]
	s_mov_b32 m0, s29
	ds_read_b128 v[194:197], v160 offset:49152
	ds_read_b128 v[198:201], v160 offset:50176
	ds_read_b128 v[202:205], v160 offset:51200
	ds_read_b128 v[206:209], v160 offset:52224
	ds_read_b128 v[210:213], v160 offset:53248
	ds_read_b128 v[214:217], v160 offset:54272
	ds_read_b128 v[218:221], v160 offset:55296
	ds_read_b128 v[222:225], v160 offset:56320
	global_load_lds_dwordx4 v[154:155], off
	s_add_i32 m0, s29, 0x2000
	s_add_u32 s84, s84, 0x80080
	v_lshl_add_u64 v[154:155], v[186:187], 0, s[8:9]
	s_addc_u32 s85, s85, 0
	s_add_i32 s29, s57, s23
	global_load_lds_dwordx4 v[154:155], off
	v_lshl_add_u64 v[154:155], s[84:85], 0, v[130:131]
	s_mov_b32 m0, s29
	s_nop 0
	global_load_lds_dwordx4 v[154:155], off
	v_lshl_add_u64 v[154:155], s[84:85], 0, v[134:135]
	s_add_i32 m0, s29, 0x2000
	s_nop 0
	global_load_lds_dwordx4 v[154:155], off
	v_lshl_add_u64 v[154:155], v[226:227], 0, s[8:9]
	s_mov_b32 m0, s92
	s_nop 0
	global_load_lds_dwordx4 v[154:155], off
	v_lshl_add_u64 v[154:155], v[228:229], 0, s[8:9]
	s_mov_b32 m0, s93
	s_nop 0
	global_load_lds_dwordx4 v[154:155], off
	s_waitcnt vmcnt(8)
	s_waitcnt lgkmcnt(0)
	s_barrier
	s_waitcnt lgkmcnt(0)
	v_mfma_f32_16x16x32_bf16 v[60:63], v[150:153], v[194:197], v[60:63]
	v_mfma_f32_16x16x32_bf16 v[52:55], v[166:169], v[194:197], v[52:55]
	v_mfma_f32_16x16x32_bf16 v[44:47], v[150:153], v[202:205], v[44:47]
	v_mfma_f32_16x16x32_bf16 v[36:39], v[166:169], v[202:205], v[36:39]
	v_mfma_f32_16x16x32_bf16 v[28:31], v[150:153], v[210:213], v[28:31]
	v_mfma_f32_16x16x32_bf16 v[20:23], v[166:169], v[210:213], v[20:23]
	v_mfma_f32_16x16x32_bf16 v[12:15], v[150:153], v[218:221], v[12:15]
	v_mfma_f32_16x16x32_bf16 v[4:7], v[166:169], v[218:221], v[4:7]
	v_mfma_f32_16x16x32_bf16 v[60:63], v[162:165], v[198:201], v[60:63]
	v_mfma_f32_16x16x32_bf16 v[52:55], v[170:173], v[198:201], v[52:55]
	v_mfma_f32_16x16x32_bf16 v[44:47], v[162:165], v[206:209], v[44:47]
	v_mfma_f32_16x16x32_bf16 v[36:39], v[170:173], v[206:209], v[36:39]
	v_mfma_f32_16x16x32_bf16 v[28:31], v[162:165], v[214:217], v[28:31]
	v_mfma_f32_16x16x32_bf16 v[20:23], v[170:173], v[214:217], v[20:23]
	v_mfma_f32_16x16x32_bf16 v[12:15], v[162:165], v[222:225], v[12:15]
	v_mfma_f32_16x16x32_bf16 v[4:7], v[170:173], v[222:225], v[4:7]
	v_mfma_f32_16x16x32_bf16 v[56:59], v[174:177], v[194:197], v[56:59]
	v_mfma_f32_16x16x32_bf16 v[48:51], v[182:185], v[194:197], v[48:51]
	v_mfma_f32_16x16x32_bf16 v[40:43], v[174:177], v[202:205], v[40:43]
	v_mfma_f32_16x16x32_bf16 v[32:35], v[182:185], v[202:205], v[32:35]
	v_mfma_f32_16x16x32_bf16 v[24:27], v[174:177], v[210:213], v[24:27]
	v_mfma_f32_16x16x32_bf16 v[16:19], v[182:185], v[210:213], v[16:19]
	v_mfma_f32_16x16x32_bf16 v[8:11], v[174:177], v[218:221], v[8:11]
	v_mfma_f32_16x16x32_bf16 v[0:3], v[182:185], v[218:221], v[0:3]
	v_mfma_f32_16x16x32_bf16 v[56:59], v[178:181], v[198:201], v[56:59]
	v_mfma_f32_16x16x32_bf16 v[48:51], v[190:193], v[198:201], v[48:51]
	v_mfma_f32_16x16x32_bf16 v[40:43], v[178:181], v[206:209], v[40:43]
	v_mfma_f32_16x16x32_bf16 v[32:35], v[190:193], v[206:209], v[32:35]
	v_mfma_f32_16x16x32_bf16 v[24:27], v[178:181], v[214:217], v[24:27]
	v_mfma_f32_16x16x32_bf16 v[16:19], v[190:193], v[214:217], v[16:19]
	v_mfma_f32_16x16x32_bf16 v[8:11], v[178:181], v[222:225], v[8:11]
	v_mfma_f32_16x16x32_bf16 v[0:3], v[190:193], v[222:225], v[0:3]
	s_barrier
	s_add_i32 s28, s28, 2
	s_add_u32 s74, s74, 0x100
	s_addc_u32 s75, s75, 0
	s_add_u32 s13, s13, 0x100
	s_addc_u32 s15, s15, 0
	s_cmp_gt_u32 s28, 29
	s_cbranch_scc0 .LBB0_276
	s_and_b64 vcc, exec, s[10:11]
	s_cbranch_vccz .LBB0_279
	s_barrier

; #define PG8_STAGE(bufoff, gbase, voff) do { _Pragma("unroll") for (int _i = 0; _i < 2; ++_i) \
;         __builtin_amdgcn_global_load_lds((const unsigned*)((const char*)(gbase) + (voff)[_i]), (PG8_LAS unsigned*)(lds + (bufoff) + ldsw + _i * 8192), 16, 0, 0); } while (0)
; #define PG8_LDA(dst, b, h) do { _Pragma("unroll") for (int m = 0; m < 4; ++m) _Pragma("unroll") for (int k = 0; k < 2; ++k) dst[m][k] = *(const PG8_LAS bf16x8*)(lds + PG8_SA(b, h) + aoff + m * 2048 + k * 1024); } while (0)
; #define PG8_LDB(dst, b, h) do { _Pragma("unroll") for (int n = 0; n < 2; ++n) _Pragma("unroll") for (int k = 0; k < 2; ++k) dst[n][k] = *(const PG8_LAS bf16x8*)(lds + PG8_SB(b, h) + boff + n * 2048 + k * 1024); } while (0)
; #define PG8_MMA(ai, bj, At, Bt) do { __builtin_amdgcn_s_setprio(1); _Pragma("unroll") for (int m = 0; m < 4; ++m) _Pragma("unroll") for (int n = 0; n < 2; ++n) _Pragma("unroll") for (int k = 0; k < 2; ++k) \
;         acc[ai][bj][m][n] = __builtin_amdgcn_mfma_f32_16x16x32_bf16(Bt[n][k], At[m][k], acc[ai][bj][m][n], 0, 0, 0); __builtin_amdgcn_s_setprio(0); } while (0)
; #define PG8_WAIT_V(n) asm volatile("s_waitcnt vmcnt(" #n ")" ::: "memory")
; #define PG8_WAIT_L(n) asm volatile("s_waitcnt lgkmcnt(" #n ")" ::: "memory")
; #define PG8_BAR __builtin_amdgcn_s_barrier()
; template <class Epi, class Sched, bool ALIGN_EPI = false, bool SP2 = false>
; __device__ __forceinline__ void gemm_phase(PG8_LAS unsigned char* lds, const Gemm g, const Sched& S, const Epi& E) {
;     ...
;             const char* a1 = cA + (size_t)(t + 1) * kstep;
;             const char* a2 = last ? nA : cA + (size_t)(t + 2) * kstep; const char* b2 = last ? nB : cB + (size_t)(t + 2) * kstep;
;             const char* a3 = a2 + kstep; const char* b3 = b2 + kstep;
;             if (last && has_next) S.a_ready(nxt);
;             if constexpr (SP2) {
;             PG8_LDB(B0, 0, 0); PG8_LDB(B1, 0, 1); PG8_SCHED; PG8_LDA(At, 0, 0); PG8_STAGE(PG8_SA(1, 1), a1 + hstep, voffA);
;             PG8_WAIT_V(8); PG8_WAIT_L(0); PG8_BAR; PG8_MMA(0, 0, At, B0); PG8_MMA(0, 1, At, B1); PG8_BAR; PG8_SCHED;
;             PG8_LDA(At, 0, 1); PG8_STAGE(PG8_SB(0, 0), b2, voffB); PG8_STAGE(PG8_SB(0, 1), b2 + hstep, voffB); PG8_STAGE(PG8_SA(0, 0), a2, voffA);
;             PG8_WAIT_V(8); PG8_WAIT_L(0); PG8_BAR; PG8_MMA(1, 0, At, B0); PG8_MMA(1, 1, At, B1); PG8_BAR; PG8_SCHED;
.LBB0_519:
	s_add_u32 s0, s40, 0x100
	s_addc_u32 s1, s41, 0
	s_mov_b32 s97, -2
	ds_read_b128 v[140:143], v150
	ds_read_b128 v[144:147], v150 offset:1024
	ds_read_b128 v[156:159], v150 offset:2048
	ds_read_b128 v[160:163], v150 offset:3072
	ds_read_b128 v[164:167], v151
	ds_read_b128 v[168:171], v151 offset:1024
	ds_read_b128 v[172:175], v151 offset:2048
	ds_read_b128 v[176:179], v151 offset:3072
	s_add_u32 s40, s14, 0x100
	s_addc_u32 s41, s15, 0
	s_cmp_eq_u32 s97, 8
	s_cselect_b32 s65, s13, s41
	s_cselect_b32 s64, s12, s40
	s_cselect_b32 s47, s3, s1
	s_cselect_b32 s46, s2, s0
	s_mov_b32 m0, s77
	v_lshl_add_u64 v[210:211], s[14:15], 0, v[136:137]
	ds_read_b128 v[180:183], v152
	ds_read_b128 v[184:187], v152 offset:1024
	ds_read_b128 v[190:193], v152 offset:2048
	ds_read_b128 v[194:197], v152 offset:3072
	ds_read_b128 v[198:201], v152 offset:4096
	ds_read_b128 v[202:205], v152 offset:5120
	ds_read_b128 v[206:209], v152 offset:6144
	ds_read_b128 v[214:217], v152 offset:7168
	global_load_lds_dwordx4 v[210:211], off
	v_lshl_add_u64 v[210:211], s[14:15], 0, v[138:139]
	s_mov_b32 m0, s78
	s_nop 0
	global_load_lds_dwordx4 v[210:211], off
	s_waitcnt vmcnt(8)
	s_waitcnt lgkmcnt(0)
	s_barrier
	s_waitcnt lgkmcnt(0)
	v_mfma_f32_16x16x32_bf16 v[124:127], v[140:143], v[180:183], 0
	v_mfma_f32_16x16x32_bf16 v[120:123], v[156:159], v[180:183], 0
	v_mfma_f32_16x16x32_bf16 v[108:111], v[140:143], v[190:193], 0
	v_mfma_f32_16x16x32_bf16 v[104:107], v[156:159], v[190:193], 0
	v_mfma_f32_16x16x32_bf16 v[92:95], v[140:143], v[198:201], 0
	v_mfma_f32_16x16x32_bf16 v[88:91], v[156:159], v[198:201], 0
	v_mfma_f32_16x16x32_bf16 v[76:79], v[140:143], v[206:209], 0
	v_mfma_f32_16x16x32_bf16 v[72:75], v[156:159], v[206:209], 0
	v_mfma_f32_16x16x32_bf16 v[124:127], v[144:147], v[184:187], v[124:127]
	v_mfma_f32_16x16x32_bf16 v[120:123], v[160:163], v[184:187], v[120:123]
	v_mfma_f32_16x16x32_bf16 v[108:111], v[144:147], v[194:197], v[108:111]
	v_mfma_f32_16x16x32_bf16 v[104:107], v[160:163], v[194:197], v[104:107]
	v_mfma_f32_16x16x32_bf16 v[92:95], v[144:147], v[202:205], v[92:95]
	v_mfma_f32_16x16x32_bf16 v[88:91], v[160:163], v[202:205], v[88:91]
	v_mfma_f32_16x16x32_bf16 v[76:79], v[144:147], v[214:217], v[76:79]
	v_mfma_f32_16x16x32_bf16 v[72:75], v[160:163], v[214:217], v[72:75]
	v_mfma_f32_16x16x32_bf16 v[116:119], v[164:167], v[180:183], 0
	v_mfma_f32_16x16x32_bf16 v[112:115], v[172:175], v[180:183], 0
	v_mfma_f32_16x16x32_bf16 v[100:103], v[164:167], v[190:193], 0
	v_mfma_f32_16x16x32_bf16 v[96:99], v[172:175], v[190:193], 0
	v_mfma_f32_16x16x32_bf16 v[84:87], v[164:167], v[198:201], 0
	v_mfma_f32_16x16x32_bf16 v[80:83], v[172:175], v[198:201], 0
	v_mfma_f32_16x16x32_bf16 v[68:71], v[164:167], v[206:209], 0
	v_mfma_f32_16x16x32_bf16 v[64:67], v[172:175], v[206:209], 0
	v_mfma_f32_16x16x32_bf16 v[116:119], v[168:171], v[184:187], v[116:119]
	v_mfma_f32_16x16x32_bf16 v[112:115], v[176:179], v[184:187], v[112:115]
	v_mfma_f32_16x16x32_bf16 v[100:103], v[168:171], v[194:197], v[100:103]
	v_mfma_f32_16x16x32_bf16 v[96:99], v[176:179], v[194:197], v[96:99]
	v_mfma_f32_16x16x32_bf16 v[84:87], v[168:171], v[202:205], v[84:87]
	v_mfma_f32_16x16x32_bf16 v[80:83], v[176:179], v[202:205], v[80:83]
	v_mfma_f32_16x16x32_bf16 v[68:71], v[168:171], v[214:217], v[68:71]
	v_mfma_f32_16x16x32_bf16 v[64:67], v[176:179], v[214:217], v[64:67]
	s_barrier
	s_mov_b32 m0, s79
	v_lshl_add_u64 v[210:211], s[46:47], 0, v[132:133]
	s_add_u32 s14, s46, 0x30000
	ds_read_b128 v[180:183], v152 offset:16384
	ds_read_b128 v[184:187], v152 offset:17408
	ds_read_b128 v[190:193], v152 offset:18432
	ds_read_b128 v[194:197], v152 offset:19456
	ds_read_b128 v[198:201], v152 offset:20480
	ds_read_b128 v[202:205], v152 offset:21504
	ds_read_b128 v[206:209], v152 offset:22528
	ds_read_b128 v[214:217], v152 offset:23552
	global_load_lds_dwordx4 v[210:211], off
	v_lshl_add_u64 v[218:219], s[46:47], 0, v[128:129]
	s_mov_b32 m0, s80
	s_addc_u32 s15, s47, 0
	global_load_lds_dwordx4 v[218:219], off
	v_lshl_add_u64 v[220:221], s[14:15], 0, v[132:133]
	s_mov_b32 m0, s81
	v_lshl_add_u64 v[222:223], s[64:65], 0, v[130:131]
	global_load_lds_dwordx4 v[220:221], off
	v_lshl_add_u64 v[220:221], s[14:15], 0, v[128:129]
	s_mov_b32 m0, s82
	s_nop 0
	global_load_lds_dwordx4 v[220:221], off
	v_lshl_add_u64 v[220:221], s[64:65], 0, v[134:135]
	s_mov_b32 m0, s56
	s_nop 0
	global_load_lds_dwordx4 v[220:221], off
	s_mov_b32 m0, s57
	s_nop 0
	global_load_lds_dwordx4 v[222:223], off
	s_waitcnt vmcnt(8)
	s_waitcnt lgkmcnt(0)
	s_barrier
	s_waitcnt lgkmcnt(0)
	v_mfma_f32_16x16x32_bf16 v[60:63], v[140:143], v[180:183], 0
	v_mfma_f32_16x16x32_bf16 v[56:59], v[156:159], v[180:183], 0
	v_mfma_f32_16x16x32_bf16 v[44:47], v[140:143], v[190:193], 0
	v_mfma_f32_16x16x32_bf16 v[40:43], v[156:159], v[190:193], 0
	v_mfma_f32_16x16x32_bf16 v[28:31], v[140:143], v[198:201], 0
	v_mfma_f32_16x16x32_bf16 v[24:27], v[156:159], v[198:201], 0
	v_mfma_f32_16x16x32_bf16 v[12:15], v[140:143], v[206:209], 0
	v_mfma_f32_16x16x32_bf16 v[8:11], v[156:159], v[206:209], 0
	v_mfma_f32_16x16x32_bf16 v[60:63], v[144:147], v[184:187], v[60:63]
	v_mfma_f32_16x16x32_bf16 v[56:59], v[160:163], v[184:187], v[56:59]
	v_mfma_f32_16x16x32_bf16 v[44:47], v[144:147], v[194:197], v[44:47]
	v_mfma_f32_16x16x32_bf16 v[40:43], v[160:163], v[194:197], v[40:43]
	v_mfma_f32_16x16x32_bf16 v[28:31], v[144:147], v[202:205], v[28:31]
	v_mfma_f32_16x16x32_bf16 v[24:27], v[160:163], v[202:205], v[24:27]
	v_mfma_f32_16x16x32_bf16 v[12:15], v[144:147], v[214:217], v[12:15]
	v_mfma_f32_16x16x32_bf16 v[8:11], v[160:163], v[214:217], v[8:11]
	v_mfma_f32_16x16x32_bf16 v[52:55], v[164:167], v[180:183], 0
	v_mfma_f32_16x16x32_bf16 v[48:51], v[172:175], v[180:183], 0
	v_mfma_f32_16x16x32_bf16 v[36:39], v[164:167], v[190:193], 0
	v_mfma_f32_16x16x32_bf16 v[32:35], v[172:175], v[190:193], 0
	v_mfma_f32_16x16x32_bf16 v[20:23], v[164:167], v[198:201], 0
	v_mfma_f32_16x16x32_bf16 v[16:19], v[172:175], v[198:201], 0
	v_mfma_f32_16x16x32_bf16 v[4:7], v[164:167], v[206:209], 0
	v_mfma_f32_16x16x32_bf16 v[0:3], v[172:175], v[206:209], 0
	v_mfma_f32_16x16x32_bf16 v[52:55], v[168:171], v[184:187], v[52:55]
	v_mfma_f32_16x16x32_bf16 v[48:51], v[176:179], v[184:187], v[48:51]
	v_mfma_f32_16x16x32_bf16 v[36:39], v[168:171], v[194:197], v[36:39]
	v_mfma_f32_16x16x32_bf16 v[32:35], v[176:179], v[194:197], v[32:35]
	v_mfma_f32_16x16x32_bf16 v[20:23], v[168:171], v[202:205], v[20:23]
	v_mfma_f32_16x16x32_bf16 v[16:19], v[176:179], v[202:205], v[16:19]
	v_mfma_f32_16x16x32_bf16 v[4:7], v[168:171], v[214:217], v[4:7]
	v_mfma_f32_16x16x32_bf16 v[0:3], v[176:179], v[214:217], v[0:3]
	s_barrier
; #define PG8_STAGE(bufoff, gbase, voff) do { _Pragma("unroll") for (int _i = 0; _i < 2; ++_i) \
;         __builtin_amdgcn_global_load_lds((const unsigned*)((const char*)(gbase) + (voff)[_i]), (PG8_LAS unsigned*)(lds + (bufoff) + ldsw + _i * 8192), 16, 0, 0); } while (0)
; #define PG8_LDA(dst, b, h) do { _Pragma("unroll") for (int m = 0; m < 4; ++m) _Pragma("unroll") for (int k = 0; k < 2; ++k) dst[m][k] = *(const PG8_LAS bf16x8*)(lds + PG8_SA(b, h) + aoff + m * 2048 + k * 1024); } while (0)
; #define PG8_LDB(dst, b, h) do { _Pragma("unroll") for (int n = 0; n < 2; ++n) _Pragma("unroll") for (int k = 0; k < 2; ++k) dst[n][k] = *(const PG8_LAS bf16x8*)(lds + PG8_SB(b, h) + boff + n * 2048 + k * 1024); } while (0)
; #define PG8_MMA(ai, bj, At, Bt) do { __builtin_amdgcn_s_setprio(1); _Pragma("unroll") for (int m = 0; m < 4; ++m) _Pragma("unroll") for (int n = 0; n < 2; ++n) _Pragma("unroll") for (int k = 0; k < 2; ++k) \
;         acc[ai][bj][m][n] = __builtin_amdgcn_mfma_f32_16x16x32_bf16(Bt[n][k], At[m][k], acc[ai][bj][m][n], 0, 0, 0); __builtin_amdgcn_s_setprio(0); } while (0)
; #define PG8_WAIT_V(n) asm volatile("s_waitcnt vmcnt(" #n ")" ::: "memory")
; #define PG8_WAIT_L(n) asm volatile("s_waitcnt lgkmcnt(" #n ")" ::: "memory")
; #define PG8_BAR __builtin_amdgcn_s_barrier()
; #define PG8_SCHED __builtin_amdgcn_sched_barrier(0)
; template <class Epi, class Sched, bool ALIGN_EPI = false, bool SP2 = false>
; __device__ __forceinline__ void gemm_phase(PG8_LAS unsigned char* lds, const Gemm g, const Sched& S, const Epi& E) {
;     ...
;             PG8_LDB(B0, 1, 0); PG8_LDB(B1, 1, 1); PG8_SCHED; PG8_LDA(At, 1, 0); PG8_STAGE(PG8_SA(0, 1), a2 + hstep, voffA);
;             PG8_WAIT_V(8); PG8_WAIT_L(0); PG8_BAR; PG8_MMA(0, 0, At, B0); PG8_MMA(0, 1, At, B1); PG8_BAR; PG8_SCHED;
;             PG8_LDA(At, 1, 1); PG8_STAGE(PG8_SB(1, 0), b3, voffB); PG8_STAGE(PG8_SB(1, 1), b3 + hstep, voffB); PG8_STAGE(PG8_SA(1, 0), a3, voffA);
;             PG8_WAIT_V(8); PG8_WAIT_L(0); PG8_BAR; PG8_MMA(1, 0, At, B0); PG8_MMA(1, 1, At, B1); PG8_BAR; PG8_SCHED;
	ds_read_b128 v[140:143], v153
	ds_read_b128 v[144:147], v153 offset:1024
	ds_read_b128 v[156:159], v153 offset:2048
	ds_read_b128 v[160:163], v153 offset:3072
	ds_read_b128 v[164:167], v154
	ds_read_b128 v[168:171], v154 offset:1024
	ds_read_b128 v[172:175], v154 offset:2048
	ds_read_b128 v[176:179], v154 offset:3072
	s_add_u32 s14, s64, 0x30000
	s_addc_u32 s15, s65, 0
	s_mov_b32 m0, s66
	v_lshl_add_u64 v[224:225], s[14:15], 0, v[134:135]
	ds_read_b128 v[180:183], v152 offset:32768
	ds_read_b128 v[184:187], v152 offset:33792
	ds_read_b128 v[190:193], v152 offset:34816
	ds_read_b128 v[194:197], v152 offset:35840
	ds_read_b128 v[198:201], v152 offset:36864
	ds_read_b128 v[202:205], v152 offset:37888
	ds_read_b128 v[206:209], v152 offset:38912
	ds_read_b128 v[214:217], v152 offset:39936
	global_load_lds_dwordx4 v[224:225], off
	v_lshl_add_u64 v[224:225], s[14:15], 0, v[130:131]
	s_mov_b32 m0, s67
	s_nop 0
	global_load_lds_dwordx4 v[224:225], off
	s_waitcnt vmcnt(8)
	s_waitcnt lgkmcnt(0)
	s_barrier
	s_waitcnt lgkmcnt(0)
	v_mfma_f32_16x16x32_bf16 v[124:127], v[140:143], v[180:183], v[124:127]
	v_mfma_f32_16x16x32_bf16 v[120:123], v[156:159], v[180:183], v[120:123]
	v_mfma_f32_16x16x32_bf16 v[108:111], v[140:143], v[190:193], v[108:111]
	v_mfma_f32_16x16x32_bf16 v[104:107], v[156:159], v[190:193], v[104:107]
	v_mfma_f32_16x16x32_bf16 v[92:95], v[140:143], v[198:201], v[92:95]
	v_mfma_f32_16x16x32_bf16 v[88:91], v[156:159], v[198:201], v[88:91]
	v_mfma_f32_16x16x32_bf16 v[76:79], v[140:143], v[206:209], v[76:79]
	v_mfma_f32_16x16x32_bf16 v[72:75], v[156:159], v[206:209], v[72:75]
	v_mfma_f32_16x16x32_bf16 v[124:127], v[144:147], v[184:187], v[124:127]
	v_mfma_f32_16x16x32_bf16 v[120:123], v[160:163], v[184:187], v[120:123]
	v_mfma_f32_16x16x32_bf16 v[108:111], v[144:147], v[194:197], v[108:111]
	v_mfma_f32_16x16x32_bf16 v[104:107], v[160:163], v[194:197], v[104:107]
	v_mfma_f32_16x16x32_bf16 v[92:95], v[144:147], v[202:205], v[92:95]
	v_mfma_f32_16x16x32_bf16 v[88:91], v[160:163], v[202:205], v[88:91]
	v_mfma_f32_16x16x32_bf16 v[76:79], v[144:147], v[214:217], v[76:79]
	v_mfma_f32_16x16x32_bf16 v[72:75], v[160:163], v[214:217], v[72:75]
	v_mfma_f32_16x16x32_bf16 v[116:119], v[164:167], v[180:183], v[116:119]
	v_mfma_f32_16x16x32_bf16 v[112:115], v[172:175], v[180:183], v[112:115]
	v_mfma_f32_16x16x32_bf16 v[100:103], v[164:167], v[190:193], v[100:103]
	v_mfma_f32_16x16x32_bf16 v[96:99], v[172:175], v[190:193], v[96:99]
	v_mfma_f32_16x16x32_bf16 v[84:87], v[164:167], v[198:201], v[84:87]
	v_mfma_f32_16x16x32_bf16 v[80:83], v[172:175], v[198:201], v[80:83]
	v_mfma_f32_16x16x32_bf16 v[68:71], v[164:167], v[206:209], v[68:71]
	v_mfma_f32_16x16x32_bf16 v[64:67], v[172:175], v[206:209], v[64:67]
	v_mfma_f32_16x16x32_bf16 v[116:119], v[168:171], v[184:187], v[116:119]
	v_mfma_f32_16x16x32_bf16 v[112:115], v[176:179], v[184:187], v[112:115]
	v_mfma_f32_16x16x32_bf16 v[100:103], v[168:171], v[194:197], v[100:103]
	v_mfma_f32_16x16x32_bf16 v[96:99], v[176:179], v[194:197], v[96:99]
	v_mfma_f32_16x16x32_bf16 v[84:87], v[168:171], v[202:205], v[84:87]
	v_mfma_f32_16x16x32_bf16 v[80:83], v[176:179], v[202:205], v[80:83]
	v_mfma_f32_16x16x32_bf16 v[68:71], v[168:171], v[214:217], v[68:71]
	v_mfma_f32_16x16x32_bf16 v[64:67], v[176:179], v[214:217], v[64:67]
	s_barrier
	s_add_i32 s14, s75, s33
	v_lshl_add_u64 v[210:211], v[210:211], 0, s[8:9]
	s_mov_b32 m0, s14
	ds_read_b128 v[180:183], v152 offset:49152
	ds_read_b128 v[184:187], v152 offset:50176
	ds_read_b128 v[190:193], v152 offset:51200
	ds_read_b128 v[194:197], v152 offset:52224
	ds_read_b128 v[198:201], v152 offset:53248
	ds_read_b128 v[202:205], v152 offset:54272
	ds_read_b128 v[206:209], v152 offset:55296
	ds_read_b128 v[214:217], v152 offset:56320
	global_load_lds_dwordx4 v[210:211], off
	s_add_i32 m0, s14, 0x2000
	s_add_u32 s14, s46, 0x30080
	v_lshl_add_u64 v[210:211], v[218:219], 0, s[8:9]
	s_addc_u32 s15, s47, 0
	s_add_i32 s46, s84, s33
	global_load_lds_dwordx4 v[210:211], off
	v_lshl_add_u64 v[210:211], s[14:15], 0, v[132:133]
	s_mov_b32 m0, s46
	s_nop 0
	global_load_lds_dwordx4 v[210:211], off
	v_lshl_add_u64 v[210:211], s[14:15], 0, v[128:129]
	s_add_i32 m0, s46, 0x2000
	s_nop 0
	global_load_lds_dwordx4 v[210:211], off
	v_lshl_add_u64 v[210:211], v[220:221], 0, s[8:9]
	s_mov_b32 m0, s68
	s_nop 0
	global_load_lds_dwordx4 v[210:211], off
	v_lshl_add_u64 v[210:211], v[222:223], 0, s[8:9]
	s_mov_b32 m0, s69
	s_nop 0
	global_load_lds_dwordx4 v[210:211], off
	s_waitcnt vmcnt(8)
	s_waitcnt lgkmcnt(0)
	s_barrier
	s_waitcnt lgkmcnt(0)
	v_mfma_f32_16x16x32_bf16 v[60:63], v[140:143], v[180:183], v[60:63]
	v_mfma_f32_16x16x32_bf16 v[56:59], v[156:159], v[180:183], v[56:59]
	v_mfma_f32_16x16x32_bf16 v[44:47], v[140:143], v[190:193], v[44:47]
	v_mfma_f32_16x16x32_bf16 v[40:43], v[156:159], v[190:193], v[40:43]
	v_mfma_f32_16x16x32_bf16 v[28:31], v[140:143], v[198:201], v[28:31]
	v_mfma_f32_16x16x32_bf16 v[24:27], v[156:159], v[198:201], v[24:27]
	v_mfma_f32_16x16x32_bf16 v[12:15], v[140:143], v[206:209], v[12:15]
	v_mfma_f32_16x16x32_bf16 v[8:11], v[156:159], v[206:209], v[8:11]
	v_mfma_f32_16x16x32_bf16 v[60:63], v[144:147], v[184:187], v[60:63]
	v_mfma_f32_16x16x32_bf16 v[56:59], v[160:163], v[184:187], v[56:59]
	v_mfma_f32_16x16x32_bf16 v[44:47], v[144:147], v[194:197], v[44:47]
	v_mfma_f32_16x16x32_bf16 v[40:43], v[160:163], v[194:197], v[40:43]
	v_mfma_f32_16x16x32_bf16 v[28:31], v[144:147], v[202:205], v[28:31]
	v_mfma_f32_16x16x32_bf16 v[24:27], v[160:163], v[202:205], v[24:27]
	v_mfma_f32_16x16x32_bf16 v[12:15], v[144:147], v[214:217], v[12:15]
	v_mfma_f32_16x16x32_bf16 v[8:11], v[160:163], v[214:217], v[8:11]
	v_mfma_f32_16x16x32_bf16 v[52:55], v[164:167], v[180:183], v[52:55]
	v_mfma_f32_16x16x32_bf16 v[48:51], v[172:175], v[180:183], v[48:51]
	v_mfma_f32_16x16x32_bf16 v[36:39], v[164:167], v[190:193], v[36:39]
	v_mfma_f32_16x16x32_bf16 v[32:35], v[172:175], v[190:193], v[32:35]
	v_mfma_f32_16x16x32_bf16 v[20:23], v[164:167], v[198:201], v[20:23]
	v_mfma_f32_16x16x32_bf16 v[16:19], v[172:175], v[198:201], v[16:19]
	v_mfma_f32_16x16x32_bf16 v[4:7], v[164:167], v[206:209], v[4:7]
	v_mfma_f32_16x16x32_bf16 v[0:3], v[172:175], v[206:209], v[0:3]
	v_mfma_f32_16x16x32_bf16 v[52:55], v[168:171], v[184:187], v[52:55]
	v_mfma_f32_16x16x32_bf16 v[48:51], v[176:179], v[184:187], v[48:51]
	v_mfma_f32_16x16x32_bf16 v[36:39], v[168:171], v[194:197], v[36:39]
	v_mfma_f32_16x16x32_bf16 v[32:35], v[176:179], v[194:197], v[32:35]
	v_mfma_f32_16x16x32_bf16 v[20:23], v[168:171], v[202:205], v[20:23]
	v_mfma_f32_16x16x32_bf16 v[16:19], v[176:179], v[202:205], v[16:19]
	v_mfma_f32_16x16x32_bf16 v[4:7], v[168:171], v[214:217], v[4:7]
	v_mfma_f32_16x16x32_bf16 v[0:3], v[176:179], v[214:217], v[0:3]
	s_barrier
	s_add_i32 s97, s97, 2
	s_add_u32 s0, s0, 0x100
	s_addc_u32 s1, s1, 0
	s_cmp_gt_u32 s97, 9
	s_mov_b64 s[14:15], s[40:41]
; #define PG8_STAGE(bufoff, gbase, voff) do { _Pragma("unroll") for (int _i = 0; _i < 2; ++_i) \
;         __builtin_amdgcn_global_load_lds((const unsigned*)((const char*)(gbase) + (voff)[_i]), (PG8_LAS unsigned*)(lds + (bufoff) + ldsw + _i * 8192), 16, 0, 0); } while (0)
; #define PG8_LDA(dst, b, h) do { _Pragma("unroll") for (int m = 0; m < 4; ++m) _Pragma("unroll") for (int k = 0; k < 2; ++k) dst[m][k] = *(const PG8_LAS bf16x8*)(lds + PG8_SA(b, h) + aoff + m * 2048 + k * 1024); } while (0)
; #define PG8_LDB(dst, b, h) do { _Pragma("unroll") for (int n = 0; n < 2; ++n) _Pragma("unroll") for (int k = 0; k < 2; ++k) dst[n][k] = *(const PG8_LAS bf16x8*)(lds + PG8_SB(b, h) + boff + n * 2048 + k * 1024); } while (0)
; #define PG8_MMA(ai, bj, At, Bt) do { __builtin_amdgcn_s_setprio(1); _Pragma("unroll") for (int m = 0; m < 4; ++m) _Pragma("unroll") for (int n = 0; n < 2; ++n) _Pragma("unroll") for (int k = 0; k < 2; ++k) \
;         acc[ai][bj][m][n] = __builtin_amdgcn_mfma_f32_16x16x32_bf16(Bt[n][k], At[m][k], acc[ai][bj][m][n], 0, 0, 0); __builtin_amdgcn_s_setprio(0); } while (0)
; #define PG8_WAIT_V(n) asm volatile("s_waitcnt vmcnt(" #n ")" ::: "memory")
; #define PG8_WAIT_L(n) asm volatile("s_waitcnt lgkmcnt(" #n ")" ::: "memory")
; #define PG8_BAR __builtin_amdgcn_s_barrier()
; #define PG8_SCHED __builtin_amdgcn_sched_barrier(0)
; template <class Epi, class Sched, bool ALIGN_EPI = false, bool SP2 = false>
; __device__ __forceinline__ void gemm_phase(PG8_LAS unsigned char* lds, const Gemm g, const Sched& S, const Epi& E) {
;     ...
;             if constexpr (SP2) {
;             PG8_LDB(B0, 0, 0); PG8_LDB(B1, 0, 1); PG8_SCHED; PG8_LDA(At, 0, 0); PG8_STAGE(PG8_SA(1, 1), a1 + hstep, voffA);
;             PG8_WAIT_V(8); PG8_WAIT_L(0); PG8_BAR; PG8_MMA(0, 0, At, B0); PG8_MMA(0, 1, At, B1); PG8_BAR; PG8_SCHED;
;             PG8_LDA(At, 0, 1); PG8_STAGE(PG8_SB(0, 0), b2, voffB); PG8_STAGE(PG8_SB(0, 1), b2 + hstep, voffB); PG8_STAGE(PG8_SA(0, 0), a2, voffA);
;             PG8_WAIT_V(8); PG8_WAIT_L(0); PG8_BAR; PG8_MMA(1, 0, At, B0); PG8_MMA(1, 1, At, B1); PG8_BAR; PG8_SCHED;
.LBB0_520:
	ds_read_b128 v[140:143], v150
	ds_read_b128 v[144:147], v150 offset:1024
	ds_read_b128 v[156:159], v150 offset:2048
	ds_read_b128 v[160:163], v150 offset:3072
	ds_read_b128 v[164:167], v151
	ds_read_b128 v[168:171], v151 offset:1024
	ds_read_b128 v[172:175], v151 offset:2048
	ds_read_b128 v[176:179], v151 offset:3072
	s_add_u32 s40, s14, 0x100
	s_addc_u32 s41, s15, 0
	s_cmp_eq_u32 s97, 8
	s_cselect_b32 s65, s13, s41
	s_cselect_b32 s64, s12, s40
	s_cselect_b32 s47, s3, s1
	s_cselect_b32 s46, s2, s0
	s_mov_b32 m0, s77
	v_lshl_add_u64 v[210:211], s[14:15], 0, v[136:137]
	ds_read_b128 v[180:183], v152
	ds_read_b128 v[184:187], v152 offset:1024
	ds_read_b128 v[190:193], v152 offset:2048
	ds_read_b128 v[194:197], v152 offset:3072
	ds_read_b128 v[198:201], v152 offset:4096
	ds_read_b128 v[202:205], v152 offset:5120
	ds_read_b128 v[206:209], v152 offset:6144
	ds_read_b128 v[214:217], v152 offset:7168
	global_load_lds_dwordx4 v[210:211], off
	v_lshl_add_u64 v[210:211], s[14:15], 0, v[138:139]
	s_mov_b32 m0, s78
	s_nop 0
	global_load_lds_dwordx4 v[210:211], off
	s_waitcnt vmcnt(8)
	s_waitcnt lgkmcnt(0)
	s_barrier
	s_waitcnt lgkmcnt(0)
	v_mfma_f32_16x16x32_bf16 v[124:127], v[140:143], v[180:183], v[124:127]
	v_mfma_f32_16x16x32_bf16 v[120:123], v[156:159], v[180:183], v[120:123]
	v_mfma_f32_16x16x32_bf16 v[108:111], v[140:143], v[190:193], v[108:111]
	v_mfma_f32_16x16x32_bf16 v[104:107], v[156:159], v[190:193], v[104:107]
	v_mfma_f32_16x16x32_bf16 v[92:95], v[140:143], v[198:201], v[92:95]
	v_mfma_f32_16x16x32_bf16 v[88:91], v[156:159], v[198:201], v[88:91]
	v_mfma_f32_16x16x32_bf16 v[76:79], v[140:143], v[206:209], v[76:79]
	v_mfma_f32_16x16x32_bf16 v[72:75], v[156:159], v[206:209], v[72:75]
	v_mfma_f32_16x16x32_bf16 v[124:127], v[144:147], v[184:187], v[124:127]
	v_mfma_f32_16x16x32_bf16 v[120:123], v[160:163], v[184:187], v[120:123]
	v_mfma_f32_16x16x32_bf16 v[108:111], v[144:147], v[194:197], v[108:111]
	v_mfma_f32_16x16x32_bf16 v[104:107], v[160:163], v[194:197], v[104:107]
	v_mfma_f32_16x16x32_bf16 v[92:95], v[144:147], v[202:205], v[92:95]
	v_mfma_f32_16x16x32_bf16 v[88:91], v[160:163], v[202:205], v[88:91]
	v_mfma_f32_16x16x32_bf16 v[76:79], v[144:147], v[214:217], v[76:79]
	v_mfma_f32_16x16x32_bf16 v[72:75], v[160:163], v[214:217], v[72:75]
	v_mfma_f32_16x16x32_bf16 v[116:119], v[164:167], v[180:183], v[116:119]
	v_mfma_f32_16x16x32_bf16 v[112:115], v[172:175], v[180:183], v[112:115]
	v_mfma_f32_16x16x32_bf16 v[100:103], v[164:167], v[190:193], v[100:103]
	v_mfma_f32_16x16x32_bf16 v[96:99], v[172:175], v[190:193], v[96:99]
	v_mfma_f32_16x16x32_bf16 v[84:87], v[164:167], v[198:201], v[84:87]
	v_mfma_f32_16x16x32_bf16 v[80:83], v[172:175], v[198:201], v[80:83]
	v_mfma_f32_16x16x32_bf16 v[68:71], v[164:167], v[206:209], v[68:71]
	v_mfma_f32_16x16x32_bf16 v[64:67], v[172:175], v[206:209], v[64:67]
	v_mfma_f32_16x16x32_bf16 v[116:119], v[168:171], v[184:187], v[116:119]
	v_mfma_f32_16x16x32_bf16 v[112:115], v[176:179], v[184:187], v[112:115]
	v_mfma_f32_16x16x32_bf16 v[100:103], v[168:171], v[194:197], v[100:103]
	v_mfma_f32_16x16x32_bf16 v[96:99], v[176:179], v[194:197], v[96:99]
	v_mfma_f32_16x16x32_bf16 v[84:87], v[168:171], v[202:205], v[84:87]
	v_mfma_f32_16x16x32_bf16 v[80:83], v[176:179], v[202:205], v[80:83]
	v_mfma_f32_16x16x32_bf16 v[68:71], v[168:171], v[214:217], v[68:71]
	v_mfma_f32_16x16x32_bf16 v[64:67], v[176:179], v[214:217], v[64:67]
	s_barrier
	s_mov_b32 m0, s79
	v_lshl_add_u64 v[210:211], s[46:47], 0, v[132:133]
	s_add_u32 s14, s46, 0x30000
	ds_read_b128 v[180:183], v152 offset:16384
	ds_read_b128 v[184:187], v152 offset:17408
	ds_read_b128 v[190:193], v152 offset:18432
	ds_read_b128 v[194:197], v152 offset:19456
	ds_read_b128 v[198:201], v152 offset:20480
	ds_read_b128 v[202:205], v152 offset:21504
	ds_read_b128 v[206:209], v152 offset:22528
	ds_read_b128 v[214:217], v152 offset:23552
	global_load_lds_dwordx4 v[210:211], off
	v_lshl_add_u64 v[218:219], s[46:47], 0, v[128:129]
	s_mov_b32 m0, s80
	s_addc_u32 s15, s47, 0
	global_load_lds_dwordx4 v[218:219], off
	v_lshl_add_u64 v[220:221], s[14:15], 0, v[132:133]
	s_mov_b32 m0, s81
	v_lshl_add_u64 v[222:223], s[64:65], 0, v[130:131]
	global_load_lds_dwordx4 v[220:221], off
	v_lshl_add_u64 v[220:221], s[14:15], 0, v[128:129]
	s_mov_b32 m0, s82
	s_nop 0
	global_load_lds_dwordx4 v[220:221], off
	v_lshl_add_u64 v[220:221], s[64:65], 0, v[134:135]
	s_mov_b32 m0, s56
	s_nop 0
	global_load_lds_dwordx4 v[220:221], off
	s_mov_b32 m0, s57
	s_nop 0
	global_load_lds_dwordx4 v[222:223], off
	s_waitcnt vmcnt(8)
	s_waitcnt lgkmcnt(0)
	s_barrier
; #define PG8_STAGE(bufoff, gbase, voff) do { _Pragma("unroll") for (int _i = 0; _i < 2; ++_i) \
;         __builtin_amdgcn_global_load_lds((const unsigned*)((const char*)(gbase) + (voff)[_i]), (PG8_LAS unsigned*)(lds + (bufoff) + ldsw + _i * 8192), 16, 0, 0); } while (0)
; #define PG8_LDA(dst, b, h) do { _Pragma("unroll") for (int m = 0; m < 4; ++m) _Pragma("unroll") for (int k = 0; k < 2; ++k) dst[m][k] = *(const PG8_LAS bf16x8*)(lds + PG8_SA(b, h) + aoff + m * 2048 + k * 1024); } while (0)
; #define PG8_LDB(dst, b, h) do { _Pragma("unroll") for (int n = 0; n < 2; ++n) _Pragma("unroll") for (int k = 0; k < 2; ++k) dst[n][k] = *(const PG8_LAS bf16x8*)(lds + PG8_SB(b, h) + boff + n * 2048 + k * 1024); } while (0)
; #define PG8_MMA(ai, bj, At, Bt) do { __builtin_amdgcn_s_setprio(1); _Pragma("unroll") for (int m = 0; m < 4; ++m) _Pragma("unroll") for (int n = 0; n < 2; ++n) _Pragma("unroll") for (int k = 0; k < 2; ++k) \
;         acc[ai][bj][m][n] = __builtin_amdgcn_mfma_f32_16x16x32_bf16(Bt[n][k], At[m][k], acc[ai][bj][m][n], 0, 0, 0); __builtin_amdgcn_s_setprio(0); } while (0)
; #define PG8_WAIT_V(n) asm volatile("s_waitcnt vmcnt(" #n ")" ::: "memory")
; #define PG8_WAIT_L(n) asm volatile("s_waitcnt lgkmcnt(" #n ")" ::: "memory")
; #define PG8_BAR __builtin_amdgcn_s_barrier()
; #define PG8_SCHED __builtin_amdgcn_sched_barrier(0)
; template <class Epi, class Sched, bool ALIGN_EPI = false, bool SP2 = false>
; __device__ __forceinline__ void gemm_phase(PG8_LAS unsigned char* lds, const Gemm g, const Sched& S, const Epi& E) {
;     ...
;             PG8_WAIT_V(8); PG8_WAIT_L(0); PG8_BAR; PG8_MMA(1, 0, At, B0); PG8_MMA(1, 1, At, B1); PG8_BAR; PG8_SCHED;
;             PG8_LDB(B0, 1, 0); PG8_LDB(B1, 1, 1); PG8_SCHED; PG8_LDA(At, 1, 0); PG8_STAGE(PG8_SA(0, 1), a2 + hstep, voffA);
;             PG8_WAIT_V(8); PG8_WAIT_L(0); PG8_BAR; PG8_MMA(0, 0, At, B0); PG8_MMA(0, 1, At, B1); PG8_BAR; PG8_SCHED;
	s_waitcnt lgkmcnt(0)
	v_mfma_f32_16x16x32_bf16 v[60:63], v[140:143], v[180:183], v[60:63]
	v_mfma_f32_16x16x32_bf16 v[56:59], v[156:159], v[180:183], v[56:59]
	v_mfma_f32_16x16x32_bf16 v[44:47], v[140:143], v[190:193], v[44:47]
	v_mfma_f32_16x16x32_bf16 v[40:43], v[156:159], v[190:193], v[40:43]
	v_mfma_f32_16x16x32_bf16 v[28:31], v[140:143], v[198:201], v[28:31]
	v_mfma_f32_16x16x32_bf16 v[24:27], v[156:159], v[198:201], v[24:27]
	v_mfma_f32_16x16x32_bf16 v[12:15], v[140:143], v[206:209], v[12:15]
	v_mfma_f32_16x16x32_bf16 v[8:11], v[156:159], v[206:209], v[8:11]
	v_mfma_f32_16x16x32_bf16 v[60:63], v[144:147], v[184:187], v[60:63]
	v_mfma_f32_16x16x32_bf16 v[56:59], v[160:163], v[184:187], v[56:59]
	v_mfma_f32_16x16x32_bf16 v[44:47], v[144:147], v[194:197], v[44:47]
	v_mfma_f32_16x16x32_bf16 v[40:43], v[160:163], v[194:197], v[40:43]
	v_mfma_f32_16x16x32_bf16 v[28:31], v[144:147], v[202:205], v[28:31]
	v_mfma_f32_16x16x32_bf16 v[24:27], v[160:163], v[202:205], v[24:27]
	v_mfma_f32_16x16x32_bf16 v[12:15], v[144:147], v[214:217], v[12:15]
	v_mfma_f32_16x16x32_bf16 v[8:11], v[160:163], v[214:217], v[8:11]
	v_mfma_f32_16x16x32_bf16 v[52:55], v[164:167], v[180:183], v[52:55]
	v_mfma_f32_16x16x32_bf16 v[48:51], v[172:175], v[180:183], v[48:51]
	v_mfma_f32_16x16x32_bf16 v[36:39], v[164:167], v[190:193], v[36:39]
	v_mfma_f32_16x16x32_bf16 v[32:35], v[172:175], v[190:193], v[32:35]
	v_mfma_f32_16x16x32_bf16 v[20:23], v[164:167], v[198:201], v[20:23]
	v_mfma_f32_16x16x32_bf16 v[16:19], v[172:175], v[198:201], v[16:19]
	v_mfma_f32_16x16x32_bf16 v[4:7], v[164:167], v[206:209], v[4:7]
	v_mfma_f32_16x16x32_bf16 v[0:3], v[172:175], v[206:209], v[0:3]
	v_mfma_f32_16x16x32_bf16 v[52:55], v[168:171], v[184:187], v[52:55]
	v_mfma_f32_16x16x32_bf16 v[48:51], v[176:179], v[184:187], v[48:51]
	v_mfma_f32_16x16x32_bf16 v[36:39], v[168:171], v[194:197], v[36:39]
	v_mfma_f32_16x16x32_bf16 v[32:35], v[176:179], v[194:197], v[32:35]
	v_mfma_f32_16x16x32_bf16 v[20:23], v[168:171], v[202:205], v[20:23]
	v_mfma_f32_16x16x32_bf16 v[16:19], v[176:179], v[202:205], v[16:19]
	v_mfma_f32_16x16x32_bf16 v[4:7], v[168:171], v[214:217], v[4:7]
	v_mfma_f32_16x16x32_bf16 v[0:3], v[176:179], v[214:217], v[0:3]
	s_barrier
	ds_read_b128 v[140:143], v153
	ds_read_b128 v[144:147], v153 offset:1024
	ds_read_b128 v[156:159], v153 offset:2048
	ds_read_b128 v[160:163], v153 offset:3072
	ds_read_b128 v[164:167], v154
	ds_read_b128 v[168:171], v154 offset:1024
	ds_read_b128 v[172:175], v154 offset:2048
	ds_read_b128 v[176:179], v154 offset:3072
	s_add_u32 s14, s64, 0x30000
	s_addc_u32 s15, s65, 0
	s_mov_b32 m0, s66
	v_lshl_add_u64 v[224:225], s[14:15], 0, v[134:135]
	ds_read_b128 v[180:183], v152 offset:32768
	ds_read_b128 v[184:187], v152 offset:33792
	ds_read_b128 v[190:193], v152 offset:34816
	ds_read_b128 v[194:197], v152 offset:35840
	ds_read_b128 v[198:201], v152 offset:36864
	ds_read_b128 v[202:205], v152 offset:37888
	ds_read_b128 v[206:209], v152 offset:38912
	ds_read_b128 v[214:217], v152 offset:39936
	global_load_lds_dwordx4 v[224:225], off
	v_lshl_add_u64 v[224:225], s[14:15], 0, v[130:131]
	s_mov_b32 m0, s67
	s_nop 0
	global_load_lds_dwordx4 v[224:225], off
	s_waitcnt vmcnt(8)
	s_waitcnt lgkmcnt(0)
	s_barrier
	s_waitcnt lgkmcnt(0)
	v_mfma_f32_16x16x32_bf16 v[124:127], v[140:143], v[180:183], v[124:127]
	v_mfma_f32_16x16x32_bf16 v[120:123], v[156:159], v[180:183], v[120:123]
	v_mfma_f32_16x16x32_bf16 v[108:111], v[140:143], v[190:193], v[108:111]
	v_mfma_f32_16x16x32_bf16 v[104:107], v[156:159], v[190:193], v[104:107]
	v_mfma_f32_16x16x32_bf16 v[92:95], v[140:143], v[198:201], v[92:95]
	v_mfma_f32_16x16x32_bf16 v[88:91], v[156:159], v[198:201], v[88:91]
	v_mfma_f32_16x16x32_bf16 v[76:79], v[140:143], v[206:209], v[76:79]
	v_mfma_f32_16x16x32_bf16 v[72:75], v[156:159], v[206:209], v[72:75]
	v_mfma_f32_16x16x32_bf16 v[124:127], v[144:147], v[184:187], v[124:127]
	v_mfma_f32_16x16x32_bf16 v[120:123], v[160:163], v[184:187], v[120:123]
	v_mfma_f32_16x16x32_bf16 v[108:111], v[144:147], v[194:197], v[108:111]
	v_mfma_f32_16x16x32_bf16 v[104:107], v[160:163], v[194:197], v[104:107]
	v_mfma_f32_16x16x32_bf16 v[92:95], v[144:147], v[202:205], v[92:95]
	v_mfma_f32_16x16x32_bf16 v[88:91], v[160:163], v[202:205], v[88:91]
	v_mfma_f32_16x16x32_bf16 v[76:79], v[144:147], v[214:217], v[76:79]
	v_mfma_f32_16x16x32_bf16 v[72:75], v[160:163], v[214:217], v[72:75]
	v_mfma_f32_16x16x32_bf16 v[116:119], v[164:167], v[180:183], v[116:119]
	v_mfma_f32_16x16x32_bf16 v[112:115], v[172:175], v[180:183], v[112:115]
	v_mfma_f32_16x16x32_bf16 v[100:103], v[164:167], v[190:193], v[100:103]
	v_mfma_f32_16x16x32_bf16 v[96:99], v[172:175], v[190:193], v[96:99]
	v_mfma_f32_16x16x32_bf16 v[84:87], v[164:167], v[198:201], v[84:87]
	v_mfma_f32_16x16x32_bf16 v[80:83], v[172:175], v[198:201], v[80:83]
	v_mfma_f32_16x16x32_bf16 v[68:71], v[164:167], v[206:209], v[68:71]
	v_mfma_f32_16x16x32_bf16 v[64:67], v[172:175], v[206:209], v[64:67]
	v_mfma_f32_16x16x32_bf16 v[116:119], v[168:171], v[184:187], v[116:119]
	v_mfma_f32_16x16x32_bf16 v[112:115], v[176:179], v[184:187], v[112:115]
	v_mfma_f32_16x16x32_bf16 v[100:103], v[168:171], v[194:197], v[100:103]
	v_mfma_f32_16x16x32_bf16 v[96:99], v[176:179], v[194:197], v[96:99]
	v_mfma_f32_16x16x32_bf16 v[84:87], v[168:171], v[202:205], v[84:87]
	v_mfma_f32_16x16x32_bf16 v[80:83], v[176:179], v[202:205], v[80:83]
	v_mfma_f32_16x16x32_bf16 v[68:71], v[168:171], v[214:217], v[68:71]
	v_mfma_f32_16x16x32_bf16 v[64:67], v[176:179], v[214:217], v[64:67]
	s_barrier
; #define PG8_STAGE(bufoff, gbase, voff) do { _Pragma("unroll") for (int _i = 0; _i < 2; ++_i) \
;         __builtin_amdgcn_global_load_lds((const unsigned*)((const char*)(gbase) + (voff)[_i]), (PG8_LAS unsigned*)(lds + (bufoff) + ldsw + _i * 8192), 16, 0, 0); } while (0)
; #define PG8_LDA(dst, b, h) do { _Pragma("unroll") for (int m = 0; m < 4; ++m) _Pragma("unroll") for (int k = 0; k < 2; ++k) dst[m][k] = *(const PG8_LAS bf16x8*)(lds + PG8_SA(b, h) + aoff + m * 2048 + k * 1024); } while (0)
; #define PG8_MMA(ai, bj, At, Bt) do { __builtin_amdgcn_s_setprio(1); _Pragma("unroll") for (int m = 0; m < 4; ++m) _Pragma("unroll") for (int n = 0; n < 2; ++n) _Pragma("unroll") for (int k = 0; k < 2; ++k) \
;         acc[ai][bj][m][n] = __builtin_amdgcn_mfma_f32_16x16x32_bf16(Bt[n][k], At[m][k], acc[ai][bj][m][n], 0, 0, 0); __builtin_amdgcn_s_setprio(0); } while (0)
; #define PG8_WAIT_V(n) asm volatile("s_waitcnt vmcnt(" #n ")" ::: "memory")
; #define PG8_WAIT_L(n) asm volatile("s_waitcnt lgkmcnt(" #n ")" ::: "memory")
; #define PG8_BAR __builtin_amdgcn_s_barrier()
; #define PG8_SCHED __builtin_amdgcn_sched_barrier(0)
; template <class Epi, class Sched, bool ALIGN_EPI = false, bool SP2 = false>
; __device__ __forceinline__ void gemm_phase(PG8_LAS unsigned char* lds, const Gemm g, const Sched& S, const Epi& E) {
;     ...
;             PG8_LDA(At, 1, 1); PG8_STAGE(PG8_SB(1, 0), b3, voffB); PG8_STAGE(PG8_SB(1, 1), b3 + hstep, voffB); PG8_STAGE(PG8_SA(1, 0), a3, voffA);
;             PG8_WAIT_V(8); PG8_WAIT_L(0); PG8_BAR; PG8_MMA(1, 0, At, B0); PG8_MMA(1, 1, At, B1); PG8_BAR; PG8_SCHED;
;     ...
;         if constexpr (ALIGN_EPI) { if (wr == 0) PG8_BAR; }
	s_add_i32 s14, s75, s33
	v_lshl_add_u64 v[210:211], v[210:211], 0, s[8:9]
	s_mov_b32 m0, s14
	ds_read_b128 v[180:183], v152 offset:49152
	ds_read_b128 v[184:187], v152 offset:50176
	ds_read_b128 v[190:193], v152 offset:51200
	ds_read_b128 v[194:197], v152 offset:52224
	ds_read_b128 v[198:201], v152 offset:53248
	ds_read_b128 v[202:205], v152 offset:54272
	ds_read_b128 v[206:209], v152 offset:55296
	ds_read_b128 v[214:217], v152 offset:56320
	global_load_lds_dwordx4 v[210:211], off
	s_add_i32 m0, s14, 0x2000
	s_add_u32 s14, s46, 0x30080
	v_lshl_add_u64 v[210:211], v[218:219], 0, s[8:9]
	s_addc_u32 s15, s47, 0
	s_add_i32 s46, s84, s33
	global_load_lds_dwordx4 v[210:211], off
	v_lshl_add_u64 v[210:211], s[14:15], 0, v[132:133]
	s_mov_b32 m0, s46
	s_nop 0
	global_load_lds_dwordx4 v[210:211], off
	v_lshl_add_u64 v[210:211], s[14:15], 0, v[128:129]
	s_add_i32 m0, s46, 0x2000
	s_nop 0
	global_load_lds_dwordx4 v[210:211], off
	v_lshl_add_u64 v[210:211], v[220:221], 0, s[8:9]
	s_mov_b32 m0, s68
	s_nop 0
	global_load_lds_dwordx4 v[210:211], off
	v_lshl_add_u64 v[210:211], v[222:223], 0, s[8:9]
	s_mov_b32 m0, s69
	s_nop 0
	global_load_lds_dwordx4 v[210:211], off
	s_waitcnt vmcnt(8)
	s_waitcnt lgkmcnt(0)
	s_barrier
	s_waitcnt lgkmcnt(0)
	v_mfma_f32_16x16x32_bf16 v[60:63], v[140:143], v[180:183], v[60:63]
	v_mfma_f32_16x16x32_bf16 v[56:59], v[156:159], v[180:183], v[56:59]
	v_mfma_f32_16x16x32_bf16 v[44:47], v[140:143], v[190:193], v[44:47]
	v_mfma_f32_16x16x32_bf16 v[40:43], v[156:159], v[190:193], v[40:43]
	v_mfma_f32_16x16x32_bf16 v[28:31], v[140:143], v[198:201], v[28:31]
	v_mfma_f32_16x16x32_bf16 v[24:27], v[156:159], v[198:201], v[24:27]
	v_mfma_f32_16x16x32_bf16 v[12:15], v[140:143], v[206:209], v[12:15]
	v_mfma_f32_16x16x32_bf16 v[8:11], v[156:159], v[206:209], v[8:11]
	v_mfma_f32_16x16x32_bf16 v[60:63], v[144:147], v[184:187], v[60:63]
	v_mfma_f32_16x16x32_bf16 v[56:59], v[160:163], v[184:187], v[56:59]
	v_mfma_f32_16x16x32_bf16 v[44:47], v[144:147], v[194:197], v[44:47]
	v_mfma_f32_16x16x32_bf16 v[40:43], v[160:163], v[194:197], v[40:43]
	v_mfma_f32_16x16x32_bf16 v[28:31], v[144:147], v[202:205], v[28:31]
	v_mfma_f32_16x16x32_bf16 v[24:27], v[160:163], v[202:205], v[24:27]
	v_mfma_f32_16x16x32_bf16 v[12:15], v[144:147], v[214:217], v[12:15]
	v_mfma_f32_16x16x32_bf16 v[8:11], v[160:163], v[214:217], v[8:11]
	v_mfma_f32_16x16x32_bf16 v[52:55], v[164:167], v[180:183], v[52:55]
	v_mfma_f32_16x16x32_bf16 v[48:51], v[172:175], v[180:183], v[48:51]
	v_mfma_f32_16x16x32_bf16 v[36:39], v[164:167], v[190:193], v[36:39]
	v_mfma_f32_16x16x32_bf16 v[32:35], v[172:175], v[190:193], v[32:35]
	v_mfma_f32_16x16x32_bf16 v[20:23], v[164:167], v[198:201], v[20:23]
	v_mfma_f32_16x16x32_bf16 v[16:19], v[172:175], v[198:201], v[16:19]
	v_mfma_f32_16x16x32_bf16 v[4:7], v[164:167], v[206:209], v[4:7]
	v_mfma_f32_16x16x32_bf16 v[0:3], v[172:175], v[206:209], v[0:3]
	v_mfma_f32_16x16x32_bf16 v[52:55], v[168:171], v[184:187], v[52:55]
	v_mfma_f32_16x16x32_bf16 v[48:51], v[176:179], v[184:187], v[48:51]
	v_mfma_f32_16x16x32_bf16 v[36:39], v[168:171], v[194:197], v[36:39]
	v_mfma_f32_16x16x32_bf16 v[32:35], v[176:179], v[194:197], v[32:35]
	v_mfma_f32_16x16x32_bf16 v[20:23], v[168:171], v[202:205], v[20:23]
	v_mfma_f32_16x16x32_bf16 v[16:19], v[176:179], v[202:205], v[16:19]
	v_mfma_f32_16x16x32_bf16 v[4:7], v[168:171], v[214:217], v[4:7]
	v_mfma_f32_16x16x32_bf16 v[0:3], v[176:179], v[214:217], v[0:3]
	s_barrier
	s_add_i32 s97, s97, 2
	s_add_u32 s0, s0, 0x100
	s_addc_u32 s1, s1, 0
	s_cmp_gt_u32 s97, 9
	s_mov_b64 s[14:15], s[40:41]
	s_cbranch_scc0 .LBB0_520
	s_and_b64 vcc, exec, s[10:11]
	s_cbranch_vccz .LBB0_523
	s_barrier

;     __device__ bool next(int i, Unit& u) const { if (i >= n) return false; const int q = first + i; u.pm = rowbase + q % rows; u.pn = q / rows; return true; }
; #define PG8_STAGE(bufoff, gbase, voff) do { _Pragma("unroll") for (int _i = 0; _i < 2; ++_i) \
;         __builtin_amdgcn_global_load_lds((const unsigned*)((const char*)(gbase) + (voff)[_i]), (PG8_LAS unsigned*)(lds + (bufoff) + ldsw + _i * 8192), 16, 0, 0); } while (0)
; #define PG8_LDA(dst, b, h) do { _Pragma("unroll") for (int m = 0; m < 4; ++m) _Pragma("unroll") for (int k = 0; k < 2; ++k) dst[m][k] = *(const PG8_LAS bf16x8*)(lds + PG8_SA(b, h) + aoff + m * 2048 + k * 1024); } while (0)
; #define PG8_WAIT_V(n) asm volatile("s_waitcnt vmcnt(" #n ")" ::: "memory")
; template <class Epi, class Sched, bool ALIGN_EPI = false, bool SP2 = false>
; __device__ __forceinline__ void gemm_phase(PG8_LAS unsigned char* lds, const Gemm g, const Sched& S, const Epi& E) {
;     ...
;         const bool has_next = S.next(ui + 1, nxt);
;         const char* nA = has_next ? (const char*)g.A + (size_t)nxt.pm * tstep : cA; const char* nB = has_next ? (const char*)g.Bt + (size_t)nxt.pn * tstep : cB;
;         constexpr int NSEG = Epi::HAS_MID ? 2 : 1; const int tseg = nt / NSEG;
; #pragma unroll
;         for (int seg = 0; seg < NSEG; ++seg) {
;         if constexpr (Epi::HAS_MID) { if (seg == 1) E.mid(acc, cur, wr, wc, fr, fq); }
;         for (int t = seg * tseg; t < (seg + 1) * tseg; t += 2) {
;             const bool last = (t == nt - 2);
;             const char* a1 = cA + (size_t)(t + 1) * kstep;
;             const char* a2 = last ? nA : cA + (size_t)(t + 2) * kstep; const char* b2 = last ? nB : cB + (size_t)(t + 2) * kstep;
;             const char* a3 = a2 + kstep; const char* b3 = b2 + kstep;
;             if (last && has_next) S.a_ready(nxt);
;             if constexpr (SP2) {
;             PG8_LDB(B0, 0, 0); PG8_LDB(B1, 0, 1); PG8_SCHED; PG8_LDA(At, 0, 0); PG8_STAGE(PG8_SA(1, 1), a1 + hstep, voffA);
;             PG8_WAIT_V(8); PG8_WAIT_L(0); PG8_BAR; PG8_MMA(0, 0, At, B0); PG8_MMA(0, 1, At, B1); PG8_BAR; PG8_SCHED;
;             PG8_LDA(At, 0, 1); PG8_STAGE(PG8_SB(0, 0), b2, voffB); PG8_STAGE(PG8_SB(0, 1), b2 + hstep, voffB); PG8_STAGE(PG8_SA(0, 0), a2, voffA);
;             PG8_WAIT_V(8); PG8_WAIT_L(0); PG8_BAR; PG8_MMA(1, 0, At, B0); PG8_MMA(1, 1, At, B1); PG8_BAR; PG8_SCHED;
.LBB0_534:
	s_ashr_i32 s41, s40, 31
	s_lshl_b64 s[46:47], s[40:41], 18
	s_add_u32 s46, s72, s46
	s_addc_u32 s47, s73, s47
	s_and_b64 s[60:61], s[0:1], exec
	s_cselect_b32 s41, s47, s63
	s_cselect_b32 s76, s46, s62
	s_ashr_i32 s37, s36, 31
	s_lshl_b64 s[60:61], s[36:37], 18
	s_add_u32 s60, s58, s60
	s_addc_u32 s61, s59, s61
	s_and_b64 s[0:1], s[0:1], exec
	s_cselect_b32 s0, s61, s65
	s_cselect_b32 s1, s60, s64
	s_add_u32 s62, s62, 0x20080
	s_addc_u32 s63, s63, 0
	s_add_u32 s37, s64, 0x100
	s_addc_u32 s77, s65, 0
	s_mov_b32 s78, -2
	ds_read_b128 v[140:143], v149
	ds_read_b128 v[152:155], v149 offset:1024
	ds_read_b128 v[156:159], v149 offset:2048
	ds_read_b128 v[160:163], v149 offset:3072
	ds_read_b128 v[164:167], v150
	ds_read_b128 v[168:171], v150 offset:1024
	ds_read_b128 v[172:175], v150 offset:2048
	ds_read_b128 v[176:179], v150 offset:3072
	s_add_u32 s64, s62, 0xfffe0080
	s_addc_u32 s65, s63, -1
	s_cmp_eq_u32 s78, 4
	s_cselect_b32 s67, s41, s65
	s_cselect_b32 s66, s76, s64
	s_cselect_b32 s65, s0, s77
	s_cselect_b32 s64, s1, s37
	v_lshl_add_u64 v[144:145], s[62:63], 0, v[136:137]
	s_add_i32 m0, s30, 0xc000
	ds_read_b128 v[180:183], v151
	ds_read_b128 v[184:187], v151 offset:1024
	ds_read_b128 v[190:193], v151 offset:2048
	ds_read_b128 v[194:197], v151 offset:3072
	ds_read_b128 v[198:201], v151 offset:4096
	ds_read_b128 v[202:205], v151 offset:5120
	ds_read_b128 v[206:209], v151 offset:6144
	ds_read_b128 v[214:217], v151 offset:7168
	global_load_lds_dwordx4 v[144:145], off
	v_lshl_add_u64 v[144:145], s[62:63], 0, v[138:139]
	s_add_i32 m0, s30, 0xe000
	s_nop 0
	global_load_lds_dwordx4 v[144:145], off
	s_waitcnt vmcnt(8)
	s_waitcnt lgkmcnt(0)
	s_barrier
	s_waitcnt lgkmcnt(0)
	v_mfma_f32_16x16x32_bf16 v[124:127], v[140:143], v[180:183], 0
	v_mfma_f32_16x16x32_bf16 v[120:123], v[156:159], v[180:183], 0
	v_mfma_f32_16x16x32_bf16 v[108:111], v[140:143], v[190:193], 0
	v_mfma_f32_16x16x32_bf16 v[104:107], v[156:159], v[190:193], 0
	v_mfma_f32_16x16x32_bf16 v[92:95], v[140:143], v[198:201], 0
	v_mfma_f32_16x16x32_bf16 v[88:91], v[156:159], v[198:201], 0
	v_mfma_f32_16x16x32_bf16 v[76:79], v[140:143], v[206:209], 0
	v_mfma_f32_16x16x32_bf16 v[72:75], v[156:159], v[206:209], 0
	v_mfma_f32_16x16x32_bf16 v[124:127], v[152:155], v[184:187], v[124:127]
	v_mfma_f32_16x16x32_bf16 v[120:123], v[160:163], v[184:187], v[120:123]
	v_mfma_f32_16x16x32_bf16 v[108:111], v[152:155], v[194:197], v[108:111]
	v_mfma_f32_16x16x32_bf16 v[104:107], v[160:163], v[194:197], v[104:107]
	v_mfma_f32_16x16x32_bf16 v[92:95], v[152:155], v[202:205], v[92:95]
	v_mfma_f32_16x16x32_bf16 v[88:91], v[160:163], v[202:205], v[88:91]
	v_mfma_f32_16x16x32_bf16 v[76:79], v[152:155], v[214:217], v[76:79]
	v_mfma_f32_16x16x32_bf16 v[72:75], v[160:163], v[214:217], v[72:75]
	v_mfma_f32_16x16x32_bf16 v[116:119], v[164:167], v[180:183], 0
	v_mfma_f32_16x16x32_bf16 v[112:115], v[172:175], v[180:183], 0
	v_mfma_f32_16x16x32_bf16 v[100:103], v[164:167], v[190:193], 0
	v_mfma_f32_16x16x32_bf16 v[96:99], v[172:175], v[190:193], 0
	v_mfma_f32_16x16x32_bf16 v[84:87], v[164:167], v[198:201], 0
	v_mfma_f32_16x16x32_bf16 v[80:83], v[172:175], v[198:201], 0
	v_mfma_f32_16x16x32_bf16 v[68:71], v[164:167], v[206:209], 0
	v_mfma_f32_16x16x32_bf16 v[64:67], v[172:175], v[206:209], 0
	v_mfma_f32_16x16x32_bf16 v[116:119], v[168:171], v[184:187], v[116:119]
	v_mfma_f32_16x16x32_bf16 v[112:115], v[176:179], v[184:187], v[112:115]
	v_mfma_f32_16x16x32_bf16 v[100:103], v[168:171], v[194:197], v[100:103]
	v_mfma_f32_16x16x32_bf16 v[96:99], v[176:179], v[194:197], v[96:99]
	v_mfma_f32_16x16x32_bf16 v[84:87], v[168:171], v[202:205], v[84:87]
	v_mfma_f32_16x16x32_bf16 v[80:83], v[176:179], v[202:205], v[80:83]
	v_mfma_f32_16x16x32_bf16 v[68:71], v[168:171], v[214:217], v[68:71]
	v_mfma_f32_16x16x32_bf16 v[64:67], v[176:179], v[214:217], v[64:67]
	s_barrier
	s_add_i32 s79, s31, s29
	v_lshl_add_u64 v[144:145], s[64:65], 0, v[132:133]
	s_mov_b32 m0, s79
	ds_read_b128 v[180:183], v151 offset:16384
	ds_read_b128 v[184:187], v151 offset:17408
	ds_read_b128 v[190:193], v151 offset:18432
	ds_read_b128 v[194:197], v151 offset:19456
	ds_read_b128 v[198:201], v151 offset:20480
	ds_read_b128 v[202:205], v151 offset:21504
	ds_read_b128 v[206:209], v151 offset:22528
	ds_read_b128 v[214:217], v151 offset:23552
	global_load_lds_dwordx4 v[144:145], off
	s_add_i32 m0, s79, 0x2000
	s_add_u32 s80, s64, 0x20000
	v_lshl_add_u64 v[210:211], s[64:65], 0, v[128:129]
	s_addc_u32 s81, s65, 0
	s_add_i32 s79, s74, s29
	global_load_lds_dwordx4 v[210:211], off
	v_lshl_add_u64 v[218:219], s[80:81], 0, v[132:133]
	s_mov_b32 m0, s79
	v_lshl_add_u64 v[220:221], s[66:67], 0, v[130:131]
	global_load_lds_dwordx4 v[218:219], off
	v_lshl_add_u64 v[218:219], s[80:81], 0, v[128:129]
	s_add_i32 m0, s79, 0x2000
	s_nop 0
	global_load_lds_dwordx4 v[218:219], off
	v_lshl_add_u64 v[218:219], s[66:67], 0, v[134:135]
	s_mov_b32 m0, s30
	s_nop 0
	global_load_lds_dwordx4 v[218:219], off
	s_mov_b32 m0, s33
	s_nop 0
	global_load_lds_dwordx4 v[220:221], off
	s_waitcnt vmcnt(8)
	s_waitcnt lgkmcnt(0)
	s_barrier
; #define PG8_STAGE(bufoff, gbase, voff) do { _Pragma("unroll") for (int _i = 0; _i < 2; ++_i) \
;         __builtin_amdgcn_global_load_lds((const unsigned*)((const char*)(gbase) + (voff)[_i]), (PG8_LAS unsigned*)(lds + (bufoff) + ldsw + _i * 8192), 16, 0, 0); } while (0)
; #define PG8_LDA(dst, b, h) do { _Pragma("unroll") for (int m = 0; m < 4; ++m) _Pragma("unroll") for (int k = 0; k < 2; ++k) dst[m][k] = *(const PG8_LAS bf16x8*)(lds + PG8_SA(b, h) + aoff + m * 2048 + k * 1024); } while (0)
; #define PG8_LDB(dst, b, h) do { _Pragma("unroll") for (int n = 0; n < 2; ++n) _Pragma("unroll") for (int k = 0; k < 2; ++k) dst[n][k] = *(const PG8_LAS bf16x8*)(lds + PG8_SB(b, h) + boff + n * 2048 + k * 1024); } while (0)
; #define PG8_MMA(ai, bj, At, Bt) do { __builtin_amdgcn_s_setprio(1); _Pragma("unroll") for (int m = 0; m < 4; ++m) _Pragma("unroll") for (int n = 0; n < 2; ++n) _Pragma("unroll") for (int k = 0; k < 2; ++k) \
;         acc[ai][bj][m][n] = __builtin_amdgcn_mfma_f32_16x16x32_bf16(Bt[n][k], At[m][k], acc[ai][bj][m][n], 0, 0, 0); __builtin_amdgcn_s_setprio(0); } while (0)
; #define PG8_WAIT_V(n) asm volatile("s_waitcnt vmcnt(" #n ")" ::: "memory")
; #define PG8_WAIT_L(n) asm volatile("s_waitcnt lgkmcnt(" #n ")" ::: "memory")
; #define PG8_BAR __builtin_amdgcn_s_barrier()
; #define PG8_SCHED __builtin_amdgcn_sched_barrier(0)
; template <class Epi, class Sched, bool ALIGN_EPI = false, bool SP2 = false>
; __device__ __forceinline__ void gemm_phase(PG8_LAS unsigned char* lds, const Gemm g, const Sched& S, const Epi& E) {
;     ...
;             PG8_WAIT_V(8); PG8_WAIT_L(0); PG8_BAR; PG8_MMA(1, 0, At, B0); PG8_MMA(1, 1, At, B1); PG8_BAR; PG8_SCHED;
;             PG8_LDB(B0, 1, 0); PG8_LDB(B1, 1, 1); PG8_SCHED; PG8_LDA(At, 1, 0); PG8_STAGE(PG8_SA(0, 1), a2 + hstep, voffA);
;             PG8_WAIT_V(8); PG8_WAIT_L(0); PG8_BAR; PG8_MMA(0, 0, At, B0); PG8_MMA(0, 1, At, B1); PG8_BAR; PG8_SCHED;
	s_waitcnt lgkmcnt(0)
	v_mfma_f32_16x16x32_bf16 v[60:63], v[140:143], v[180:183], 0
	v_mfma_f32_16x16x32_bf16 v[56:59], v[156:159], v[180:183], 0
	v_mfma_f32_16x16x32_bf16 v[44:47], v[140:143], v[190:193], 0
	v_mfma_f32_16x16x32_bf16 v[40:43], v[156:159], v[190:193], 0
	v_mfma_f32_16x16x32_bf16 v[28:31], v[140:143], v[198:201], 0
	v_mfma_f32_16x16x32_bf16 v[24:27], v[156:159], v[198:201], 0
	v_mfma_f32_16x16x32_bf16 v[12:15], v[140:143], v[206:209], 0
	v_mfma_f32_16x16x32_bf16 v[8:11], v[156:159], v[206:209], 0
	v_mfma_f32_16x16x32_bf16 v[60:63], v[152:155], v[184:187], v[60:63]
	v_mfma_f32_16x16x32_bf16 v[56:59], v[160:163], v[184:187], v[56:59]
	v_mfma_f32_16x16x32_bf16 v[44:47], v[152:155], v[194:197], v[44:47]
	v_mfma_f32_16x16x32_bf16 v[40:43], v[160:163], v[194:197], v[40:43]
	v_mfma_f32_16x16x32_bf16 v[28:31], v[152:155], v[202:205], v[28:31]
	v_mfma_f32_16x16x32_bf16 v[24:27], v[160:163], v[202:205], v[24:27]
	v_mfma_f32_16x16x32_bf16 v[12:15], v[152:155], v[214:217], v[12:15]
	v_mfma_f32_16x16x32_bf16 v[8:11], v[160:163], v[214:217], v[8:11]
	v_mfma_f32_16x16x32_bf16 v[52:55], v[164:167], v[180:183], 0
	v_mfma_f32_16x16x32_bf16 v[48:51], v[172:175], v[180:183], 0
	v_mfma_f32_16x16x32_bf16 v[36:39], v[164:167], v[190:193], 0
	v_mfma_f32_16x16x32_bf16 v[32:35], v[172:175], v[190:193], 0
	v_mfma_f32_16x16x32_bf16 v[20:23], v[164:167], v[198:201], 0
	v_mfma_f32_16x16x32_bf16 v[16:19], v[172:175], v[198:201], 0
	v_mfma_f32_16x16x32_bf16 v[4:7], v[164:167], v[206:209], 0
	v_mfma_f32_16x16x32_bf16 v[0:3], v[172:175], v[206:209], 0
	v_mfma_f32_16x16x32_bf16 v[52:55], v[168:171], v[184:187], v[52:55]
	v_mfma_f32_16x16x32_bf16 v[48:51], v[176:179], v[184:187], v[48:51]
	v_mfma_f32_16x16x32_bf16 v[36:39], v[168:171], v[194:197], v[36:39]
	v_mfma_f32_16x16x32_bf16 v[32:35], v[176:179], v[194:197], v[32:35]
	v_mfma_f32_16x16x32_bf16 v[20:23], v[168:171], v[202:205], v[20:23]
	v_mfma_f32_16x16x32_bf16 v[16:19], v[176:179], v[202:205], v[16:19]
	v_mfma_f32_16x16x32_bf16 v[4:7], v[168:171], v[214:217], v[4:7]
	v_mfma_f32_16x16x32_bf16 v[0:3], v[176:179], v[214:217], v[0:3]
	s_barrier
	v_add_u32_e32 v160, s75, v147
	v_add_u32_e32 v176, s84, v147
	ds_read_b128 v[140:143], v160
	ds_read_b128 v[152:155], v160 offset:1024
	ds_read_b128 v[156:159], v160 offset:2048
	ds_read_b128 v[160:163], v160 offset:3072
	ds_read_b128 v[164:167], v176
	ds_read_b128 v[168:171], v176 offset:1024
	ds_read_b128 v[172:175], v176 offset:2048
	ds_read_b128 v[176:179], v176 offset:3072
	s_add_u32 s66, s66, 0x20000
	s_addc_u32 s67, s67, 0
	s_mov_b32 m0, s56
	v_lshl_add_u64 v[222:223], s[66:67], 0, v[134:135]
	ds_read_b128 v[180:183], v151 offset:32768
	ds_read_b128 v[184:187], v151 offset:33792
	ds_read_b128 v[190:193], v151 offset:34816
	ds_read_b128 v[194:197], v151 offset:35840
	ds_read_b128 v[198:201], v151 offset:36864
	ds_read_b128 v[202:205], v151 offset:37888
	ds_read_b128 v[206:209], v151 offset:38912
	ds_read_b128 v[214:217], v151 offset:39936
	global_load_lds_dwordx4 v[222:223], off
	v_lshl_add_u64 v[222:223], s[66:67], 0, v[130:131]
	s_mov_b32 m0, s57
	s_nop 0
	global_load_lds_dwordx4 v[222:223], off
	s_waitcnt vmcnt(8)
	s_waitcnt lgkmcnt(0)
	s_barrier
	s_waitcnt lgkmcnt(0)
	v_mfma_f32_16x16x32_bf16 v[124:127], v[140:143], v[180:183], v[124:127]
	v_mfma_f32_16x16x32_bf16 v[120:123], v[156:159], v[180:183], v[120:123]
	v_mfma_f32_16x16x32_bf16 v[108:111], v[140:143], v[190:193], v[108:111]
	v_mfma_f32_16x16x32_bf16 v[104:107], v[156:159], v[190:193], v[104:107]
	v_mfma_f32_16x16x32_bf16 v[92:95], v[140:143], v[198:201], v[92:95]
	v_mfma_f32_16x16x32_bf16 v[88:91], v[156:159], v[198:201], v[88:91]
	v_mfma_f32_16x16x32_bf16 v[76:79], v[140:143], v[206:209], v[76:79]
	v_mfma_f32_16x16x32_bf16 v[72:75], v[156:159], v[206:209], v[72:75]
	v_mfma_f32_16x16x32_bf16 v[124:127], v[152:155], v[184:187], v[124:127]
	v_mfma_f32_16x16x32_bf16 v[120:123], v[160:163], v[184:187], v[120:123]
	v_mfma_f32_16x16x32_bf16 v[108:111], v[152:155], v[194:197], v[108:111]
	v_mfma_f32_16x16x32_bf16 v[104:107], v[160:163], v[194:197], v[104:107]
	v_mfma_f32_16x16x32_bf16 v[92:95], v[152:155], v[202:205], v[92:95]
	v_mfma_f32_16x16x32_bf16 v[88:91], v[160:163], v[202:205], v[88:91]
	v_mfma_f32_16x16x32_bf16 v[76:79], v[152:155], v[214:217], v[76:79]
	v_mfma_f32_16x16x32_bf16 v[72:75], v[160:163], v[214:217], v[72:75]
	v_mfma_f32_16x16x32_bf16 v[116:119], v[164:167], v[180:183], v[116:119]
	v_mfma_f32_16x16x32_bf16 v[112:115], v[172:175], v[180:183], v[112:115]
	v_mfma_f32_16x16x32_bf16 v[100:103], v[164:167], v[190:193], v[100:103]
	v_mfma_f32_16x16x32_bf16 v[96:99], v[172:175], v[190:193], v[96:99]
	v_mfma_f32_16x16x32_bf16 v[84:87], v[164:167], v[198:201], v[84:87]
	v_mfma_f32_16x16x32_bf16 v[80:83], v[172:175], v[198:201], v[80:83]
	v_mfma_f32_16x16x32_bf16 v[68:71], v[164:167], v[206:209], v[68:71]
	v_mfma_f32_16x16x32_bf16 v[64:67], v[172:175], v[206:209], v[64:67]
	v_mfma_f32_16x16x32_bf16 v[116:119], v[168:171], v[184:187], v[116:119]
	v_mfma_f32_16x16x32_bf16 v[112:115], v[176:179], v[184:187], v[112:115]
	v_mfma_f32_16x16x32_bf16 v[100:103], v[168:171], v[194:197], v[100:103]
	v_mfma_f32_16x16x32_bf16 v[96:99], v[176:179], v[194:197], v[96:99]
	v_mfma_f32_16x16x32_bf16 v[84:87], v[168:171], v[202:205], v[84:87]
	v_mfma_f32_16x16x32_bf16 v[80:83], v[176:179], v[202:205], v[80:83]
	v_mfma_f32_16x16x32_bf16 v[68:71], v[168:171], v[214:217], v[68:71]
	v_mfma_f32_16x16x32_bf16 v[64:67], v[176:179], v[214:217], v[64:67]
	s_barrier
; #define PG8_STAGE(bufoff, gbase, voff) do { _Pragma("unroll") for (int _i = 0; _i < 2; ++_i) \
;         __builtin_amdgcn_global_load_lds((const unsigned*)((const char*)(gbase) + (voff)[_i]), (PG8_LAS unsigned*)(lds + (bufoff) + ldsw + _i * 8192), 16, 0, 0); } while (0)
; #define PG8_LDA(dst, b, h) do { _Pragma("unroll") for (int m = 0; m < 4; ++m) _Pragma("unroll") for (int k = 0; k < 2; ++k) dst[m][k] = *(const PG8_LAS bf16x8*)(lds + PG8_SA(b, h) + aoff + m * 2048 + k * 1024); } while (0)
; #define PG8_LDB(dst, b, h) do { _Pragma("unroll") for (int n = 0; n < 2; ++n) _Pragma("unroll") for (int k = 0; k < 2; ++k) dst[n][k] = *(const PG8_LAS bf16x8*)(lds + PG8_SB(b, h) + boff + n * 2048 + k * 1024); } while (0)
; #define PG8_MMA(ai, bj, At, Bt) do { __builtin_amdgcn_s_setprio(1); _Pragma("unroll") for (int m = 0; m < 4; ++m) _Pragma("unroll") for (int n = 0; n < 2; ++n) _Pragma("unroll") for (int k = 0; k < 2; ++k) \
;         acc[ai][bj][m][n] = __builtin_amdgcn_mfma_f32_16x16x32_bf16(Bt[n][k], At[m][k], acc[ai][bj][m][n], 0, 0, 0); __builtin_amdgcn_s_setprio(0); } while (0)
; #define PG8_WAIT_V(n) asm volatile("s_waitcnt vmcnt(" #n ")" ::: "memory")
; #define PG8_WAIT_L(n) asm volatile("s_waitcnt lgkmcnt(" #n ")" ::: "memory")
; #define PG8_BAR __builtin_amdgcn_s_barrier()
; #define PG8_SCHED __builtin_amdgcn_sched_barrier(0)
; template <class Epi, class Sched, bool ALIGN_EPI = false, bool SP2 = false>
; __device__ __forceinline__ void gemm_phase(PG8_LAS unsigned char* lds, const Gemm g, const Sched& S, const Epi& E) {
;     ...
;             if constexpr (SP2) {
;             PG8_LDB(B0, 0, 0); PG8_LDB(B1, 0, 1); PG8_SCHED; PG8_LDA(At, 0, 0); PG8_STAGE(PG8_SA(1, 1), a1 + hstep, voffA);
;             PG8_WAIT_V(8); PG8_WAIT_L(0); PG8_BAR; PG8_MMA(0, 0, At, B0); PG8_MMA(0, 1, At, B1); PG8_BAR; PG8_SCHED;
;     ...
;             PG8_LDA(At, 1, 1); PG8_STAGE(PG8_SB(1, 0), b3, voffB); PG8_STAGE(PG8_SB(1, 1), b3 + hstep, voffB); PG8_STAGE(PG8_SA(1, 0), a3, voffA);
;             PG8_WAIT_V(8); PG8_WAIT_L(0); PG8_BAR; PG8_MMA(1, 0, At, B0); PG8_MMA(1, 1, At, B1); PG8_BAR; PG8_SCHED;
	s_add_i32 s66, s75, s29
	v_lshl_add_u64 v[144:145], v[144:145], 0, s[12:13]
	s_mov_b32 m0, s66
	ds_read_b128 v[180:183], v151 offset:49152
	ds_read_b128 v[184:187], v151 offset:50176
	ds_read_b128 v[190:193], v151 offset:51200
	ds_read_b128 v[194:197], v151 offset:52224
	ds_read_b128 v[198:201], v151 offset:53248
	ds_read_b128 v[202:205], v151 offset:54272
	ds_read_b128 v[206:209], v151 offset:55296
	ds_read_b128 v[214:217], v151 offset:56320
	global_load_lds_dwordx4 v[144:145], off
	s_add_i32 m0, s66, 0x2000
	s_add_u32 s64, s64, 0x20080
	v_lshl_add_u64 v[144:145], v[210:211], 0, s[12:13]
	s_addc_u32 s65, s65, 0
	s_add_i32 s66, s84, s29
	global_load_lds_dwordx4 v[144:145], off
	v_lshl_add_u64 v[144:145], s[64:65], 0, v[132:133]
	s_mov_b32 m0, s66
	s_nop 0
	global_load_lds_dwordx4 v[144:145], off
	v_lshl_add_u64 v[144:145], s[64:65], 0, v[128:129]
	s_add_i32 m0, s66, 0x2000
	s_nop 0
	global_load_lds_dwordx4 v[144:145], off
	v_lshl_add_u64 v[144:145], v[218:219], 0, s[12:13]
	s_mov_b32 m0, s68
	s_nop 0
	global_load_lds_dwordx4 v[144:145], off
	v_lshl_add_u64 v[144:145], v[220:221], 0, s[12:13]
	s_mov_b32 m0, s69
	s_nop 0
	global_load_lds_dwordx4 v[144:145], off
	s_waitcnt vmcnt(8)
	s_waitcnt lgkmcnt(0)
	s_barrier
	s_waitcnt lgkmcnt(0)
	v_mfma_f32_16x16x32_bf16 v[60:63], v[140:143], v[180:183], v[60:63]
	v_mfma_f32_16x16x32_bf16 v[56:59], v[156:159], v[180:183], v[56:59]
	v_mfma_f32_16x16x32_bf16 v[44:47], v[140:143], v[190:193], v[44:47]
	v_mfma_f32_16x16x32_bf16 v[40:43], v[156:159], v[190:193], v[40:43]
	v_mfma_f32_16x16x32_bf16 v[28:31], v[140:143], v[198:201], v[28:31]
	v_mfma_f32_16x16x32_bf16 v[24:27], v[156:159], v[198:201], v[24:27]
	v_mfma_f32_16x16x32_bf16 v[12:15], v[140:143], v[206:209], v[12:15]
	v_mfma_f32_16x16x32_bf16 v[8:11], v[156:159], v[206:209], v[8:11]
	v_mfma_f32_16x16x32_bf16 v[60:63], v[152:155], v[184:187], v[60:63]
	v_mfma_f32_16x16x32_bf16 v[56:59], v[160:163], v[184:187], v[56:59]
	v_mfma_f32_16x16x32_bf16 v[44:47], v[152:155], v[194:197], v[44:47]
	v_mfma_f32_16x16x32_bf16 v[40:43], v[160:163], v[194:197], v[40:43]
	v_mfma_f32_16x16x32_bf16 v[28:31], v[152:155], v[202:205], v[28:31]
	v_mfma_f32_16x16x32_bf16 v[24:27], v[160:163], v[202:205], v[24:27]
	v_mfma_f32_16x16x32_bf16 v[12:15], v[152:155], v[214:217], v[12:15]
	v_mfma_f32_16x16x32_bf16 v[8:11], v[160:163], v[214:217], v[8:11]
	v_mfma_f32_16x16x32_bf16 v[52:55], v[164:167], v[180:183], v[52:55]
	v_mfma_f32_16x16x32_bf16 v[48:51], v[172:175], v[180:183], v[48:51]
	v_mfma_f32_16x16x32_bf16 v[36:39], v[164:167], v[190:193], v[36:39]
	v_mfma_f32_16x16x32_bf16 v[32:35], v[172:175], v[190:193], v[32:35]
	v_mfma_f32_16x16x32_bf16 v[20:23], v[164:167], v[198:201], v[20:23]
	v_mfma_f32_16x16x32_bf16 v[16:19], v[172:175], v[198:201], v[16:19]
	v_mfma_f32_16x16x32_bf16 v[4:7], v[164:167], v[206:209], v[4:7]
	v_mfma_f32_16x16x32_bf16 v[0:3], v[172:175], v[206:209], v[0:3]
	v_mfma_f32_16x16x32_bf16 v[52:55], v[168:171], v[184:187], v[52:55]
	v_mfma_f32_16x16x32_bf16 v[48:51], v[176:179], v[184:187], v[48:51]
	v_mfma_f32_16x16x32_bf16 v[36:39], v[168:171], v[194:197], v[36:39]
	v_mfma_f32_16x16x32_bf16 v[32:35], v[176:179], v[194:197], v[32:35]
	v_mfma_f32_16x16x32_bf16 v[20:23], v[168:171], v[202:205], v[20:23]
	v_mfma_f32_16x16x32_bf16 v[16:19], v[176:179], v[202:205], v[16:19]
	v_mfma_f32_16x16x32_bf16 v[4:7], v[168:171], v[214:217], v[4:7]
	v_mfma_f32_16x16x32_bf16 v[0:3], v[176:179], v[214:217], v[0:3]
	s_barrier
	s_add_i32 s78, s78, 2
	s_add_u32 s62, s62, 0x100
	s_addc_u32 s63, s63, 0
	s_add_u32 s37, s37, 0x100
	s_addc_u32 s77, s77, 0
	s_cmp_gt_u32 s78, 5
.LBB0_535:
	ds_read_b128 v[140:143], v149
	ds_read_b128 v[152:155], v149 offset:1024
	ds_read_b128 v[156:159], v149 offset:2048
	ds_read_b128 v[160:163], v149 offset:3072
	ds_read_b128 v[164:167], v150
	ds_read_b128 v[168:171], v150 offset:1024
	ds_read_b128 v[172:175], v150 offset:2048
	ds_read_b128 v[176:179], v150 offset:3072
	s_add_u32 s64, s62, 0xfffe0080
	s_addc_u32 s65, s63, -1
	s_cmp_eq_u32 s78, 4
	s_cselect_b32 s67, s41, s65
	s_cselect_b32 s66, s76, s64
	s_cselect_b32 s65, s0, s77
	s_cselect_b32 s64, s1, s37
	v_lshl_add_u64 v[144:145], s[62:63], 0, v[136:137]
	s_add_i32 m0, s30, 0xc000
	ds_read_b128 v[180:183], v151
	ds_read_b128 v[184:187], v151 offset:1024
	ds_read_b128 v[190:193], v151 offset:2048
	ds_read_b128 v[194:197], v151 offset:3072
	ds_read_b128 v[198:201], v151 offset:4096
	ds_read_b128 v[202:205], v151 offset:5120
	ds_read_b128 v[206:209], v151 offset:6144
	ds_read_b128 v[214:217], v151 offset:7168
	global_load_lds_dwordx4 v[144:145], off
	v_lshl_add_u64 v[144:145], s[62:63], 0, v[138:139]
	s_add_i32 m0, s30, 0xe000
	s_nop 0
	global_load_lds_dwordx4 v[144:145], off
	s_waitcnt vmcnt(8)
	s_waitcnt lgkmcnt(0)
	s_barrier
; #define PG8_STAGE(bufoff, gbase, voff) do { _Pragma("unroll") for (int _i = 0; _i < 2; ++_i) \
;         __builtin_amdgcn_global_load_lds((const unsigned*)((const char*)(gbase) + (voff)[_i]), (PG8_LAS unsigned*)(lds + (bufoff) + ldsw + _i * 8192), 16, 0, 0); } while (0)
; #define PG8_LDA(dst, b, h) do { _Pragma("unroll") for (int m = 0; m < 4; ++m) _Pragma("unroll") for (int k = 0; k < 2; ++k) dst[m][k] = *(const PG8_LAS bf16x8*)(lds + PG8_SA(b, h) + aoff + m * 2048 + k * 1024); } while (0)
; #define PG8_MMA(ai, bj, At, Bt) do { __builtin_amdgcn_s_setprio(1); _Pragma("unroll") for (int m = 0; m < 4; ++m) _Pragma("unroll") for (int n = 0; n < 2; ++n) _Pragma("unroll") for (int k = 0; k < 2; ++k) \
;         acc[ai][bj][m][n] = __builtin_amdgcn_mfma_f32_16x16x32_bf16(Bt[n][k], At[m][k], acc[ai][bj][m][n], 0, 0, 0); __builtin_amdgcn_s_setprio(0); } while (0)
; #define PG8_WAIT_V(n) asm volatile("s_waitcnt vmcnt(" #n ")" ::: "memory")
; #define PG8_WAIT_L(n) asm volatile("s_waitcnt lgkmcnt(" #n ")" ::: "memory")
; #define PG8_BAR __builtin_amdgcn_s_barrier()
; #define PG8_SCHED __builtin_amdgcn_sched_barrier(0)
; template <class Epi, class Sched, bool ALIGN_EPI = false, bool SP2 = false>
; __device__ __forceinline__ void gemm_phase(PG8_LAS unsigned char* lds, const Gemm g, const Sched& S, const Epi& E) {
;     ...
;             PG8_WAIT_V(8); PG8_WAIT_L(0); PG8_BAR; PG8_MMA(0, 0, At, B0); PG8_MMA(0, 1, At, B1); PG8_BAR; PG8_SCHED;
;             PG8_LDA(At, 0, 1); PG8_STAGE(PG8_SB(0, 0), b2, voffB); PG8_STAGE(PG8_SB(0, 1), b2 + hstep, voffB); PG8_STAGE(PG8_SA(0, 0), a2, voffA);
;             PG8_WAIT_V(8); PG8_WAIT_L(0); PG8_BAR; PG8_MMA(1, 0, At, B0); PG8_MMA(1, 1, At, B1); PG8_BAR; PG8_SCHED;
	s_waitcnt lgkmcnt(0)
	v_mfma_f32_16x16x32_bf16 v[124:127], v[140:143], v[180:183], v[124:127]
	v_mfma_f32_16x16x32_bf16 v[120:123], v[156:159], v[180:183], v[120:123]
	v_mfma_f32_16x16x32_bf16 v[108:111], v[140:143], v[190:193], v[108:111]
	v_mfma_f32_16x16x32_bf16 v[104:107], v[156:159], v[190:193], v[104:107]
	v_mfma_f32_16x16x32_bf16 v[92:95], v[140:143], v[198:201], v[92:95]
	v_mfma_f32_16x16x32_bf16 v[88:91], v[156:159], v[198:201], v[88:91]
	v_mfma_f32_16x16x32_bf16 v[76:79], v[140:143], v[206:209], v[76:79]
	v_mfma_f32_16x16x32_bf16 v[72:75], v[156:159], v[206:209], v[72:75]
	v_mfma_f32_16x16x32_bf16 v[124:127], v[152:155], v[184:187], v[124:127]
	v_mfma_f32_16x16x32_bf16 v[120:123], v[160:163], v[184:187], v[120:123]
	v_mfma_f32_16x16x32_bf16 v[108:111], v[152:155], v[194:197], v[108:111]
	v_mfma_f32_16x16x32_bf16 v[104:107], v[160:163], v[194:197], v[104:107]
	v_mfma_f32_16x16x32_bf16 v[92:95], v[152:155], v[202:205], v[92:95]
	v_mfma_f32_16x16x32_bf16 v[88:91], v[160:163], v[202:205], v[88:91]
	v_mfma_f32_16x16x32_bf16 v[76:79], v[152:155], v[214:217], v[76:79]
	v_mfma_f32_16x16x32_bf16 v[72:75], v[160:163], v[214:217], v[72:75]
	v_mfma_f32_16x16x32_bf16 v[116:119], v[164:167], v[180:183], v[116:119]
	v_mfma_f32_16x16x32_bf16 v[112:115], v[172:175], v[180:183], v[112:115]
	v_mfma_f32_16x16x32_bf16 v[100:103], v[164:167], v[190:193], v[100:103]
	v_mfma_f32_16x16x32_bf16 v[96:99], v[172:175], v[190:193], v[96:99]
	v_mfma_f32_16x16x32_bf16 v[84:87], v[164:167], v[198:201], v[84:87]
	v_mfma_f32_16x16x32_bf16 v[80:83], v[172:175], v[198:201], v[80:83]
	v_mfma_f32_16x16x32_bf16 v[68:71], v[164:167], v[206:209], v[68:71]
	v_mfma_f32_16x16x32_bf16 v[64:67], v[172:175], v[206:209], v[64:67]
	v_mfma_f32_16x16x32_bf16 v[116:119], v[168:171], v[184:187], v[116:119]
	v_mfma_f32_16x16x32_bf16 v[112:115], v[176:179], v[184:187], v[112:115]
	v_mfma_f32_16x16x32_bf16 v[100:103], v[168:171], v[194:197], v[100:103]
	v_mfma_f32_16x16x32_bf16 v[96:99], v[176:179], v[194:197], v[96:99]
	v_mfma_f32_16x16x32_bf16 v[84:87], v[168:171], v[202:205], v[84:87]
	v_mfma_f32_16x16x32_bf16 v[80:83], v[176:179], v[202:205], v[80:83]
	v_mfma_f32_16x16x32_bf16 v[68:71], v[168:171], v[214:217], v[68:71]
	v_mfma_f32_16x16x32_bf16 v[64:67], v[176:179], v[214:217], v[64:67]
	s_barrier
	s_add_i32 s79, s31, s29
	v_lshl_add_u64 v[144:145], s[64:65], 0, v[132:133]
	s_mov_b32 m0, s79
	ds_read_b128 v[180:183], v151 offset:16384
	ds_read_b128 v[184:187], v151 offset:17408
	ds_read_b128 v[190:193], v151 offset:18432
	ds_read_b128 v[194:197], v151 offset:19456
	ds_read_b128 v[198:201], v151 offset:20480
	ds_read_b128 v[202:205], v151 offset:21504
	ds_read_b128 v[206:209], v151 offset:22528
	ds_read_b128 v[214:217], v151 offset:23552
	global_load_lds_dwordx4 v[144:145], off
	s_add_i32 m0, s79, 0x2000
	s_add_u32 s80, s64, 0x20000
	v_lshl_add_u64 v[210:211], s[64:65], 0, v[128:129]
	s_addc_u32 s81, s65, 0
	s_add_i32 s79, s74, s29
	global_load_lds_dwordx4 v[210:211], off
	v_lshl_add_u64 v[218:219], s[80:81], 0, v[132:133]
	s_mov_b32 m0, s79
	v_lshl_add_u64 v[220:221], s[66:67], 0, v[130:131]
	global_load_lds_dwordx4 v[218:219], off
	v_lshl_add_u64 v[218:219], s[80:81], 0, v[128:129]
	s_add_i32 m0, s79, 0x2000
	s_nop 0
	global_load_lds_dwordx4 v[218:219], off
	v_lshl_add_u64 v[218:219], s[66:67], 0, v[134:135]
	s_mov_b32 m0, s30
	s_nop 0
	global_load_lds_dwordx4 v[218:219], off
	s_mov_b32 m0, s33
	s_nop 0
	global_load_lds_dwordx4 v[220:221], off
	s_waitcnt vmcnt(8)
	s_waitcnt lgkmcnt(0)
	s_barrier
	s_waitcnt lgkmcnt(0)
	v_mfma_f32_16x16x32_bf16 v[60:63], v[140:143], v[180:183], v[60:63]
	v_mfma_f32_16x16x32_bf16 v[56:59], v[156:159], v[180:183], v[56:59]
	v_mfma_f32_16x16x32_bf16 v[44:47], v[140:143], v[190:193], v[44:47]
	v_mfma_f32_16x16x32_bf16 v[40:43], v[156:159], v[190:193], v[40:43]
	v_mfma_f32_16x16x32_bf16 v[28:31], v[140:143], v[198:201], v[28:31]
	v_mfma_f32_16x16x32_bf16 v[24:27], v[156:159], v[198:201], v[24:27]
	v_mfma_f32_16x16x32_bf16 v[12:15], v[140:143], v[206:209], v[12:15]
	v_mfma_f32_16x16x32_bf16 v[8:11], v[156:159], v[206:209], v[8:11]
	v_mfma_f32_16x16x32_bf16 v[60:63], v[152:155], v[184:187], v[60:63]
	v_mfma_f32_16x16x32_bf16 v[56:59], v[160:163], v[184:187], v[56:59]
	v_mfma_f32_16x16x32_bf16 v[44:47], v[152:155], v[194:197], v[44:47]
	v_mfma_f32_16x16x32_bf16 v[40:43], v[160:163], v[194:197], v[40:43]
	v_mfma_f32_16x16x32_bf16 v[28:31], v[152:155], v[202:205], v[28:31]
	v_mfma_f32_16x16x32_bf16 v[24:27], v[160:163], v[202:205], v[24:27]
	v_mfma_f32_16x16x32_bf16 v[12:15], v[152:155], v[214:217], v[12:15]
	v_mfma_f32_16x16x32_bf16 v[8:11], v[160:163], v[214:217], v[8:11]
	v_mfma_f32_16x16x32_bf16 v[52:55], v[164:167], v[180:183], v[52:55]
	v_mfma_f32_16x16x32_bf16 v[48:51], v[172:175], v[180:183], v[48:51]
	v_mfma_f32_16x16x32_bf16 v[36:39], v[164:167], v[190:193], v[36:39]
	v_mfma_f32_16x16x32_bf16 v[32:35], v[172:175], v[190:193], v[32:35]
	v_mfma_f32_16x16x32_bf16 v[20:23], v[164:167], v[198:201], v[20:23]
	v_mfma_f32_16x16x32_bf16 v[16:19], v[172:175], v[198:201], v[16:19]
	v_mfma_f32_16x16x32_bf16 v[4:7], v[164:167], v[206:209], v[4:7]
	v_mfma_f32_16x16x32_bf16 v[0:3], v[172:175], v[206:209], v[0:3]
	v_mfma_f32_16x16x32_bf16 v[52:55], v[168:171], v[184:187], v[52:55]
	v_mfma_f32_16x16x32_bf16 v[48:51], v[176:179], v[184:187], v[48:51]
	v_mfma_f32_16x16x32_bf16 v[36:39], v[168:171], v[194:197], v[36:39]
	v_mfma_f32_16x16x32_bf16 v[32:35], v[176:179], v[194:197], v[32:35]
	v_mfma_f32_16x16x32_bf16 v[20:23], v[168:171], v[202:205], v[20:23]
	v_mfma_f32_16x16x32_bf16 v[16:19], v[176:179], v[202:205], v[16:19]
	v_mfma_f32_16x16x32_bf16 v[4:7], v[168:171], v[214:217], v[4:7]
	v_mfma_f32_16x16x32_bf16 v[0:3], v[176:179], v[214:217], v[0:3]
	s_barrier
; #define PG8_STAGE(bufoff, gbase, voff) do { _Pragma("unroll") for (int _i = 0; _i < 2; ++_i) \
;         __builtin_amdgcn_global_load_lds((const unsigned*)((const char*)(gbase) + (voff)[_i]), (PG8_LAS unsigned*)(lds + (bufoff) + ldsw + _i * 8192), 16, 0, 0); } while (0)
; #define PG8_LDA(dst, b, h) do { _Pragma("unroll") for (int m = 0; m < 4; ++m) _Pragma("unroll") for (int k = 0; k < 2; ++k) dst[m][k] = *(const PG8_LAS bf16x8*)(lds + PG8_SA(b, h) + aoff + m * 2048 + k * 1024); } while (0)
; #define PG8_LDB(dst, b, h) do { _Pragma("unroll") for (int n = 0; n < 2; ++n) _Pragma("unroll") for (int k = 0; k < 2; ++k) dst[n][k] = *(const PG8_LAS bf16x8*)(lds + PG8_SB(b, h) + boff + n * 2048 + k * 1024); } while (0)
; #define PG8_MMA(ai, bj, At, Bt) do { __builtin_amdgcn_s_setprio(1); _Pragma("unroll") for (int m = 0; m < 4; ++m) _Pragma("unroll") for (int n = 0; n < 2; ++n) _Pragma("unroll") for (int k = 0; k < 2; ++k) \
;         acc[ai][bj][m][n] = __builtin_amdgcn_mfma_f32_16x16x32_bf16(Bt[n][k], At[m][k], acc[ai][bj][m][n], 0, 0, 0); __builtin_amdgcn_s_setprio(0); } while (0)
; #define PG8_WAIT_V(n) asm volatile("s_waitcnt vmcnt(" #n ")" ::: "memory")
; #define PG8_WAIT_L(n) asm volatile("s_waitcnt lgkmcnt(" #n ")" ::: "memory")
; #define PG8_BAR __builtin_amdgcn_s_barrier()
; #define PG8_SCHED __builtin_amdgcn_sched_barrier(0)
; template <class Epi, class Sched, bool ALIGN_EPI = false, bool SP2 = false>
; __device__ __forceinline__ void gemm_phase(PG8_LAS unsigned char* lds, const Gemm g, const Sched& S, const Epi& E) {
;     ...
;             PG8_LDB(B0, 1, 0); PG8_LDB(B1, 1, 1); PG8_SCHED; PG8_LDA(At, 1, 0); PG8_STAGE(PG8_SA(0, 1), a2 + hstep, voffA);
;             PG8_WAIT_V(8); PG8_WAIT_L(0); PG8_BAR; PG8_MMA(0, 0, At, B0); PG8_MMA(0, 1, At, B1); PG8_BAR; PG8_SCHED;
	v_add_u32_e32 v160, s75, v147
	v_add_u32_e32 v176, s84, v147
	ds_read_b128 v[140:143], v160
	ds_read_b128 v[152:155], v160 offset:1024
	ds_read_b128 v[156:159], v160 offset:2048
	ds_read_b128 v[160:163], v160 offset:3072
	ds_read_b128 v[164:167], v176
	ds_read_b128 v[168:171], v176 offset:1024
	ds_read_b128 v[172:175], v176 offset:2048
	ds_read_b128 v[176:179], v176 offset:3072
	s_add_u32 s66, s66, 0x20000
	s_addc_u32 s67, s67, 0
	s_mov_b32 m0, s56
	v_lshl_add_u64 v[222:223], s[66:67], 0, v[134:135]
	ds_read_b128 v[180:183], v151 offset:32768
	ds_read_b128 v[184:187], v151 offset:33792
	ds_read_b128 v[190:193], v151 offset:34816
	ds_read_b128 v[194:197], v151 offset:35840
	ds_read_b128 v[198:201], v151 offset:36864
	ds_read_b128 v[202:205], v151 offset:37888
	ds_read_b128 v[206:209], v151 offset:38912
	ds_read_b128 v[214:217], v151 offset:39936
	global_load_lds_dwordx4 v[222:223], off
	v_lshl_add_u64 v[222:223], s[66:67], 0, v[130:131]
	s_mov_b32 m0, s57
	s_nop 0
	global_load_lds_dwordx4 v[222:223], off
	s_waitcnt vmcnt(8)
	s_waitcnt lgkmcnt(0)
	s_barrier
	s_waitcnt lgkmcnt(0)
	v_mfma_f32_16x16x32_bf16 v[124:127], v[140:143], v[180:183], v[124:127]
	v_mfma_f32_16x16x32_bf16 v[120:123], v[156:159], v[180:183], v[120:123]
	v_mfma_f32_16x16x32_bf16 v[108:111], v[140:143], v[190:193], v[108:111]
	v_mfma_f32_16x16x32_bf16 v[104:107], v[156:159], v[190:193], v[104:107]
	v_mfma_f32_16x16x32_bf16 v[92:95], v[140:143], v[198:201], v[92:95]
	v_mfma_f32_16x16x32_bf16 v[88:91], v[156:159], v[198:201], v[88:91]
	v_mfma_f32_16x16x32_bf16 v[76:79], v[140:143], v[206:209], v[76:79]
	v_mfma_f32_16x16x32_bf16 v[72:75], v[156:159], v[206:209], v[72:75]
	v_mfma_f32_16x16x32_bf16 v[124:127], v[152:155], v[184:187], v[124:127]
	v_mfma_f32_16x16x32_bf16 v[120:123], v[160:163], v[184:187], v[120:123]
	v_mfma_f32_16x16x32_bf16 v[108:111], v[152:155], v[194:197], v[108:111]
	v_mfma_f32_16x16x32_bf16 v[104:107], v[160:163], v[194:197], v[104:107]
	v_mfma_f32_16x16x32_bf16 v[92:95], v[152:155], v[202:205], v[92:95]
	v_mfma_f32_16x16x32_bf16 v[88:91], v[160:163], v[202:205], v[88:91]
	v_mfma_f32_16x16x32_bf16 v[76:79], v[152:155], v[214:217], v[76:79]
	v_mfma_f32_16x16x32_bf16 v[72:75], v[160:163], v[214:217], v[72:75]
	v_mfma_f32_16x16x32_bf16 v[116:119], v[164:167], v[180:183], v[116:119]
	v_mfma_f32_16x16x32_bf16 v[112:115], v[172:175], v[180:183], v[112:115]
	v_mfma_f32_16x16x32_bf16 v[100:103], v[164:167], v[190:193], v[100:103]
	v_mfma_f32_16x16x32_bf16 v[96:99], v[172:175], v[190:193], v[96:99]
	v_mfma_f32_16x16x32_bf16 v[84:87], v[164:167], v[198:201], v[84:87]
	v_mfma_f32_16x16x32_bf16 v[80:83], v[172:175], v[198:201], v[80:83]
	v_mfma_f32_16x16x32_bf16 v[68:71], v[164:167], v[206:209], v[68:71]
	v_mfma_f32_16x16x32_bf16 v[64:67], v[172:175], v[206:209], v[64:67]
	v_mfma_f32_16x16x32_bf16 v[116:119], v[168:171], v[184:187], v[116:119]
	v_mfma_f32_16x16x32_bf16 v[112:115], v[176:179], v[184:187], v[112:115]
	v_mfma_f32_16x16x32_bf16 v[100:103], v[168:171], v[194:197], v[100:103]
	v_mfma_f32_16x16x32_bf16 v[96:99], v[176:179], v[194:197], v[96:99]
	v_mfma_f32_16x16x32_bf16 v[84:87], v[168:171], v[202:205], v[84:87]
	v_mfma_f32_16x16x32_bf16 v[80:83], v[176:179], v[202:205], v[80:83]
	v_mfma_f32_16x16x32_bf16 v[68:71], v[168:171], v[214:217], v[68:71]
	v_mfma_f32_16x16x32_bf16 v[64:67], v[176:179], v[214:217], v[64:67]
	s_barrier
; #define PG8_STAGE(bufoff, gbase, voff) do { _Pragma("unroll") for (int _i = 0; _i < 2; ++_i) \
;         __builtin_amdgcn_global_load_lds((const unsigned*)((const char*)(gbase) + (voff)[_i]), (PG8_LAS unsigned*)(lds + (bufoff) + ldsw + _i * 8192), 16, 0, 0); } while (0)
; #define PG8_LDA(dst, b, h) do { _Pragma("unroll") for (int m = 0; m < 4; ++m) _Pragma("unroll") for (int k = 0; k < 2; ++k) dst[m][k] = *(const PG8_LAS bf16x8*)(lds + PG8_SA(b, h) + aoff + m * 2048 + k * 1024); } while (0)
; #define PG8_MMA(ai, bj, At, Bt) do { __builtin_amdgcn_s_setprio(1); _Pragma("unroll") for (int m = 0; m < 4; ++m) _Pragma("unroll") for (int n = 0; n < 2; ++n) _Pragma("unroll") for (int k = 0; k < 2; ++k) \
;         acc[ai][bj][m][n] = __builtin_amdgcn_mfma_f32_16x16x32_bf16(Bt[n][k], At[m][k], acc[ai][bj][m][n], 0, 0, 0); __builtin_amdgcn_s_setprio(0); } while (0)
; #define PG8_WAIT_V(n) asm volatile("s_waitcnt vmcnt(" #n ")" ::: "memory")
; #define PG8_WAIT_L(n) asm volatile("s_waitcnt lgkmcnt(" #n ")" ::: "memory")
; #define PG8_BAR __builtin_amdgcn_s_barrier()
; #define PG8_SCHED __builtin_amdgcn_sched_barrier(0)
; template <class Epi, class Sched, bool ALIGN_EPI = false, bool SP2 = false>
; __device__ __forceinline__ void gemm_phase(PG8_LAS unsigned char* lds, const Gemm g, const Sched& S, const Epi& E) {
;     ...
;             PG8_LDA(At, 1, 1); PG8_STAGE(PG8_SB(1, 0), b3, voffB); PG8_STAGE(PG8_SB(1, 1), b3 + hstep, voffB); PG8_STAGE(PG8_SA(1, 0), a3, voffA);
;             PG8_WAIT_V(8); PG8_WAIT_L(0); PG8_BAR; PG8_MMA(1, 0, At, B0); PG8_MMA(1, 1, At, B1); PG8_BAR; PG8_SCHED;
;     ...
;         if constexpr (ALIGN_EPI) { if (wr == 0) PG8_BAR; }
	s_add_i32 s66, s75, s29
	v_lshl_add_u64 v[144:145], v[144:145], 0, s[12:13]
	s_mov_b32 m0, s66
	ds_read_b128 v[180:183], v151 offset:49152
	ds_read_b128 v[184:187], v151 offset:50176
	ds_read_b128 v[190:193], v151 offset:51200
	ds_read_b128 v[194:197], v151 offset:52224
	ds_read_b128 v[198:201], v151 offset:53248
	ds_read_b128 v[202:205], v151 offset:54272
	ds_read_b128 v[206:209], v151 offset:55296
	ds_read_b128 v[214:217], v151 offset:56320
	global_load_lds_dwordx4 v[144:145], off
	s_add_i32 m0, s66, 0x2000
	s_add_u32 s64, s64, 0x20080
	v_lshl_add_u64 v[144:145], v[210:211], 0, s[12:13]
	s_addc_u32 s65, s65, 0
	s_add_i32 s66, s84, s29
	global_load_lds_dwordx4 v[144:145], off
	v_lshl_add_u64 v[144:145], s[64:65], 0, v[132:133]
	s_mov_b32 m0, s66
	s_nop 0
	global_load_lds_dwordx4 v[144:145], off
	v_lshl_add_u64 v[144:145], s[64:65], 0, v[128:129]
	s_add_i32 m0, s66, 0x2000
	s_nop 0
	global_load_lds_dwordx4 v[144:145], off
	v_lshl_add_u64 v[144:145], v[218:219], 0, s[12:13]
	s_mov_b32 m0, s68
	s_nop 0
	global_load_lds_dwordx4 v[144:145], off
	v_lshl_add_u64 v[144:145], v[220:221], 0, s[12:13]
	s_mov_b32 m0, s69
	s_nop 0
	global_load_lds_dwordx4 v[144:145], off
	s_waitcnt vmcnt(8)
	s_waitcnt lgkmcnt(0)
	s_barrier
	s_waitcnt lgkmcnt(0)
	v_mfma_f32_16x16x32_bf16 v[60:63], v[140:143], v[180:183], v[60:63]
	v_mfma_f32_16x16x32_bf16 v[56:59], v[156:159], v[180:183], v[56:59]
	v_mfma_f32_16x16x32_bf16 v[44:47], v[140:143], v[190:193], v[44:47]
	v_mfma_f32_16x16x32_bf16 v[40:43], v[156:159], v[190:193], v[40:43]
	v_mfma_f32_16x16x32_bf16 v[28:31], v[140:143], v[198:201], v[28:31]
	v_mfma_f32_16x16x32_bf16 v[24:27], v[156:159], v[198:201], v[24:27]
	v_mfma_f32_16x16x32_bf16 v[12:15], v[140:143], v[206:209], v[12:15]
	v_mfma_f32_16x16x32_bf16 v[8:11], v[156:159], v[206:209], v[8:11]
	v_mfma_f32_16x16x32_bf16 v[60:63], v[152:155], v[184:187], v[60:63]
	v_mfma_f32_16x16x32_bf16 v[56:59], v[160:163], v[184:187], v[56:59]
	v_mfma_f32_16x16x32_bf16 v[44:47], v[152:155], v[194:197], v[44:47]
	v_mfma_f32_16x16x32_bf16 v[40:43], v[160:163], v[194:197], v[40:43]
	v_mfma_f32_16x16x32_bf16 v[28:31], v[152:155], v[202:205], v[28:31]
	v_mfma_f32_16x16x32_bf16 v[24:27], v[160:163], v[202:205], v[24:27]
	v_mfma_f32_16x16x32_bf16 v[12:15], v[152:155], v[214:217], v[12:15]
	v_mfma_f32_16x16x32_bf16 v[8:11], v[160:163], v[214:217], v[8:11]
	v_mfma_f32_16x16x32_bf16 v[52:55], v[164:167], v[180:183], v[52:55]
	v_mfma_f32_16x16x32_bf16 v[48:51], v[172:175], v[180:183], v[48:51]
	v_mfma_f32_16x16x32_bf16 v[36:39], v[164:167], v[190:193], v[36:39]
	v_mfma_f32_16x16x32_bf16 v[32:35], v[172:175], v[190:193], v[32:35]
	v_mfma_f32_16x16x32_bf16 v[20:23], v[164:167], v[198:201], v[20:23]
	v_mfma_f32_16x16x32_bf16 v[16:19], v[172:175], v[198:201], v[16:19]
	v_mfma_f32_16x16x32_bf16 v[4:7], v[164:167], v[206:209], v[4:7]
	v_mfma_f32_16x16x32_bf16 v[0:3], v[172:175], v[206:209], v[0:3]
	v_mfma_f32_16x16x32_bf16 v[52:55], v[168:171], v[184:187], v[52:55]
	v_mfma_f32_16x16x32_bf16 v[48:51], v[176:179], v[184:187], v[48:51]
	v_mfma_f32_16x16x32_bf16 v[36:39], v[168:171], v[194:197], v[36:39]
	v_mfma_f32_16x16x32_bf16 v[32:35], v[176:179], v[194:197], v[32:35]
	v_mfma_f32_16x16x32_bf16 v[20:23], v[168:171], v[202:205], v[20:23]
	v_mfma_f32_16x16x32_bf16 v[16:19], v[176:179], v[202:205], v[16:19]
	v_mfma_f32_16x16x32_bf16 v[4:7], v[168:171], v[214:217], v[4:7]
	v_mfma_f32_16x16x32_bf16 v[0:3], v[176:179], v[214:217], v[0:3]
	s_barrier
	s_add_i32 s78, s78, 2
	s_add_u32 s62, s62, 0x100
	s_addc_u32 s63, s63, 0
	s_add_u32 s37, s37, 0x100
	s_addc_u32 s77, s77, 0
	s_cmp_gt_u32 s78, 5
	s_cbranch_scc0 .LBB0_535
	s_and_b64 vcc, exec, s[14:15]
	s_cbranch_vccz .LBB0_538
	s_barrier

; #define PG8_STAGE(bufoff, gbase, voff) do { _Pragma("unroll") for (int _i = 0; _i < 2; ++_i) \
;         __builtin_amdgcn_global_load_lds((const unsigned*)((const char*)(gbase) + (voff)[_i]), (PG8_LAS unsigned*)(lds + (bufoff) + ldsw + _i * 8192), 16, 0, 0); } while (0)
; #define PG8_LDA(dst, b, h) do { _Pragma("unroll") for (int m = 0; m < 4; ++m) _Pragma("unroll") for (int k = 0; k < 2; ++k) dst[m][k] = *(const PG8_LAS bf16x8*)(lds + PG8_SA(b, h) + aoff + m * 2048 + k * 1024); } while (0)
; #define PG8_LDB(dst, b, h) do { _Pragma("unroll") for (int n = 0; n < 2; ++n) _Pragma("unroll") for (int k = 0; k < 2; ++k) dst[n][k] = *(const PG8_LAS bf16x8*)(lds + PG8_SB(b, h) + boff + n * 2048 + k * 1024); } while (0)
; #define PG8_MMA(ai, bj, At, Bt) do { __builtin_amdgcn_s_setprio(1); _Pragma("unroll") for (int m = 0; m < 4; ++m) _Pragma("unroll") for (int n = 0; n < 2; ++n) _Pragma("unroll") for (int k = 0; k < 2; ++k) \
;         acc[ai][bj][m][n] = __builtin_amdgcn_mfma_f32_16x16x32_bf16(Bt[n][k], At[m][k], acc[ai][bj][m][n], 0, 0, 0); __builtin_amdgcn_s_setprio(0); } while (0)
; #define PG8_WAIT_V(n) asm volatile("s_waitcnt vmcnt(" #n ")" ::: "memory")
; #define PG8_BAR __builtin_amdgcn_s_barrier()
; template <class Epi, class Sched, bool ALIGN_EPI = false, bool SP2 = false>
; __device__ __forceinline__ void gemm_phase(PG8_LAS unsigned char* lds, const Gemm g, const Sched& S, const Epi& E) {
;     ...
;         for (int t = seg * tseg; t < (seg + 1) * tseg; t += 2) {
;             const bool last = (t == nt - 2);
;             const char* a1 = cA + (size_t)(t + 1) * kstep;
;             const char* a2 = last ? nA : cA + (size_t)(t + 2) * kstep; const char* b2 = last ? nB : cB + (size_t)(t + 2) * kstep;
;             const char* a3 = a2 + kstep; const char* b3 = b2 + kstep;
;             if (last && has_next) S.a_ready(nxt);
;             if constexpr (SP2) {
;             PG8_LDB(B0, 0, 0); PG8_LDB(B1, 0, 1); PG8_SCHED; PG8_LDA(At, 0, 0); PG8_STAGE(PG8_SA(1, 1), a1 + hstep, voffA);
;             PG8_WAIT_V(8); PG8_WAIT_L(0); PG8_BAR; PG8_MMA(0, 0, At, B0); PG8_MMA(0, 1, At, B1); PG8_BAR; PG8_SCHED;
;             PG8_LDA(At, 0, 1); PG8_STAGE(PG8_SB(0, 0), b2, voffB); PG8_STAGE(PG8_SB(0, 1), b2 + hstep, voffB); PG8_STAGE(PG8_SA(0, 0), a2, voffA);
;             PG8_WAIT_V(8); PG8_WAIT_L(0); PG8_BAR; PG8_MMA(1, 0, At, B0); PG8_MMA(1, 1, At, B1); PG8_BAR; PG8_SCHED;
.LBB0_702:
	v_lshl_add_u64 v[148:149], s[62:63], 0, v[136:137]
	v_lshl_add_u64 v[150:151], s[62:63], 0, v[138:139]
	v_lshl_add_u64 v[152:153], s[60:61], 0, v[140:141]
	v_lshl_add_u64 v[154:155], s[60:61], 0, v[142:143]
	s_mov_b32 s59, -2
	s_mov_b64 s[64:65], 0
	ds_read_b128 v[162:165], v159
	ds_read_b128 v[166:169], v159 offset:1024
	ds_read_b128 v[170:173], v159 offset:2048
	ds_read_b128 v[174:177], v159 offset:3072
	ds_read_b128 v[178:181], v160
	ds_read_b128 v[182:185], v160 offset:1024
	ds_read_b128 v[190:193], v160 offset:2048
	ds_read_b128 v[194:197], v160 offset:3072
	v_lshl_add_u64 v[210:211], v[148:149], 0, s[64:65]
	s_mov_b32 m0, s77
	v_lshl_add_u64 v[186:187], v[210:211], 0, s[10:11]
	v_lshl_add_u64 v[234:235], v[150:151], 0, s[64:65]
	ds_read_b128 v[198:201], v161
	ds_read_b128 v[202:205], v161 offset:1024
	ds_read_b128 v[206:209], v161 offset:2048
	ds_read_b128 v[214:217], v161 offset:3072
	ds_read_b128 v[218:221], v161 offset:4096
	ds_read_b128 v[222:225], v161 offset:5120
	ds_read_b128 v[226:229], v161 offset:6144
	ds_read_b128 v[230:233], v161 offset:7168
	global_load_lds_dwordx4 v[186:187], off
	v_lshl_add_u64 v[186:187], v[234:235], 0, s[10:11]
	s_mov_b32 m0, s78
	s_nop 0
	global_load_lds_dwordx4 v[186:187], off
	s_waitcnt vmcnt(8)
	s_waitcnt lgkmcnt(0)
	s_barrier
	s_waitcnt lgkmcnt(0)
	v_mfma_f32_16x16x32_bf16 v[124:127], v[162:165], v[198:201], 0
	v_mfma_f32_16x16x32_bf16 v[120:123], v[170:173], v[198:201], 0
	v_mfma_f32_16x16x32_bf16 v[116:119], v[162:165], v[206:209], 0
	v_mfma_f32_16x16x32_bf16 v[112:115], v[170:173], v[206:209], 0
	v_mfma_f32_16x16x32_bf16 v[108:111], v[162:165], v[218:221], 0
	v_mfma_f32_16x16x32_bf16 v[104:107], v[170:173], v[218:221], 0
	v_mfma_f32_16x16x32_bf16 v[100:103], v[162:165], v[226:229], 0
	v_mfma_f32_16x16x32_bf16 v[96:99], v[170:173], v[226:229], 0
	v_mfma_f32_16x16x32_bf16 v[124:127], v[166:169], v[202:205], v[124:127]
	v_mfma_f32_16x16x32_bf16 v[120:123], v[174:177], v[202:205], v[120:123]
	v_mfma_f32_16x16x32_bf16 v[116:119], v[166:169], v[214:217], v[116:119]
	v_mfma_f32_16x16x32_bf16 v[112:115], v[174:177], v[214:217], v[112:115]
	v_mfma_f32_16x16x32_bf16 v[108:111], v[166:169], v[222:225], v[108:111]
	v_mfma_f32_16x16x32_bf16 v[104:107], v[174:177], v[222:225], v[104:107]
	v_mfma_f32_16x16x32_bf16 v[100:103], v[166:169], v[230:233], v[100:103]
	v_mfma_f32_16x16x32_bf16 v[96:99], v[174:177], v[230:233], v[96:99]
	v_mfma_f32_16x16x32_bf16 v[88:91], v[178:181], v[198:201], 0
	v_mfma_f32_16x16x32_bf16 v[92:95], v[190:193], v[198:201], 0
	v_mfma_f32_16x16x32_bf16 v[80:83], v[178:181], v[206:209], 0
	v_mfma_f32_16x16x32_bf16 v[84:87], v[190:193], v[206:209], 0
	v_mfma_f32_16x16x32_bf16 v[72:75], v[178:181], v[218:221], 0
	v_mfma_f32_16x16x32_bf16 v[76:79], v[190:193], v[218:221], 0
	v_mfma_f32_16x16x32_bf16 v[64:67], v[178:181], v[226:229], 0
	v_mfma_f32_16x16x32_bf16 v[68:71], v[190:193], v[226:229], 0
	v_mfma_f32_16x16x32_bf16 v[88:91], v[182:185], v[202:205], v[88:91]
	v_mfma_f32_16x16x32_bf16 v[92:95], v[194:197], v[202:205], v[92:95]
	v_mfma_f32_16x16x32_bf16 v[80:83], v[182:185], v[214:217], v[80:83]
	v_mfma_f32_16x16x32_bf16 v[84:87], v[194:197], v[214:217], v[84:87]
	v_mfma_f32_16x16x32_bf16 v[72:75], v[182:185], v[222:225], v[72:75]
	v_mfma_f32_16x16x32_bf16 v[76:79], v[194:197], v[222:225], v[76:79]
	v_mfma_f32_16x16x32_bf16 v[64:67], v[182:185], v[230:233], v[64:67]
	v_mfma_f32_16x16x32_bf16 v[68:71], v[194:197], v[230:233], v[68:71]
	s_barrier
	v_lshl_add_u64 v[236:237], v[152:153], 0, s[64:65]
	s_mov_b32 m0, s79
	v_lshl_add_u64 v[186:187], v[236:237], 0, s[14:15]
	v_lshl_add_u64 v[238:239], v[154:155], 0, s[64:65]
	ds_read_b128 v[198:201], v161 offset:16384
	ds_read_b128 v[202:205], v161 offset:17408
	ds_read_b128 v[206:209], v161 offset:18432
	ds_read_b128 v[214:217], v161 offset:19456
	ds_read_b128 v[218:221], v161 offset:20480
	ds_read_b128 v[222:225], v161 offset:21504
	ds_read_b128 v[226:229], v161 offset:22528
	ds_read_b128 v[230:233], v161 offset:23552
	global_load_lds_dwordx4 v[186:187], off
	v_lshl_add_u64 v[186:187], v[238:239], 0, s[14:15]
	s_mov_b32 m0, s80
	s_add_i32 s0, s74, s23
	global_load_lds_dwordx4 v[186:187], off
	v_lshl_add_u64 v[186:187], v[236:237], 0, s[36:37]
	s_mov_b32 m0, s0
	s_add_i32 s1, s0, 0x2000
	global_load_lds_dwordx4 v[186:187], off
	v_lshl_add_u64 v[186:187], v[238:239], 0, s[36:37]
	s_mov_b32 m0, s1
	s_nop 0
	global_load_lds_dwordx4 v[186:187], off
	v_lshl_add_u64 v[186:187], v[210:211], 0, s[14:15]
	s_mov_b32 m0, s28
	s_nop 0
	global_load_lds_dwordx4 v[186:187], off
	v_lshl_add_u64 v[186:187], v[234:235], 0, s[14:15]
	s_mov_b32 m0, s29
	s_nop 0
	global_load_lds_dwordx4 v[186:187], off
	s_waitcnt vmcnt(8)
	s_waitcnt lgkmcnt(0)
	s_barrier
; #define PG8_STAGE(bufoff, gbase, voff) do { _Pragma("unroll") for (int _i = 0; _i < 2; ++_i) \
;         __builtin_amdgcn_global_load_lds((const unsigned*)((const char*)(gbase) + (voff)[_i]), (PG8_LAS unsigned*)(lds + (bufoff) + ldsw + _i * 8192), 16, 0, 0); } while (0)
; #define PG8_LDA(dst, b, h) do { _Pragma("unroll") for (int m = 0; m < 4; ++m) _Pragma("unroll") for (int k = 0; k < 2; ++k) dst[m][k] = *(const PG8_LAS bf16x8*)(lds + PG8_SA(b, h) + aoff + m * 2048 + k * 1024); } while (0)
; #define PG8_LDB(dst, b, h) do { _Pragma("unroll") for (int n = 0; n < 2; ++n) _Pragma("unroll") for (int k = 0; k < 2; ++k) dst[n][k] = *(const PG8_LAS bf16x8*)(lds + PG8_SB(b, h) + boff + n * 2048 + k * 1024); } while (0)
; #define PG8_MMA(ai, bj, At, Bt) do { __builtin_amdgcn_s_setprio(1); _Pragma("unroll") for (int m = 0; m < 4; ++m) _Pragma("unroll") for (int n = 0; n < 2; ++n) _Pragma("unroll") for (int k = 0; k < 2; ++k) \
;         acc[ai][bj][m][n] = __builtin_amdgcn_mfma_f32_16x16x32_bf16(Bt[n][k], At[m][k], acc[ai][bj][m][n], 0, 0, 0); __builtin_amdgcn_s_setprio(0); } while (0)
; #define PG8_WAIT_V(n) asm volatile("s_waitcnt vmcnt(" #n ")" ::: "memory")
; #define PG8_WAIT_L(n) asm volatile("s_waitcnt lgkmcnt(" #n ")" ::: "memory")
; #define PG8_BAR __builtin_amdgcn_s_barrier()
; #define PG8_SCHED __builtin_amdgcn_sched_barrier(0)
; template <class Epi, class Sched, bool ALIGN_EPI = false, bool SP2 = false>
; __device__ __forceinline__ void gemm_phase(PG8_LAS unsigned char* lds, const Gemm g, const Sched& S, const Epi& E) {
;     ...
;             PG8_WAIT_V(8); PG8_WAIT_L(0); PG8_BAR; PG8_MMA(1, 0, At, B0); PG8_MMA(1, 1, At, B1); PG8_BAR; PG8_SCHED;
;             PG8_LDB(B0, 1, 0); PG8_LDB(B1, 1, 1); PG8_SCHED; PG8_LDA(At, 1, 0); PG8_STAGE(PG8_SA(0, 1), a2 + hstep, voffA);
;             PG8_WAIT_V(8); PG8_WAIT_L(0); PG8_BAR; PG8_MMA(0, 0, At, B0); PG8_MMA(0, 1, At, B1); PG8_BAR; PG8_SCHED;
	s_waitcnt lgkmcnt(0)
	v_mfma_f32_16x16x32_bf16 v[60:63], v[162:165], v[198:201], 0
	v_mfma_f32_16x16x32_bf16 v[56:59], v[170:173], v[198:201], 0
	v_mfma_f32_16x16x32_bf16 v[44:47], v[162:165], v[206:209], 0
	v_mfma_f32_16x16x32_bf16 v[40:43], v[170:173], v[206:209], 0
	v_mfma_f32_16x16x32_bf16 v[28:31], v[162:165], v[218:221], 0
	v_mfma_f32_16x16x32_bf16 v[24:27], v[170:173], v[218:221], 0
	v_mfma_f32_16x16x32_bf16 v[12:15], v[162:165], v[226:229], 0
	v_mfma_f32_16x16x32_bf16 v[8:11], v[170:173], v[226:229], 0
	v_mfma_f32_16x16x32_bf16 v[60:63], v[166:169], v[202:205], v[60:63]
	v_mfma_f32_16x16x32_bf16 v[56:59], v[174:177], v[202:205], v[56:59]
	v_mfma_f32_16x16x32_bf16 v[44:47], v[166:169], v[214:217], v[44:47]
	v_mfma_f32_16x16x32_bf16 v[40:43], v[174:177], v[214:217], v[40:43]
	v_mfma_f32_16x16x32_bf16 v[28:31], v[166:169], v[222:225], v[28:31]
	v_mfma_f32_16x16x32_bf16 v[24:27], v[174:177], v[222:225], v[24:27]
	v_mfma_f32_16x16x32_bf16 v[12:15], v[166:169], v[230:233], v[12:15]
	v_mfma_f32_16x16x32_bf16 v[8:11], v[174:177], v[230:233], v[8:11]
	v_mfma_f32_16x16x32_bf16 v[52:55], v[178:181], v[198:201], 0
	v_mfma_f32_16x16x32_bf16 v[48:51], v[190:193], v[198:201], 0
	v_mfma_f32_16x16x32_bf16 v[36:39], v[178:181], v[206:209], 0
	v_mfma_f32_16x16x32_bf16 v[32:35], v[190:193], v[206:209], 0
	v_mfma_f32_16x16x32_bf16 v[20:23], v[178:181], v[218:221], 0
	v_mfma_f32_16x16x32_bf16 v[16:19], v[190:193], v[218:221], 0
	v_mfma_f32_16x16x32_bf16 v[4:7], v[178:181], v[226:229], 0
	v_mfma_f32_16x16x32_bf16 v[0:3], v[190:193], v[226:229], 0
	v_mfma_f32_16x16x32_bf16 v[52:55], v[182:185], v[202:205], v[52:55]
	v_mfma_f32_16x16x32_bf16 v[48:51], v[194:197], v[202:205], v[48:51]
	v_mfma_f32_16x16x32_bf16 v[36:39], v[182:185], v[214:217], v[36:39]
	v_mfma_f32_16x16x32_bf16 v[32:35], v[194:197], v[214:217], v[32:35]
	v_mfma_f32_16x16x32_bf16 v[20:23], v[182:185], v[222:225], v[20:23]
	v_mfma_f32_16x16x32_bf16 v[16:19], v[194:197], v[222:225], v[16:19]
	v_mfma_f32_16x16x32_bf16 v[4:7], v[182:185], v[230:233], v[4:7]
	v_mfma_f32_16x16x32_bf16 v[0:3], v[194:197], v[230:233], v[0:3]
	s_barrier
	v_add_u32_e32 v162, s75, v157
	v_add_u32_e32 v163, s84, v157
	ds_read_b128 v[164:167], v162
	ds_read_b128 v[168:171], v162 offset:1024
	ds_read_b128 v[172:175], v162 offset:2048
	ds_read_b128 v[176:179], v162 offset:3072
	ds_read_b128 v[180:183], v163
	ds_read_b128 v[184:187], v163 offset:1024
	ds_read_b128 v[190:193], v163 offset:2048
	ds_read_b128 v[194:197], v163 offset:3072
	s_mov_b32 m0, s30
	v_lshl_add_u64 v[240:241], v[210:211], 0, s[36:37]
	ds_read_b128 v[198:201], v161 offset:32768
	ds_read_b128 v[202:205], v161 offset:33792
	ds_read_b128 v[206:209], v161 offset:34816
	ds_read_b128 v[214:217], v161 offset:35840
	ds_read_b128 v[218:221], v161 offset:36864
	ds_read_b128 v[222:225], v161 offset:37888
	ds_read_b128 v[226:229], v161 offset:38912
	ds_read_b128 v[230:233], v161 offset:39936
	global_load_lds_dwordx4 v[240:241], off
	v_lshl_add_u64 v[240:241], v[234:235], 0, s[36:37]
	s_mov_b32 m0, s33
	s_nop 0
	global_load_lds_dwordx4 v[240:241], off
	s_waitcnt vmcnt(8)
	s_waitcnt lgkmcnt(0)
	s_barrier
	s_waitcnt lgkmcnt(0)
	v_mfma_f32_16x16x32_bf16 v[124:127], v[164:167], v[198:201], v[124:127]
	v_mfma_f32_16x16x32_bf16 v[120:123], v[172:175], v[198:201], v[120:123]
	v_mfma_f32_16x16x32_bf16 v[116:119], v[164:167], v[206:209], v[116:119]
	v_mfma_f32_16x16x32_bf16 v[112:115], v[172:175], v[206:209], v[112:115]
	v_mfma_f32_16x16x32_bf16 v[108:111], v[164:167], v[218:221], v[108:111]
	v_mfma_f32_16x16x32_bf16 v[104:107], v[172:175], v[218:221], v[104:107]
	v_mfma_f32_16x16x32_bf16 v[100:103], v[164:167], v[226:229], v[100:103]
	v_mfma_f32_16x16x32_bf16 v[96:99], v[172:175], v[226:229], v[96:99]
	v_mfma_f32_16x16x32_bf16 v[124:127], v[168:171], v[202:205], v[124:127]
	v_mfma_f32_16x16x32_bf16 v[120:123], v[176:179], v[202:205], v[120:123]
	v_mfma_f32_16x16x32_bf16 v[116:119], v[168:171], v[214:217], v[116:119]
	v_mfma_f32_16x16x32_bf16 v[112:115], v[176:179], v[214:217], v[112:115]
	v_mfma_f32_16x16x32_bf16 v[108:111], v[168:171], v[222:225], v[108:111]
	v_mfma_f32_16x16x32_bf16 v[104:107], v[176:179], v[222:225], v[104:107]
	v_mfma_f32_16x16x32_bf16 v[100:103], v[168:171], v[230:233], v[100:103]
	v_mfma_f32_16x16x32_bf16 v[96:99], v[176:179], v[230:233], v[96:99]
	v_mfma_f32_16x16x32_bf16 v[88:91], v[180:183], v[198:201], v[88:91]
	v_mfma_f32_16x16x32_bf16 v[92:95], v[190:193], v[198:201], v[92:95]
	v_mfma_f32_16x16x32_bf16 v[80:83], v[180:183], v[206:209], v[80:83]
	v_mfma_f32_16x16x32_bf16 v[84:87], v[190:193], v[206:209], v[84:87]
	v_mfma_f32_16x16x32_bf16 v[72:75], v[180:183], v[218:221], v[72:75]
	v_mfma_f32_16x16x32_bf16 v[76:79], v[190:193], v[218:221], v[76:79]
	v_mfma_f32_16x16x32_bf16 v[64:67], v[180:183], v[226:229], v[64:67]
	v_mfma_f32_16x16x32_bf16 v[68:71], v[190:193], v[226:229], v[68:71]
	v_mfma_f32_16x16x32_bf16 v[88:91], v[184:187], v[202:205], v[88:91]
	v_mfma_f32_16x16x32_bf16 v[92:95], v[194:197], v[202:205], v[92:95]
	v_mfma_f32_16x16x32_bf16 v[80:83], v[184:187], v[214:217], v[80:83]
	v_mfma_f32_16x16x32_bf16 v[84:87], v[194:197], v[214:217], v[84:87]
	v_mfma_f32_16x16x32_bf16 v[72:75], v[184:187], v[222:225], v[72:75]
	v_mfma_f32_16x16x32_bf16 v[76:79], v[194:197], v[222:225], v[76:79]
	v_mfma_f32_16x16x32_bf16 v[64:67], v[184:187], v[230:233], v[64:67]
	v_mfma_f32_16x16x32_bf16 v[68:71], v[194:197], v[230:233], v[68:71]
	s_barrier
; #define PG8_STAGE(bufoff, gbase, voff) do { _Pragma("unroll") for (int _i = 0; _i < 2; ++_i) \
;         __builtin_amdgcn_global_load_lds((const unsigned*)((const char*)(gbase) + (voff)[_i]), (PG8_LAS unsigned*)(lds + (bufoff) + ldsw + _i * 8192), 16, 0, 0); } while (0)
; #define PG8_LDA(dst, b, h) do { _Pragma("unroll") for (int m = 0; m < 4; ++m) _Pragma("unroll") for (int k = 0; k < 2; ++k) dst[m][k] = *(const PG8_LAS bf16x8*)(lds + PG8_SA(b, h) + aoff + m * 2048 + k * 1024); } while (0)
; #define PG8_LDB(dst, b, h) do { _Pragma("unroll") for (int n = 0; n < 2; ++n) _Pragma("unroll") for (int k = 0; k < 2; ++k) dst[n][k] = *(const PG8_LAS bf16x8*)(lds + PG8_SB(b, h) + boff + n * 2048 + k * 1024); } while (0)
; #define PG8_MMA(ai, bj, At, Bt) do { __builtin_amdgcn_s_setprio(1); _Pragma("unroll") for (int m = 0; m < 4; ++m) _Pragma("unroll") for (int n = 0; n < 2; ++n) _Pragma("unroll") for (int k = 0; k < 2; ++k) \
;         acc[ai][bj][m][n] = __builtin_amdgcn_mfma_f32_16x16x32_bf16(Bt[n][k], At[m][k], acc[ai][bj][m][n], 0, 0, 0); __builtin_amdgcn_s_setprio(0); } while (0)
; #define PG8_WAIT_V(n) asm volatile("s_waitcnt vmcnt(" #n ")" ::: "memory")
; #define PG8_WAIT_L(n) asm volatile("s_waitcnt lgkmcnt(" #n ")" ::: "memory")
; #define PG8_BAR __builtin_amdgcn_s_barrier()
; #define PG8_SCHED __builtin_amdgcn_sched_barrier(0)
; template <class Epi, class Sched, bool ALIGN_EPI = false, bool SP2 = false>
; __device__ __forceinline__ void gemm_phase(PG8_LAS unsigned char* lds, const Gemm g, const Sched& S, const Epi& E) {
;     ...
;             if constexpr (SP2) {
;             PG8_LDB(B0, 0, 0); PG8_LDB(B1, 0, 1); PG8_SCHED; PG8_LDA(At, 0, 0); PG8_STAGE(PG8_SA(1, 1), a1 + hstep, voffA);
;             PG8_WAIT_V(8); PG8_WAIT_L(0); PG8_BAR; PG8_MMA(0, 0, At, B0); PG8_MMA(0, 1, At, B1); PG8_BAR; PG8_SCHED;
;     ...
;             PG8_LDA(At, 1, 1); PG8_STAGE(PG8_SB(1, 0), b3, voffB); PG8_STAGE(PG8_SB(1, 1), b3 + hstep, voffB); PG8_STAGE(PG8_SA(1, 0), a3, voffA);
;             PG8_WAIT_V(8); PG8_WAIT_L(0); PG8_BAR; PG8_MMA(1, 0, At, B0); PG8_MMA(1, 1, At, B1); PG8_BAR; PG8_SCHED;
	s_add_i32 s82, s75, s23
	v_lshl_add_u64 v[240:241], v[236:237], 0, s[40:41]
	s_mov_b32 m0, s82
	s_add_i32 s83, s82, 0x2000
	ds_read_b128 v[198:201], v161 offset:49152
	ds_read_b128 v[202:205], v161 offset:50176
	ds_read_b128 v[206:209], v161 offset:51200
	ds_read_b128 v[214:217], v161 offset:52224
	ds_read_b128 v[218:221], v161 offset:53248
	ds_read_b128 v[222:225], v161 offset:54272
	ds_read_b128 v[226:229], v161 offset:55296
	ds_read_b128 v[230:233], v161 offset:56320
	global_load_lds_dwordx4 v[240:241], off
	v_lshl_add_u64 v[240:241], v[238:239], 0, s[40:41]
	s_mov_b32 m0, s83
	s_add_i32 s85, s84, s23
	global_load_lds_dwordx4 v[240:241], off
	v_lshl_add_u64 v[236:237], v[236:237], 0, s[46:47]
	s_mov_b32 m0, s85
	s_add_i32 s86, s85, 0x2000
	global_load_lds_dwordx4 v[236:237], off
	v_lshl_add_u64 v[236:237], v[238:239], 0, s[46:47]
	s_mov_b32 m0, s86
	v_lshl_add_u64 v[210:211], v[210:211], 0, s[40:41]
	global_load_lds_dwordx4 v[236:237], off
	s_mov_b32 m0, s71
	s_nop 0
	global_load_lds_dwordx4 v[210:211], off
	v_lshl_add_u64 v[210:211], v[234:235], 0, s[40:41]
	s_mov_b32 m0, s76
	s_nop 0
	global_load_lds_dwordx4 v[210:211], off
	s_waitcnt vmcnt(8)
	s_waitcnt lgkmcnt(0)
	s_barrier
	s_waitcnt lgkmcnt(0)
	v_mfma_f32_16x16x32_bf16 v[60:63], v[164:167], v[198:201], v[60:63]
	v_mfma_f32_16x16x32_bf16 v[56:59], v[172:175], v[198:201], v[56:59]
	v_mfma_f32_16x16x32_bf16 v[44:47], v[164:167], v[206:209], v[44:47]
	v_mfma_f32_16x16x32_bf16 v[40:43], v[172:175], v[206:209], v[40:43]
	v_mfma_f32_16x16x32_bf16 v[28:31], v[164:167], v[218:221], v[28:31]
	v_mfma_f32_16x16x32_bf16 v[24:27], v[172:175], v[218:221], v[24:27]
	v_mfma_f32_16x16x32_bf16 v[12:15], v[164:167], v[226:229], v[12:15]
	v_mfma_f32_16x16x32_bf16 v[8:11], v[172:175], v[226:229], v[8:11]
	v_mfma_f32_16x16x32_bf16 v[60:63], v[168:171], v[202:205], v[60:63]
	v_mfma_f32_16x16x32_bf16 v[56:59], v[176:179], v[202:205], v[56:59]
	v_mfma_f32_16x16x32_bf16 v[44:47], v[168:171], v[214:217], v[44:47]
	v_mfma_f32_16x16x32_bf16 v[40:43], v[176:179], v[214:217], v[40:43]
	v_mfma_f32_16x16x32_bf16 v[28:31], v[168:171], v[222:225], v[28:31]
	v_mfma_f32_16x16x32_bf16 v[24:27], v[176:179], v[222:225], v[24:27]
	v_mfma_f32_16x16x32_bf16 v[12:15], v[168:171], v[230:233], v[12:15]
	v_mfma_f32_16x16x32_bf16 v[8:11], v[176:179], v[230:233], v[8:11]
	v_mfma_f32_16x16x32_bf16 v[52:55], v[180:183], v[198:201], v[52:55]
	v_mfma_f32_16x16x32_bf16 v[48:51], v[190:193], v[198:201], v[48:51]
	v_mfma_f32_16x16x32_bf16 v[36:39], v[180:183], v[206:209], v[36:39]
	v_mfma_f32_16x16x32_bf16 v[32:35], v[190:193], v[206:209], v[32:35]
	v_mfma_f32_16x16x32_bf16 v[20:23], v[180:183], v[218:221], v[20:23]
	v_mfma_f32_16x16x32_bf16 v[16:19], v[190:193], v[218:221], v[16:19]
	v_mfma_f32_16x16x32_bf16 v[4:7], v[180:183], v[226:229], v[4:7]
	v_mfma_f32_16x16x32_bf16 v[0:3], v[190:193], v[226:229], v[0:3]
	v_mfma_f32_16x16x32_bf16 v[52:55], v[184:187], v[202:205], v[52:55]
	v_mfma_f32_16x16x32_bf16 v[48:51], v[194:197], v[202:205], v[48:51]
	v_mfma_f32_16x16x32_bf16 v[36:39], v[184:187], v[214:217], v[36:39]
	v_mfma_f32_16x16x32_bf16 v[32:35], v[194:197], v[214:217], v[32:35]
	v_mfma_f32_16x16x32_bf16 v[20:23], v[184:187], v[222:225], v[20:23]
	v_mfma_f32_16x16x32_bf16 v[16:19], v[194:197], v[222:225], v[16:19]
	v_mfma_f32_16x16x32_bf16 v[4:7], v[184:187], v[230:233], v[4:7]
	v_mfma_f32_16x16x32_bf16 v[0:3], v[194:197], v[230:233], v[0:3]
	s_barrier
	s_add_i32 s59, s59, 2
	s_add_u32 s64, s64, 0x100
	s_addc_u32 s65, s65, 0
	s_cmp_gt_u32 s59, 13
.LBB0_703:
	ds_read_b128 v[162:165], v159
	ds_read_b128 v[166:169], v159 offset:1024
	ds_read_b128 v[170:173], v159 offset:2048
	ds_read_b128 v[174:177], v159 offset:3072
	ds_read_b128 v[178:181], v160
	ds_read_b128 v[182:185], v160 offset:1024
	ds_read_b128 v[190:193], v160 offset:2048
	ds_read_b128 v[194:197], v160 offset:3072
	v_lshl_add_u64 v[210:211], v[148:149], 0, s[64:65]
	s_mov_b32 m0, s77
	v_lshl_add_u64 v[186:187], v[210:211], 0, s[10:11]
	v_lshl_add_u64 v[234:235], v[150:151], 0, s[64:65]
	ds_read_b128 v[198:201], v161
	ds_read_b128 v[202:205], v161 offset:1024
	ds_read_b128 v[206:209], v161 offset:2048
	ds_read_b128 v[214:217], v161 offset:3072
	ds_read_b128 v[218:221], v161 offset:4096
	ds_read_b128 v[222:225], v161 offset:5120
	ds_read_b128 v[226:229], v161 offset:6144
	ds_read_b128 v[230:233], v161 offset:7168
	global_load_lds_dwordx4 v[186:187], off
	v_lshl_add_u64 v[186:187], v[234:235], 0, s[10:11]
	s_mov_b32 m0, s78
	s_nop 0
	global_load_lds_dwordx4 v[186:187], off
	s_waitcnt vmcnt(8)
	s_waitcnt lgkmcnt(0)
	s_barrier
; #define PG8_STAGE(bufoff, gbase, voff) do { _Pragma("unroll") for (int _i = 0; _i < 2; ++_i) \
;         __builtin_amdgcn_global_load_lds((const unsigned*)((const char*)(gbase) + (voff)[_i]), (PG8_LAS unsigned*)(lds + (bufoff) + ldsw + _i * 8192), 16, 0, 0); } while (0)
; #define PG8_LDA(dst, b, h) do { _Pragma("unroll") for (int m = 0; m < 4; ++m) _Pragma("unroll") for (int k = 0; k < 2; ++k) dst[m][k] = *(const PG8_LAS bf16x8*)(lds + PG8_SA(b, h) + aoff + m * 2048 + k * 1024); } while (0)
; #define PG8_MMA(ai, bj, At, Bt) do { __builtin_amdgcn_s_setprio(1); _Pragma("unroll") for (int m = 0; m < 4; ++m) _Pragma("unroll") for (int n = 0; n < 2; ++n) _Pragma("unroll") for (int k = 0; k < 2; ++k) \
;         acc[ai][bj][m][n] = __builtin_amdgcn_mfma_f32_16x16x32_bf16(Bt[n][k], At[m][k], acc[ai][bj][m][n], 0, 0, 0); __builtin_amdgcn_s_setprio(0); } while (0)
; #define PG8_WAIT_V(n) asm volatile("s_waitcnt vmcnt(" #n ")" ::: "memory")
; #define PG8_WAIT_L(n) asm volatile("s_waitcnt lgkmcnt(" #n ")" ::: "memory")
; #define PG8_BAR __builtin_amdgcn_s_barrier()
; #define PG8_SCHED __builtin_amdgcn_sched_barrier(0)
; template <class Epi, class Sched, bool ALIGN_EPI = false, bool SP2 = false>
; __device__ __forceinline__ void gemm_phase(PG8_LAS unsigned char* lds, const Gemm g, const Sched& S, const Epi& E) {
;     ...
;             PG8_WAIT_V(8); PG8_WAIT_L(0); PG8_BAR; PG8_MMA(0, 0, At, B0); PG8_MMA(0, 1, At, B1); PG8_BAR; PG8_SCHED;
;             PG8_LDA(At, 0, 1); PG8_STAGE(PG8_SB(0, 0), b2, voffB); PG8_STAGE(PG8_SB(0, 1), b2 + hstep, voffB); PG8_STAGE(PG8_SA(0, 0), a2, voffA);
;             PG8_WAIT_V(8); PG8_WAIT_L(0); PG8_BAR; PG8_MMA(1, 0, At, B0); PG8_MMA(1, 1, At, B1); PG8_BAR; PG8_SCHED;
	s_waitcnt lgkmcnt(0)
	v_mfma_f32_16x16x32_bf16 v[124:127], v[162:165], v[198:201], v[124:127]
	v_mfma_f32_16x16x32_bf16 v[120:123], v[170:173], v[198:201], v[120:123]
	v_mfma_f32_16x16x32_bf16 v[116:119], v[162:165], v[206:209], v[116:119]
	v_mfma_f32_16x16x32_bf16 v[112:115], v[170:173], v[206:209], v[112:115]
	v_mfma_f32_16x16x32_bf16 v[108:111], v[162:165], v[218:221], v[108:111]
	v_mfma_f32_16x16x32_bf16 v[104:107], v[170:173], v[218:221], v[104:107]
	v_mfma_f32_16x16x32_bf16 v[100:103], v[162:165], v[226:229], v[100:103]
	v_mfma_f32_16x16x32_bf16 v[96:99], v[170:173], v[226:229], v[96:99]
	v_mfma_f32_16x16x32_bf16 v[124:127], v[166:169], v[202:205], v[124:127]
	v_mfma_f32_16x16x32_bf16 v[120:123], v[174:177], v[202:205], v[120:123]
	v_mfma_f32_16x16x32_bf16 v[116:119], v[166:169], v[214:217], v[116:119]
	v_mfma_f32_16x16x32_bf16 v[112:115], v[174:177], v[214:217], v[112:115]
	v_mfma_f32_16x16x32_bf16 v[108:111], v[166:169], v[222:225], v[108:111]
	v_mfma_f32_16x16x32_bf16 v[104:107], v[174:177], v[222:225], v[104:107]
	v_mfma_f32_16x16x32_bf16 v[100:103], v[166:169], v[230:233], v[100:103]
	v_mfma_f32_16x16x32_bf16 v[96:99], v[174:177], v[230:233], v[96:99]
	v_mfma_f32_16x16x32_bf16 v[88:91], v[178:181], v[198:201], v[88:91]
	v_mfma_f32_16x16x32_bf16 v[92:95], v[190:193], v[198:201], v[92:95]
	v_mfma_f32_16x16x32_bf16 v[80:83], v[178:181], v[206:209], v[80:83]
	v_mfma_f32_16x16x32_bf16 v[84:87], v[190:193], v[206:209], v[84:87]
	v_mfma_f32_16x16x32_bf16 v[72:75], v[178:181], v[218:221], v[72:75]
	v_mfma_f32_16x16x32_bf16 v[76:79], v[190:193], v[218:221], v[76:79]
	v_mfma_f32_16x16x32_bf16 v[64:67], v[178:181], v[226:229], v[64:67]
	v_mfma_f32_16x16x32_bf16 v[68:71], v[190:193], v[226:229], v[68:71]
	v_mfma_f32_16x16x32_bf16 v[88:91], v[182:185], v[202:205], v[88:91]
	v_mfma_f32_16x16x32_bf16 v[92:95], v[194:197], v[202:205], v[92:95]
	v_mfma_f32_16x16x32_bf16 v[80:83], v[182:185], v[214:217], v[80:83]
	v_mfma_f32_16x16x32_bf16 v[84:87], v[194:197], v[214:217], v[84:87]
	v_mfma_f32_16x16x32_bf16 v[72:75], v[182:185], v[222:225], v[72:75]
	v_mfma_f32_16x16x32_bf16 v[76:79], v[194:197], v[222:225], v[76:79]
	v_mfma_f32_16x16x32_bf16 v[64:67], v[182:185], v[230:233], v[64:67]
	v_mfma_f32_16x16x32_bf16 v[68:71], v[194:197], v[230:233], v[68:71]
	s_barrier
	v_lshl_add_u64 v[236:237], v[152:153], 0, s[64:65]
	s_mov_b32 m0, s79
	v_lshl_add_u64 v[186:187], v[236:237], 0, s[14:15]
	v_lshl_add_u64 v[238:239], v[154:155], 0, s[64:65]
	ds_read_b128 v[198:201], v161 offset:16384
	ds_read_b128 v[202:205], v161 offset:17408
	ds_read_b128 v[206:209], v161 offset:18432
	ds_read_b128 v[214:217], v161 offset:19456
	ds_read_b128 v[218:221], v161 offset:20480
	ds_read_b128 v[222:225], v161 offset:21504
	ds_read_b128 v[226:229], v161 offset:22528
	ds_read_b128 v[230:233], v161 offset:23552
	global_load_lds_dwordx4 v[186:187], off
	v_lshl_add_u64 v[186:187], v[238:239], 0, s[14:15]
	s_mov_b32 m0, s80
	s_add_i32 s0, s74, s23
	global_load_lds_dwordx4 v[186:187], off
	v_lshl_add_u64 v[186:187], v[236:237], 0, s[36:37]
	s_mov_b32 m0, s0
	s_add_i32 s1, s0, 0x2000
	global_load_lds_dwordx4 v[186:187], off
	v_lshl_add_u64 v[186:187], v[238:239], 0, s[36:37]
	s_mov_b32 m0, s1
	s_nop 0
	global_load_lds_dwordx4 v[186:187], off
	v_lshl_add_u64 v[186:187], v[210:211], 0, s[14:15]
	s_mov_b32 m0, s28
	s_nop 0
	global_load_lds_dwordx4 v[186:187], off
	v_lshl_add_u64 v[186:187], v[234:235], 0, s[14:15]
	s_mov_b32 m0, s29
	s_nop 0
	global_load_lds_dwordx4 v[186:187], off
	s_waitcnt vmcnt(8)
	s_waitcnt lgkmcnt(0)
	s_barrier
	s_waitcnt lgkmcnt(0)
	v_mfma_f32_16x16x32_bf16 v[60:63], v[162:165], v[198:201], v[60:63]
	v_mfma_f32_16x16x32_bf16 v[56:59], v[170:173], v[198:201], v[56:59]
	v_mfma_f32_16x16x32_bf16 v[44:47], v[162:165], v[206:209], v[44:47]
	v_mfma_f32_16x16x32_bf16 v[40:43], v[170:173], v[206:209], v[40:43]
	v_mfma_f32_16x16x32_bf16 v[28:31], v[162:165], v[218:221], v[28:31]
	v_mfma_f32_16x16x32_bf16 v[24:27], v[170:173], v[218:221], v[24:27]
	v_mfma_f32_16x16x32_bf16 v[12:15], v[162:165], v[226:229], v[12:15]
	v_mfma_f32_16x16x32_bf16 v[8:11], v[170:173], v[226:229], v[8:11]
	v_mfma_f32_16x16x32_bf16 v[60:63], v[166:169], v[202:205], v[60:63]
	v_mfma_f32_16x16x32_bf16 v[56:59], v[174:177], v[202:205], v[56:59]
	v_mfma_f32_16x16x32_bf16 v[44:47], v[166:169], v[214:217], v[44:47]
	v_mfma_f32_16x16x32_bf16 v[40:43], v[174:177], v[214:217], v[40:43]
	v_mfma_f32_16x16x32_bf16 v[28:31], v[166:169], v[222:225], v[28:31]
	v_mfma_f32_16x16x32_bf16 v[24:27], v[174:177], v[222:225], v[24:27]
	v_mfma_f32_16x16x32_bf16 v[12:15], v[166:169], v[230:233], v[12:15]
	v_mfma_f32_16x16x32_bf16 v[8:11], v[174:177], v[230:233], v[8:11]
	v_mfma_f32_16x16x32_bf16 v[52:55], v[178:181], v[198:201], v[52:55]
	v_mfma_f32_16x16x32_bf16 v[48:51], v[190:193], v[198:201], v[48:51]
	v_mfma_f32_16x16x32_bf16 v[36:39], v[178:181], v[206:209], v[36:39]
	v_mfma_f32_16x16x32_bf16 v[32:35], v[190:193], v[206:209], v[32:35]
	v_mfma_f32_16x16x32_bf16 v[20:23], v[178:181], v[218:221], v[20:23]
	v_mfma_f32_16x16x32_bf16 v[16:19], v[190:193], v[218:221], v[16:19]
	v_mfma_f32_16x16x32_bf16 v[4:7], v[178:181], v[226:229], v[4:7]
	v_mfma_f32_16x16x32_bf16 v[0:3], v[190:193], v[226:229], v[0:3]
	v_mfma_f32_16x16x32_bf16 v[52:55], v[182:185], v[202:205], v[52:55]
	v_mfma_f32_16x16x32_bf16 v[48:51], v[194:197], v[202:205], v[48:51]
	v_mfma_f32_16x16x32_bf16 v[36:39], v[182:185], v[214:217], v[36:39]
	v_mfma_f32_16x16x32_bf16 v[32:35], v[194:197], v[214:217], v[32:35]
	v_mfma_f32_16x16x32_bf16 v[20:23], v[182:185], v[222:225], v[20:23]
	v_mfma_f32_16x16x32_bf16 v[16:19], v[194:197], v[222:225], v[16:19]
	v_mfma_f32_16x16x32_bf16 v[4:7], v[182:185], v[230:233], v[4:7]
	v_mfma_f32_16x16x32_bf16 v[0:3], v[194:197], v[230:233], v[0:3]
	s_barrier
; #define PG8_STAGE(bufoff, gbase, voff) do { _Pragma("unroll") for (int _i = 0; _i < 2; ++_i) \
;         __builtin_amdgcn_global_load_lds((const unsigned*)((const char*)(gbase) + (voff)[_i]), (PG8_LAS unsigned*)(lds + (bufoff) + ldsw + _i * 8192), 16, 0, 0); } while (0)
; #define PG8_LDA(dst, b, h) do { _Pragma("unroll") for (int m = 0; m < 4; ++m) _Pragma("unroll") for (int k = 0; k < 2; ++k) dst[m][k] = *(const PG8_LAS bf16x8*)(lds + PG8_SA(b, h) + aoff + m * 2048 + k * 1024); } while (0)
; #define PG8_LDB(dst, b, h) do { _Pragma("unroll") for (int n = 0; n < 2; ++n) _Pragma("unroll") for (int k = 0; k < 2; ++k) dst[n][k] = *(const PG8_LAS bf16x8*)(lds + PG8_SB(b, h) + boff + n * 2048 + k * 1024); } while (0)
; #define PG8_MMA(ai, bj, At, Bt) do { __builtin_amdgcn_s_setprio(1); _Pragma("unroll") for (int m = 0; m < 4; ++m) _Pragma("unroll") for (int n = 0; n < 2; ++n) _Pragma("unroll") for (int k = 0; k < 2; ++k) \
;         acc[ai][bj][m][n] = __builtin_amdgcn_mfma_f32_16x16x32_bf16(Bt[n][k], At[m][k], acc[ai][bj][m][n], 0, 0, 0); __builtin_amdgcn_s_setprio(0); } while (0)
; #define PG8_WAIT_V(n) asm volatile("s_waitcnt vmcnt(" #n ")" ::: "memory")
; #define PG8_WAIT_L(n) asm volatile("s_waitcnt lgkmcnt(" #n ")" ::: "memory")
; #define PG8_BAR __builtin_amdgcn_s_barrier()
; #define PG8_SCHED __builtin_amdgcn_sched_barrier(0)
; template <class Epi, class Sched, bool ALIGN_EPI = false, bool SP2 = false>
; __device__ __forceinline__ void gemm_phase(PG8_LAS unsigned char* lds, const Gemm g, const Sched& S, const Epi& E) {
;     ...
;             PG8_LDB(B0, 1, 0); PG8_LDB(B1, 1, 1); PG8_SCHED; PG8_LDA(At, 1, 0); PG8_STAGE(PG8_SA(0, 1), a2 + hstep, voffA);
;             PG8_WAIT_V(8); PG8_WAIT_L(0); PG8_BAR; PG8_MMA(0, 0, At, B0); PG8_MMA(0, 1, At, B1); PG8_BAR; PG8_SCHED;
;             PG8_LDA(At, 1, 1); PG8_STAGE(PG8_SB(1, 0), b3, voffB); PG8_STAGE(PG8_SB(1, 1), b3 + hstep, voffB); PG8_STAGE(PG8_SA(1, 0), a3, voffA);
;             PG8_WAIT_V(8); PG8_WAIT_L(0); PG8_BAR; PG8_MMA(1, 0, At, B0); PG8_MMA(1, 1, At, B1); PG8_BAR; PG8_SCHED;
	v_add_u32_e32 v162, s75, v157
	v_add_u32_e32 v163, s84, v157
	ds_read_b128 v[164:167], v162
	ds_read_b128 v[168:171], v162 offset:1024
	ds_read_b128 v[172:175], v162 offset:2048
	ds_read_b128 v[176:179], v162 offset:3072
	ds_read_b128 v[180:183], v163
	ds_read_b128 v[184:187], v163 offset:1024
	ds_read_b128 v[190:193], v163 offset:2048
	ds_read_b128 v[194:197], v163 offset:3072
	s_mov_b32 m0, s30
	v_lshl_add_u64 v[240:241], v[210:211], 0, s[36:37]
	ds_read_b128 v[198:201], v161 offset:32768
	ds_read_b128 v[202:205], v161 offset:33792
	ds_read_b128 v[206:209], v161 offset:34816
	ds_read_b128 v[214:217], v161 offset:35840
	ds_read_b128 v[218:221], v161 offset:36864
	ds_read_b128 v[222:225], v161 offset:37888
	ds_read_b128 v[226:229], v161 offset:38912
	ds_read_b128 v[230:233], v161 offset:39936
	global_load_lds_dwordx4 v[240:241], off
	v_lshl_add_u64 v[240:241], v[234:235], 0, s[36:37]
	s_mov_b32 m0, s33
	s_nop 0
	global_load_lds_dwordx4 v[240:241], off
	s_waitcnt vmcnt(8)
	s_waitcnt lgkmcnt(0)
	s_barrier
	s_waitcnt lgkmcnt(0)
	v_mfma_f32_16x16x32_bf16 v[124:127], v[164:167], v[198:201], v[124:127]
	v_mfma_f32_16x16x32_bf16 v[120:123], v[172:175], v[198:201], v[120:123]
	v_mfma_f32_16x16x32_bf16 v[116:119], v[164:167], v[206:209], v[116:119]
	v_mfma_f32_16x16x32_bf16 v[112:115], v[172:175], v[206:209], v[112:115]
	v_mfma_f32_16x16x32_bf16 v[108:111], v[164:167], v[218:221], v[108:111]
	v_mfma_f32_16x16x32_bf16 v[104:107], v[172:175], v[218:221], v[104:107]
	v_mfma_f32_16x16x32_bf16 v[100:103], v[164:167], v[226:229], v[100:103]
	v_mfma_f32_16x16x32_bf16 v[96:99], v[172:175], v[226:229], v[96:99]
	v_mfma_f32_16x16x32_bf16 v[124:127], v[168:171], v[202:205], v[124:127]
	v_mfma_f32_16x16x32_bf16 v[120:123], v[176:179], v[202:205], v[120:123]
	v_mfma_f32_16x16x32_bf16 v[116:119], v[168:171], v[214:217], v[116:119]
	v_mfma_f32_16x16x32_bf16 v[112:115], v[176:179], v[214:217], v[112:115]
	v_mfma_f32_16x16x32_bf16 v[108:111], v[168:171], v[222:225], v[108:111]
	v_mfma_f32_16x16x32_bf16 v[104:107], v[176:179], v[222:225], v[104:107]
	v_mfma_f32_16x16x32_bf16 v[100:103], v[168:171], v[230:233], v[100:103]
	v_mfma_f32_16x16x32_bf16 v[96:99], v[176:179], v[230:233], v[96:99]
	v_mfma_f32_16x16x32_bf16 v[88:91], v[180:183], v[198:201], v[88:91]
	v_mfma_f32_16x16x32_bf16 v[92:95], v[190:193], v[198:201], v[92:95]
	v_mfma_f32_16x16x32_bf16 v[80:83], v[180:183], v[206:209], v[80:83]
	v_mfma_f32_16x16x32_bf16 v[84:87], v[190:193], v[206:209], v[84:87]
	v_mfma_f32_16x16x32_bf16 v[72:75], v[180:183], v[218:221], v[72:75]
	v_mfma_f32_16x16x32_bf16 v[76:79], v[190:193], v[218:221], v[76:79]
	v_mfma_f32_16x16x32_bf16 v[64:67], v[180:183], v[226:229], v[64:67]
	v_mfma_f32_16x16x32_bf16 v[68:71], v[190:193], v[226:229], v[68:71]
	v_mfma_f32_16x16x32_bf16 v[88:91], v[184:187], v[202:205], v[88:91]
	v_mfma_f32_16x16x32_bf16 v[92:95], v[194:197], v[202:205], v[92:95]
	v_mfma_f32_16x16x32_bf16 v[80:83], v[184:187], v[214:217], v[80:83]
	v_mfma_f32_16x16x32_bf16 v[84:87], v[194:197], v[214:217], v[84:87]
	v_mfma_f32_16x16x32_bf16 v[72:75], v[184:187], v[222:225], v[72:75]
	v_mfma_f32_16x16x32_bf16 v[76:79], v[194:197], v[222:225], v[76:79]
	v_mfma_f32_16x16x32_bf16 v[64:67], v[184:187], v[230:233], v[64:67]
	v_mfma_f32_16x16x32_bf16 v[68:71], v[194:197], v[230:233], v[68:71]
	s_barrier
	s_add_i32 s82, s75, s23
	v_lshl_add_u64 v[240:241], v[236:237], 0, s[40:41]
	s_mov_b32 m0, s82
	s_add_i32 s83, s82, 0x2000
	ds_read_b128 v[198:201], v161 offset:49152
	ds_read_b128 v[202:205], v161 offset:50176
	ds_read_b128 v[206:209], v161 offset:51200
	ds_read_b128 v[214:217], v161 offset:52224
	ds_read_b128 v[218:221], v161 offset:53248
	ds_read_b128 v[222:225], v161 offset:54272
	ds_read_b128 v[226:229], v161 offset:55296
	ds_read_b128 v[230:233], v161 offset:56320
	global_load_lds_dwordx4 v[240:241], off
	v_lshl_add_u64 v[240:241], v[238:239], 0, s[40:41]
	s_mov_b32 m0, s83
	s_add_i32 s85, s84, s23
	global_load_lds_dwordx4 v[240:241], off
	v_lshl_add_u64 v[236:237], v[236:237], 0, s[46:47]
	s_mov_b32 m0, s85
	s_add_i32 s86, s85, 0x2000
	global_load_lds_dwordx4 v[236:237], off
	v_lshl_add_u64 v[236:237], v[238:239], 0, s[46:47]
	s_mov_b32 m0, s86
	v_lshl_add_u64 v[210:211], v[210:211], 0, s[40:41]
	global_load_lds_dwordx4 v[236:237], off
	s_mov_b32 m0, s71
	s_nop 0
	global_load_lds_dwordx4 v[210:211], off
	v_lshl_add_u64 v[210:211], v[234:235], 0, s[40:41]
	s_mov_b32 m0, s76
	s_nop 0
	global_load_lds_dwordx4 v[210:211], off
	s_waitcnt vmcnt(8)
	s_waitcnt lgkmcnt(0)
	s_barrier
	s_waitcnt lgkmcnt(0)
	v_mfma_f32_16x16x32_bf16 v[60:63], v[164:167], v[198:201], v[60:63]
	v_mfma_f32_16x16x32_bf16 v[56:59], v[172:175], v[198:201], v[56:59]
	v_mfma_f32_16x16x32_bf16 v[44:47], v[164:167], v[206:209], v[44:47]
	v_mfma_f32_16x16x32_bf16 v[40:43], v[172:175], v[206:209], v[40:43]
	v_mfma_f32_16x16x32_bf16 v[28:31], v[164:167], v[218:221], v[28:31]
	v_mfma_f32_16x16x32_bf16 v[24:27], v[172:175], v[218:221], v[24:27]
	v_mfma_f32_16x16x32_bf16 v[12:15], v[164:167], v[226:229], v[12:15]
	v_mfma_f32_16x16x32_bf16 v[8:11], v[172:175], v[226:229], v[8:11]
	v_mfma_f32_16x16x32_bf16 v[60:63], v[168:171], v[202:205], v[60:63]
	v_mfma_f32_16x16x32_bf16 v[56:59], v[176:179], v[202:205], v[56:59]
	v_mfma_f32_16x16x32_bf16 v[44:47], v[168:171], v[214:217], v[44:47]
	v_mfma_f32_16x16x32_bf16 v[40:43], v[176:179], v[214:217], v[40:43]
	v_mfma_f32_16x16x32_bf16 v[28:31], v[168:171], v[222:225], v[28:31]
	v_mfma_f32_16x16x32_bf16 v[24:27], v[176:179], v[222:225], v[24:27]
	v_mfma_f32_16x16x32_bf16 v[12:15], v[168:171], v[230:233], v[12:15]
	v_mfma_f32_16x16x32_bf16 v[8:11], v[176:179], v[230:233], v[8:11]
	v_mfma_f32_16x16x32_bf16 v[52:55], v[180:183], v[198:201], v[52:55]
	v_mfma_f32_16x16x32_bf16 v[48:51], v[190:193], v[198:201], v[48:51]
	v_mfma_f32_16x16x32_bf16 v[36:39], v[180:183], v[206:209], v[36:39]
	v_mfma_f32_16x16x32_bf16 v[32:35], v[190:193], v[206:209], v[32:35]
	v_mfma_f32_16x16x32_bf16 v[20:23], v[180:183], v[218:221], v[20:23]
	v_mfma_f32_16x16x32_bf16 v[16:19], v[190:193], v[218:221], v[16:19]
	v_mfma_f32_16x16x32_bf16 v[4:7], v[180:183], v[226:229], v[4:7]
	v_mfma_f32_16x16x32_bf16 v[0:3], v[190:193], v[226:229], v[0:3]
	v_mfma_f32_16x16x32_bf16 v[52:55], v[184:187], v[202:205], v[52:55]
	v_mfma_f32_16x16x32_bf16 v[48:51], v[194:197], v[202:205], v[48:51]
	v_mfma_f32_16x16x32_bf16 v[36:39], v[184:187], v[214:217], v[36:39]
	v_mfma_f32_16x16x32_bf16 v[32:35], v[194:197], v[214:217], v[32:35]
	v_mfma_f32_16x16x32_bf16 v[20:23], v[184:187], v[222:225], v[20:23]
	v_mfma_f32_16x16x32_bf16 v[16:19], v[194:197], v[222:225], v[16:19]
	v_mfma_f32_16x16x32_bf16 v[4:7], v[184:187], v[230:233], v[4:7]
	v_mfma_f32_16x16x32_bf16 v[0:3], v[194:197], v[230:233], v[0:3]
	s_barrier
; __device__ __forceinline__ float bflo(unsigned w) { return __uint_as_float(w << 16); }
; __device__ __forceinline__ float bfhi(unsigned w) { return __uint_as_float(w & 0xffff0000u); }
;     __device__ bool next(int i, Unit& u) const { if (i >= n) return false; const int q = first + i; u.pm = rowbase + q % rows; u.pn = q / rows; return true; }
;     __device__ __forceinline__ void mid(f32x4 (&acc)[2][2][4][2], const Unit& u, int wr, int wc, int fr, int fq) const {
;         int row0 = u.pm * BM + wr * 64 + fr, col0 = u.pn * BM + wc * 32 + 8 * fq;
;         asm volatile("" : "+v"(row0), "+v"(col0) :: "memory");
; #pragma unroll
;         for (int ai = 0; ai < 2; ++ai)
; #pragma unroll
;             for (int m = 0; m < 4; ++m) {
;                 int roff = row0 + ai * HALF + m * 16; asm volatile("" : "+v"(roff) :: "memory"); const bf16_t* gp = gates + (size_t)roff * 4096 + col0;
; #pragma unroll
;                 for (int bj = 0; bj < 2; ++bj) { const u32x4 a = __builtin_nontemporal_load((const u32x4*)(gp + bj * HALF));
;                     f32x4 r0, r1;
;                     r0[0] = bflo(a[0]); r0[1] = bfhi(a[0]); r0[2] = bflo(a[1]); r0[3] = bfhi(a[1]); r1[0] = bflo(a[2]); r1[1] = bfhi(a[2]); r1[2] = bflo(a[3]); r1[3] = bfhi(a[3]);
;                     acc[ai][bj][m][0] = acc[ai][bj][m][0] * r0; acc[ai][bj][m][1] = acc[ai][bj][m][1] * r1; }
;                 asm volatile("" : "+v"(acc[ai][0][m][0]), "+v"(acc[ai][0][m][1]), "+v"(acc[ai][1][m][0]), "+v"(acc[ai][1][m][1]));
;                 __builtin_amdgcn_sched_barrier(0);
; template <class Epi, class Sched, bool ALIGN_EPI = false, bool SP2 = false>
; __device__ __forceinline__ void gemm_phase(PG8_LAS unsigned char* lds, const Gemm g, const Sched& S, const Epi& E) {
;     ...
;         const bool has_next = S.next(ui + 1, nxt);
;         const char* nA = has_next ? (const char*)g.A + (size_t)nxt.pm * tstep : cA; const char* nB = has_next ? (const char*)g.Bt + (size_t)nxt.pn * tstep : cB;
	s_add_i32 s59, s59, 2
	s_add_u32 s64, s64, 0x100
	s_addc_u32 s65, s65, 0
	s_cmp_gt_u32 s59, 13
	s_cbranch_scc0 .LBB0_703
	v_lshl_add_u32 v148, s68, 8, v156
	v_lshl_or_b32 v150, s57, 8, v158
	v_ashrrev_i32_e32 v153, 31, v148
	v_mov_b32_e32 v152, v148
	v_ashrrev_i32_e32 v155, 31, v150
	v_mov_b32_e32 v154, v150
	v_lshlrev_b64 v[152:153], 13, v[152:153]
	v_lshlrev_b64 v[154:155], 1, v[154:155]
	v_lshl_add_u64 v[152:153], s[18:19], 0, v[152:153]
	v_lshl_add_u64 v[152:153], v[152:153], 0, v[154:155]
	s_mov_b64 s[64:65], 0x20000
	s_mov_b64 s[66:67], 0xa0000
	global_load_dwordx4 v[164:167], v[152:153], off nt
	global_load_dwordx4 v[168:171], v[152:153], off offset:256 nt
	v_lshl_add_u64 v[152:153], v[152:153], 0, s[64:65]
	global_load_dwordx4 v[172:175], v[152:153], off nt
	global_load_dwordx4 v[176:179], v[152:153], off offset:256 nt
	v_lshl_add_u64 v[152:153], v[152:153], 0, s[64:65]
	global_load_dwordx4 v[180:183], v[152:153], off nt
	global_load_dwordx4 v[184:187], v[152:153], off offset:256 nt
	v_lshl_add_u64 v[152:153], v[152:153], 0, s[64:65]
	global_load_dwordx4 v[190:193], v[152:153], off nt
	global_load_dwordx4 v[194:197], v[152:153], off offset:256 nt
	v_lshl_add_u64 v[152:153], v[152:153], 0, s[66:67]
	global_load_dwordx4 v[198:201], v[152:153], off nt
	global_load_dwordx4 v[202:205], v[152:153], off offset:256 nt
	v_lshl_add_u64 v[152:153], v[152:153], 0, s[64:65]
	global_load_dwordx4 v[206:209], v[152:153], off nt
	global_load_dwordx4 v[214:217], v[152:153], off offset:256 nt
	v_lshl_add_u64 v[152:153], v[152:153], 0, s[64:65]
	global_load_dwordx4 v[218:221], v[152:153], off nt
	global_load_dwordx4 v[222:225], v[152:153], off offset:256 nt
	v_lshl_add_u64 v[152:153], v[152:153], 0, s[64:65]
	global_load_dwordx4 v[226:229], v[152:153], off nt
	global_load_dwordx4 v[230:233], v[152:153], off offset:256 nt
	s_ashr_i32 s59, s58, 31
	s_lshl_b64 s[64:65], s[58:59], 20
	s_add_u32 s64, s72, s64
	s_addc_u32 s65, s73, s65
	s_ashr_i32 s57, s56, 31
	s_lshl_b64 s[66:67], s[56:57], 20
	s_add_u32 s66, s88, s66
	s_addc_u32 s67, s89, s67
	s_and_b64 s[68:69], s[2:3], exec
	s_cselect_b32 s57, s65, s63
	s_cselect_b32 s59, s64, s62
	s_cselect_b32 s87, s67, s61
	s_cselect_b32 s90, s66, s60
	s_waitcnt vmcnt(15)
	v_lshlrev_b32_e32 v234, 16, v164
	v_and_b32_e32 v235, 0xffff0000, v164
	v_lshlrev_b32_e32 v164, 16, v165
	v_and_b32_e32 v165, 0xffff0000, v165
	v_lshlrev_b32_e32 v236, 16, v166
	v_and_b32_e32 v237, 0xffff0000, v166
	v_lshlrev_b32_e32 v166, 16, v167
	v_and_b32_e32 v167, 0xffff0000, v167
	v_pk_mul_f32 v[124:125], v[124:125], v[234:235]
	v_pk_mul_f32 v[126:127], v[126:127], v[164:165]
	v_pk_mul_f32 v[120:121], v[120:121], v[236:237]
	v_pk_mul_f32 v[122:123], v[122:123], v[166:167]
	s_waitcnt vmcnt(14)
	v_lshlrev_b32_e32 v238, 16, v168
	v_and_b32_e32 v239, 0xffff0000, v168
	v_lshlrev_b32_e32 v168, 16, v169
	v_and_b32_e32 v169, 0xffff0000, v169
	v_lshlrev_b32_e32 v240, 16, v170
	v_and_b32_e32 v241, 0xffff0000, v170
	v_lshlrev_b32_e32 v170, 16, v171
	v_and_b32_e32 v171, 0xffff0000, v171
	v_pk_mul_f32 v[88:89], v[88:89], v[238:239]
	v_pk_mul_f32 v[90:91], v[90:91], v[168:169]
	v_pk_mul_f32 v[92:93], v[92:93], v[240:241]
	v_pk_mul_f32 v[94:95], v[94:95], v[170:171]
	s_waitcnt vmcnt(13)
	v_lshlrev_b32_e32 v234, 16, v172
	v_and_b32_e32 v235, 0xffff0000, v172
	v_lshlrev_b32_e32 v172, 16, v173
	v_and_b32_e32 v173, 0xffff0000, v173
	v_lshlrev_b32_e32 v236, 16, v174
	v_and_b32_e32 v237, 0xffff0000, v174
	v_lshlrev_b32_e32 v174, 16, v175
	v_and_b32_e32 v175, 0xffff0000, v175
	v_pk_mul_f32 v[116:117], v[116:117], v[234:235]
	v_pk_mul_f32 v[118:119], v[118:119], v[172:173]
	v_pk_mul_f32 v[112:113], v[112:113], v[236:237]
	v_pk_mul_f32 v[114:115], v[114:115], v[174:175]
	s_waitcnt vmcnt(12)
	v_lshlrev_b32_e32 v238, 16, v176
	v_and_b32_e32 v239, 0xffff0000, v176
	v_lshlrev_b32_e32 v176, 16, v177
	v_and_b32_e32 v177, 0xffff0000, v177
	v_lshlrev_b32_e32 v240, 16, v178
	v_and_b32_e32 v241, 0xffff0000, v178
	v_lshlrev_b32_e32 v178, 16, v179
	v_and_b32_e32 v179, 0xffff0000, v179
	v_pk_mul_f32 v[80:81], v[80:81], v[238:239]
	v_pk_mul_f32 v[82:83], v[82:83], v[176:177]
	v_pk_mul_f32 v[84:85], v[84:85], v[240:241]
	v_pk_mul_f32 v[86:87], v[86:87], v[178:179]
	s_waitcnt vmcnt(11)
	v_lshlrev_b32_e32 v234, 16, v180
	v_and_b32_e32 v235, 0xffff0000, v180
	v_lshlrev_b32_e32 v180, 16, v181
	v_and_b32_e32 v181, 0xffff0000, v181
	v_lshlrev_b32_e32 v236, 16, v182
	v_and_b32_e32 v237, 0xffff0000, v182
	v_lshlrev_b32_e32 v182, 16, v183
	v_and_b32_e32 v183, 0xffff0000, v183
	v_pk_mul_f32 v[108:109], v[108:109], v[234:235]
	v_pk_mul_f32 v[110:111], v[110:111], v[180:181]
	v_pk_mul_f32 v[104:105], v[104:105], v[236:237]
	v_pk_mul_f32 v[106:107], v[106:107], v[182:183]
	s_waitcnt vmcnt(10)
	v_lshlrev_b32_e32 v238, 16, v184
	v_and_b32_e32 v239, 0xffff0000, v184
	v_lshlrev_b32_e32 v184, 16, v185
	v_and_b32_e32 v185, 0xffff0000, v185
	v_lshlrev_b32_e32 v240, 16, v186
	v_and_b32_e32 v241, 0xffff0000, v186
	v_lshlrev_b32_e32 v186, 16, v187
	v_and_b32_e32 v187, 0xffff0000, v187
	v_pk_mul_f32 v[72:73], v[72:73], v[238:239]
	v_pk_mul_f32 v[74:75], v[74:75], v[184:185]
	v_pk_mul_f32 v[76:77], v[76:77], v[240:241]
	v_pk_mul_f32 v[78:79], v[78:79], v[186:187]
	s_waitcnt vmcnt(9)
	v_lshlrev_b32_e32 v234, 16, v190
	v_and_b32_e32 v235, 0xffff0000, v190
	v_lshlrev_b32_e32 v190, 16, v191
	v_and_b32_e32 v191, 0xffff0000, v191
	v_lshlrev_b32_e32 v236, 16, v192
	v_and_b32_e32 v237, 0xffff0000, v192
	v_lshlrev_b32_e32 v192, 16, v193
	v_and_b32_e32 v193, 0xffff0000, v193
	v_pk_mul_f32 v[100:101], v[100:101], v[234:235]
	v_pk_mul_f32 v[102:103], v[102:103], v[190:191]
	v_pk_mul_f32 v[96:97], v[96:97], v[236:237]
	v_pk_mul_f32 v[98:99], v[98:99], v[192:193]
	s_waitcnt vmcnt(8)
; __device__ __forceinline__ float bflo(unsigned w) { return __uint_as_float(w << 16); }
; __device__ __forceinline__ float bfhi(unsigned w) { return __uint_as_float(w & 0xffff0000u); }
;     __device__ __forceinline__ void mid(f32x4 (&acc)[2][2][4][2], const Unit& u, int wr, int wc, int fr, int fq) const {
;     ...
;             for (int m = 0; m < 4; ++m) {
;                 int roff = row0 + ai * HALF + m * 16; asm volatile("" : "+v"(roff) :: "memory"); const bf16_t* gp = gates + (size_t)roff * 4096 + col0;
; #pragma unroll
;                 for (int bj = 0; bj < 2; ++bj) { const u32x4 a = __builtin_nontemporal_load((const u32x4*)(gp + bj * HALF));
;                     f32x4 r0, r1;
;                     r0[0] = bflo(a[0]); r0[1] = bfhi(a[0]); r0[2] = bflo(a[1]); r0[3] = bfhi(a[1]); r1[0] = bflo(a[2]); r1[1] = bfhi(a[2]); r1[2] = bflo(a[3]); r1[3] = bfhi(a[3]);
;                     acc[ai][bj][m][0] = acc[ai][bj][m][0] * r0; acc[ai][bj][m][1] = acc[ai][bj][m][1] * r1; }
;                 asm volatile("" : "+v"(acc[ai][0][m][0]), "+v"(acc[ai][0][m][1]), "+v"(acc[ai][1][m][0]), "+v"(acc[ai][1][m][1]));
;                 __builtin_amdgcn_sched_barrier(0);
; template <class Epi, class Sched, bool ALIGN_EPI = false, bool SP2 = false>
; __device__ __forceinline__ void gemm_phase(PG8_LAS unsigned char* lds, const Gemm g, const Sched& S, const Epi& E) {
;     ...
;         for (int t = seg * tseg; t < (seg + 1) * tseg; t += 2) {
;             const bool last = (t == nt - 2);
;             const char* a1 = cA + (size_t)(t + 1) * kstep;
;             const char* a2 = last ? nA : cA + (size_t)(t + 2) * kstep; const char* b2 = last ? nB : cB + (size_t)(t + 2) * kstep;
;             const char* a3 = a2 + kstep; const char* b3 = b2 + kstep;
	v_lshlrev_b32_e32 v238, 16, v194
	v_and_b32_e32 v239, 0xffff0000, v194
	v_lshlrev_b32_e32 v194, 16, v195
	v_and_b32_e32 v195, 0xffff0000, v195
	v_lshlrev_b32_e32 v240, 16, v196
	v_and_b32_e32 v241, 0xffff0000, v196
	v_lshlrev_b32_e32 v196, 16, v197
	v_and_b32_e32 v197, 0xffff0000, v197
	v_pk_mul_f32 v[64:65], v[64:65], v[238:239]
	v_pk_mul_f32 v[66:67], v[66:67], v[194:195]
	v_pk_mul_f32 v[68:69], v[68:69], v[240:241]
	v_pk_mul_f32 v[70:71], v[70:71], v[196:197]
	s_waitcnt vmcnt(7)
	v_lshlrev_b32_e32 v234, 16, v198
	v_and_b32_e32 v235, 0xffff0000, v198
	v_lshlrev_b32_e32 v198, 16, v199
	v_and_b32_e32 v199, 0xffff0000, v199
	v_lshlrev_b32_e32 v236, 16, v200
	v_and_b32_e32 v237, 0xffff0000, v200
	v_lshlrev_b32_e32 v200, 16, v201
	v_and_b32_e32 v201, 0xffff0000, v201
	v_pk_mul_f32 v[60:61], v[60:61], v[234:235]
	v_pk_mul_f32 v[62:63], v[62:63], v[198:199]
	v_pk_mul_f32 v[56:57], v[56:57], v[236:237]
	v_pk_mul_f32 v[58:59], v[58:59], v[200:201]
	s_waitcnt vmcnt(6)
	v_lshlrev_b32_e32 v238, 16, v202
	v_and_b32_e32 v239, 0xffff0000, v202
	v_lshlrev_b32_e32 v202, 16, v203
	v_and_b32_e32 v203, 0xffff0000, v203
	v_lshlrev_b32_e32 v240, 16, v204
	v_and_b32_e32 v241, 0xffff0000, v204
	v_lshlrev_b32_e32 v204, 16, v205
	v_and_b32_e32 v205, 0xffff0000, v205
	v_pk_mul_f32 v[52:53], v[52:53], v[238:239]
	v_pk_mul_f32 v[54:55], v[54:55], v[202:203]
	v_pk_mul_f32 v[48:49], v[48:49], v[240:241]
	v_pk_mul_f32 v[50:51], v[50:51], v[204:205]
	s_waitcnt vmcnt(5)
	v_lshlrev_b32_e32 v234, 16, v206
	v_and_b32_e32 v235, 0xffff0000, v206
	v_lshlrev_b32_e32 v206, 16, v207
	v_and_b32_e32 v207, 0xffff0000, v207
	v_lshlrev_b32_e32 v236, 16, v208
	v_and_b32_e32 v237, 0xffff0000, v208
	v_lshlrev_b32_e32 v208, 16, v209
	v_and_b32_e32 v209, 0xffff0000, v209
	v_pk_mul_f32 v[44:45], v[44:45], v[234:235]
	v_pk_mul_f32 v[46:47], v[46:47], v[206:207]
	v_pk_mul_f32 v[40:41], v[40:41], v[236:237]
	v_pk_mul_f32 v[42:43], v[42:43], v[208:209]
	s_waitcnt vmcnt(4)
	v_lshlrev_b32_e32 v238, 16, v214
	v_and_b32_e32 v239, 0xffff0000, v214
	v_lshlrev_b32_e32 v214, 16, v215
	v_and_b32_e32 v215, 0xffff0000, v215
	v_lshlrev_b32_e32 v240, 16, v216
	v_and_b32_e32 v241, 0xffff0000, v216
	v_lshlrev_b32_e32 v216, 16, v217
	v_and_b32_e32 v217, 0xffff0000, v217
	v_pk_mul_f32 v[36:37], v[36:37], v[238:239]
	v_pk_mul_f32 v[38:39], v[38:39], v[214:215]
	v_pk_mul_f32 v[32:33], v[32:33], v[240:241]
	v_pk_mul_f32 v[34:35], v[34:35], v[216:217]
	s_waitcnt vmcnt(3)
	v_lshlrev_b32_e32 v234, 16, v218
	v_and_b32_e32 v235, 0xffff0000, v218
	v_lshlrev_b32_e32 v218, 16, v219
	v_and_b32_e32 v219, 0xffff0000, v219
	v_lshlrev_b32_e32 v236, 16, v220
	v_and_b32_e32 v237, 0xffff0000, v220
	v_lshlrev_b32_e32 v220, 16, v221
	v_and_b32_e32 v221, 0xffff0000, v221
	v_pk_mul_f32 v[28:29], v[28:29], v[234:235]
	v_pk_mul_f32 v[30:31], v[30:31], v[218:219]
	v_pk_mul_f32 v[24:25], v[24:25], v[236:237]
	v_pk_mul_f32 v[26:27], v[26:27], v[220:221]
	s_waitcnt vmcnt(2)
	v_lshlrev_b32_e32 v238, 16, v222
	v_and_b32_e32 v239, 0xffff0000, v222
	v_lshlrev_b32_e32 v222, 16, v223
	v_and_b32_e32 v223, 0xffff0000, v223
	v_lshlrev_b32_e32 v240, 16, v224
	v_and_b32_e32 v241, 0xffff0000, v224
	v_lshlrev_b32_e32 v224, 16, v225
	v_and_b32_e32 v225, 0xffff0000, v225
	v_pk_mul_f32 v[20:21], v[20:21], v[238:239]
	v_pk_mul_f32 v[22:23], v[22:23], v[222:223]
	v_pk_mul_f32 v[16:17], v[16:17], v[240:241]
	v_pk_mul_f32 v[18:19], v[18:19], v[224:225]
	s_waitcnt vmcnt(1)
	v_lshlrev_b32_e32 v234, 16, v226
	v_and_b32_e32 v235, 0xffff0000, v226
	v_lshlrev_b32_e32 v226, 16, v227
	v_and_b32_e32 v227, 0xffff0000, v227
	v_lshlrev_b32_e32 v236, 16, v228
	v_and_b32_e32 v237, 0xffff0000, v228
	v_lshlrev_b32_e32 v228, 16, v229
	v_and_b32_e32 v229, 0xffff0000, v229
	v_pk_mul_f32 v[12:13], v[12:13], v[234:235]
	v_pk_mul_f32 v[14:15], v[14:15], v[226:227]
	v_pk_mul_f32 v[8:9], v[8:9], v[236:237]
	v_pk_mul_f32 v[10:11], v[10:11], v[228:229]
	s_waitcnt vmcnt(0)
	v_lshlrev_b32_e32 v238, 16, v230
	v_and_b32_e32 v239, 0xffff0000, v230
	v_lshlrev_b32_e32 v230, 16, v231
	v_and_b32_e32 v231, 0xffff0000, v231
	v_lshlrev_b32_e32 v240, 16, v232
	v_and_b32_e32 v241, 0xffff0000, v232
	v_lshlrev_b32_e32 v232, 16, v233
	v_and_b32_e32 v233, 0xffff0000, v233
	v_pk_mul_f32 v[4:5], v[4:5], v[238:239]
	v_pk_mul_f32 v[6:7], v[6:7], v[230:231]
	v_pk_mul_f32 v[0:1], v[0:1], v[240:241]
	v_pk_mul_f32 v[2:3], v[2:3], v[232:233]
	s_add_u32 s62, s62, 0x80880
	s_addc_u32 s63, s63, 0
	s_add_u32 s91, s60, 0x900
	s_addc_u32 s92, s61, 0
	s_mov_b32 s93, 14
; #define PG8_STAGE(bufoff, gbase, voff) do { _Pragma("unroll") for (int _i = 0; _i < 2; ++_i) \
;         __builtin_amdgcn_global_load_lds((const unsigned*)((const char*)(gbase) + (voff)[_i]), (PG8_LAS unsigned*)(lds + (bufoff) + ldsw + _i * 8192), 16, 0, 0); } while (0)
; #define PG8_LDA(dst, b, h) do { _Pragma("unroll") for (int m = 0; m < 4; ++m) _Pragma("unroll") for (int k = 0; k < 2; ++k) dst[m][k] = *(const PG8_LAS bf16x8*)(lds + PG8_SA(b, h) + aoff + m * 2048 + k * 1024); } while (0)
; #define PG8_WAIT_V(n) asm volatile("s_waitcnt vmcnt(" #n ")" ::: "memory")
; #define PG8_WAIT_L(n) asm volatile("s_waitcnt lgkmcnt(" #n ")" ::: "memory")
; #define PG8_BAR __builtin_amdgcn_s_barrier()
; template <class Epi, class Sched, bool ALIGN_EPI = false, bool SP2 = false>
; __device__ __forceinline__ void gemm_phase(PG8_LAS unsigned char* lds, const Gemm g, const Sched& S, const Epi& E) {
;     ...
;         for (int t = seg * tseg; t < (seg + 1) * tseg; t += 2) {
;             const bool last = (t == nt - 2);
;             const char* a1 = cA + (size_t)(t + 1) * kstep;
;             const char* a2 = last ? nA : cA + (size_t)(t + 2) * kstep; const char* b2 = last ? nB : cB + (size_t)(t + 2) * kstep;
;             const char* a3 = a2 + kstep; const char* b3 = b2 + kstep;
;             if (last && has_next) S.a_ready(nxt);
;             if constexpr (SP2) {
;             PG8_LDB(B0, 0, 0); PG8_LDB(B1, 0, 1); PG8_SCHED; PG8_LDA(At, 0, 0); PG8_STAGE(PG8_SA(1, 1), a1 + hstep, voffA);
;             PG8_WAIT_V(8); PG8_WAIT_L(0); PG8_BAR; PG8_MMA(0, 0, At, B0); PG8_MMA(0, 1, At, B1); PG8_BAR; PG8_SCHED;
;             PG8_LDA(At, 0, 1); PG8_STAGE(PG8_SB(0, 0), b2, voffB); PG8_STAGE(PG8_SB(0, 1), b2 + hstep, voffB); PG8_STAGE(PG8_SA(0, 0), a2, voffA);
;             PG8_WAIT_V(8); PG8_WAIT_L(0); PG8_BAR; PG8_MMA(1, 0, At, B0); PG8_MMA(1, 1, At, B1); PG8_BAR; PG8_SCHED;
;             PG8_LDB(B0, 1, 0); PG8_LDB(B1, 1, 1); PG8_SCHED; PG8_LDA(At, 1, 0); PG8_STAGE(PG8_SA(0, 1), a2 + hstep, voffA);
;             PG8_WAIT_V(8); PG8_WAIT_L(0); PG8_BAR; PG8_MMA(0, 0, At, B0); PG8_MMA(0, 1, At, B1); PG8_BAR; PG8_SCHED;
;             PG8_LDA(At, 1, 1); PG8_STAGE(PG8_SB(1, 0), b3, voffB); PG8_STAGE(PG8_SB(1, 1), b3 + hstep, voffB); PG8_STAGE(PG8_SA(1, 0), a3, voffA);
;             PG8_WAIT_V(8); PG8_WAIT_L(0); PG8_BAR; PG8_MMA(1, 0, At, B0); PG8_MMA(1, 1, At, B1); PG8_BAR; PG8_SCHED;
.LBB0_705:
	ds_read_b128 v[152:155], v159
	ds_read_b128 v[164:167], v159 offset:1024
	ds_read_b128 v[168:171], v159 offset:2048
	ds_read_b128 v[172:175], v159 offset:3072
	ds_read_b128 v[176:179], v160
	ds_read_b128 v[180:183], v160 offset:1024
	ds_read_b128 v[184:187], v160 offset:2048
	ds_read_b128 v[190:193], v160 offset:3072
	s_add_u32 s60, s62, 0xfff80080
	s_addc_u32 s61, s63, -1
	s_cmp_eq_u32 s93, 28
	s_cselect_b32 s69, s57, s61
	s_cselect_b32 s68, s59, s60
	s_cselect_b32 s61, s87, s92
	s_cselect_b32 s60, s90, s91
	s_mov_b32 m0, s77
	v_lshl_add_u64 v[210:211], s[62:63], 0, v[136:137]
	ds_read_b128 v[194:197], v161
	ds_read_b128 v[198:201], v161 offset:1024
	ds_read_b128 v[202:205], v161 offset:2048
	ds_read_b128 v[206:209], v161 offset:3072
	ds_read_b128 v[214:217], v161 offset:4096
	ds_read_b128 v[218:221], v161 offset:5120
	ds_read_b128 v[222:225], v161 offset:6144
	ds_read_b128 v[226:229], v161 offset:7168
	global_load_lds_dwordx4 v[210:211], off
	v_lshl_add_u64 v[210:211], s[62:63], 0, v[132:133]
	s_mov_b32 m0, s78
	s_nop 0
	global_load_lds_dwordx4 v[210:211], off
	s_waitcnt vmcnt(8)
	s_waitcnt lgkmcnt(0)
	s_barrier
	s_waitcnt lgkmcnt(0)
	v_mfma_f32_16x16x32_bf16 v[124:127], v[152:155], v[194:197], v[124:127]
	v_mfma_f32_16x16x32_bf16 v[120:123], v[168:171], v[194:197], v[120:123]
	v_mfma_f32_16x16x32_bf16 v[116:119], v[152:155], v[202:205], v[116:119]
	v_mfma_f32_16x16x32_bf16 v[112:115], v[168:171], v[202:205], v[112:115]
	v_mfma_f32_16x16x32_bf16 v[108:111], v[152:155], v[214:217], v[108:111]
	v_mfma_f32_16x16x32_bf16 v[104:107], v[168:171], v[214:217], v[104:107]
	v_mfma_f32_16x16x32_bf16 v[100:103], v[152:155], v[222:225], v[100:103]
	v_mfma_f32_16x16x32_bf16 v[96:99], v[168:171], v[222:225], v[96:99]
	v_mfma_f32_16x16x32_bf16 v[124:127], v[164:167], v[198:201], v[124:127]
	v_mfma_f32_16x16x32_bf16 v[120:123], v[172:175], v[198:201], v[120:123]
	v_mfma_f32_16x16x32_bf16 v[116:119], v[164:167], v[206:209], v[116:119]
	v_mfma_f32_16x16x32_bf16 v[112:115], v[172:175], v[206:209], v[112:115]
	v_mfma_f32_16x16x32_bf16 v[108:111], v[164:167], v[218:221], v[108:111]
	v_mfma_f32_16x16x32_bf16 v[104:107], v[172:175], v[218:221], v[104:107]
	v_mfma_f32_16x16x32_bf16 v[100:103], v[164:167], v[226:229], v[100:103]
	v_mfma_f32_16x16x32_bf16 v[96:99], v[172:175], v[226:229], v[96:99]
	v_mfma_f32_16x16x32_bf16 v[88:91], v[176:179], v[194:197], v[88:91]
	v_mfma_f32_16x16x32_bf16 v[92:95], v[184:187], v[194:197], v[92:95]
	v_mfma_f32_16x16x32_bf16 v[80:83], v[176:179], v[202:205], v[80:83]
	v_mfma_f32_16x16x32_bf16 v[84:87], v[184:187], v[202:205], v[84:87]
	v_mfma_f32_16x16x32_bf16 v[72:75], v[176:179], v[214:217], v[72:75]
	v_mfma_f32_16x16x32_bf16 v[76:79], v[184:187], v[214:217], v[76:79]
	v_mfma_f32_16x16x32_bf16 v[64:67], v[176:179], v[222:225], v[64:67]
	v_mfma_f32_16x16x32_bf16 v[68:71], v[184:187], v[222:225], v[68:71]
	v_mfma_f32_16x16x32_bf16 v[88:91], v[180:183], v[198:201], v[88:91]
	v_mfma_f32_16x16x32_bf16 v[92:95], v[190:193], v[198:201], v[92:95]
	v_mfma_f32_16x16x32_bf16 v[80:83], v[180:183], v[206:209], v[80:83]
	v_mfma_f32_16x16x32_bf16 v[84:87], v[190:193], v[206:209], v[84:87]
	v_mfma_f32_16x16x32_bf16 v[72:75], v[180:183], v[218:221], v[72:75]
	v_mfma_f32_16x16x32_bf16 v[76:79], v[190:193], v[218:221], v[76:79]
	v_mfma_f32_16x16x32_bf16 v[64:67], v[180:183], v[226:229], v[64:67]
	v_mfma_f32_16x16x32_bf16 v[68:71], v[190:193], v[226:229], v[68:71]
	s_barrier
	s_mov_b32 m0, s79
	v_lshl_add_u64 v[210:211], s[60:61], 0, v[130:131]
	s_add_u32 s94, s60, 0x80000
	ds_read_b128 v[194:197], v161 offset:16384
	ds_read_b128 v[198:201], v161 offset:17408
	ds_read_b128 v[202:205], v161 offset:18432
	ds_read_b128 v[206:209], v161 offset:19456
	ds_read_b128 v[214:217], v161 offset:20480
	ds_read_b128 v[218:221], v161 offset:21504
	ds_read_b128 v[222:225], v161 offset:22528
	ds_read_b128 v[226:229], v161 offset:23552
	global_load_lds_dwordx4 v[210:211], off
	v_lshl_add_u64 v[230:231], s[60:61], 0, v[134:135]
	s_mov_b32 m0, s80
	s_addc_u32 s95, s61, 0
	global_load_lds_dwordx4 v[230:231], off
	v_lshl_add_u64 v[232:233], s[94:95], 0, v[130:131]
	s_mov_b32 m0, s0
	v_lshl_add_u64 v[234:235], s[68:69], 0, v[132:133]
	global_load_lds_dwordx4 v[232:233], off
	v_lshl_add_u64 v[232:233], s[94:95], 0, v[134:135]
	s_mov_b32 m0, s1
	s_nop 0
	global_load_lds_dwordx4 v[232:233], off
	v_lshl_add_u64 v[232:233], s[68:69], 0, v[128:129]
	s_mov_b32 m0, s28
	s_nop 0
	global_load_lds_dwordx4 v[232:233], off
	s_mov_b32 m0, s29
	s_nop 0
	global_load_lds_dwordx4 v[234:235], off
	s_waitcnt vmcnt(8)
	s_waitcnt lgkmcnt(0)
	s_barrier
; #define PG8_STAGE(bufoff, gbase, voff) do { _Pragma("unroll") for (int _i = 0; _i < 2; ++_i) \
;         __builtin_amdgcn_global_load_lds((const unsigned*)((const char*)(gbase) + (voff)[_i]), (PG8_LAS unsigned*)(lds + (bufoff) + ldsw + _i * 8192), 16, 0, 0); } while (0)
; #define PG8_LDA(dst, b, h) do { _Pragma("unroll") for (int m = 0; m < 4; ++m) _Pragma("unroll") for (int k = 0; k < 2; ++k) dst[m][k] = *(const PG8_LAS bf16x8*)(lds + PG8_SA(b, h) + aoff + m * 2048 + k * 1024); } while (0)
; #define PG8_LDB(dst, b, h) do { _Pragma("unroll") for (int n = 0; n < 2; ++n) _Pragma("unroll") for (int k = 0; k < 2; ++k) dst[n][k] = *(const PG8_LAS bf16x8*)(lds + PG8_SB(b, h) + boff + n * 2048 + k * 1024); } while (0)
; #define PG8_MMA(ai, bj, At, Bt) do { __builtin_amdgcn_s_setprio(1); _Pragma("unroll") for (int m = 0; m < 4; ++m) _Pragma("unroll") for (int n = 0; n < 2; ++n) _Pragma("unroll") for (int k = 0; k < 2; ++k) \
;         acc[ai][bj][m][n] = __builtin_amdgcn_mfma_f32_16x16x32_bf16(Bt[n][k], At[m][k], acc[ai][bj][m][n], 0, 0, 0); __builtin_amdgcn_s_setprio(0); } while (0)
; #define PG8_WAIT_V(n) asm volatile("s_waitcnt vmcnt(" #n ")" ::: "memory")
; template <class Epi, class Sched, bool ALIGN_EPI = false, bool SP2 = false>
; __device__ __forceinline__ void gemm_phase(PG8_LAS unsigned char* lds, const Gemm g, const Sched& S, const Epi& E) {
;     ...
;             PG8_LDB(B0, 0, 0); PG8_LDB(B1, 0, 1); PG8_SCHED; PG8_LDA(At, 0, 0); PG8_STAGE(PG8_SA(1, 1), a1 + hstep, voffA);
;             PG8_WAIT_V(8); PG8_WAIT_L(0); PG8_BAR; PG8_MMA(0, 0, At, B0); PG8_MMA(0, 1, At, B1); PG8_BAR; PG8_SCHED;
;             PG8_LDA(At, 0, 1); PG8_STAGE(PG8_SB(0, 0), b2, voffB); PG8_STAGE(PG8_SB(0, 1), b2 + hstep, voffB); PG8_STAGE(PG8_SA(0, 0), a2, voffA);
;             PG8_WAIT_V(8); PG8_WAIT_L(0); PG8_BAR; PG8_MMA(1, 0, At, B0); PG8_MMA(1, 1, At, B1); PG8_BAR; PG8_SCHED;
;             PG8_LDB(B0, 1, 0); PG8_LDB(B1, 1, 1); PG8_SCHED; PG8_LDA(At, 1, 0); PG8_STAGE(PG8_SA(0, 1), a2 + hstep, voffA);
;             PG8_WAIT_V(8); PG8_WAIT_L(0); PG8_BAR; PG8_MMA(0, 0, At, B0); PG8_MMA(0, 1, At, B1); PG8_BAR; PG8_SCHED;
;             PG8_LDA(At, 1, 1); PG8_STAGE(PG8_SB(1, 0), b3, voffB); PG8_STAGE(PG8_SB(1, 1), b3 + hstep, voffB); PG8_STAGE(PG8_SA(1, 0), a3, voffA);
;             PG8_WAIT_V(8); PG8_WAIT_L(0); PG8_BAR; PG8_MMA(1, 0, At, B0); PG8_MMA(1, 1, At, B1); PG8_BAR; PG8_SCHED;
	s_waitcnt lgkmcnt(0)
	v_mfma_f32_16x16x32_bf16 v[60:63], v[152:155], v[194:197], v[60:63]
	v_mfma_f32_16x16x32_bf16 v[56:59], v[168:171], v[194:197], v[56:59]
	v_mfma_f32_16x16x32_bf16 v[44:47], v[152:155], v[202:205], v[44:47]
	v_mfma_f32_16x16x32_bf16 v[40:43], v[168:171], v[202:205], v[40:43]
	v_mfma_f32_16x16x32_bf16 v[28:31], v[152:155], v[214:217], v[28:31]
	v_mfma_f32_16x16x32_bf16 v[24:27], v[168:171], v[214:217], v[24:27]
	v_mfma_f32_16x16x32_bf16 v[12:15], v[152:155], v[222:225], v[12:15]
	v_mfma_f32_16x16x32_bf16 v[8:11], v[168:171], v[222:225], v[8:11]
	v_mfma_f32_16x16x32_bf16 v[60:63], v[164:167], v[198:201], v[60:63]
	v_mfma_f32_16x16x32_bf16 v[56:59], v[172:175], v[198:201], v[56:59]
	v_mfma_f32_16x16x32_bf16 v[44:47], v[164:167], v[206:209], v[44:47]
	v_mfma_f32_16x16x32_bf16 v[40:43], v[172:175], v[206:209], v[40:43]
	v_mfma_f32_16x16x32_bf16 v[28:31], v[164:167], v[218:221], v[28:31]
	v_mfma_f32_16x16x32_bf16 v[24:27], v[172:175], v[218:221], v[24:27]
	v_mfma_f32_16x16x32_bf16 v[12:15], v[164:167], v[226:229], v[12:15]
	v_mfma_f32_16x16x32_bf16 v[8:11], v[172:175], v[226:229], v[8:11]
	v_mfma_f32_16x16x32_bf16 v[52:55], v[176:179], v[194:197], v[52:55]
	v_mfma_f32_16x16x32_bf16 v[48:51], v[184:187], v[194:197], v[48:51]
	v_mfma_f32_16x16x32_bf16 v[36:39], v[176:179], v[202:205], v[36:39]
	v_mfma_f32_16x16x32_bf16 v[32:35], v[184:187], v[202:205], v[32:35]
	v_mfma_f32_16x16x32_bf16 v[20:23], v[176:179], v[214:217], v[20:23]
	v_mfma_f32_16x16x32_bf16 v[16:19], v[184:187], v[214:217], v[16:19]
	v_mfma_f32_16x16x32_bf16 v[4:7], v[176:179], v[222:225], v[4:7]
	v_mfma_f32_16x16x32_bf16 v[0:3], v[184:187], v[222:225], v[0:3]
	v_mfma_f32_16x16x32_bf16 v[52:55], v[180:183], v[198:201], v[52:55]
	v_mfma_f32_16x16x32_bf16 v[48:51], v[190:193], v[198:201], v[48:51]
	v_mfma_f32_16x16x32_bf16 v[36:39], v[180:183], v[206:209], v[36:39]
	v_mfma_f32_16x16x32_bf16 v[32:35], v[190:193], v[206:209], v[32:35]
	v_mfma_f32_16x16x32_bf16 v[20:23], v[180:183], v[218:221], v[20:23]
	v_mfma_f32_16x16x32_bf16 v[16:19], v[190:193], v[218:221], v[16:19]
	v_mfma_f32_16x16x32_bf16 v[4:7], v[180:183], v[226:229], v[4:7]
	v_mfma_f32_16x16x32_bf16 v[0:3], v[190:193], v[226:229], v[0:3]
	s_barrier
	ds_read_b128 v[152:155], v162
	ds_read_b128 v[164:167], v162 offset:1024
	ds_read_b128 v[168:171], v162 offset:2048
	ds_read_b128 v[172:175], v162 offset:3072
	ds_read_b128 v[176:179], v163
	ds_read_b128 v[180:183], v163 offset:1024
	ds_read_b128 v[184:187], v163 offset:2048
	ds_read_b128 v[190:193], v163 offset:3072
	s_add_u32 s68, s68, 0x80000
	s_addc_u32 s69, s69, 0
	s_mov_b32 m0, s30
	v_lshl_add_u64 v[236:237], s[68:69], 0, v[128:129]
	ds_read_b128 v[194:197], v161 offset:32768
	ds_read_b128 v[198:201], v161 offset:33792
	ds_read_b128 v[202:205], v161 offset:34816
	ds_read_b128 v[206:209], v161 offset:35840
	ds_read_b128 v[214:217], v161 offset:36864
	ds_read_b128 v[218:221], v161 offset:37888
	ds_read_b128 v[222:225], v161 offset:38912
	ds_read_b128 v[226:229], v161 offset:39936
	global_load_lds_dwordx4 v[236:237], off
	v_lshl_add_u64 v[236:237], s[68:69], 0, v[132:133]
	s_mov_b32 m0, s33
	s_nop 0
	global_load_lds_dwordx4 v[236:237], off
	s_waitcnt vmcnt(8)
	s_waitcnt lgkmcnt(0)
	s_barrier
	s_waitcnt lgkmcnt(0)
	v_mfma_f32_16x16x32_bf16 v[124:127], v[152:155], v[194:197], v[124:127]
	v_mfma_f32_16x16x32_bf16 v[120:123], v[168:171], v[194:197], v[120:123]
	v_mfma_f32_16x16x32_bf16 v[116:119], v[152:155], v[202:205], v[116:119]
	v_mfma_f32_16x16x32_bf16 v[112:115], v[168:171], v[202:205], v[112:115]
	v_mfma_f32_16x16x32_bf16 v[108:111], v[152:155], v[214:217], v[108:111]
	v_mfma_f32_16x16x32_bf16 v[104:107], v[168:171], v[214:217], v[104:107]
	v_mfma_f32_16x16x32_bf16 v[100:103], v[152:155], v[222:225], v[100:103]
	v_mfma_f32_16x16x32_bf16 v[96:99], v[168:171], v[222:225], v[96:99]
	v_mfma_f32_16x16x32_bf16 v[124:127], v[164:167], v[198:201], v[124:127]
	v_mfma_f32_16x16x32_bf16 v[120:123], v[172:175], v[198:201], v[120:123]
	v_mfma_f32_16x16x32_bf16 v[116:119], v[164:167], v[206:209], v[116:119]
	v_mfma_f32_16x16x32_bf16 v[112:115], v[172:175], v[206:209], v[112:115]
	v_mfma_f32_16x16x32_bf16 v[108:111], v[164:167], v[218:221], v[108:111]
	v_mfma_f32_16x16x32_bf16 v[104:107], v[172:175], v[218:221], v[104:107]
	v_mfma_f32_16x16x32_bf16 v[100:103], v[164:167], v[226:229], v[100:103]
	v_mfma_f32_16x16x32_bf16 v[96:99], v[172:175], v[226:229], v[96:99]
	v_mfma_f32_16x16x32_bf16 v[88:91], v[176:179], v[194:197], v[88:91]
	v_mfma_f32_16x16x32_bf16 v[92:95], v[184:187], v[194:197], v[92:95]
	v_mfma_f32_16x16x32_bf16 v[80:83], v[176:179], v[202:205], v[80:83]
	v_mfma_f32_16x16x32_bf16 v[84:87], v[184:187], v[202:205], v[84:87]
	v_mfma_f32_16x16x32_bf16 v[72:75], v[176:179], v[214:217], v[72:75]
	v_mfma_f32_16x16x32_bf16 v[76:79], v[184:187], v[214:217], v[76:79]
	v_mfma_f32_16x16x32_bf16 v[64:67], v[176:179], v[222:225], v[64:67]
	v_mfma_f32_16x16x32_bf16 v[68:71], v[184:187], v[222:225], v[68:71]
	v_mfma_f32_16x16x32_bf16 v[88:91], v[180:183], v[198:201], v[88:91]
	v_mfma_f32_16x16x32_bf16 v[92:95], v[190:193], v[198:201], v[92:95]
	v_mfma_f32_16x16x32_bf16 v[80:83], v[180:183], v[206:209], v[80:83]
	v_mfma_f32_16x16x32_bf16 v[84:87], v[190:193], v[206:209], v[84:87]
	v_mfma_f32_16x16x32_bf16 v[72:75], v[180:183], v[218:221], v[72:75]
	v_mfma_f32_16x16x32_bf16 v[76:79], v[190:193], v[218:221], v[76:79]
	v_mfma_f32_16x16x32_bf16 v[64:67], v[180:183], v[226:229], v[64:67]
	v_mfma_f32_16x16x32_bf16 v[68:71], v[190:193], v[226:229], v[68:71]
	s_barrier
; #define PG8_STAGE(bufoff, gbase, voff) do { _Pragma("unroll") for (int _i = 0; _i < 2; ++_i) \
;         __builtin_amdgcn_global_load_lds((const unsigned*)((const char*)(gbase) + (voff)[_i]), (PG8_LAS unsigned*)(lds + (bufoff) + ldsw + _i * 8192), 16, 0, 0); } while (0)
; #define PG8_LDA(dst, b, h) do { _Pragma("unroll") for (int m = 0; m < 4; ++m) _Pragma("unroll") for (int k = 0; k < 2; ++k) dst[m][k] = *(const PG8_LAS bf16x8*)(lds + PG8_SA(b, h) + aoff + m * 2048 + k * 1024); } while (0)
; #define PG8_WAIT_V(n) asm volatile("s_waitcnt vmcnt(" #n ")" ::: "memory")
; #define PG8_WAIT_L(n) asm volatile("s_waitcnt lgkmcnt(" #n ")" ::: "memory")
; #define PG8_BAR __builtin_amdgcn_s_barrier()
; template <class Epi, class Sched, bool ALIGN_EPI = false, bool SP2 = false>
; __device__ __forceinline__ void gemm_phase(PG8_LAS unsigned char* lds, const Gemm g, const Sched& S, const Epi& E) {
;     ...
;         for (int t = seg * tseg; t < (seg + 1) * tseg; t += 2) {
;             const bool last = (t == nt - 2);
;             const char* a1 = cA + (size_t)(t + 1) * kstep;
;             const char* a2 = last ? nA : cA + (size_t)(t + 2) * kstep; const char* b2 = last ? nB : cB + (size_t)(t + 2) * kstep;
;             const char* a3 = a2 + kstep; const char* b3 = b2 + kstep;
;             if (last && has_next) S.a_ready(nxt);
;             if constexpr (SP2) {
;             PG8_LDB(B0, 0, 0); PG8_LDB(B1, 0, 1); PG8_SCHED; PG8_LDA(At, 0, 0); PG8_STAGE(PG8_SA(1, 1), a1 + hstep, voffA);
;             PG8_WAIT_V(8); PG8_WAIT_L(0); PG8_BAR; PG8_MMA(0, 0, At, B0); PG8_MMA(0, 1, At, B1); PG8_BAR; PG8_SCHED;
;             PG8_LDA(At, 0, 1); PG8_STAGE(PG8_SB(0, 0), b2, voffB); PG8_STAGE(PG8_SB(0, 1), b2 + hstep, voffB); PG8_STAGE(PG8_SA(0, 0), a2, voffA);
;             PG8_WAIT_V(8); PG8_WAIT_L(0); PG8_BAR; PG8_MMA(1, 0, At, B0); PG8_MMA(1, 1, At, B1); PG8_BAR; PG8_SCHED;
;             PG8_LDB(B0, 1, 0); PG8_LDB(B1, 1, 1); PG8_SCHED; PG8_LDA(At, 1, 0); PG8_STAGE(PG8_SA(0, 1), a2 + hstep, voffA);
;             PG8_WAIT_V(8); PG8_WAIT_L(0); PG8_BAR; PG8_MMA(0, 0, At, B0); PG8_MMA(0, 1, At, B1); PG8_BAR; PG8_SCHED;
;             PG8_LDA(At, 1, 1); PG8_STAGE(PG8_SB(1, 0), b3, voffB); PG8_STAGE(PG8_SB(1, 1), b3 + hstep, voffB); PG8_STAGE(PG8_SA(1, 0), a3, voffA);
;             PG8_WAIT_V(8); PG8_WAIT_L(0); PG8_BAR; PG8_MMA(1, 0, At, B0); PG8_MMA(1, 1, At, B1); PG8_BAR; PG8_SCHED;
	s_mov_b32 m0, s82
	v_lshl_add_u64 v[210:211], v[210:211], 0, s[8:9]
	s_add_u32 s60, s60, 0x80080
	ds_read_b128 v[194:197], v161 offset:49152
	ds_read_b128 v[198:201], v161 offset:50176
	ds_read_b128 v[202:205], v161 offset:51200
	ds_read_b128 v[206:209], v161 offset:52224
	ds_read_b128 v[214:217], v161 offset:53248
	ds_read_b128 v[218:221], v161 offset:54272
	ds_read_b128 v[222:225], v161 offset:55296
	ds_read_b128 v[226:229], v161 offset:56320
	global_load_lds_dwordx4 v[210:211], off
	v_lshl_add_u64 v[210:211], v[230:231], 0, s[8:9]
	s_mov_b32 m0, s83
	s_addc_u32 s61, s61, 0
	global_load_lds_dwordx4 v[210:211], off
	v_lshl_add_u64 v[210:211], s[60:61], 0, v[130:131]
	s_mov_b32 m0, s85
	s_nop 0
	global_load_lds_dwordx4 v[210:211], off
	v_lshl_add_u64 v[210:211], s[60:61], 0, v[134:135]
	s_mov_b32 m0, s86
	s_nop 0
	global_load_lds_dwordx4 v[210:211], off
	v_lshl_add_u64 v[210:211], v[232:233], 0, s[8:9]
	s_mov_b32 m0, s71
	s_nop 0
	global_load_lds_dwordx4 v[210:211], off
	v_lshl_add_u64 v[210:211], v[234:235], 0, s[8:9]
	s_mov_b32 m0, s76
	s_nop 0
	global_load_lds_dwordx4 v[210:211], off
	s_waitcnt vmcnt(8)
	s_waitcnt lgkmcnt(0)
	s_barrier
	s_waitcnt lgkmcnt(0)
	v_mfma_f32_16x16x32_bf16 v[60:63], v[152:155], v[194:197], v[60:63]
	v_mfma_f32_16x16x32_bf16 v[56:59], v[168:171], v[194:197], v[56:59]
	v_mfma_f32_16x16x32_bf16 v[44:47], v[152:155], v[202:205], v[44:47]
	v_mfma_f32_16x16x32_bf16 v[40:43], v[168:171], v[202:205], v[40:43]
	v_mfma_f32_16x16x32_bf16 v[28:31], v[152:155], v[214:217], v[28:31]
	v_mfma_f32_16x16x32_bf16 v[24:27], v[168:171], v[214:217], v[24:27]
	v_mfma_f32_16x16x32_bf16 v[12:15], v[152:155], v[222:225], v[12:15]
	v_mfma_f32_16x16x32_bf16 v[8:11], v[168:171], v[222:225], v[8:11]
	v_mfma_f32_16x16x32_bf16 v[60:63], v[164:167], v[198:201], v[60:63]
	v_mfma_f32_16x16x32_bf16 v[56:59], v[172:175], v[198:201], v[56:59]
	v_mfma_f32_16x16x32_bf16 v[44:47], v[164:167], v[206:209], v[44:47]
	v_mfma_f32_16x16x32_bf16 v[40:43], v[172:175], v[206:209], v[40:43]
	v_mfma_f32_16x16x32_bf16 v[28:31], v[164:167], v[218:221], v[28:31]
	v_mfma_f32_16x16x32_bf16 v[24:27], v[172:175], v[218:221], v[24:27]
	v_mfma_f32_16x16x32_bf16 v[12:15], v[164:167], v[226:229], v[12:15]
	v_mfma_f32_16x16x32_bf16 v[8:11], v[172:175], v[226:229], v[8:11]
	v_mfma_f32_16x16x32_bf16 v[52:55], v[176:179], v[194:197], v[52:55]
	v_mfma_f32_16x16x32_bf16 v[48:51], v[184:187], v[194:197], v[48:51]
	v_mfma_f32_16x16x32_bf16 v[36:39], v[176:179], v[202:205], v[36:39]
	v_mfma_f32_16x16x32_bf16 v[32:35], v[184:187], v[202:205], v[32:35]
	v_mfma_f32_16x16x32_bf16 v[20:23], v[176:179], v[214:217], v[20:23]
	v_mfma_f32_16x16x32_bf16 v[16:19], v[184:187], v[214:217], v[16:19]
	v_mfma_f32_16x16x32_bf16 v[4:7], v[176:179], v[222:225], v[4:7]
	v_mfma_f32_16x16x32_bf16 v[0:3], v[184:187], v[222:225], v[0:3]
	v_mfma_f32_16x16x32_bf16 v[52:55], v[180:183], v[198:201], v[52:55]
	v_mfma_f32_16x16x32_bf16 v[48:51], v[190:193], v[198:201], v[48:51]
	v_mfma_f32_16x16x32_bf16 v[36:39], v[180:183], v[206:209], v[36:39]
	v_mfma_f32_16x16x32_bf16 v[32:35], v[190:193], v[206:209], v[32:35]
	v_mfma_f32_16x16x32_bf16 v[20:23], v[180:183], v[218:221], v[20:23]
	v_mfma_f32_16x16x32_bf16 v[16:19], v[190:193], v[218:221], v[16:19]
	v_mfma_f32_16x16x32_bf16 v[4:7], v[180:183], v[226:229], v[4:7]
	v_mfma_f32_16x16x32_bf16 v[0:3], v[190:193], v[226:229], v[0:3]
	s_barrier
	s_add_i32 s93, s93, 2
	s_add_u32 s62, s62, 0x100
	s_addc_u32 s63, s63, 0
	s_add_u32 s91, s91, 0x100
	s_addc_u32 s92, s92, 0
	s_cmp_lt_u32 s93, 30
	s_cbranch_scc1 .LBB0_705
	s_and_b64 vcc, exec, s[12:13]
	s_cbranch_vccz .LBB0_708
	s_barrier

;     __device__ bool next(int i, Unit& u) const { if (i >= n) return false; const int q = first + i; u.pm = rowbase + q % rows; u.pn = q / rows; return true; }
; #define PG8_WAIT_V(n) asm volatile("s_waitcnt vmcnt(" #n ")" ::: "memory")
; template <class Epi, class Sched, bool ALIGN_EPI = false, bool SP2 = false>
; __device__ __forceinline__ void gemm_phase(PG8_LAS unsigned char* lds, const Gemm g, const Sched& S, const Epi& E) {
;     ...
;         const bool has_next = S.next(ui + 1, nxt);
;         const char* nA = has_next ? (const char*)g.A + (size_t)nxt.pm * tstep : cA; const char* nB = has_next ? (const char*)g.Bt + (size_t)nxt.pn * tstep : cB;
;         constexpr int NSEG = Epi::HAS_MID ? 2 : 1; const int tseg = nt / NSEG;
; #pragma unroll
;         for (int seg = 0; seg < NSEG; ++seg) {
;         if constexpr (Epi::HAS_MID) { if (seg == 1) E.mid(acc, cur, wr, wc, fr, fq); }
;         for (int t = seg * tseg; t < (seg + 1) * tseg; t += 2) {
;             const bool last = (t == nt - 2);
;             const char* a1 = cA + (size_t)(t + 1) * kstep;
;             const char* a2 = last ? nA : cA + (size_t)(t + 2) * kstep; const char* b2 = last ? nB : cB + (size_t)(t + 2) * kstep;
;             const char* a3 = a2 + kstep; const char* b3 = b2 + kstep;
;             if (last && has_next) S.a_ready(nxt);
;             if constexpr (SP2) {
;             PG8_LDB(B0, 0, 0); PG8_LDB(B1, 0, 1); PG8_SCHED; PG8_LDA(At, 0, 0); PG8_STAGE(PG8_SA(1, 1), a1 + hstep, voffA);
;             PG8_WAIT_V(8); PG8_WAIT_L(0); PG8_BAR; PG8_MMA(0, 0, At, B0); PG8_MMA(0, 1, At, B1); PG8_BAR; PG8_SCHED;
;             PG8_LDA(At, 0, 1); PG8_STAGE(PG8_SB(0, 0), b2, voffB); PG8_STAGE(PG8_SB(0, 1), b2 + hstep, voffB); PG8_STAGE(PG8_SA(0, 0), a2, voffA);
;             PG8_WAIT_V(8); PG8_WAIT_L(0); PG8_BAR; PG8_MMA(1, 0, At, B0); PG8_MMA(1, 1, At, B1); PG8_BAR; PG8_SCHED;
;             PG8_LDB(B0, 1, 0); PG8_LDB(B1, 1, 1); PG8_SCHED; PG8_LDA(At, 1, 0); PG8_STAGE(PG8_SA(0, 1), a2 + hstep, voffA);
;             PG8_WAIT_V(8); PG8_WAIT_L(0); PG8_BAR; PG8_MMA(0, 0, At, B0); PG8_MMA(0, 1, At, B1); PG8_BAR; PG8_SCHED;
;             PG8_LDA(At, 1, 1); PG8_STAGE(PG8_SB(1, 0), b3, voffB); PG8_STAGE(PG8_SB(1, 1), b3 + hstep, voffB); PG8_STAGE(PG8_SA(1, 0), a3, voffA);
;             PG8_WAIT_V(8); PG8_WAIT_L(0); PG8_BAR; PG8_MMA(1, 0, At, B0); PG8_MMA(1, 1, At, B1); PG8_BAR; PG8_SCHED;
.LBB0_780:
	s_ashr_i32 s47, s46, 31
	s_lshl_b64 s[0:1], s[46:47], 20
	s_add_u32 s56, s54, s0
	s_addc_u32 s57, s55, s1
	s_and_b64 s[0:1], s[4:5], exec
	s_cselect_b32 s0, s57, s63
	s_cselect_b32 s1, s56, s62
	s_ashr_i32 s41, s40, 31
	s_lshl_b64 s[58:59], s[40:41], 20
	s_add_u32 s58, s20, s58
	s_addc_u32 s59, s21, s59
	s_and_b64 s[66:67], s[4:5], exec
	s_cselect_b32 s41, s59, s65
	s_cselect_b32 s47, s58, s64
	s_add_u32 s62, s62, 0x80080
	s_addc_u32 s63, s63, 0
	s_add_u32 s71, s64, 0x100
	s_addc_u32 s76, s65, 0
	s_mov_b32 s77, -2
	ds_read_b128 v[128:131], v169
	ds_read_b128 v[132:135], v169 offset:1024
	ds_read_b128 v[136:139], v169 offset:2048
	ds_read_b128 v[140:143], v169 offset:3072
	ds_read_b128 v[160:163], v170
	ds_read_b128 v[172:175], v170 offset:1024
	ds_read_b128 v[176:179], v170 offset:2048
	ds_read_b128 v[180:183], v170 offset:3072
	s_add_u32 s64, s62, 0xfff80080
	s_addc_u32 s65, s63, -1
	s_cmp_eq_u32 s77, 28
	s_cselect_b32 s67, s0, s65
	s_cselect_b32 s66, s1, s64
	s_cselect_b32 s65, s41, s76
	s_cselect_b32 s64, s47, s71
	v_lshl_add_u64 v[164:165], s[62:63], 0, v[152:153]
	s_add_i32 m0, s3, 0xc000
	ds_read_b128 v[184:187], v171
	ds_read_b128 v[190:193], v171 offset:1024
	ds_read_b128 v[194:197], v171 offset:2048
	ds_read_b128 v[198:201], v171 offset:3072
	ds_read_b128 v[202:205], v171 offset:4096
	ds_read_b128 v[206:209], v171 offset:5120
	ds_read_b128 v[214:217], v171 offset:6144
	ds_read_b128 v[218:221], v171 offset:7168
	global_load_lds_dwordx4 v[164:165], off
	v_lshl_add_u64 v[164:165], s[62:63], 0, v[154:155]
	s_add_i32 m0, s3, 0xe000
	s_nop 0
	global_load_lds_dwordx4 v[164:165], off
	s_waitcnt vmcnt(8)
	s_waitcnt lgkmcnt(0)
	s_barrier
	s_waitcnt lgkmcnt(0)
	v_mfma_f32_16x16x32_bf16 v[124:127], v[128:131], v[184:187], 0
	v_mfma_f32_16x16x32_bf16 v[120:123], v[136:139], v[184:187], 0
	v_mfma_f32_16x16x32_bf16 v[108:111], v[128:131], v[194:197], 0
	v_mfma_f32_16x16x32_bf16 v[104:107], v[136:139], v[194:197], 0
	v_mfma_f32_16x16x32_bf16 v[92:95], v[128:131], v[202:205], 0
	v_mfma_f32_16x16x32_bf16 v[88:91], v[136:139], v[202:205], 0
	v_mfma_f32_16x16x32_bf16 v[76:79], v[128:131], v[214:217], 0
	v_mfma_f32_16x16x32_bf16 v[72:75], v[136:139], v[214:217], 0
	v_mfma_f32_16x16x32_bf16 v[124:127], v[132:135], v[190:193], v[124:127]
	v_mfma_f32_16x16x32_bf16 v[120:123], v[140:143], v[190:193], v[120:123]
	v_mfma_f32_16x16x32_bf16 v[108:111], v[132:135], v[198:201], v[108:111]
	v_mfma_f32_16x16x32_bf16 v[104:107], v[140:143], v[198:201], v[104:107]
	v_mfma_f32_16x16x32_bf16 v[92:95], v[132:135], v[206:209], v[92:95]
	v_mfma_f32_16x16x32_bf16 v[88:91], v[140:143], v[206:209], v[88:91]
	v_mfma_f32_16x16x32_bf16 v[76:79], v[132:135], v[218:221], v[76:79]
	v_mfma_f32_16x16x32_bf16 v[72:75], v[140:143], v[218:221], v[72:75]
	v_mfma_f32_16x16x32_bf16 v[116:119], v[160:163], v[184:187], 0
	v_mfma_f32_16x16x32_bf16 v[112:115], v[176:179], v[184:187], 0
	v_mfma_f32_16x16x32_bf16 v[100:103], v[160:163], v[194:197], 0
	v_mfma_f32_16x16x32_bf16 v[96:99], v[176:179], v[194:197], 0
	v_mfma_f32_16x16x32_bf16 v[84:87], v[160:163], v[202:205], 0
	v_mfma_f32_16x16x32_bf16 v[80:83], v[176:179], v[202:205], 0
	v_mfma_f32_16x16x32_bf16 v[68:71], v[160:163], v[214:217], 0
	v_mfma_f32_16x16x32_bf16 v[64:67], v[176:179], v[214:217], 0
	v_mfma_f32_16x16x32_bf16 v[116:119], v[172:175], v[190:193], v[116:119]
	v_mfma_f32_16x16x32_bf16 v[112:115], v[180:183], v[190:193], v[112:115]
	v_mfma_f32_16x16x32_bf16 v[100:103], v[172:175], v[198:201], v[100:103]
	v_mfma_f32_16x16x32_bf16 v[96:99], v[180:183], v[198:201], v[96:99]
	v_mfma_f32_16x16x32_bf16 v[84:87], v[172:175], v[206:209], v[84:87]
	v_mfma_f32_16x16x32_bf16 v[80:83], v[180:183], v[206:209], v[80:83]
	v_mfma_f32_16x16x32_bf16 v[68:71], v[172:175], v[218:221], v[68:71]
	v_mfma_f32_16x16x32_bf16 v[64:67], v[180:183], v[218:221], v[64:67]
	s_barrier
	s_add_i32 s78, s31, s2
	v_lshl_add_u64 v[164:165], s[64:65], 0, v[146:147]
	s_mov_b32 m0, s78
	ds_read_b128 v[184:187], v171 offset:16384
	ds_read_b128 v[190:193], v171 offset:17408
	ds_read_b128 v[194:197], v171 offset:18432
	ds_read_b128 v[198:201], v171 offset:19456
	ds_read_b128 v[202:205], v171 offset:20480
	ds_read_b128 v[206:209], v171 offset:21504
	ds_read_b128 v[214:217], v171 offset:22528
	ds_read_b128 v[218:221], v171 offset:23552
	global_load_lds_dwordx4 v[164:165], off
	s_add_i32 m0, s78, 0x2000
	s_add_u32 s78, s64, 0x80000
	v_lshl_add_u64 v[210:211], s[64:65], 0, v[150:151]
	s_addc_u32 s79, s65, 0
	s_add_i32 s80, s74, s2
	global_load_lds_dwordx4 v[210:211], off
	v_lshl_add_u64 v[222:223], s[78:79], 0, v[146:147]
	s_mov_b32 m0, s80
	v_lshl_add_u64 v[224:225], s[66:67], 0, v[148:149]
	global_load_lds_dwordx4 v[222:223], off
	v_lshl_add_u64 v[222:223], s[78:79], 0, v[150:151]
	s_add_i32 m0, s80, 0x2000
	s_nop 0
	global_load_lds_dwordx4 v[222:223], off
	v_lshl_add_u64 v[222:223], s[66:67], 0, v[144:145]
	s_mov_b32 m0, s3
	s_nop 0
	global_load_lds_dwordx4 v[222:223], off
	s_mov_b32 m0, s23
	s_nop 0
	global_load_lds_dwordx4 v[224:225], off
	s_waitcnt vmcnt(8)
	s_waitcnt lgkmcnt(0)
	s_barrier
; #define PG8_STAGE(bufoff, gbase, voff) do { _Pragma("unroll") for (int _i = 0; _i < 2; ++_i) \
;         __builtin_amdgcn_global_load_lds((const unsigned*)((const char*)(gbase) + (voff)[_i]), (PG8_LAS unsigned*)(lds + (bufoff) + ldsw + _i * 8192), 16, 0, 0); } while (0)
; #define PG8_LDA(dst, b, h) do { _Pragma("unroll") for (int m = 0; m < 4; ++m) _Pragma("unroll") for (int k = 0; k < 2; ++k) dst[m][k] = *(const PG8_LAS bf16x8*)(lds + PG8_SA(b, h) + aoff + m * 2048 + k * 1024); } while (0)
; #define PG8_WAIT_V(n) asm volatile("s_waitcnt vmcnt(" #n ")" ::: "memory")
; #define PG8_WAIT_L(n) asm volatile("s_waitcnt lgkmcnt(" #n ")" ::: "memory")
; #define PG8_BAR __builtin_amdgcn_s_barrier()
; template <class Epi, class Sched, bool ALIGN_EPI = false, bool SP2 = false>
; __device__ __forceinline__ void gemm_phase(PG8_LAS unsigned char* lds, const Gemm g, const Sched& S, const Epi& E) {
;     ...
;         for (int t = seg * tseg; t < (seg + 1) * tseg; t += 2) {
;             const bool last = (t == nt - 2);
;             const char* a1 = cA + (size_t)(t + 1) * kstep;
;             const char* a2 = last ? nA : cA + (size_t)(t + 2) * kstep; const char* b2 = last ? nB : cB + (size_t)(t + 2) * kstep;
;             const char* a3 = a2 + kstep; const char* b3 = b2 + kstep;
;             if (last && has_next) S.a_ready(nxt);
;             if constexpr (SP2) {
;             PG8_LDB(B0, 0, 0); PG8_LDB(B1, 0, 1); PG8_SCHED; PG8_LDA(At, 0, 0); PG8_STAGE(PG8_SA(1, 1), a1 + hstep, voffA);
;             PG8_WAIT_V(8); PG8_WAIT_L(0); PG8_BAR; PG8_MMA(0, 0, At, B0); PG8_MMA(0, 1, At, B1); PG8_BAR; PG8_SCHED;
;             PG8_LDA(At, 0, 1); PG8_STAGE(PG8_SB(0, 0), b2, voffB); PG8_STAGE(PG8_SB(0, 1), b2 + hstep, voffB); PG8_STAGE(PG8_SA(0, 0), a2, voffA);
;             PG8_WAIT_V(8); PG8_WAIT_L(0); PG8_BAR; PG8_MMA(1, 0, At, B0); PG8_MMA(1, 1, At, B1); PG8_BAR; PG8_SCHED;
;             PG8_LDB(B0, 1, 0); PG8_LDB(B1, 1, 1); PG8_SCHED; PG8_LDA(At, 1, 0); PG8_STAGE(PG8_SA(0, 1), a2 + hstep, voffA);
;             PG8_WAIT_V(8); PG8_WAIT_L(0); PG8_BAR; PG8_MMA(0, 0, At, B0); PG8_MMA(0, 1, At, B1); PG8_BAR; PG8_SCHED;
;             PG8_LDA(At, 1, 1); PG8_STAGE(PG8_SB(1, 0), b3, voffB); PG8_STAGE(PG8_SB(1, 1), b3 + hstep, voffB); PG8_STAGE(PG8_SA(1, 0), a3, voffA);
;             PG8_WAIT_V(8); PG8_WAIT_L(0); PG8_BAR; PG8_MMA(1, 0, At, B0); PG8_MMA(1, 1, At, B1); PG8_BAR; PG8_SCHED;
	s_waitcnt lgkmcnt(0)
	v_mfma_f32_16x16x32_bf16 v[60:63], v[128:131], v[184:187], 0
	v_mfma_f32_16x16x32_bf16 v[56:59], v[136:139], v[184:187], 0
	v_mfma_f32_16x16x32_bf16 v[44:47], v[128:131], v[194:197], 0
	v_mfma_f32_16x16x32_bf16 v[40:43], v[136:139], v[194:197], 0
	v_mfma_f32_16x16x32_bf16 v[28:31], v[128:131], v[202:205], 0
	v_mfma_f32_16x16x32_bf16 v[24:27], v[136:139], v[202:205], 0
	v_mfma_f32_16x16x32_bf16 v[12:15], v[128:131], v[214:217], 0
	v_mfma_f32_16x16x32_bf16 v[8:11], v[136:139], v[214:217], 0
	v_mfma_f32_16x16x32_bf16 v[60:63], v[132:135], v[190:193], v[60:63]
	v_mfma_f32_16x16x32_bf16 v[56:59], v[140:143], v[190:193], v[56:59]
	v_mfma_f32_16x16x32_bf16 v[44:47], v[132:135], v[198:201], v[44:47]
	v_mfma_f32_16x16x32_bf16 v[40:43], v[140:143], v[198:201], v[40:43]
	v_mfma_f32_16x16x32_bf16 v[28:31], v[132:135], v[206:209], v[28:31]
	v_mfma_f32_16x16x32_bf16 v[24:27], v[140:143], v[206:209], v[24:27]
	v_mfma_f32_16x16x32_bf16 v[12:15], v[132:135], v[218:221], v[12:15]
	v_mfma_f32_16x16x32_bf16 v[8:11], v[140:143], v[218:221], v[8:11]
	v_mfma_f32_16x16x32_bf16 v[52:55], v[160:163], v[184:187], 0
	v_mfma_f32_16x16x32_bf16 v[48:51], v[176:179], v[184:187], 0
	v_mfma_f32_16x16x32_bf16 v[36:39], v[160:163], v[194:197], 0
	v_mfma_f32_16x16x32_bf16 v[32:35], v[176:179], v[194:197], 0
	v_mfma_f32_16x16x32_bf16 v[20:23], v[160:163], v[202:205], 0
	v_mfma_f32_16x16x32_bf16 v[16:19], v[176:179], v[202:205], 0
	v_mfma_f32_16x16x32_bf16 v[4:7], v[160:163], v[214:217], 0
	v_mfma_f32_16x16x32_bf16 v[0:3], v[176:179], v[214:217], 0
	v_mfma_f32_16x16x32_bf16 v[52:55], v[172:175], v[190:193], v[52:55]
	v_mfma_f32_16x16x32_bf16 v[48:51], v[180:183], v[190:193], v[48:51]
	v_mfma_f32_16x16x32_bf16 v[36:39], v[172:175], v[198:201], v[36:39]
	v_mfma_f32_16x16x32_bf16 v[32:35], v[180:183], v[198:201], v[32:35]
	v_mfma_f32_16x16x32_bf16 v[20:23], v[172:175], v[206:209], v[20:23]
	v_mfma_f32_16x16x32_bf16 v[16:19], v[180:183], v[206:209], v[16:19]
	v_mfma_f32_16x16x32_bf16 v[4:7], v[172:175], v[218:221], v[4:7]
	v_mfma_f32_16x16x32_bf16 v[0:3], v[180:183], v[218:221], v[0:3]
	s_barrier
	v_add_u32_e32 v140, s75, v167
	v_add_u32_e32 v180, s84, v167
	ds_read_b128 v[128:131], v140
	ds_read_b128 v[132:135], v140 offset:1024
	ds_read_b128 v[136:139], v140 offset:2048
	ds_read_b128 v[140:143], v140 offset:3072
	ds_read_b128 v[160:163], v180
	ds_read_b128 v[172:175], v180 offset:1024
	ds_read_b128 v[176:179], v180 offset:2048
	ds_read_b128 v[180:183], v180 offset:3072
	s_add_u32 s66, s66, 0x80000
	s_addc_u32 s67, s67, 0
	s_mov_b32 m0, s28
	v_lshl_add_u64 v[226:227], s[66:67], 0, v[144:145]
	ds_read_b128 v[184:187], v171 offset:32768
	ds_read_b128 v[190:193], v171 offset:33792
	ds_read_b128 v[194:197], v171 offset:34816
	ds_read_b128 v[198:201], v171 offset:35840
	ds_read_b128 v[202:205], v171 offset:36864
	ds_read_b128 v[206:209], v171 offset:37888
	ds_read_b128 v[214:217], v171 offset:38912
	ds_read_b128 v[218:221], v171 offset:39936
	global_load_lds_dwordx4 v[226:227], off
	v_lshl_add_u64 v[226:227], s[66:67], 0, v[148:149]
	s_mov_b32 m0, s29
	s_nop 0
	global_load_lds_dwordx4 v[226:227], off
	s_waitcnt vmcnt(8)
	s_waitcnt lgkmcnt(0)
	s_barrier
	s_waitcnt lgkmcnt(0)
	v_mfma_f32_16x16x32_bf16 v[124:127], v[128:131], v[184:187], v[124:127]
	v_mfma_f32_16x16x32_bf16 v[120:123], v[136:139], v[184:187], v[120:123]
	v_mfma_f32_16x16x32_bf16 v[108:111], v[128:131], v[194:197], v[108:111]
	v_mfma_f32_16x16x32_bf16 v[104:107], v[136:139], v[194:197], v[104:107]
	v_mfma_f32_16x16x32_bf16 v[92:95], v[128:131], v[202:205], v[92:95]
	v_mfma_f32_16x16x32_bf16 v[88:91], v[136:139], v[202:205], v[88:91]
	v_mfma_f32_16x16x32_bf16 v[76:79], v[128:131], v[214:217], v[76:79]
	v_mfma_f32_16x16x32_bf16 v[72:75], v[136:139], v[214:217], v[72:75]
	v_mfma_f32_16x16x32_bf16 v[124:127], v[132:135], v[190:193], v[124:127]
	v_mfma_f32_16x16x32_bf16 v[120:123], v[140:143], v[190:193], v[120:123]
	v_mfma_f32_16x16x32_bf16 v[108:111], v[132:135], v[198:201], v[108:111]
	v_mfma_f32_16x16x32_bf16 v[104:107], v[140:143], v[198:201], v[104:107]
	v_mfma_f32_16x16x32_bf16 v[92:95], v[132:135], v[206:209], v[92:95]
	v_mfma_f32_16x16x32_bf16 v[88:91], v[140:143], v[206:209], v[88:91]
	v_mfma_f32_16x16x32_bf16 v[76:79], v[132:135], v[218:221], v[76:79]
	v_mfma_f32_16x16x32_bf16 v[72:75], v[140:143], v[218:221], v[72:75]
	v_mfma_f32_16x16x32_bf16 v[116:119], v[160:163], v[184:187], v[116:119]
	v_mfma_f32_16x16x32_bf16 v[112:115], v[176:179], v[184:187], v[112:115]
	v_mfma_f32_16x16x32_bf16 v[100:103], v[160:163], v[194:197], v[100:103]
	v_mfma_f32_16x16x32_bf16 v[96:99], v[176:179], v[194:197], v[96:99]
	v_mfma_f32_16x16x32_bf16 v[84:87], v[160:163], v[202:205], v[84:87]
	v_mfma_f32_16x16x32_bf16 v[80:83], v[176:179], v[202:205], v[80:83]
	v_mfma_f32_16x16x32_bf16 v[68:71], v[160:163], v[214:217], v[68:71]
	v_mfma_f32_16x16x32_bf16 v[64:67], v[176:179], v[214:217], v[64:67]
	v_mfma_f32_16x16x32_bf16 v[116:119], v[172:175], v[190:193], v[116:119]
	v_mfma_f32_16x16x32_bf16 v[112:115], v[180:183], v[190:193], v[112:115]
	v_mfma_f32_16x16x32_bf16 v[100:103], v[172:175], v[198:201], v[100:103]
	v_mfma_f32_16x16x32_bf16 v[96:99], v[180:183], v[198:201], v[96:99]
	v_mfma_f32_16x16x32_bf16 v[84:87], v[172:175], v[206:209], v[84:87]
	v_mfma_f32_16x16x32_bf16 v[80:83], v[180:183], v[206:209], v[80:83]
	v_mfma_f32_16x16x32_bf16 v[68:71], v[172:175], v[218:221], v[68:71]
	v_mfma_f32_16x16x32_bf16 v[64:67], v[180:183], v[218:221], v[64:67]
	s_barrier
; #define PG8_STAGE(bufoff, gbase, voff) do { _Pragma("unroll") for (int _i = 0; _i < 2; ++_i) \
;         __builtin_amdgcn_global_load_lds((const unsigned*)((const char*)(gbase) + (voff)[_i]), (PG8_LAS unsigned*)(lds + (bufoff) + ldsw + _i * 8192), 16, 0, 0); } while (0)
; #define PG8_LDA(dst, b, h) do { _Pragma("unroll") for (int m = 0; m < 4; ++m) _Pragma("unroll") for (int k = 0; k < 2; ++k) dst[m][k] = *(const PG8_LAS bf16x8*)(lds + PG8_SA(b, h) + aoff + m * 2048 + k * 1024); } while (0)
; #define PG8_WAIT_V(n) asm volatile("s_waitcnt vmcnt(" #n ")" ::: "memory")
; #define PG8_WAIT_L(n) asm volatile("s_waitcnt lgkmcnt(" #n ")" ::: "memory")
; #define PG8_BAR __builtin_amdgcn_s_barrier()
; template <class Epi, class Sched, bool ALIGN_EPI = false, bool SP2 = false>
; __device__ __forceinline__ void gemm_phase(PG8_LAS unsigned char* lds, const Gemm g, const Sched& S, const Epi& E) {
;     ...
;         for (int t = seg * tseg; t < (seg + 1) * tseg; t += 2) {
;             const bool last = (t == nt - 2);
;             const char* a1 = cA + (size_t)(t + 1) * kstep;
;             const char* a2 = last ? nA : cA + (size_t)(t + 2) * kstep; const char* b2 = last ? nB : cB + (size_t)(t + 2) * kstep;
;             const char* a3 = a2 + kstep; const char* b3 = b2 + kstep;
;             if (last && has_next) S.a_ready(nxt);
;             if constexpr (SP2) {
;             PG8_LDB(B0, 0, 0); PG8_LDB(B1, 0, 1); PG8_SCHED; PG8_LDA(At, 0, 0); PG8_STAGE(PG8_SA(1, 1), a1 + hstep, voffA);
;             PG8_WAIT_V(8); PG8_WAIT_L(0); PG8_BAR; PG8_MMA(0, 0, At, B0); PG8_MMA(0, 1, At, B1); PG8_BAR; PG8_SCHED;
;             PG8_LDA(At, 0, 1); PG8_STAGE(PG8_SB(0, 0), b2, voffB); PG8_STAGE(PG8_SB(0, 1), b2 + hstep, voffB); PG8_STAGE(PG8_SA(0, 0), a2, voffA);
;             PG8_WAIT_V(8); PG8_WAIT_L(0); PG8_BAR; PG8_MMA(1, 0, At, B0); PG8_MMA(1, 1, At, B1); PG8_BAR; PG8_SCHED;
;             PG8_LDB(B0, 1, 0); PG8_LDB(B1, 1, 1); PG8_SCHED; PG8_LDA(At, 1, 0); PG8_STAGE(PG8_SA(0, 1), a2 + hstep, voffA);
;             PG8_WAIT_V(8); PG8_WAIT_L(0); PG8_BAR; PG8_MMA(0, 0, At, B0); PG8_MMA(0, 1, At, B1); PG8_BAR; PG8_SCHED;
;             PG8_LDA(At, 1, 1); PG8_STAGE(PG8_SB(1, 0), b3, voffB); PG8_STAGE(PG8_SB(1, 1), b3 + hstep, voffB); PG8_STAGE(PG8_SA(1, 0), a3, voffA);
;             PG8_WAIT_V(8); PG8_WAIT_L(0); PG8_BAR; PG8_MMA(1, 0, At, B0); PG8_MMA(1, 1, At, B1); PG8_BAR; PG8_SCHED;
	s_add_i32 s66, s75, s2
	v_lshl_add_u64 v[164:165], v[164:165], 0, s[8:9]
	s_mov_b32 m0, s66
	ds_read_b128 v[184:187], v171 offset:49152
	ds_read_b128 v[190:193], v171 offset:50176
	ds_read_b128 v[194:197], v171 offset:51200
	ds_read_b128 v[198:201], v171 offset:52224
	ds_read_b128 v[202:205], v171 offset:53248
	ds_read_b128 v[206:209], v171 offset:54272
	ds_read_b128 v[214:217], v171 offset:55296
	ds_read_b128 v[218:221], v171 offset:56320
	global_load_lds_dwordx4 v[164:165], off
	s_add_i32 m0, s66, 0x2000
	s_add_u32 s64, s64, 0x80080
	v_lshl_add_u64 v[164:165], v[210:211], 0, s[8:9]
	s_addc_u32 s65, s65, 0
	s_add_i32 s66, s84, s2
	global_load_lds_dwordx4 v[164:165], off
	v_lshl_add_u64 v[164:165], s[64:65], 0, v[146:147]
	s_mov_b32 m0, s66
	s_nop 0
	global_load_lds_dwordx4 v[164:165], off
	v_lshl_add_u64 v[164:165], s[64:65], 0, v[150:151]
	s_add_i32 m0, s66, 0x2000
	s_nop 0
	global_load_lds_dwordx4 v[164:165], off
	v_lshl_add_u64 v[164:165], v[222:223], 0, s[8:9]
	s_mov_b32 m0, s68
	s_nop 0
	global_load_lds_dwordx4 v[164:165], off
	v_lshl_add_u64 v[164:165], v[224:225], 0, s[8:9]
	s_mov_b32 m0, s69
	s_nop 0
	global_load_lds_dwordx4 v[164:165], off
	s_waitcnt vmcnt(8)
	s_waitcnt lgkmcnt(0)
	s_barrier
	s_waitcnt lgkmcnt(0)
	v_mfma_f32_16x16x32_bf16 v[60:63], v[128:131], v[184:187], v[60:63]
	v_mfma_f32_16x16x32_bf16 v[56:59], v[136:139], v[184:187], v[56:59]
	v_mfma_f32_16x16x32_bf16 v[44:47], v[128:131], v[194:197], v[44:47]
	v_mfma_f32_16x16x32_bf16 v[40:43], v[136:139], v[194:197], v[40:43]
	v_mfma_f32_16x16x32_bf16 v[28:31], v[128:131], v[202:205], v[28:31]
	v_mfma_f32_16x16x32_bf16 v[24:27], v[136:139], v[202:205], v[24:27]
	v_mfma_f32_16x16x32_bf16 v[12:15], v[128:131], v[214:217], v[12:15]
	v_mfma_f32_16x16x32_bf16 v[8:11], v[136:139], v[214:217], v[8:11]
	v_mfma_f32_16x16x32_bf16 v[60:63], v[132:135], v[190:193], v[60:63]
	v_mfma_f32_16x16x32_bf16 v[56:59], v[140:143], v[190:193], v[56:59]
	v_mfma_f32_16x16x32_bf16 v[44:47], v[132:135], v[198:201], v[44:47]
	v_mfma_f32_16x16x32_bf16 v[40:43], v[140:143], v[198:201], v[40:43]
	v_mfma_f32_16x16x32_bf16 v[28:31], v[132:135], v[206:209], v[28:31]
	v_mfma_f32_16x16x32_bf16 v[24:27], v[140:143], v[206:209], v[24:27]
	v_mfma_f32_16x16x32_bf16 v[12:15], v[132:135], v[218:221], v[12:15]
	v_mfma_f32_16x16x32_bf16 v[8:11], v[140:143], v[218:221], v[8:11]
	v_mfma_f32_16x16x32_bf16 v[52:55], v[160:163], v[184:187], v[52:55]
	v_mfma_f32_16x16x32_bf16 v[48:51], v[176:179], v[184:187], v[48:51]
	v_mfma_f32_16x16x32_bf16 v[36:39], v[160:163], v[194:197], v[36:39]
	v_mfma_f32_16x16x32_bf16 v[32:35], v[176:179], v[194:197], v[32:35]
	v_mfma_f32_16x16x32_bf16 v[20:23], v[160:163], v[202:205], v[20:23]
	v_mfma_f32_16x16x32_bf16 v[16:19], v[176:179], v[202:205], v[16:19]
	v_mfma_f32_16x16x32_bf16 v[4:7], v[160:163], v[214:217], v[4:7]
	v_mfma_f32_16x16x32_bf16 v[0:3], v[176:179], v[214:217], v[0:3]
	v_mfma_f32_16x16x32_bf16 v[52:55], v[172:175], v[190:193], v[52:55]
	v_mfma_f32_16x16x32_bf16 v[48:51], v[180:183], v[190:193], v[48:51]
	v_mfma_f32_16x16x32_bf16 v[36:39], v[172:175], v[198:201], v[36:39]
	v_mfma_f32_16x16x32_bf16 v[32:35], v[180:183], v[198:201], v[32:35]
	v_mfma_f32_16x16x32_bf16 v[20:23], v[172:175], v[206:209], v[20:23]
	v_mfma_f32_16x16x32_bf16 v[16:19], v[180:183], v[206:209], v[16:19]
	v_mfma_f32_16x16x32_bf16 v[4:7], v[172:175], v[218:221], v[4:7]
	v_mfma_f32_16x16x32_bf16 v[0:3], v[180:183], v[218:221], v[0:3]
	s_barrier
	s_add_i32 s77, s77, 2
	s_add_u32 s62, s62, 0x100
	s_addc_u32 s63, s63, 0
	s_add_u32 s71, s71, 0x100
	s_addc_u32 s76, s76, 0
	s_cmp_gt_u32 s77, 29
.LBB0_781:
	ds_read_b128 v[128:131], v169
	ds_read_b128 v[132:135], v169 offset:1024
	ds_read_b128 v[136:139], v169 offset:2048
	ds_read_b128 v[140:143], v169 offset:3072
	ds_read_b128 v[160:163], v170
	ds_read_b128 v[172:175], v170 offset:1024
	ds_read_b128 v[176:179], v170 offset:2048
	ds_read_b128 v[180:183], v170 offset:3072
	s_add_u32 s64, s62, 0xfff80080
	s_addc_u32 s65, s63, -1
	s_cmp_eq_u32 s77, 28
	s_cselect_b32 s67, s0, s65
	s_cselect_b32 s66, s1, s64
	s_cselect_b32 s65, s41, s76
	s_cselect_b32 s64, s47, s71
	v_lshl_add_u64 v[164:165], s[62:63], 0, v[152:153]
	s_add_i32 m0, s3, 0xc000
	ds_read_b128 v[184:187], v171
	ds_read_b128 v[190:193], v171 offset:1024
	ds_read_b128 v[194:197], v171 offset:2048
	ds_read_b128 v[198:201], v171 offset:3072
	ds_read_b128 v[202:205], v171 offset:4096
	ds_read_b128 v[206:209], v171 offset:5120
	ds_read_b128 v[214:217], v171 offset:6144
	ds_read_b128 v[218:221], v171 offset:7168
	global_load_lds_dwordx4 v[164:165], off
	v_lshl_add_u64 v[164:165], s[62:63], 0, v[154:155]
	s_add_i32 m0, s3, 0xe000
	s_nop 0
	global_load_lds_dwordx4 v[164:165], off
	s_waitcnt vmcnt(8)
	s_waitcnt lgkmcnt(0)
	s_barrier
; #define PG8_STAGE(bufoff, gbase, voff) do { _Pragma("unroll") for (int _i = 0; _i < 2; ++_i) \
;         __builtin_amdgcn_global_load_lds((const unsigned*)((const char*)(gbase) + (voff)[_i]), (PG8_LAS unsigned*)(lds + (bufoff) + ldsw + _i * 8192), 16, 0, 0); } while (0)
; #define PG8_LDA(dst, b, h) do { _Pragma("unroll") for (int m = 0; m < 4; ++m) _Pragma("unroll") for (int k = 0; k < 2; ++k) dst[m][k] = *(const PG8_LAS bf16x8*)(lds + PG8_SA(b, h) + aoff + m * 2048 + k * 1024); } while (0)
; #define PG8_WAIT_V(n) asm volatile("s_waitcnt vmcnt(" #n ")" ::: "memory")
; #define PG8_WAIT_L(n) asm volatile("s_waitcnt lgkmcnt(" #n ")" ::: "memory")
; #define PG8_BAR __builtin_amdgcn_s_barrier()
; template <class Epi, class Sched, bool ALIGN_EPI = false, bool SP2 = false>
; __device__ __forceinline__ void gemm_phase(PG8_LAS unsigned char* lds, const Gemm g, const Sched& S, const Epi& E) {
;     ...
;         for (int t = seg * tseg; t < (seg + 1) * tseg; t += 2) {
;             const bool last = (t == nt - 2);
;             const char* a1 = cA + (size_t)(t + 1) * kstep;
;             const char* a2 = last ? nA : cA + (size_t)(t + 2) * kstep; const char* b2 = last ? nB : cB + (size_t)(t + 2) * kstep;
;             const char* a3 = a2 + kstep; const char* b3 = b2 + kstep;
;             if (last && has_next) S.a_ready(nxt);
;             if constexpr (SP2) {
;             PG8_LDB(B0, 0, 0); PG8_LDB(B1, 0, 1); PG8_SCHED; PG8_LDA(At, 0, 0); PG8_STAGE(PG8_SA(1, 1), a1 + hstep, voffA);
;             PG8_WAIT_V(8); PG8_WAIT_L(0); PG8_BAR; PG8_MMA(0, 0, At, B0); PG8_MMA(0, 1, At, B1); PG8_BAR; PG8_SCHED;
;             PG8_LDA(At, 0, 1); PG8_STAGE(PG8_SB(0, 0), b2, voffB); PG8_STAGE(PG8_SB(0, 1), b2 + hstep, voffB); PG8_STAGE(PG8_SA(0, 0), a2, voffA);
;             PG8_WAIT_V(8); PG8_WAIT_L(0); PG8_BAR; PG8_MMA(1, 0, At, B0); PG8_MMA(1, 1, At, B1); PG8_BAR; PG8_SCHED;
;             PG8_LDB(B0, 1, 0); PG8_LDB(B1, 1, 1); PG8_SCHED; PG8_LDA(At, 1, 0); PG8_STAGE(PG8_SA(0, 1), a2 + hstep, voffA);
;             PG8_WAIT_V(8); PG8_WAIT_L(0); PG8_BAR; PG8_MMA(0, 0, At, B0); PG8_MMA(0, 1, At, B1); PG8_BAR; PG8_SCHED;
;             PG8_LDA(At, 1, 1); PG8_STAGE(PG8_SB(1, 0), b3, voffB); PG8_STAGE(PG8_SB(1, 1), b3 + hstep, voffB); PG8_STAGE(PG8_SA(1, 0), a3, voffA);
;             PG8_WAIT_V(8); PG8_WAIT_L(0); PG8_BAR; PG8_MMA(1, 0, At, B0); PG8_MMA(1, 1, At, B1); PG8_BAR; PG8_SCHED;
	s_waitcnt lgkmcnt(0)
	v_mfma_f32_16x16x32_bf16 v[124:127], v[128:131], v[184:187], v[124:127]
	v_mfma_f32_16x16x32_bf16 v[120:123], v[136:139], v[184:187], v[120:123]
	v_mfma_f32_16x16x32_bf16 v[108:111], v[128:131], v[194:197], v[108:111]
	v_mfma_f32_16x16x32_bf16 v[104:107], v[136:139], v[194:197], v[104:107]
	v_mfma_f32_16x16x32_bf16 v[92:95], v[128:131], v[202:205], v[92:95]
	v_mfma_f32_16x16x32_bf16 v[88:91], v[136:139], v[202:205], v[88:91]
	v_mfma_f32_16x16x32_bf16 v[76:79], v[128:131], v[214:217], v[76:79]
	v_mfma_f32_16x16x32_bf16 v[72:75], v[136:139], v[214:217], v[72:75]
	v_mfma_f32_16x16x32_bf16 v[124:127], v[132:135], v[190:193], v[124:127]
	v_mfma_f32_16x16x32_bf16 v[120:123], v[140:143], v[190:193], v[120:123]
	v_mfma_f32_16x16x32_bf16 v[108:111], v[132:135], v[198:201], v[108:111]
	v_mfma_f32_16x16x32_bf16 v[104:107], v[140:143], v[198:201], v[104:107]
	v_mfma_f32_16x16x32_bf16 v[92:95], v[132:135], v[206:209], v[92:95]
	v_mfma_f32_16x16x32_bf16 v[88:91], v[140:143], v[206:209], v[88:91]
	v_mfma_f32_16x16x32_bf16 v[76:79], v[132:135], v[218:221], v[76:79]
	v_mfma_f32_16x16x32_bf16 v[72:75], v[140:143], v[218:221], v[72:75]
	v_mfma_f32_16x16x32_bf16 v[116:119], v[160:163], v[184:187], v[116:119]
	v_mfma_f32_16x16x32_bf16 v[112:115], v[176:179], v[184:187], v[112:115]
	v_mfma_f32_16x16x32_bf16 v[100:103], v[160:163], v[194:197], v[100:103]
	v_mfma_f32_16x16x32_bf16 v[96:99], v[176:179], v[194:197], v[96:99]
	v_mfma_f32_16x16x32_bf16 v[84:87], v[160:163], v[202:205], v[84:87]
	v_mfma_f32_16x16x32_bf16 v[80:83], v[176:179], v[202:205], v[80:83]
	v_mfma_f32_16x16x32_bf16 v[68:71], v[160:163], v[214:217], v[68:71]
	v_mfma_f32_16x16x32_bf16 v[64:67], v[176:179], v[214:217], v[64:67]
	v_mfma_f32_16x16x32_bf16 v[116:119], v[172:175], v[190:193], v[116:119]
	v_mfma_f32_16x16x32_bf16 v[112:115], v[180:183], v[190:193], v[112:115]
	v_mfma_f32_16x16x32_bf16 v[100:103], v[172:175], v[198:201], v[100:103]
	v_mfma_f32_16x16x32_bf16 v[96:99], v[180:183], v[198:201], v[96:99]
	v_mfma_f32_16x16x32_bf16 v[84:87], v[172:175], v[206:209], v[84:87]
	v_mfma_f32_16x16x32_bf16 v[80:83], v[180:183], v[206:209], v[80:83]
	v_mfma_f32_16x16x32_bf16 v[68:71], v[172:175], v[218:221], v[68:71]
	v_mfma_f32_16x16x32_bf16 v[64:67], v[180:183], v[218:221], v[64:67]
	s_barrier
	s_add_i32 s78, s31, s2
	v_lshl_add_u64 v[164:165], s[64:65], 0, v[146:147]
	s_mov_b32 m0, s78
	ds_read_b128 v[184:187], v171 offset:16384
	ds_read_b128 v[190:193], v171 offset:17408
	ds_read_b128 v[194:197], v171 offset:18432
	ds_read_b128 v[198:201], v171 offset:19456
	ds_read_b128 v[202:205], v171 offset:20480
	ds_read_b128 v[206:209], v171 offset:21504
	ds_read_b128 v[214:217], v171 offset:22528
	ds_read_b128 v[218:221], v171 offset:23552
	global_load_lds_dwordx4 v[164:165], off
	s_add_i32 m0, s78, 0x2000
	s_add_u32 s78, s64, 0x80000
	v_lshl_add_u64 v[210:211], s[64:65], 0, v[150:151]
	s_addc_u32 s79, s65, 0
	s_add_i32 s80, s74, s2
	global_load_lds_dwordx4 v[210:211], off
	v_lshl_add_u64 v[222:223], s[78:79], 0, v[146:147]
	s_mov_b32 m0, s80
	v_lshl_add_u64 v[224:225], s[66:67], 0, v[148:149]
	global_load_lds_dwordx4 v[222:223], off
	v_lshl_add_u64 v[222:223], s[78:79], 0, v[150:151]
	s_add_i32 m0, s80, 0x2000
	s_nop 0
	global_load_lds_dwordx4 v[222:223], off
	v_lshl_add_u64 v[222:223], s[66:67], 0, v[144:145]
	s_mov_b32 m0, s3
	s_nop 0
	global_load_lds_dwordx4 v[222:223], off
	s_mov_b32 m0, s23
	s_nop 0
	global_load_lds_dwordx4 v[224:225], off
	s_waitcnt vmcnt(8)
	s_waitcnt lgkmcnt(0)
	s_barrier
	s_waitcnt lgkmcnt(0)
	v_mfma_f32_16x16x32_bf16 v[60:63], v[128:131], v[184:187], v[60:63]
	v_mfma_f32_16x16x32_bf16 v[56:59], v[136:139], v[184:187], v[56:59]
	v_mfma_f32_16x16x32_bf16 v[44:47], v[128:131], v[194:197], v[44:47]
	v_mfma_f32_16x16x32_bf16 v[40:43], v[136:139], v[194:197], v[40:43]
	v_mfma_f32_16x16x32_bf16 v[28:31], v[128:131], v[202:205], v[28:31]
	v_mfma_f32_16x16x32_bf16 v[24:27], v[136:139], v[202:205], v[24:27]
	v_mfma_f32_16x16x32_bf16 v[12:15], v[128:131], v[214:217], v[12:15]
	v_mfma_f32_16x16x32_bf16 v[8:11], v[136:139], v[214:217], v[8:11]
	v_mfma_f32_16x16x32_bf16 v[60:63], v[132:135], v[190:193], v[60:63]
	v_mfma_f32_16x16x32_bf16 v[56:59], v[140:143], v[190:193], v[56:59]
	v_mfma_f32_16x16x32_bf16 v[44:47], v[132:135], v[198:201], v[44:47]
	v_mfma_f32_16x16x32_bf16 v[40:43], v[140:143], v[198:201], v[40:43]
	v_mfma_f32_16x16x32_bf16 v[28:31], v[132:135], v[206:209], v[28:31]
	v_mfma_f32_16x16x32_bf16 v[24:27], v[140:143], v[206:209], v[24:27]
	v_mfma_f32_16x16x32_bf16 v[12:15], v[132:135], v[218:221], v[12:15]
	v_mfma_f32_16x16x32_bf16 v[8:11], v[140:143], v[218:221], v[8:11]
	v_mfma_f32_16x16x32_bf16 v[52:55], v[160:163], v[184:187], v[52:55]
	v_mfma_f32_16x16x32_bf16 v[48:51], v[176:179], v[184:187], v[48:51]
	v_mfma_f32_16x16x32_bf16 v[36:39], v[160:163], v[194:197], v[36:39]
	v_mfma_f32_16x16x32_bf16 v[32:35], v[176:179], v[194:197], v[32:35]
	v_mfma_f32_16x16x32_bf16 v[20:23], v[160:163], v[202:205], v[20:23]
	v_mfma_f32_16x16x32_bf16 v[16:19], v[176:179], v[202:205], v[16:19]
	v_mfma_f32_16x16x32_bf16 v[4:7], v[160:163], v[214:217], v[4:7]
	v_mfma_f32_16x16x32_bf16 v[0:3], v[176:179], v[214:217], v[0:3]
	v_mfma_f32_16x16x32_bf16 v[52:55], v[172:175], v[190:193], v[52:55]
	v_mfma_f32_16x16x32_bf16 v[48:51], v[180:183], v[190:193], v[48:51]
	v_mfma_f32_16x16x32_bf16 v[36:39], v[172:175], v[198:201], v[36:39]
	v_mfma_f32_16x16x32_bf16 v[32:35], v[180:183], v[198:201], v[32:35]
	v_mfma_f32_16x16x32_bf16 v[20:23], v[172:175], v[206:209], v[20:23]
	v_mfma_f32_16x16x32_bf16 v[16:19], v[180:183], v[206:209], v[16:19]
	v_mfma_f32_16x16x32_bf16 v[4:7], v[172:175], v[218:221], v[4:7]
	v_mfma_f32_16x16x32_bf16 v[0:3], v[180:183], v[218:221], v[0:3]
	s_barrier
; #define PG8_STAGE(bufoff, gbase, voff) do { _Pragma("unroll") for (int _i = 0; _i < 2; ++_i) \
;         __builtin_amdgcn_global_load_lds((const unsigned*)((const char*)(gbase) + (voff)[_i]), (PG8_LAS unsigned*)(lds + (bufoff) + ldsw + _i * 8192), 16, 0, 0); } while (0)
; #define PG8_LDA(dst, b, h) do { _Pragma("unroll") for (int m = 0; m < 4; ++m) _Pragma("unroll") for (int k = 0; k < 2; ++k) dst[m][k] = *(const PG8_LAS bf16x8*)(lds + PG8_SA(b, h) + aoff + m * 2048 + k * 1024); } while (0)
; #define PG8_LDB(dst, b, h) do { _Pragma("unroll") for (int n = 0; n < 2; ++n) _Pragma("unroll") for (int k = 0; k < 2; ++k) dst[n][k] = *(const PG8_LAS bf16x8*)(lds + PG8_SB(b, h) + boff + n * 2048 + k * 1024); } while (0)
; #define PG8_MMA(ai, bj, At, Bt) do { __builtin_amdgcn_s_setprio(1); _Pragma("unroll") for (int m = 0; m < 4; ++m) _Pragma("unroll") for (int n = 0; n < 2; ++n) _Pragma("unroll") for (int k = 0; k < 2; ++k) \
;         acc[ai][bj][m][n] = __builtin_amdgcn_mfma_f32_16x16x32_bf16(Bt[n][k], At[m][k], acc[ai][bj][m][n], 0, 0, 0); __builtin_amdgcn_s_setprio(0); } while (0)
; #define PG8_WAIT_V(n) asm volatile("s_waitcnt vmcnt(" #n ")" ::: "memory")
; template <class Epi, class Sched, bool ALIGN_EPI = false, bool SP2 = false>
; __device__ __forceinline__ void gemm_phase(PG8_LAS unsigned char* lds, const Gemm g, const Sched& S, const Epi& E) {
;     ...
;             PG8_LDB(B0, 0, 0); PG8_LDB(B1, 0, 1); PG8_SCHED; PG8_LDA(At, 0, 0); PG8_STAGE(PG8_SA(1, 1), a1 + hstep, voffA);
;             PG8_WAIT_V(8); PG8_WAIT_L(0); PG8_BAR; PG8_MMA(0, 0, At, B0); PG8_MMA(0, 1, At, B1); PG8_BAR; PG8_SCHED;
;             PG8_LDA(At, 0, 1); PG8_STAGE(PG8_SB(0, 0), b2, voffB); PG8_STAGE(PG8_SB(0, 1), b2 + hstep, voffB); PG8_STAGE(PG8_SA(0, 0), a2, voffA);
;             PG8_WAIT_V(8); PG8_WAIT_L(0); PG8_BAR; PG8_MMA(1, 0, At, B0); PG8_MMA(1, 1, At, B1); PG8_BAR; PG8_SCHED;
;             PG8_LDB(B0, 1, 0); PG8_LDB(B1, 1, 1); PG8_SCHED; PG8_LDA(At, 1, 0); PG8_STAGE(PG8_SA(0, 1), a2 + hstep, voffA);
;             PG8_WAIT_V(8); PG8_WAIT_L(0); PG8_BAR; PG8_MMA(0, 0, At, B0); PG8_MMA(0, 1, At, B1); PG8_BAR; PG8_SCHED;
;             PG8_LDA(At, 1, 1); PG8_STAGE(PG8_SB(1, 0), b3, voffB); PG8_STAGE(PG8_SB(1, 1), b3 + hstep, voffB); PG8_STAGE(PG8_SA(1, 0), a3, voffA);
;             PG8_WAIT_V(8); PG8_WAIT_L(0); PG8_BAR; PG8_MMA(1, 0, At, B0); PG8_MMA(1, 1, At, B1); PG8_BAR; PG8_SCHED;
	v_add_u32_e32 v140, s75, v167
	v_add_u32_e32 v180, s84, v167
	ds_read_b128 v[128:131], v140
	ds_read_b128 v[132:135], v140 offset:1024
	ds_read_b128 v[136:139], v140 offset:2048
	ds_read_b128 v[140:143], v140 offset:3072
	ds_read_b128 v[160:163], v180
	ds_read_b128 v[172:175], v180 offset:1024
	ds_read_b128 v[176:179], v180 offset:2048
	ds_read_b128 v[180:183], v180 offset:3072
	s_add_u32 s66, s66, 0x80000
	s_addc_u32 s67, s67, 0
	s_mov_b32 m0, s28
	v_lshl_add_u64 v[226:227], s[66:67], 0, v[144:145]
	ds_read_b128 v[184:187], v171 offset:32768
	ds_read_b128 v[190:193], v171 offset:33792
	ds_read_b128 v[194:197], v171 offset:34816
	ds_read_b128 v[198:201], v171 offset:35840
	ds_read_b128 v[202:205], v171 offset:36864
	ds_read_b128 v[206:209], v171 offset:37888
	ds_read_b128 v[214:217], v171 offset:38912
	ds_read_b128 v[218:221], v171 offset:39936
	global_load_lds_dwordx4 v[226:227], off
	v_lshl_add_u64 v[226:227], s[66:67], 0, v[148:149]
	s_mov_b32 m0, s29
	s_nop 0
	global_load_lds_dwordx4 v[226:227], off
	s_waitcnt vmcnt(8)
	s_waitcnt lgkmcnt(0)
	s_barrier
	s_waitcnt lgkmcnt(0)
	v_mfma_f32_16x16x32_bf16 v[124:127], v[128:131], v[184:187], v[124:127]
	v_mfma_f32_16x16x32_bf16 v[120:123], v[136:139], v[184:187], v[120:123]
	v_mfma_f32_16x16x32_bf16 v[108:111], v[128:131], v[194:197], v[108:111]
	v_mfma_f32_16x16x32_bf16 v[104:107], v[136:139], v[194:197], v[104:107]
	v_mfma_f32_16x16x32_bf16 v[92:95], v[128:131], v[202:205], v[92:95]
	v_mfma_f32_16x16x32_bf16 v[88:91], v[136:139], v[202:205], v[88:91]
	v_mfma_f32_16x16x32_bf16 v[76:79], v[128:131], v[214:217], v[76:79]
	v_mfma_f32_16x16x32_bf16 v[72:75], v[136:139], v[214:217], v[72:75]
	v_mfma_f32_16x16x32_bf16 v[124:127], v[132:135], v[190:193], v[124:127]
	v_mfma_f32_16x16x32_bf16 v[120:123], v[140:143], v[190:193], v[120:123]
	v_mfma_f32_16x16x32_bf16 v[108:111], v[132:135], v[198:201], v[108:111]
	v_mfma_f32_16x16x32_bf16 v[104:107], v[140:143], v[198:201], v[104:107]
	v_mfma_f32_16x16x32_bf16 v[92:95], v[132:135], v[206:209], v[92:95]
	v_mfma_f32_16x16x32_bf16 v[88:91], v[140:143], v[206:209], v[88:91]
	v_mfma_f32_16x16x32_bf16 v[76:79], v[132:135], v[218:221], v[76:79]
	v_mfma_f32_16x16x32_bf16 v[72:75], v[140:143], v[218:221], v[72:75]
	v_mfma_f32_16x16x32_bf16 v[116:119], v[160:163], v[184:187], v[116:119]
	v_mfma_f32_16x16x32_bf16 v[112:115], v[176:179], v[184:187], v[112:115]
	v_mfma_f32_16x16x32_bf16 v[100:103], v[160:163], v[194:197], v[100:103]
	v_mfma_f32_16x16x32_bf16 v[96:99], v[176:179], v[194:197], v[96:99]
	v_mfma_f32_16x16x32_bf16 v[84:87], v[160:163], v[202:205], v[84:87]
	v_mfma_f32_16x16x32_bf16 v[80:83], v[176:179], v[202:205], v[80:83]
	v_mfma_f32_16x16x32_bf16 v[68:71], v[160:163], v[214:217], v[68:71]
	v_mfma_f32_16x16x32_bf16 v[64:67], v[176:179], v[214:217], v[64:67]
	v_mfma_f32_16x16x32_bf16 v[116:119], v[172:175], v[190:193], v[116:119]
	v_mfma_f32_16x16x32_bf16 v[112:115], v[180:183], v[190:193], v[112:115]
	v_mfma_f32_16x16x32_bf16 v[100:103], v[172:175], v[198:201], v[100:103]
	v_mfma_f32_16x16x32_bf16 v[96:99], v[180:183], v[198:201], v[96:99]
	v_mfma_f32_16x16x32_bf16 v[84:87], v[172:175], v[206:209], v[84:87]
	v_mfma_f32_16x16x32_bf16 v[80:83], v[180:183], v[206:209], v[80:83]
	v_mfma_f32_16x16x32_bf16 v[68:71], v[172:175], v[218:221], v[68:71]
	v_mfma_f32_16x16x32_bf16 v[64:67], v[180:183], v[218:221], v[64:67]
	s_barrier
; #define PG8_STAGE(bufoff, gbase, voff) do { _Pragma("unroll") for (int _i = 0; _i < 2; ++_i) \
;         __builtin_amdgcn_global_load_lds((const unsigned*)((const char*)(gbase) + (voff)[_i]), (PG8_LAS unsigned*)(lds + (bufoff) + ldsw + _i * 8192), 16, 0, 0); } while (0)
; #define PG8_LDA(dst, b, h) do { _Pragma("unroll") for (int m = 0; m < 4; ++m) _Pragma("unroll") for (int k = 0; k < 2; ++k) dst[m][k] = *(const PG8_LAS bf16x8*)(lds + PG8_SA(b, h) + aoff + m * 2048 + k * 1024); } while (0)
; #define PG8_WAIT_V(n) asm volatile("s_waitcnt vmcnt(" #n ")" ::: "memory")
; #define PG8_WAIT_L(n) asm volatile("s_waitcnt lgkmcnt(" #n ")" ::: "memory")
; #define PG8_BAR __builtin_amdgcn_s_barrier()
; template <class Epi, class Sched, bool ALIGN_EPI = false, bool SP2 = false>
; __device__ __forceinline__ void gemm_phase(PG8_LAS unsigned char* lds, const Gemm g, const Sched& S, const Epi& E) {
;     ...
;         for (int t = seg * tseg; t < (seg + 1) * tseg; t += 2) {
;             const bool last = (t == nt - 2);
;             const char* a1 = cA + (size_t)(t + 1) * kstep;
;             const char* a2 = last ? nA : cA + (size_t)(t + 2) * kstep; const char* b2 = last ? nB : cB + (size_t)(t + 2) * kstep;
;             const char* a3 = a2 + kstep; const char* b3 = b2 + kstep;
;             if (last && has_next) S.a_ready(nxt);
;             if constexpr (SP2) {
;             PG8_LDB(B0, 0, 0); PG8_LDB(B1, 0, 1); PG8_SCHED; PG8_LDA(At, 0, 0); PG8_STAGE(PG8_SA(1, 1), a1 + hstep, voffA);
;             PG8_WAIT_V(8); PG8_WAIT_L(0); PG8_BAR; PG8_MMA(0, 0, At, B0); PG8_MMA(0, 1, At, B1); PG8_BAR; PG8_SCHED;
;             PG8_LDA(At, 0, 1); PG8_STAGE(PG8_SB(0, 0), b2, voffB); PG8_STAGE(PG8_SB(0, 1), b2 + hstep, voffB); PG8_STAGE(PG8_SA(0, 0), a2, voffA);
;             PG8_WAIT_V(8); PG8_WAIT_L(0); PG8_BAR; PG8_MMA(1, 0, At, B0); PG8_MMA(1, 1, At, B1); PG8_BAR; PG8_SCHED;
;             PG8_LDB(B0, 1, 0); PG8_LDB(B1, 1, 1); PG8_SCHED; PG8_LDA(At, 1, 0); PG8_STAGE(PG8_SA(0, 1), a2 + hstep, voffA);
;             PG8_WAIT_V(8); PG8_WAIT_L(0); PG8_BAR; PG8_MMA(0, 0, At, B0); PG8_MMA(0, 1, At, B1); PG8_BAR; PG8_SCHED;
;             PG8_LDA(At, 1, 1); PG8_STAGE(PG8_SB(1, 0), b3, voffB); PG8_STAGE(PG8_SB(1, 1), b3 + hstep, voffB); PG8_STAGE(PG8_SA(1, 0), a3, voffA);
;             PG8_WAIT_V(8); PG8_WAIT_L(0); PG8_BAR; PG8_MMA(1, 0, At, B0); PG8_MMA(1, 1, At, B1); PG8_BAR; PG8_SCHED;
	s_add_i32 s66, s75, s2
	v_lshl_add_u64 v[164:165], v[164:165], 0, s[8:9]
	s_mov_b32 m0, s66
	ds_read_b128 v[184:187], v171 offset:49152
	ds_read_b128 v[190:193], v171 offset:50176
	ds_read_b128 v[194:197], v171 offset:51200
	ds_read_b128 v[198:201], v171 offset:52224
	ds_read_b128 v[202:205], v171 offset:53248
	ds_read_b128 v[206:209], v171 offset:54272
	ds_read_b128 v[214:217], v171 offset:55296
	ds_read_b128 v[218:221], v171 offset:56320
	global_load_lds_dwordx4 v[164:165], off
	s_add_i32 m0, s66, 0x2000
	s_add_u32 s64, s64, 0x80080
	v_lshl_add_u64 v[164:165], v[210:211], 0, s[8:9]
	s_addc_u32 s65, s65, 0
	s_add_i32 s66, s84, s2
	global_load_lds_dwordx4 v[164:165], off
	v_lshl_add_u64 v[164:165], s[64:65], 0, v[146:147]
	s_mov_b32 m0, s66
	s_nop 0
	global_load_lds_dwordx4 v[164:165], off
	v_lshl_add_u64 v[164:165], s[64:65], 0, v[150:151]
	s_add_i32 m0, s66, 0x2000
	s_nop 0
	global_load_lds_dwordx4 v[164:165], off
	v_lshl_add_u64 v[164:165], v[222:223], 0, s[8:9]
	s_mov_b32 m0, s68
	s_nop 0
	global_load_lds_dwordx4 v[164:165], off
	v_lshl_add_u64 v[164:165], v[224:225], 0, s[8:9]
	s_mov_b32 m0, s69
	s_nop 0
	global_load_lds_dwordx4 v[164:165], off
	s_waitcnt vmcnt(8)
	s_waitcnt lgkmcnt(0)
	s_barrier
	s_waitcnt lgkmcnt(0)
	v_mfma_f32_16x16x32_bf16 v[60:63], v[128:131], v[184:187], v[60:63]
	v_mfma_f32_16x16x32_bf16 v[56:59], v[136:139], v[184:187], v[56:59]
	v_mfma_f32_16x16x32_bf16 v[44:47], v[128:131], v[194:197], v[44:47]
	v_mfma_f32_16x16x32_bf16 v[40:43], v[136:139], v[194:197], v[40:43]
	v_mfma_f32_16x16x32_bf16 v[28:31], v[128:131], v[202:205], v[28:31]
	v_mfma_f32_16x16x32_bf16 v[24:27], v[136:139], v[202:205], v[24:27]
	v_mfma_f32_16x16x32_bf16 v[12:15], v[128:131], v[214:217], v[12:15]
	v_mfma_f32_16x16x32_bf16 v[8:11], v[136:139], v[214:217], v[8:11]
	v_mfma_f32_16x16x32_bf16 v[60:63], v[132:135], v[190:193], v[60:63]
	v_mfma_f32_16x16x32_bf16 v[56:59], v[140:143], v[190:193], v[56:59]
	v_mfma_f32_16x16x32_bf16 v[44:47], v[132:135], v[198:201], v[44:47]
	v_mfma_f32_16x16x32_bf16 v[40:43], v[140:143], v[198:201], v[40:43]
	v_mfma_f32_16x16x32_bf16 v[28:31], v[132:135], v[206:209], v[28:31]
	v_mfma_f32_16x16x32_bf16 v[24:27], v[140:143], v[206:209], v[24:27]
	v_mfma_f32_16x16x32_bf16 v[12:15], v[132:135], v[218:221], v[12:15]
	v_mfma_f32_16x16x32_bf16 v[8:11], v[140:143], v[218:221], v[8:11]
	v_mfma_f32_16x16x32_bf16 v[52:55], v[160:163], v[184:187], v[52:55]
	v_mfma_f32_16x16x32_bf16 v[48:51], v[176:179], v[184:187], v[48:51]
	v_mfma_f32_16x16x32_bf16 v[36:39], v[160:163], v[194:197], v[36:39]
	v_mfma_f32_16x16x32_bf16 v[32:35], v[176:179], v[194:197], v[32:35]
	v_mfma_f32_16x16x32_bf16 v[20:23], v[160:163], v[202:205], v[20:23]
	v_mfma_f32_16x16x32_bf16 v[16:19], v[176:179], v[202:205], v[16:19]
	v_mfma_f32_16x16x32_bf16 v[4:7], v[160:163], v[214:217], v[4:7]
	v_mfma_f32_16x16x32_bf16 v[0:3], v[176:179], v[214:217], v[0:3]
	v_mfma_f32_16x16x32_bf16 v[52:55], v[172:175], v[190:193], v[52:55]
	v_mfma_f32_16x16x32_bf16 v[48:51], v[180:183], v[190:193], v[48:51]
	v_mfma_f32_16x16x32_bf16 v[36:39], v[172:175], v[198:201], v[36:39]
	v_mfma_f32_16x16x32_bf16 v[32:35], v[180:183], v[198:201], v[32:35]
	v_mfma_f32_16x16x32_bf16 v[20:23], v[172:175], v[206:209], v[20:23]
	v_mfma_f32_16x16x32_bf16 v[16:19], v[180:183], v[206:209], v[16:19]
	v_mfma_f32_16x16x32_bf16 v[4:7], v[172:175], v[218:221], v[4:7]
	v_mfma_f32_16x16x32_bf16 v[0:3], v[180:183], v[218:221], v[0:3]
	s_barrier
	s_add_i32 s77, s77, 2
	s_add_u32 s62, s62, 0x100
	s_addc_u32 s63, s63, 0
	s_add_u32 s71, s71, 0x100
	s_addc_u32 s76, s76, 0
	s_cmp_gt_u32 s77, 29
	s_cbranch_scc0 .LBB0_781
	s_and_b64 vcc, exec, s[10:11]
	s_cbranch_vccz .LBB0_784
	s_barrier

;     __device__ void init(int G_, int c_) { so.init(16384, 7168, G_, c_); G = G_; c = c_; }
;     __device__ bool next(int i, Unit& u) const { if (i >= n) return false; const int q = first + i; u.pm = rowbase + q % rows; u.pn = q / rows; return true; }
; #define LAS __attribute__((address_space(3)))
;     __host__ __device__ bool next(int i, Unit& u) const {
;         const long L = (long)i * G + c; if (L >= nwg) return false;
;         int wgid = (int)L; { const int q = nwg / NXCD, r = nwg % NXCD, xcd = wgid % NXCD, off = wgid / NXCD; wgid = (xcd < r ? xcd * (q + 1) : r * (q + 1) + (xcd - r) * q) + off; }
;         const int nig = WGM * nN, gid = wgid / nig, fm = gid * WGM, gsz = (nM - fm) < WGM ? (nM - fm) : WGM;
;         u.pm = fm + ((wgid % nig) % gsz); u.pn = (wgid % nig) / gsz; return true;
;     }
; __global__ void __launch_bounds__(NTHR, 2) fwd_megakernel(Args A) {
;     ...
;         pg8::Gemm g{Z2, WUP, MLAT, NUP, DM}; pg8::StaticOrder S; S.init(MLAT, NUP, G, blk);
;         pg8::EpiUpConv E{H, A.conv_w, A.conv_b, PART, RAWB, (LAS float*)(lds + EX_OFF)};
;         pg8::gemm_phase<pg8::EpiUpConv, pg8::StaticOrder, true, true>(lds, g, S, E);
.LBB0_917:
	s_or_b64 exec, exec, s[4:5]
	v_mov_b32_e32 v14, v189
	s_cmpk_lt_i32 s22, 0xb00
	s_waitcnt lgkmcnt(0)
	s_barrier
	s_mov_b32 s98, 0
	s_cselect_b32 s99, 1, 0
	v_writelane_b32 v243, s0, 0
	v_writelane_b32 v243, s1, 1
	v_writelane_b32 v243, s2, 2
	v_writelane_b32 v243, s3, 3
	v_writelane_b32 v243, s4, 4
	v_writelane_b32 v243, s5, 5
	v_writelane_b32 v243, s6, 6
	v_writelane_b32 v243, s7, 7
	v_writelane_b32 v243, s8, 8
	v_writelane_b32 v243, s9, 9
	v_writelane_b32 v243, s10, 10
	v_writelane_b32 v243, s11, 11
	v_writelane_b32 v243, s12, 12
	v_writelane_b32 v243, s13, 13
	v_writelane_b32 v243, s14, 14
	v_writelane_b32 v243, s15, 15
	v_writelane_b32 v243, s16, 16
	v_writelane_b32 v243, s17, 17
	v_writelane_b32 v243, s18, 18
	v_writelane_b32 v243, s19, 19
	v_writelane_b32 v243, s20, 20
	v_writelane_b32 v243, s21, 21
	v_writelane_b32 v243, s22, 22
	v_writelane_b32 v243, s23, 23
	v_writelane_b32 v243, s24, 24
	v_writelane_b32 v243, s25, 25
	v_writelane_b32 v243, s26, 26
	v_writelane_b32 v243, s27, 27
	v_writelane_b32 v243, s28, 28
	v_writelane_b32 v243, s29, 29
	v_writelane_b32 v243, s30, 30
	v_writelane_b32 v243, s31, 31
	v_writelane_b32 v243, s32, 32
	v_writelane_b32 v243, s33, 33
	v_writelane_b32 v243, s34, 34
	v_writelane_b32 v243, s35, 35
	v_writelane_b32 v243, s36, 36
	v_writelane_b32 v243, s37, 37
	v_writelane_b32 v243, s38, 38
	v_writelane_b32 v243, s39, 39
	v_writelane_b32 v243, s40, 40
	v_writelane_b32 v243, s41, 41
	v_writelane_b32 v243, s42, 42
	v_writelane_b32 v243, s43, 43
	v_writelane_b32 v243, s44, 44
	v_writelane_b32 v243, s45, 45
	v_writelane_b32 v243, s46, 46
	v_writelane_b32 v243, s47, 47
	v_writelane_b32 v243, s48, 48
	v_writelane_b32 v243, s49, 49
	v_writelane_b32 v243, s50, 50
	v_writelane_b32 v243, s51, 51
	v_writelane_b32 v243, s52, 52
	v_writelane_b32 v243, s53, 53
	v_writelane_b32 v243, s54, 54
	v_writelane_b32 v243, s55, 55
	v_writelane_b32 v243, s56, 56
	v_writelane_b32 v243, s57, 57
	v_writelane_b32 v243, s58, 58
	v_writelane_b32 v243, s59, 59
	v_writelane_b32 v243, s60, 60
	v_writelane_b32 v243, s61, 61
	v_writelane_b32 v243, s62, 62
	v_writelane_b32 v243, s63, 63
	v_writelane_b32 v244, s64, 0
	v_writelane_b32 v244, s65, 1
	v_writelane_b32 v244, s66, 2
	v_writelane_b32 v244, s67, 3
	v_writelane_b32 v244, s68, 4
	v_writelane_b32 v244, s69, 5
	v_writelane_b32 v244, s70, 6
	v_writelane_b32 v244, s71, 7
	v_writelane_b32 v244, s72, 8
	v_writelane_b32 v244, s73, 9
	v_writelane_b32 v244, s74, 10
	v_writelane_b32 v244, s75, 11
	v_writelane_b32 v244, s76, 12
	v_writelane_b32 v244, s77, 13
	v_writelane_b32 v244, s78, 14
	v_writelane_b32 v244, s79, 15
	v_writelane_b32 v244, s80, 16
	v_writelane_b32 v244, s81, 17
	v_writelane_b32 v244, s82, 18
	v_writelane_b32 v244, s83, 19
	v_writelane_b32 v244, s84, 20
	v_writelane_b32 v244, s85, 21
	v_writelane_b32 v244, s86, 22
	v_writelane_b32 v244, s87, 23
	v_writelane_b32 v244, s88, 24
	v_writelane_b32 v244, s89, 25
	v_writelane_b32 v244, s90, 26
	v_writelane_b32 v244, s91, 27
	v_writelane_b32 v244, s92, 28
	v_writelane_b32 v244, s93, 29
	v_writelane_b32 v244, s94, 30
	v_writelane_b32 v244, s95, 31
	v_writelane_b32 v244, s96, 32
	v_writelane_b32 v244, s97, 33
	v_writelane_b32 v244, vcc_lo, 34
	v_writelane_b32 v244, vcc_hi, 35
	v_mov_b32_e32 v245, v14
	v_mov_b32_e32 v246, v242
	s_nop 1
	s_nop 0
	s_nop 0
	s_nop 0
.Lrerun_P10:
	s_cselect_b64 s[0:1], -1, 0
	s_cmpk_gt_i32 s22, 0xaff
	v_readfirstlane_b32 s4, v14
	s_cbranch_scc1 .LBB0_919
	s_lshr_b32 s2, s44, 29
	s_add_i32 s2, s22, s2
	s_ashr_i32 s3, s2, 3
	s_and_b32 s2, s2, -8
	s_sub_i32 s2, s22, s2
	s_cmp_lt_i32 s2, 0
	s_movk_i32 s5, 0x161
	s_cselect_b32 s5, s5, 0x160
	s_mul_i32 s2, s2, s5
	s_add_i32 s2, s2, s3
	s_mul_hi_i32 s3, s2, 0x2e8ba2e9
	s_lshr_b32 s5, s3, 31
	s_ashr_i32 s3, s3, 6
	s_add_i32 s3, s3, s5
	s_lshl_b32 s5, s3, 3
	s_mulk_i32 s3, 0x160
	s_sub_i32 s2, s2, s3
	s_sext_i32_i16 s3, s2
	s_bfe_u32 s3, s3, 0x3001c
	s_add_i32 s3, s2, s3
	s_sext_i32_i16 s6, s3
	s_and_b32 s3, s3, 0xfff8
	s_sub_i32 s2, s2, s3
	s_sext_i32_i16 s2, s2
	s_add_i32 s94, s5, s2
	s_ashr_i32 s14, s6, 3

;     __device__ bool next(int i, Unit& u) const { if (i >= n) return false; const int q = first + i; u.pm = rowbase + q % rows; u.pn = q / rows; return true; }
; #define PG8_WAIT_V(n) asm volatile("s_waitcnt vmcnt(" #n ")" ::: "memory")
; template <class Epi, class Sched, bool ALIGN_EPI = false, bool SP2 = false>
; __device__ __forceinline__ void gemm_phase(PG8_LAS unsigned char* lds, const Gemm g, const Sched& S, const Epi& E) {
;     ...
;         const bool has_next = S.next(ui + 1, nxt);
;         const char* nA = has_next ? (const char*)g.A + (size_t)nxt.pm * tstep : cA; const char* nB = has_next ? (const char*)g.Bt + (size_t)nxt.pn * tstep : cB;
;         constexpr int NSEG = Epi::HAS_MID ? 2 : 1; const int tseg = nt / NSEG;
; #pragma unroll
;         for (int seg = 0; seg < NSEG; ++seg) {
;         if constexpr (Epi::HAS_MID) { if (seg == 1) E.mid(acc, cur, wr, wc, fr, fq); }
;         for (int t = seg * tseg; t < (seg + 1) * tseg; t += 2) {
;             const bool last = (t == nt - 2);
;             const char* a1 = cA + (size_t)(t + 1) * kstep;
;             const char* a2 = last ? nA : cA + (size_t)(t + 2) * kstep; const char* b2 = last ? nB : cB + (size_t)(t + 2) * kstep;
;             const char* a3 = a2 + kstep; const char* b3 = b2 + kstep;
;             if (last && has_next) S.a_ready(nxt);
;             if constexpr (SP2) {
;             PG8_LDB(B0, 0, 0); PG8_LDB(B1, 0, 1); PG8_SCHED; PG8_LDA(At, 0, 0); PG8_STAGE(PG8_SA(1, 1), a1 + hstep, voffA);
;             PG8_WAIT_V(8); PG8_WAIT_L(0); PG8_BAR; PG8_MMA(0, 0, At, B0); PG8_MMA(0, 1, At, B1); PG8_BAR; PG8_SCHED;
;             PG8_LDA(At, 0, 1); PG8_STAGE(PG8_SB(0, 0), b2, voffB); PG8_STAGE(PG8_SB(0, 1), b2 + hstep, voffB); PG8_STAGE(PG8_SA(0, 0), a2, voffA);
;             PG8_WAIT_V(8); PG8_WAIT_L(0); PG8_BAR; PG8_MMA(1, 0, At, B0); PG8_MMA(1, 1, At, B1); PG8_BAR; PG8_SCHED;
;             PG8_LDB(B0, 1, 0); PG8_LDB(B1, 1, 1); PG8_SCHED; PG8_LDA(At, 1, 0); PG8_STAGE(PG8_SA(0, 1), a2 + hstep, voffA);
;             PG8_WAIT_V(8); PG8_WAIT_L(0); PG8_BAR; PG8_MMA(0, 0, At, B0); PG8_MMA(0, 1, At, B1); PG8_BAR; PG8_SCHED;
;             PG8_LDA(At, 1, 1); PG8_STAGE(PG8_SB(1, 0), b3, voffB); PG8_STAGE(PG8_SB(1, 1), b3 + hstep, voffB); PG8_STAGE(PG8_SA(1, 0), a3, voffA);
;             PG8_WAIT_V(8); PG8_WAIT_L(0); PG8_BAR; PG8_MMA(1, 0, At, B0); PG8_MMA(1, 1, At, B1); PG8_BAR; PG8_SCHED;
.LBB0_927:
	s_ashr_i32 s89, s88, 31
	s_lshl_b64 s[0:1], s[88:89], 20
	s_add_u32 s90, s54, s0
	s_addc_u32 s91, s55, s1
	s_and_b64 s[0:1], s[12:13], exec
	s_cselect_b32 s0, s91, s17
	s_cselect_b32 s1, s90, s16
	s_ashr_i32 s87, s86, 31
	s_lshl_b64 s[20:21], s[86:87], 20
	v_readlane_b32 s56, v242, 24
	v_readlane_b32 s57, v242, 25
	s_add_u32 s92, s56, s20
	s_addc_u32 s93, s57, s21
	s_and_b64 s[20:21], s[12:13], exec
	s_cselect_b32 s15, s93, s19
	s_cselect_b32 s87, s92, s18
	s_add_u32 s16, s16, 0x80080
	s_addc_u32 s17, s17, 0
	s_add_u32 s89, s18, 0x100
	s_addc_u32 s96, s19, 0
	s_mov_b32 s97, -2
	ds_read_b128 v[118:121], v225
	ds_read_b128 v[122:125], v225 offset:1024
	ds_read_b128 v[126:129], v225 offset:2048
	ds_read_b128 v[130:133], v225 offset:3072
	ds_read_b128 v[134:137], v226
	ds_read_b128 v[138:141], v226 offset:1024
	ds_read_b128 v[142:145], v226 offset:2048
	ds_read_b128 v[146:149], v226 offset:3072
	s_add_u32 s18, s16, 0xfff80080
	s_addc_u32 s19, s17, -1
	s_cmp_eq_u32 s97, 28
	s_cselect_b32 s21, s0, s19
	s_cselect_b32 s20, s1, s18
	s_cselect_b32 s19, s15, s96
	s_cselect_b32 s18, s87, s89
	v_lshl_add_u64 v[112:113], s[16:17], 0, v[190:191]
	s_add_i32 m0, s29, 0xc000
	ds_read_b128 v[162:165], v227
	ds_read_b128 v[166:169], v227 offset:1024
	ds_read_b128 v[170:173], v227 offset:2048
	ds_read_b128 v[174:177], v227 offset:3072
	ds_read_b128 v[198:201], v227 offset:4096
	ds_read_b128 v[202:205], v227 offset:5120
	ds_read_b128 v[206:209], v227 offset:6144
	ds_read_b128 v[228:231], v227 offset:7168
	global_load_lds_dwordx4 v[112:113], off
	v_lshl_add_u64 v[112:113], s[16:17], 0, v[192:193]
	s_add_i32 m0, s29, 0xe000
	s_nop 0
	global_load_lds_dwordx4 v[112:113], off
	s_waitcnt vmcnt(8)
	s_waitcnt lgkmcnt(0)
	s_barrier
	s_waitcnt lgkmcnt(0)
	v_mfma_f32_16x16x32_bf16 v[158:161], v[118:121], v[162:165], 0
	v_mfma_f32_16x16x32_bf16 v[60:63], v[126:129], v[162:165], 0
	v_mfma_f32_16x16x32_bf16 v[154:157], v[118:121], v[170:173], 0
	v_mfma_f32_16x16x32_bf16 v[52:55], v[126:129], v[170:173], 0
	v_mfma_f32_16x16x32_bf16 v[112:115], v[118:121], v[198:201], 0
	v_mfma_f32_16x16x32_bf16 v[44:47], v[126:129], v[198:201], 0
	v_mfma_f32_16x16x32_bf16 v[100:103], v[118:121], v[206:209], 0
	v_mfma_f32_16x16x32_bf16 v[36:39], v[126:129], v[206:209], 0
	v_mfma_f32_16x16x32_bf16 v[158:161], v[122:125], v[166:169], v[158:161]
	v_mfma_f32_16x16x32_bf16 v[60:63], v[130:133], v[166:169], v[60:63]
	v_mfma_f32_16x16x32_bf16 v[154:157], v[122:125], v[174:177], v[154:157]
	v_mfma_f32_16x16x32_bf16 v[52:55], v[130:133], v[174:177], v[52:55]
	v_mfma_f32_16x16x32_bf16 v[112:115], v[122:125], v[202:205], v[112:115]
	v_mfma_f32_16x16x32_bf16 v[44:47], v[130:133], v[202:205], v[44:47]
	v_mfma_f32_16x16x32_bf16 v[100:103], v[122:125], v[228:231], v[100:103]
	v_mfma_f32_16x16x32_bf16 v[36:39], v[130:133], v[228:231], v[36:39]
	v_mfma_f32_16x16x32_bf16 v[108:111], v[134:137], v[162:165], 0
	v_mfma_f32_16x16x32_bf16 v[56:59], v[142:145], v[162:165], 0
	v_mfma_f32_16x16x32_bf16 v[150:153], v[134:137], v[170:173], 0
	v_mfma_f32_16x16x32_bf16 v[48:51], v[142:145], v[170:173], 0
	v_mfma_f32_16x16x32_bf16 v[104:107], v[134:137], v[198:201], 0
	v_mfma_f32_16x16x32_bf16 v[40:43], v[142:145], v[198:201], 0
	v_mfma_f32_16x16x32_bf16 v[96:99], v[134:137], v[206:209], 0
	v_mfma_f32_16x16x32_bf16 v[32:35], v[142:145], v[206:209], 0
	v_mfma_f32_16x16x32_bf16 v[108:111], v[138:141], v[166:169], v[108:111]
	v_mfma_f32_16x16x32_bf16 v[56:59], v[146:149], v[166:169], v[56:59]
	v_mfma_f32_16x16x32_bf16 v[150:153], v[138:141], v[174:177], v[150:153]
	v_mfma_f32_16x16x32_bf16 v[48:51], v[146:149], v[174:177], v[48:51]
	v_mfma_f32_16x16x32_bf16 v[104:107], v[138:141], v[202:205], v[104:107]
	v_mfma_f32_16x16x32_bf16 v[40:43], v[146:149], v[202:205], v[40:43]
	v_mfma_f32_16x16x32_bf16 v[96:99], v[138:141], v[228:231], v[96:99]
	v_mfma_f32_16x16x32_bf16 v[32:35], v[146:149], v[228:231], v[32:35]
	s_barrier
	s_add_i32 vcc_lo, s31, s28
	v_lshl_add_u64 v[210:211], s[18:19], 0, v[180:181]
	s_mov_b32 m0, vcc_lo
	ds_read_b128 v[162:165], v227 offset:16384
	ds_read_b128 v[166:169], v227 offset:17408
	ds_read_b128 v[170:173], v227 offset:18432
	ds_read_b128 v[174:177], v227 offset:19456
	ds_read_b128 v[198:201], v227 offset:20480
	ds_read_b128 v[202:205], v227 offset:21504
	ds_read_b128 v[206:209], v227 offset:22528
	ds_read_b128 v[228:231], v227 offset:23552
	global_load_lds_dwordx4 v[210:211], off
	s_add_i32 m0, vcc_lo, 0x2000
	s_add_u32 vcc_lo, s18, 0x80000
	v_lshl_add_u64 v[232:233], s[18:19], 0, v[184:185]
	s_addc_u32 vcc_hi, s19, 0
	s_add_i32 s22, s74, s28
	global_load_lds_dwordx4 v[232:233], off
	v_lshl_add_u64 v[116:117], vcc, 0, v[180:181]
	s_mov_b32 m0, s22
	v_lshl_add_u64 v[234:235], s[20:21], 0, v[178:179]
	global_load_lds_dwordx4 v[116:117], off
	v_lshl_add_u64 v[116:117], vcc, 0, v[184:185]
	s_add_i32 m0, s22, 0x2000
	v_lshl_add_u64 v[236:237], s[20:21], 0, v[182:183]
	global_load_lds_dwordx4 v[116:117], off
	s_mov_b32 m0, s29
	s_nop 0
	global_load_lds_dwordx4 v[234:235], off
	s_mov_b32 m0, s85
	s_nop 0
	global_load_lds_dwordx4 v[236:237], off
	s_waitcnt vmcnt(8)
	s_waitcnt lgkmcnt(0)
	s_barrier
; #define PG8_STAGE(bufoff, gbase, voff) do { _Pragma("unroll") for (int _i = 0; _i < 2; ++_i) \
;         __builtin_amdgcn_global_load_lds((const unsigned*)((const char*)(gbase) + (voff)[_i]), (PG8_LAS unsigned*)(lds + (bufoff) + ldsw + _i * 8192), 16, 0, 0); } while (0)
; #define PG8_LDA(dst, b, h) do { _Pragma("unroll") for (int m = 0; m < 4; ++m) _Pragma("unroll") for (int k = 0; k < 2; ++k) dst[m][k] = *(const PG8_LAS bf16x8*)(lds + PG8_SA(b, h) + aoff + m * 2048 + k * 1024); } while (0)
; #define PG8_WAIT_V(n) asm volatile("s_waitcnt vmcnt(" #n ")" ::: "memory")
; #define PG8_WAIT_L(n) asm volatile("s_waitcnt lgkmcnt(" #n ")" ::: "memory")
; #define PG8_BAR __builtin_amdgcn_s_barrier()
; template <class Epi, class Sched, bool ALIGN_EPI = false, bool SP2 = false>
; __device__ __forceinline__ void gemm_phase(PG8_LAS unsigned char* lds, const Gemm g, const Sched& S, const Epi& E) {
;     ...
;         for (int t = seg * tseg; t < (seg + 1) * tseg; t += 2) {
;             const bool last = (t == nt - 2);
;             const char* a1 = cA + (size_t)(t + 1) * kstep;
;             const char* a2 = last ? nA : cA + (size_t)(t + 2) * kstep; const char* b2 = last ? nB : cB + (size_t)(t + 2) * kstep;
;             const char* a3 = a2 + kstep; const char* b3 = b2 + kstep;
;             if (last && has_next) S.a_ready(nxt);
;             if constexpr (SP2) {
;             PG8_LDB(B0, 0, 0); PG8_LDB(B1, 0, 1); PG8_SCHED; PG8_LDA(At, 0, 0); PG8_STAGE(PG8_SA(1, 1), a1 + hstep, voffA);
;             PG8_WAIT_V(8); PG8_WAIT_L(0); PG8_BAR; PG8_MMA(0, 0, At, B0); PG8_MMA(0, 1, At, B1); PG8_BAR; PG8_SCHED;
;             PG8_LDA(At, 0, 1); PG8_STAGE(PG8_SB(0, 0), b2, voffB); PG8_STAGE(PG8_SB(0, 1), b2 + hstep, voffB); PG8_STAGE(PG8_SA(0, 0), a2, voffA);
;             PG8_WAIT_V(8); PG8_WAIT_L(0); PG8_BAR; PG8_MMA(1, 0, At, B0); PG8_MMA(1, 1, At, B1); PG8_BAR; PG8_SCHED;
;             PG8_LDB(B0, 1, 0); PG8_LDB(B1, 1, 1); PG8_SCHED; PG8_LDA(At, 1, 0); PG8_STAGE(PG8_SA(0, 1), a2 + hstep, voffA);
;             PG8_WAIT_V(8); PG8_WAIT_L(0); PG8_BAR; PG8_MMA(0, 0, At, B0); PG8_MMA(0, 1, At, B1); PG8_BAR; PG8_SCHED;
;             PG8_LDA(At, 1, 1); PG8_STAGE(PG8_SB(1, 0), b3, voffB); PG8_STAGE(PG8_SB(1, 1), b3 + hstep, voffB); PG8_STAGE(PG8_SA(1, 0), a3, voffA);
;             PG8_WAIT_V(8); PG8_WAIT_L(0); PG8_BAR; PG8_MMA(1, 0, At, B0); PG8_MMA(1, 1, At, B1); PG8_BAR; PG8_SCHED;
	s_waitcnt lgkmcnt(0)
	v_mfma_f32_16x16x32_bf16 v[92:95], v[118:121], v[162:165], 0
	v_mfma_f32_16x16x32_bf16 v[28:31], v[126:129], v[162:165], 0
	v_mfma_f32_16x16x32_bf16 v[84:87], v[118:121], v[170:173], 0
	v_mfma_f32_16x16x32_bf16 v[20:23], v[126:129], v[170:173], 0
	v_mfma_f32_16x16x32_bf16 v[76:79], v[118:121], v[198:201], 0
	v_mfma_f32_16x16x32_bf16 v[12:15], v[126:129], v[198:201], 0
	v_mfma_f32_16x16x32_bf16 v[68:71], v[118:121], v[206:209], 0
	v_mfma_f32_16x16x32_bf16 v[4:7], v[126:129], v[206:209], 0
	v_mfma_f32_16x16x32_bf16 v[92:95], v[122:125], v[166:169], v[92:95]
	v_mfma_f32_16x16x32_bf16 v[28:31], v[130:133], v[166:169], v[28:31]
	v_mfma_f32_16x16x32_bf16 v[84:87], v[122:125], v[174:177], v[84:87]
	v_mfma_f32_16x16x32_bf16 v[20:23], v[130:133], v[174:177], v[20:23]
	v_mfma_f32_16x16x32_bf16 v[76:79], v[122:125], v[202:205], v[76:79]
	v_mfma_f32_16x16x32_bf16 v[12:15], v[130:133], v[202:205], v[12:15]
	v_mfma_f32_16x16x32_bf16 v[68:71], v[122:125], v[228:231], v[68:71]
	v_mfma_f32_16x16x32_bf16 v[4:7], v[130:133], v[228:231], v[4:7]
	v_mfma_f32_16x16x32_bf16 v[88:91], v[134:137], v[162:165], 0
	v_mfma_f32_16x16x32_bf16 v[24:27], v[142:145], v[162:165], 0
	v_mfma_f32_16x16x32_bf16 v[80:83], v[134:137], v[170:173], 0
	v_mfma_f32_16x16x32_bf16 v[16:19], v[142:145], v[170:173], 0
	v_mfma_f32_16x16x32_bf16 v[72:75], v[134:137], v[198:201], 0
	v_mfma_f32_16x16x32_bf16 v[8:11], v[142:145], v[198:201], 0
	v_mfma_f32_16x16x32_bf16 v[64:67], v[134:137], v[206:209], 0
	v_mfma_f32_16x16x32_bf16 v[0:3], v[142:145], v[206:209], 0
	v_mfma_f32_16x16x32_bf16 v[88:91], v[138:141], v[166:169], v[88:91]
	v_mfma_f32_16x16x32_bf16 v[24:27], v[146:149], v[166:169], v[24:27]
	v_mfma_f32_16x16x32_bf16 v[80:83], v[138:141], v[174:177], v[80:83]
	v_mfma_f32_16x16x32_bf16 v[16:19], v[146:149], v[174:177], v[16:19]
	v_mfma_f32_16x16x32_bf16 v[72:75], v[138:141], v[202:205], v[72:75]
	v_mfma_f32_16x16x32_bf16 v[8:11], v[146:149], v[202:205], v[8:11]
	v_mfma_f32_16x16x32_bf16 v[64:67], v[138:141], v[228:231], v[64:67]
	v_mfma_f32_16x16x32_bf16 v[0:3], v[146:149], v[228:231], v[0:3]
	s_barrier
	v_add_u32_e32 v116, s75, v214
	ds_read_b128 v[118:121], v116
	ds_read_b128 v[122:125], v116 offset:1024
	ds_read_b128 v[126:129], v116 offset:2048
	ds_read_b128 v[130:133], v116 offset:3072
	v_add_u32_e32 v116, s84, v214
	ds_read_b128 v[134:137], v116
	ds_read_b128 v[138:141], v116 offset:1024
	ds_read_b128 v[142:145], v116 offset:2048
	ds_read_b128 v[146:149], v116 offset:3072
	s_add_u32 s20, s20, 0x80000
	s_addc_u32 s21, s21, 0
	s_mov_b32 m0, s95
	v_lshl_add_u64 v[116:117], s[20:21], 0, v[178:179]
	ds_read_b128 v[162:165], v227 offset:32768
	ds_read_b128 v[166:169], v227 offset:33792
	ds_read_b128 v[170:173], v227 offset:34816
	ds_read_b128 v[174:177], v227 offset:35840
	ds_read_b128 v[198:201], v227 offset:36864
	ds_read_b128 v[202:205], v227 offset:37888
	ds_read_b128 v[206:209], v227 offset:38912
	ds_read_b128 v[228:231], v227 offset:39936
	global_load_lds_dwordx4 v[116:117], off
	v_lshl_add_u64 v[116:117], s[20:21], 0, v[182:183]
	s_mov_b32 m0, s2
	s_nop 0
	global_load_lds_dwordx4 v[116:117], off
	s_waitcnt vmcnt(8)
	s_waitcnt lgkmcnt(0)
	s_barrier
	s_waitcnt lgkmcnt(0)
	v_mfma_f32_16x16x32_bf16 v[158:161], v[118:121], v[162:165], v[158:161]
	v_mfma_f32_16x16x32_bf16 v[60:63], v[126:129], v[162:165], v[60:63]
	v_mfma_f32_16x16x32_bf16 v[154:157], v[118:121], v[170:173], v[154:157]
	v_mfma_f32_16x16x32_bf16 v[52:55], v[126:129], v[170:173], v[52:55]
	v_mfma_f32_16x16x32_bf16 v[112:115], v[118:121], v[198:201], v[112:115]
	v_mfma_f32_16x16x32_bf16 v[44:47], v[126:129], v[198:201], v[44:47]
	v_mfma_f32_16x16x32_bf16 v[100:103], v[118:121], v[206:209], v[100:103]
	v_mfma_f32_16x16x32_bf16 v[36:39], v[126:129], v[206:209], v[36:39]
	v_mfma_f32_16x16x32_bf16 v[158:161], v[122:125], v[166:169], v[158:161]
	v_mfma_f32_16x16x32_bf16 v[60:63], v[130:133], v[166:169], v[60:63]
	v_mfma_f32_16x16x32_bf16 v[154:157], v[122:125], v[174:177], v[154:157]
	v_mfma_f32_16x16x32_bf16 v[52:55], v[130:133], v[174:177], v[52:55]
	v_mfma_f32_16x16x32_bf16 v[114:117], v[122:125], v[202:205], v[112:115]
	v_mfma_f32_16x16x32_bf16 v[44:47], v[130:133], v[202:205], v[44:47]
	v_mfma_f32_16x16x32_bf16 v[100:103], v[122:125], v[228:231], v[100:103]
	v_mfma_f32_16x16x32_bf16 v[36:39], v[130:133], v[228:231], v[36:39]
	v_mfma_f32_16x16x32_bf16 v[108:111], v[134:137], v[162:165], v[108:111]
	v_mfma_f32_16x16x32_bf16 v[56:59], v[142:145], v[162:165], v[56:59]
	v_mfma_f32_16x16x32_bf16 v[150:153], v[134:137], v[170:173], v[150:153]
	v_mfma_f32_16x16x32_bf16 v[48:51], v[142:145], v[170:173], v[48:51]
	v_mfma_f32_16x16x32_bf16 v[104:107], v[134:137], v[198:201], v[104:107]
	v_mfma_f32_16x16x32_bf16 v[40:43], v[142:145], v[198:201], v[40:43]
	v_mfma_f32_16x16x32_bf16 v[96:99], v[134:137], v[206:209], v[96:99]
	v_mfma_f32_16x16x32_bf16 v[32:35], v[142:145], v[206:209], v[32:35]
	v_mfma_f32_16x16x32_bf16 v[108:111], v[138:141], v[166:169], v[108:111]
	v_mfma_f32_16x16x32_bf16 v[56:59], v[146:149], v[166:169], v[56:59]
	v_mfma_f32_16x16x32_bf16 v[150:153], v[138:141], v[174:177], v[150:153]
	v_mfma_f32_16x16x32_bf16 v[48:51], v[146:149], v[174:177], v[48:51]
	v_mfma_f32_16x16x32_bf16 v[104:107], v[138:141], v[202:205], v[104:107]
	v_mfma_f32_16x16x32_bf16 v[40:43], v[146:149], v[202:205], v[40:43]
	v_mfma_f32_16x16x32_bf16 v[96:99], v[138:141], v[228:231], v[96:99]
	v_mfma_f32_16x16x32_bf16 v[32:35], v[146:149], v[228:231], v[32:35]
	s_barrier
; #define PG8_STAGE(bufoff, gbase, voff) do { _Pragma("unroll") for (int _i = 0; _i < 2; ++_i) \
;         __builtin_amdgcn_global_load_lds((const unsigned*)((const char*)(gbase) + (voff)[_i]), (PG8_LAS unsigned*)(lds + (bufoff) + ldsw + _i * 8192), 16, 0, 0); } while (0)
; #define PG8_LDA(dst, b, h) do { _Pragma("unroll") for (int m = 0; m < 4; ++m) _Pragma("unroll") for (int k = 0; k < 2; ++k) dst[m][k] = *(const PG8_LAS bf16x8*)(lds + PG8_SA(b, h) + aoff + m * 2048 + k * 1024); } while (0)
; #define PG8_WAIT_V(n) asm volatile("s_waitcnt vmcnt(" #n ")" ::: "memory")
; #define PG8_WAIT_L(n) asm volatile("s_waitcnt lgkmcnt(" #n ")" ::: "memory")
; #define PG8_BAR __builtin_amdgcn_s_barrier()
; template <class Epi, class Sched, bool ALIGN_EPI = false, bool SP2 = false>
; __device__ __forceinline__ void gemm_phase(PG8_LAS unsigned char* lds, const Gemm g, const Sched& S, const Epi& E) {
;     ...
;         for (int t = seg * tseg; t < (seg + 1) * tseg; t += 2) {
;             const bool last = (t == nt - 2);
;             const char* a1 = cA + (size_t)(t + 1) * kstep;
;             const char* a2 = last ? nA : cA + (size_t)(t + 2) * kstep; const char* b2 = last ? nB : cB + (size_t)(t + 2) * kstep;
;             const char* a3 = a2 + kstep; const char* b3 = b2 + kstep;
;             if (last && has_next) S.a_ready(nxt);
;             if constexpr (SP2) {
;             PG8_LDB(B0, 0, 0); PG8_LDB(B1, 0, 1); PG8_SCHED; PG8_LDA(At, 0, 0); PG8_STAGE(PG8_SA(1, 1), a1 + hstep, voffA);
;             PG8_WAIT_V(8); PG8_WAIT_L(0); PG8_BAR; PG8_MMA(0, 0, At, B0); PG8_MMA(0, 1, At, B1); PG8_BAR; PG8_SCHED;
;             PG8_LDA(At, 0, 1); PG8_STAGE(PG8_SB(0, 0), b2, voffB); PG8_STAGE(PG8_SB(0, 1), b2 + hstep, voffB); PG8_STAGE(PG8_SA(0, 0), a2, voffA);
;             PG8_WAIT_V(8); PG8_WAIT_L(0); PG8_BAR; PG8_MMA(1, 0, At, B0); PG8_MMA(1, 1, At, B1); PG8_BAR; PG8_SCHED;
;             PG8_LDB(B0, 1, 0); PG8_LDB(B1, 1, 1); PG8_SCHED; PG8_LDA(At, 1, 0); PG8_STAGE(PG8_SA(0, 1), a2 + hstep, voffA);
;             PG8_WAIT_V(8); PG8_WAIT_L(0); PG8_BAR; PG8_MMA(0, 0, At, B0); PG8_MMA(0, 1, At, B1); PG8_BAR; PG8_SCHED;
;             PG8_LDA(At, 1, 1); PG8_STAGE(PG8_SB(1, 0), b3, voffB); PG8_STAGE(PG8_SB(1, 1), b3 + hstep, voffB); PG8_STAGE(PG8_SA(1, 0), a3, voffA);
;             PG8_WAIT_V(8); PG8_WAIT_L(0); PG8_BAR; PG8_MMA(1, 0, At, B0); PG8_MMA(1, 1, At, B1); PG8_BAR; PG8_SCHED;
	s_add_i32 s20, s75, s28
	v_lshl_add_u64 v[112:113], v[210:211], 0, s[46:47]
	s_mov_b32 m0, s20
	ds_read_b128 v[162:165], v227 offset:49152
	ds_read_b128 v[166:169], v227 offset:50176
	ds_read_b128 v[170:173], v227 offset:51200
	ds_read_b128 v[174:177], v227 offset:52224
	ds_read_b128 v[198:201], v227 offset:53248
	ds_read_b128 v[202:205], v227 offset:54272
	ds_read_b128 v[206:209], v227 offset:55296
	ds_read_b128 v[228:231], v227 offset:56320
	global_load_lds_dwordx4 v[112:113], off
	s_add_i32 m0, s20, 0x2000
	s_add_u32 s18, s18, 0x80080
	v_lshl_add_u64 v[112:113], v[232:233], 0, s[46:47]
	s_addc_u32 s19, s19, 0
	s_add_i32 s20, s84, s28
	global_load_lds_dwordx4 v[112:113], off
	v_lshl_add_u64 v[112:113], s[18:19], 0, v[180:181]
	s_mov_b32 m0, s20
	s_nop 0
	global_load_lds_dwordx4 v[112:113], off
	v_lshl_add_u64 v[112:113], s[18:19], 0, v[184:185]
	s_add_i32 m0, s20, 0x2000
	s_nop 0
	global_load_lds_dwordx4 v[112:113], off
	v_lshl_add_u64 v[112:113], v[234:235], 0, s[46:47]
	s_mov_b32 m0, s30
	s_nop 0
	global_load_lds_dwordx4 v[112:113], off
	v_lshl_add_u64 v[112:113], v[236:237], 0, s[46:47]
	s_mov_b32 m0, s23
	s_nop 0
	global_load_lds_dwordx4 v[112:113], off
	s_waitcnt vmcnt(8)
	s_waitcnt lgkmcnt(0)
	s_barrier
	s_waitcnt lgkmcnt(0)
	v_mfma_f32_16x16x32_bf16 v[92:95], v[118:121], v[162:165], v[92:95]
	v_mfma_f32_16x16x32_bf16 v[28:31], v[126:129], v[162:165], v[28:31]
	v_mfma_f32_16x16x32_bf16 v[84:87], v[118:121], v[170:173], v[84:87]
	v_mfma_f32_16x16x32_bf16 v[20:23], v[126:129], v[170:173], v[20:23]
	v_mfma_f32_16x16x32_bf16 v[76:79], v[118:121], v[198:201], v[76:79]
	v_mfma_f32_16x16x32_bf16 v[12:15], v[126:129], v[198:201], v[12:15]
	v_mfma_f32_16x16x32_bf16 v[68:71], v[118:121], v[206:209], v[68:71]
	v_mfma_f32_16x16x32_bf16 v[4:7], v[126:129], v[206:209], v[4:7]
	v_mfma_f32_16x16x32_bf16 v[92:95], v[122:125], v[166:169], v[92:95]
	v_mfma_f32_16x16x32_bf16 v[28:31], v[130:133], v[166:169], v[28:31]
	v_mfma_f32_16x16x32_bf16 v[84:87], v[122:125], v[174:177], v[84:87]
	v_mfma_f32_16x16x32_bf16 v[20:23], v[130:133], v[174:177], v[20:23]
	v_mfma_f32_16x16x32_bf16 v[76:79], v[122:125], v[202:205], v[76:79]
	v_mfma_f32_16x16x32_bf16 v[12:15], v[130:133], v[202:205], v[12:15]
	v_mfma_f32_16x16x32_bf16 v[68:71], v[122:125], v[228:231], v[68:71]
	v_mfma_f32_16x16x32_bf16 v[4:7], v[130:133], v[228:231], v[4:7]
	v_mfma_f32_16x16x32_bf16 v[88:91], v[134:137], v[162:165], v[88:91]
	v_mfma_f32_16x16x32_bf16 v[24:27], v[142:145], v[162:165], v[24:27]
	v_mfma_f32_16x16x32_bf16 v[80:83], v[134:137], v[170:173], v[80:83]
	v_mfma_f32_16x16x32_bf16 v[16:19], v[142:145], v[170:173], v[16:19]
	v_mfma_f32_16x16x32_bf16 v[72:75], v[134:137], v[198:201], v[72:75]
	v_mfma_f32_16x16x32_bf16 v[8:11], v[142:145], v[198:201], v[8:11]
	v_mfma_f32_16x16x32_bf16 v[64:67], v[134:137], v[206:209], v[64:67]
	v_mfma_f32_16x16x32_bf16 v[0:3], v[142:145], v[206:209], v[0:3]
	v_mfma_f32_16x16x32_bf16 v[88:91], v[138:141], v[166:169], v[88:91]
	v_mfma_f32_16x16x32_bf16 v[24:27], v[146:149], v[166:169], v[24:27]
	v_mfma_f32_16x16x32_bf16 v[80:83], v[138:141], v[174:177], v[80:83]
	v_mfma_f32_16x16x32_bf16 v[16:19], v[146:149], v[174:177], v[16:19]
	v_mfma_f32_16x16x32_bf16 v[72:75], v[138:141], v[202:205], v[72:75]
	v_mfma_f32_16x16x32_bf16 v[8:11], v[146:149], v[202:205], v[8:11]
	v_mfma_f32_16x16x32_bf16 v[64:67], v[138:141], v[228:231], v[64:67]
	v_mfma_f32_16x16x32_bf16 v[0:3], v[146:149], v[228:231], v[0:3]
	s_barrier
	s_add_i32 s97, s97, 2
	s_add_u32 s16, s16, 0x100
	s_addc_u32 s17, s17, 0
	s_add_u32 s89, s89, 0x100
	s_addc_u32 s96, s96, 0
	s_cmp_gt_u32 s97, 29
.LBB0_928:
	ds_read_b128 v[118:121], v225
	ds_read_b128 v[122:125], v225 offset:1024
	ds_read_b128 v[126:129], v225 offset:2048
	ds_read_b128 v[130:133], v225 offset:3072
	ds_read_b128 v[134:137], v226
	ds_read_b128 v[138:141], v226 offset:1024
	ds_read_b128 v[142:145], v226 offset:2048
	ds_read_b128 v[146:149], v226 offset:3072
	s_add_u32 s18, s16, 0xfff80080
	s_addc_u32 s19, s17, -1
	s_cmp_eq_u32 s97, 28
	s_cselect_b32 s21, s0, s19
	s_cselect_b32 s20, s1, s18
	s_cselect_b32 s19, s15, s96
	s_cselect_b32 s18, s87, s89
	v_lshl_add_u64 v[112:113], s[16:17], 0, v[190:191]
	s_add_i32 m0, s29, 0xc000
	ds_read_b128 v[162:165], v227
	ds_read_b128 v[166:169], v227 offset:1024
	ds_read_b128 v[170:173], v227 offset:2048
	ds_read_b128 v[174:177], v227 offset:3072
	ds_read_b128 v[198:201], v227 offset:4096
	ds_read_b128 v[202:205], v227 offset:5120
	ds_read_b128 v[206:209], v227 offset:6144
	ds_read_b128 v[228:231], v227 offset:7168
	global_load_lds_dwordx4 v[112:113], off
	v_lshl_add_u64 v[112:113], s[16:17], 0, v[192:193]
	s_add_i32 m0, s29, 0xe000
	s_nop 0
	global_load_lds_dwordx4 v[112:113], off
	s_waitcnt vmcnt(8)
	s_waitcnt lgkmcnt(0)
	s_barrier
; #define PG8_STAGE(bufoff, gbase, voff) do { _Pragma("unroll") for (int _i = 0; _i < 2; ++_i) \
;         __builtin_amdgcn_global_load_lds((const unsigned*)((const char*)(gbase) + (voff)[_i]), (PG8_LAS unsigned*)(lds + (bufoff) + ldsw + _i * 8192), 16, 0, 0); } while (0)
; #define PG8_LDA(dst, b, h) do { _Pragma("unroll") for (int m = 0; m < 4; ++m) _Pragma("unroll") for (int k = 0; k < 2; ++k) dst[m][k] = *(const PG8_LAS bf16x8*)(lds + PG8_SA(b, h) + aoff + m * 2048 + k * 1024); } while (0)
; #define PG8_WAIT_V(n) asm volatile("s_waitcnt vmcnt(" #n ")" ::: "memory")
; #define PG8_WAIT_L(n) asm volatile("s_waitcnt lgkmcnt(" #n ")" ::: "memory")
; #define PG8_BAR __builtin_amdgcn_s_barrier()
; template <class Epi, class Sched, bool ALIGN_EPI = false, bool SP2 = false>
; __device__ __forceinline__ void gemm_phase(PG8_LAS unsigned char* lds, const Gemm g, const Sched& S, const Epi& E) {
;     ...
;         for (int t = seg * tseg; t < (seg + 1) * tseg; t += 2) {
;             const bool last = (t == nt - 2);
;             const char* a1 = cA + (size_t)(t + 1) * kstep;
;             const char* a2 = last ? nA : cA + (size_t)(t + 2) * kstep; const char* b2 = last ? nB : cB + (size_t)(t + 2) * kstep;
;             const char* a3 = a2 + kstep; const char* b3 = b2 + kstep;
;             if (last && has_next) S.a_ready(nxt);
;             if constexpr (SP2) {
;             PG8_LDB(B0, 0, 0); PG8_LDB(B1, 0, 1); PG8_SCHED; PG8_LDA(At, 0, 0); PG8_STAGE(PG8_SA(1, 1), a1 + hstep, voffA);
;             PG8_WAIT_V(8); PG8_WAIT_L(0); PG8_BAR; PG8_MMA(0, 0, At, B0); PG8_MMA(0, 1, At, B1); PG8_BAR; PG8_SCHED;
;             PG8_LDA(At, 0, 1); PG8_STAGE(PG8_SB(0, 0), b2, voffB); PG8_STAGE(PG8_SB(0, 1), b2 + hstep, voffB); PG8_STAGE(PG8_SA(0, 0), a2, voffA);
;             PG8_WAIT_V(8); PG8_WAIT_L(0); PG8_BAR; PG8_MMA(1, 0, At, B0); PG8_MMA(1, 1, At, B1); PG8_BAR; PG8_SCHED;
;             PG8_LDB(B0, 1, 0); PG8_LDB(B1, 1, 1); PG8_SCHED; PG8_LDA(At, 1, 0); PG8_STAGE(PG8_SA(0, 1), a2 + hstep, voffA);
;             PG8_WAIT_V(8); PG8_WAIT_L(0); PG8_BAR; PG8_MMA(0, 0, At, B0); PG8_MMA(0, 1, At, B1); PG8_BAR; PG8_SCHED;
;             PG8_LDA(At, 1, 1); PG8_STAGE(PG8_SB(1, 0), b3, voffB); PG8_STAGE(PG8_SB(1, 1), b3 + hstep, voffB); PG8_STAGE(PG8_SA(1, 0), a3, voffA);
;             PG8_WAIT_V(8); PG8_WAIT_L(0); PG8_BAR; PG8_MMA(1, 0, At, B0); PG8_MMA(1, 1, At, B1); PG8_BAR; PG8_SCHED;
	s_waitcnt lgkmcnt(0)
	v_mfma_f32_16x16x32_bf16 v[158:161], v[118:121], v[162:165], v[158:161]
	v_mfma_f32_16x16x32_bf16 v[60:63], v[126:129], v[162:165], v[60:63]
	v_mfma_f32_16x16x32_bf16 v[154:157], v[118:121], v[170:173], v[154:157]
	v_mfma_f32_16x16x32_bf16 v[52:55], v[126:129], v[170:173], v[52:55]
	v_mfma_f32_16x16x32_bf16 v[112:115], v[118:121], v[198:201], v[114:117]
	v_mfma_f32_16x16x32_bf16 v[44:47], v[126:129], v[198:201], v[44:47]
	v_mfma_f32_16x16x32_bf16 v[100:103], v[118:121], v[206:209], v[100:103]
	v_mfma_f32_16x16x32_bf16 v[36:39], v[126:129], v[206:209], v[36:39]
	v_mfma_f32_16x16x32_bf16 v[158:161], v[122:125], v[166:169], v[158:161]
	v_mfma_f32_16x16x32_bf16 v[60:63], v[130:133], v[166:169], v[60:63]
	v_mfma_f32_16x16x32_bf16 v[154:157], v[122:125], v[174:177], v[154:157]
	v_mfma_f32_16x16x32_bf16 v[52:55], v[130:133], v[174:177], v[52:55]
	v_mfma_f32_16x16x32_bf16 v[112:115], v[122:125], v[202:205], v[112:115]
	v_mfma_f32_16x16x32_bf16 v[44:47], v[130:133], v[202:205], v[44:47]
	v_mfma_f32_16x16x32_bf16 v[100:103], v[122:125], v[228:231], v[100:103]
	v_mfma_f32_16x16x32_bf16 v[36:39], v[130:133], v[228:231], v[36:39]
	v_mfma_f32_16x16x32_bf16 v[108:111], v[134:137], v[162:165], v[108:111]
	v_mfma_f32_16x16x32_bf16 v[56:59], v[142:145], v[162:165], v[56:59]
	v_mfma_f32_16x16x32_bf16 v[150:153], v[134:137], v[170:173], v[150:153]
	v_mfma_f32_16x16x32_bf16 v[48:51], v[142:145], v[170:173], v[48:51]
	v_mfma_f32_16x16x32_bf16 v[104:107], v[134:137], v[198:201], v[104:107]
	v_mfma_f32_16x16x32_bf16 v[40:43], v[142:145], v[198:201], v[40:43]
	v_mfma_f32_16x16x32_bf16 v[96:99], v[134:137], v[206:209], v[96:99]
	v_mfma_f32_16x16x32_bf16 v[32:35], v[142:145], v[206:209], v[32:35]
	v_mfma_f32_16x16x32_bf16 v[108:111], v[138:141], v[166:169], v[108:111]
	v_mfma_f32_16x16x32_bf16 v[56:59], v[146:149], v[166:169], v[56:59]
	v_mfma_f32_16x16x32_bf16 v[150:153], v[138:141], v[174:177], v[150:153]
	v_mfma_f32_16x16x32_bf16 v[48:51], v[146:149], v[174:177], v[48:51]
	v_mfma_f32_16x16x32_bf16 v[104:107], v[138:141], v[202:205], v[104:107]
	v_mfma_f32_16x16x32_bf16 v[40:43], v[146:149], v[202:205], v[40:43]
	v_mfma_f32_16x16x32_bf16 v[96:99], v[138:141], v[228:231], v[96:99]
	v_mfma_f32_16x16x32_bf16 v[32:35], v[146:149], v[228:231], v[32:35]
	s_barrier
	s_add_i32 vcc_lo, s31, s28
	v_lshl_add_u64 v[210:211], s[18:19], 0, v[180:181]
	s_mov_b32 m0, vcc_lo
	ds_read_b128 v[162:165], v227 offset:16384
	ds_read_b128 v[166:169], v227 offset:17408
	ds_read_b128 v[170:173], v227 offset:18432
	ds_read_b128 v[174:177], v227 offset:19456
	ds_read_b128 v[198:201], v227 offset:20480
	ds_read_b128 v[202:205], v227 offset:21504
	ds_read_b128 v[206:209], v227 offset:22528
	ds_read_b128 v[228:231], v227 offset:23552
	global_load_lds_dwordx4 v[210:211], off
	s_add_i32 m0, vcc_lo, 0x2000
	s_add_u32 vcc_lo, s18, 0x80000
	v_lshl_add_u64 v[232:233], s[18:19], 0, v[184:185]
	s_addc_u32 vcc_hi, s19, 0
	s_add_i32 s22, s74, s28
	global_load_lds_dwordx4 v[232:233], off
	v_lshl_add_u64 v[116:117], vcc, 0, v[180:181]
	s_mov_b32 m0, s22
	v_lshl_add_u64 v[234:235], s[20:21], 0, v[178:179]
	global_load_lds_dwordx4 v[116:117], off
	v_lshl_add_u64 v[116:117], vcc, 0, v[184:185]
	s_add_i32 m0, s22, 0x2000
	v_lshl_add_u64 v[236:237], s[20:21], 0, v[182:183]
	global_load_lds_dwordx4 v[116:117], off
	s_mov_b32 m0, s29
	s_nop 0
	global_load_lds_dwordx4 v[234:235], off
	s_mov_b32 m0, s85
	s_nop 0
	global_load_lds_dwordx4 v[236:237], off
	s_waitcnt vmcnt(8)
	s_waitcnt lgkmcnt(0)
	s_barrier
	s_waitcnt lgkmcnt(0)
	v_mfma_f32_16x16x32_bf16 v[92:95], v[118:121], v[162:165], v[92:95]
	v_mfma_f32_16x16x32_bf16 v[28:31], v[126:129], v[162:165], v[28:31]
	v_mfma_f32_16x16x32_bf16 v[84:87], v[118:121], v[170:173], v[84:87]
	v_mfma_f32_16x16x32_bf16 v[20:23], v[126:129], v[170:173], v[20:23]
	v_mfma_f32_16x16x32_bf16 v[76:79], v[118:121], v[198:201], v[76:79]
	v_mfma_f32_16x16x32_bf16 v[12:15], v[126:129], v[198:201], v[12:15]
	v_mfma_f32_16x16x32_bf16 v[68:71], v[118:121], v[206:209], v[68:71]
	v_mfma_f32_16x16x32_bf16 v[4:7], v[126:129], v[206:209], v[4:7]
	v_mfma_f32_16x16x32_bf16 v[92:95], v[122:125], v[166:169], v[92:95]
	v_mfma_f32_16x16x32_bf16 v[28:31], v[130:133], v[166:169], v[28:31]
	v_mfma_f32_16x16x32_bf16 v[84:87], v[122:125], v[174:177], v[84:87]
	v_mfma_f32_16x16x32_bf16 v[20:23], v[130:133], v[174:177], v[20:23]
	v_mfma_f32_16x16x32_bf16 v[76:79], v[122:125], v[202:205], v[76:79]
	v_mfma_f32_16x16x32_bf16 v[12:15], v[130:133], v[202:205], v[12:15]
	v_mfma_f32_16x16x32_bf16 v[68:71], v[122:125], v[228:231], v[68:71]
	v_mfma_f32_16x16x32_bf16 v[4:7], v[130:133], v[228:231], v[4:7]
	v_mfma_f32_16x16x32_bf16 v[88:91], v[134:137], v[162:165], v[88:91]
	v_mfma_f32_16x16x32_bf16 v[24:27], v[142:145], v[162:165], v[24:27]
	v_mfma_f32_16x16x32_bf16 v[80:83], v[134:137], v[170:173], v[80:83]
	v_mfma_f32_16x16x32_bf16 v[16:19], v[142:145], v[170:173], v[16:19]
	v_mfma_f32_16x16x32_bf16 v[72:75], v[134:137], v[198:201], v[72:75]
	v_mfma_f32_16x16x32_bf16 v[8:11], v[142:145], v[198:201], v[8:11]
	v_mfma_f32_16x16x32_bf16 v[64:67], v[134:137], v[206:209], v[64:67]
	v_mfma_f32_16x16x32_bf16 v[0:3], v[142:145], v[206:209], v[0:3]
	v_mfma_f32_16x16x32_bf16 v[88:91], v[138:141], v[166:169], v[88:91]
	v_mfma_f32_16x16x32_bf16 v[24:27], v[146:149], v[166:169], v[24:27]
	v_mfma_f32_16x16x32_bf16 v[80:83], v[138:141], v[174:177], v[80:83]
	v_mfma_f32_16x16x32_bf16 v[16:19], v[146:149], v[174:177], v[16:19]
	v_mfma_f32_16x16x32_bf16 v[72:75], v[138:141], v[202:205], v[72:75]
	v_mfma_f32_16x16x32_bf16 v[8:11], v[146:149], v[202:205], v[8:11]
	v_mfma_f32_16x16x32_bf16 v[64:67], v[138:141], v[228:231], v[64:67]
	v_mfma_f32_16x16x32_bf16 v[0:3], v[146:149], v[228:231], v[0:3]
	s_barrier
; #define PG8_STAGE(bufoff, gbase, voff) do { _Pragma("unroll") for (int _i = 0; _i < 2; ++_i) \
;         __builtin_amdgcn_global_load_lds((const unsigned*)((const char*)(gbase) + (voff)[_i]), (PG8_LAS unsigned*)(lds + (bufoff) + ldsw + _i * 8192), 16, 0, 0); } while (0)
; #define PG8_LDA(dst, b, h) do { _Pragma("unroll") for (int m = 0; m < 4; ++m) _Pragma("unroll") for (int k = 0; k < 2; ++k) dst[m][k] = *(const PG8_LAS bf16x8*)(lds + PG8_SA(b, h) + aoff + m * 2048 + k * 1024); } while (0)
; #define PG8_LDB(dst, b, h) do { _Pragma("unroll") for (int n = 0; n < 2; ++n) _Pragma("unroll") for (int k = 0; k < 2; ++k) dst[n][k] = *(const PG8_LAS bf16x8*)(lds + PG8_SB(b, h) + boff + n * 2048 + k * 1024); } while (0)
; #define PG8_MMA(ai, bj, At, Bt) do { __builtin_amdgcn_s_setprio(1); _Pragma("unroll") for (int m = 0; m < 4; ++m) _Pragma("unroll") for (int n = 0; n < 2; ++n) _Pragma("unroll") for (int k = 0; k < 2; ++k) \
;         acc[ai][bj][m][n] = __builtin_amdgcn_mfma_f32_16x16x32_bf16(Bt[n][k], At[m][k], acc[ai][bj][m][n], 0, 0, 0); __builtin_amdgcn_s_setprio(0); } while (0)
; #define PG8_WAIT_V(n) asm volatile("s_waitcnt vmcnt(" #n ")" ::: "memory")
; template <class Epi, class Sched, bool ALIGN_EPI = false, bool SP2 = false>
; __device__ __forceinline__ void gemm_phase(PG8_LAS unsigned char* lds, const Gemm g, const Sched& S, const Epi& E) {
;     ...
;             PG8_LDB(B0, 0, 0); PG8_LDB(B1, 0, 1); PG8_SCHED; PG8_LDA(At, 0, 0); PG8_STAGE(PG8_SA(1, 1), a1 + hstep, voffA);
;             PG8_WAIT_V(8); PG8_WAIT_L(0); PG8_BAR; PG8_MMA(0, 0, At, B0); PG8_MMA(0, 1, At, B1); PG8_BAR; PG8_SCHED;
;             PG8_LDA(At, 0, 1); PG8_STAGE(PG8_SB(0, 0), b2, voffB); PG8_STAGE(PG8_SB(0, 1), b2 + hstep, voffB); PG8_STAGE(PG8_SA(0, 0), a2, voffA);
;             PG8_WAIT_V(8); PG8_WAIT_L(0); PG8_BAR; PG8_MMA(1, 0, At, B0); PG8_MMA(1, 1, At, B1); PG8_BAR; PG8_SCHED;
;             PG8_LDB(B0, 1, 0); PG8_LDB(B1, 1, 1); PG8_SCHED; PG8_LDA(At, 1, 0); PG8_STAGE(PG8_SA(0, 1), a2 + hstep, voffA);
;             PG8_WAIT_V(8); PG8_WAIT_L(0); PG8_BAR; PG8_MMA(0, 0, At, B0); PG8_MMA(0, 1, At, B1); PG8_BAR; PG8_SCHED;
;             PG8_LDA(At, 1, 1); PG8_STAGE(PG8_SB(1, 0), b3, voffB); PG8_STAGE(PG8_SB(1, 1), b3 + hstep, voffB); PG8_STAGE(PG8_SA(1, 0), a3, voffA);
;             PG8_WAIT_V(8); PG8_WAIT_L(0); PG8_BAR; PG8_MMA(1, 0, At, B0); PG8_MMA(1, 1, At, B1); PG8_BAR; PG8_SCHED;
	v_add_u32_e32 v116, s75, v214
	ds_read_b128 v[118:121], v116
	ds_read_b128 v[122:125], v116 offset:1024
	ds_read_b128 v[126:129], v116 offset:2048
	ds_read_b128 v[130:133], v116 offset:3072
	v_add_u32_e32 v116, s84, v214
	ds_read_b128 v[134:137], v116
	ds_read_b128 v[138:141], v116 offset:1024
	ds_read_b128 v[142:145], v116 offset:2048
	ds_read_b128 v[146:149], v116 offset:3072
	s_add_u32 s20, s20, 0x80000
	s_addc_u32 s21, s21, 0
	s_mov_b32 m0, s95
	v_lshl_add_u64 v[116:117], s[20:21], 0, v[178:179]
	ds_read_b128 v[162:165], v227 offset:32768
	ds_read_b128 v[166:169], v227 offset:33792
	ds_read_b128 v[170:173], v227 offset:34816
	ds_read_b128 v[174:177], v227 offset:35840
	ds_read_b128 v[198:201], v227 offset:36864
	ds_read_b128 v[202:205], v227 offset:37888
	ds_read_b128 v[206:209], v227 offset:38912
	ds_read_b128 v[228:231], v227 offset:39936
	global_load_lds_dwordx4 v[116:117], off
	v_lshl_add_u64 v[116:117], s[20:21], 0, v[182:183]
	s_mov_b32 m0, s2
	s_nop 0
	global_load_lds_dwordx4 v[116:117], off
	s_waitcnt vmcnt(8)
	s_waitcnt lgkmcnt(0)
	s_barrier
	s_waitcnt lgkmcnt(0)
	v_mfma_f32_16x16x32_bf16 v[158:161], v[118:121], v[162:165], v[158:161]
	v_mfma_f32_16x16x32_bf16 v[60:63], v[126:129], v[162:165], v[60:63]
	v_mfma_f32_16x16x32_bf16 v[154:157], v[118:121], v[170:173], v[154:157]
	v_mfma_f32_16x16x32_bf16 v[52:55], v[126:129], v[170:173], v[52:55]
	v_mfma_f32_16x16x32_bf16 v[112:115], v[118:121], v[198:201], v[112:115]
	v_mfma_f32_16x16x32_bf16 v[44:47], v[126:129], v[198:201], v[44:47]
	v_mfma_f32_16x16x32_bf16 v[100:103], v[118:121], v[206:209], v[100:103]
	v_mfma_f32_16x16x32_bf16 v[36:39], v[126:129], v[206:209], v[36:39]
	v_mfma_f32_16x16x32_bf16 v[158:161], v[122:125], v[166:169], v[158:161]
	v_mfma_f32_16x16x32_bf16 v[60:63], v[130:133], v[166:169], v[60:63]
	v_mfma_f32_16x16x32_bf16 v[154:157], v[122:125], v[174:177], v[154:157]
	v_mfma_f32_16x16x32_bf16 v[52:55], v[130:133], v[174:177], v[52:55]
	v_mfma_f32_16x16x32_bf16 v[114:117], v[122:125], v[202:205], v[112:115]
	v_mfma_f32_16x16x32_bf16 v[44:47], v[130:133], v[202:205], v[44:47]
	v_mfma_f32_16x16x32_bf16 v[100:103], v[122:125], v[228:231], v[100:103]
	v_mfma_f32_16x16x32_bf16 v[36:39], v[130:133], v[228:231], v[36:39]
	v_mfma_f32_16x16x32_bf16 v[108:111], v[134:137], v[162:165], v[108:111]
	v_mfma_f32_16x16x32_bf16 v[56:59], v[142:145], v[162:165], v[56:59]
	v_mfma_f32_16x16x32_bf16 v[150:153], v[134:137], v[170:173], v[150:153]
	v_mfma_f32_16x16x32_bf16 v[48:51], v[142:145], v[170:173], v[48:51]
	v_mfma_f32_16x16x32_bf16 v[104:107], v[134:137], v[198:201], v[104:107]
	v_mfma_f32_16x16x32_bf16 v[40:43], v[142:145], v[198:201], v[40:43]
	v_mfma_f32_16x16x32_bf16 v[96:99], v[134:137], v[206:209], v[96:99]
	v_mfma_f32_16x16x32_bf16 v[32:35], v[142:145], v[206:209], v[32:35]
	v_mfma_f32_16x16x32_bf16 v[108:111], v[138:141], v[166:169], v[108:111]
	v_mfma_f32_16x16x32_bf16 v[56:59], v[146:149], v[166:169], v[56:59]
	v_mfma_f32_16x16x32_bf16 v[150:153], v[138:141], v[174:177], v[150:153]
	v_mfma_f32_16x16x32_bf16 v[48:51], v[146:149], v[174:177], v[48:51]
	v_mfma_f32_16x16x32_bf16 v[104:107], v[138:141], v[202:205], v[104:107]
	v_mfma_f32_16x16x32_bf16 v[40:43], v[146:149], v[202:205], v[40:43]
	v_mfma_f32_16x16x32_bf16 v[96:99], v[138:141], v[228:231], v[96:99]
	v_mfma_f32_16x16x32_bf16 v[32:35], v[146:149], v[228:231], v[32:35]
	s_barrier
; #define PG8_STAGE(bufoff, gbase, voff) do { _Pragma("unroll") for (int _i = 0; _i < 2; ++_i) \
;         __builtin_amdgcn_global_load_lds((const unsigned*)((const char*)(gbase) + (voff)[_i]), (PG8_LAS unsigned*)(lds + (bufoff) + ldsw + _i * 8192), 16, 0, 0); } while (0)
; #define PG8_LDA(dst, b, h) do { _Pragma("unroll") for (int m = 0; m < 4; ++m) _Pragma("unroll") for (int k = 0; k < 2; ++k) dst[m][k] = *(const PG8_LAS bf16x8*)(lds + PG8_SA(b, h) + aoff + m * 2048 + k * 1024); } while (0)
; #define PG8_WAIT_V(n) asm volatile("s_waitcnt vmcnt(" #n ")" ::: "memory")
; #define PG8_BAR __builtin_amdgcn_s_barrier()
; template <class Epi, class Sched, bool ALIGN_EPI = false, bool SP2 = false>
; __device__ __forceinline__ void gemm_phase(PG8_LAS unsigned char* lds, const Gemm g, const Sched& S, const Epi& E) {
;     ...
;         for (int t = seg * tseg; t < (seg + 1) * tseg; t += 2) {
;             const bool last = (t == nt - 2);
;             const char* a1 = cA + (size_t)(t + 1) * kstep;
;             const char* a2 = last ? nA : cA + (size_t)(t + 2) * kstep; const char* b2 = last ? nB : cB + (size_t)(t + 2) * kstep;
;             const char* a3 = a2 + kstep; const char* b3 = b2 + kstep;
;             if (last && has_next) S.a_ready(nxt);
;             if constexpr (SP2) {
;             PG8_LDB(B0, 0, 0); PG8_LDB(B1, 0, 1); PG8_SCHED; PG8_LDA(At, 0, 0); PG8_STAGE(PG8_SA(1, 1), a1 + hstep, voffA);
;             PG8_WAIT_V(8); PG8_WAIT_L(0); PG8_BAR; PG8_MMA(0, 0, At, B0); PG8_MMA(0, 1, At, B1); PG8_BAR; PG8_SCHED;
;             PG8_LDA(At, 0, 1); PG8_STAGE(PG8_SB(0, 0), b2, voffB); PG8_STAGE(PG8_SB(0, 1), b2 + hstep, voffB); PG8_STAGE(PG8_SA(0, 0), a2, voffA);
;             PG8_WAIT_V(8); PG8_WAIT_L(0); PG8_BAR; PG8_MMA(1, 0, At, B0); PG8_MMA(1, 1, At, B1); PG8_BAR; PG8_SCHED;
;             PG8_LDB(B0, 1, 0); PG8_LDB(B1, 1, 1); PG8_SCHED; PG8_LDA(At, 1, 0); PG8_STAGE(PG8_SA(0, 1), a2 + hstep, voffA);
;             PG8_WAIT_V(8); PG8_WAIT_L(0); PG8_BAR; PG8_MMA(0, 0, At, B0); PG8_MMA(0, 1, At, B1); PG8_BAR; PG8_SCHED;
;             PG8_LDA(At, 1, 1); PG8_STAGE(PG8_SB(1, 0), b3, voffB); PG8_STAGE(PG8_SB(1, 1), b3 + hstep, voffB); PG8_STAGE(PG8_SA(1, 0), a3, voffA);
;             PG8_WAIT_V(8); PG8_WAIT_L(0); PG8_BAR; PG8_MMA(1, 0, At, B0); PG8_MMA(1, 1, At, B1); PG8_BAR; PG8_SCHED;
;     ...
;         if constexpr (ALIGN_EPI) { if (wr == 0) PG8_BAR; }
	s_add_i32 s20, s75, s28
	v_lshl_add_u64 v[112:113], v[210:211], 0, s[46:47]
	s_mov_b32 m0, s20
	ds_read_b128 v[162:165], v227 offset:49152
	ds_read_b128 v[166:169], v227 offset:50176
	ds_read_b128 v[170:173], v227 offset:51200
	ds_read_b128 v[174:177], v227 offset:52224
	ds_read_b128 v[198:201], v227 offset:53248
	ds_read_b128 v[202:205], v227 offset:54272
	ds_read_b128 v[206:209], v227 offset:55296
	ds_read_b128 v[228:231], v227 offset:56320
	global_load_lds_dwordx4 v[112:113], off
	s_add_i32 m0, s20, 0x2000
	s_add_u32 s18, s18, 0x80080
	v_lshl_add_u64 v[112:113], v[232:233], 0, s[46:47]
	s_addc_u32 s19, s19, 0
	s_add_i32 s20, s84, s28
	global_load_lds_dwordx4 v[112:113], off
	v_lshl_add_u64 v[112:113], s[18:19], 0, v[180:181]
	s_mov_b32 m0, s20
	s_nop 0
	global_load_lds_dwordx4 v[112:113], off
	v_lshl_add_u64 v[112:113], s[18:19], 0, v[184:185]
	s_add_i32 m0, s20, 0x2000
	s_nop 0
	global_load_lds_dwordx4 v[112:113], off
	v_lshl_add_u64 v[112:113], v[234:235], 0, s[46:47]
	s_mov_b32 m0, s30
	s_nop 0
	global_load_lds_dwordx4 v[112:113], off
	v_lshl_add_u64 v[112:113], v[236:237], 0, s[46:47]
	s_mov_b32 m0, s23
	s_nop 0
	global_load_lds_dwordx4 v[112:113], off
	s_waitcnt vmcnt(8)
	s_waitcnt lgkmcnt(0)
	s_barrier
	s_waitcnt lgkmcnt(0)
	v_mfma_f32_16x16x32_bf16 v[92:95], v[118:121], v[162:165], v[92:95]
	v_mfma_f32_16x16x32_bf16 v[28:31], v[126:129], v[162:165], v[28:31]
	v_mfma_f32_16x16x32_bf16 v[84:87], v[118:121], v[170:173], v[84:87]
	v_mfma_f32_16x16x32_bf16 v[20:23], v[126:129], v[170:173], v[20:23]
	v_mfma_f32_16x16x32_bf16 v[76:79], v[118:121], v[198:201], v[76:79]
	v_mfma_f32_16x16x32_bf16 v[12:15], v[126:129], v[198:201], v[12:15]
	v_mfma_f32_16x16x32_bf16 v[68:71], v[118:121], v[206:209], v[68:71]
	v_mfma_f32_16x16x32_bf16 v[4:7], v[126:129], v[206:209], v[4:7]
	v_mfma_f32_16x16x32_bf16 v[92:95], v[122:125], v[166:169], v[92:95]
	v_mfma_f32_16x16x32_bf16 v[28:31], v[130:133], v[166:169], v[28:31]
	v_mfma_f32_16x16x32_bf16 v[84:87], v[122:125], v[174:177], v[84:87]
	v_mfma_f32_16x16x32_bf16 v[20:23], v[130:133], v[174:177], v[20:23]
	v_mfma_f32_16x16x32_bf16 v[76:79], v[122:125], v[202:205], v[76:79]
	v_mfma_f32_16x16x32_bf16 v[12:15], v[130:133], v[202:205], v[12:15]
	v_mfma_f32_16x16x32_bf16 v[68:71], v[122:125], v[228:231], v[68:71]
	v_mfma_f32_16x16x32_bf16 v[4:7], v[130:133], v[228:231], v[4:7]
	v_mfma_f32_16x16x32_bf16 v[88:91], v[134:137], v[162:165], v[88:91]
	v_mfma_f32_16x16x32_bf16 v[24:27], v[142:145], v[162:165], v[24:27]
	v_mfma_f32_16x16x32_bf16 v[80:83], v[134:137], v[170:173], v[80:83]
	v_mfma_f32_16x16x32_bf16 v[16:19], v[142:145], v[170:173], v[16:19]
	v_mfma_f32_16x16x32_bf16 v[72:75], v[134:137], v[198:201], v[72:75]
	v_mfma_f32_16x16x32_bf16 v[8:11], v[142:145], v[198:201], v[8:11]
	v_mfma_f32_16x16x32_bf16 v[64:67], v[134:137], v[206:209], v[64:67]
	v_mfma_f32_16x16x32_bf16 v[0:3], v[142:145], v[206:209], v[0:3]
	v_mfma_f32_16x16x32_bf16 v[88:91], v[138:141], v[166:169], v[88:91]
	v_mfma_f32_16x16x32_bf16 v[24:27], v[146:149], v[166:169], v[24:27]
	v_mfma_f32_16x16x32_bf16 v[80:83], v[138:141], v[174:177], v[80:83]
	v_mfma_f32_16x16x32_bf16 v[16:19], v[146:149], v[174:177], v[16:19]
	v_mfma_f32_16x16x32_bf16 v[72:75], v[138:141], v[202:205], v[72:75]
	v_mfma_f32_16x16x32_bf16 v[8:11], v[146:149], v[202:205], v[8:11]
	v_mfma_f32_16x16x32_bf16 v[64:67], v[138:141], v[228:231], v[64:67]
	v_mfma_f32_16x16x32_bf16 v[0:3], v[146:149], v[228:231], v[0:3]
	s_barrier
	s_add_i32 s97, s97, 2
	s_add_u32 s16, s16, 0x100
	s_addc_u32 s17, s17, 0
	s_add_u32 s89, s89, 0x100
	s_addc_u32 s96, s96, 0
	s_cmp_gt_u32 s97, 29
	s_cbranch_scc0 .LBB0_928
	v_readlane_b32 s0, v242, 20
	v_readlane_b32 s1, v242, 21
	s_and_b64 vcc, exec, s[0:1]
	s_cbranch_vccz .LBB0_931
	s_barrier

; __device__ __forceinline__ unsigned xb_ld(unsigned* p)              { return __hip_atomic_load(p, __ATOMIC_RELAXED, __HIP_MEMORY_SCOPE_AGENT); }
; __device__ __forceinline__ unsigned xb_add(unsigned* p, unsigned v) { return __hip_atomic_fetch_add(p, v, __ATOMIC_RELAXED, __HIP_MEMORY_SCOPE_AGENT); }
; __device__ __forceinline__ void xcd_barrier_complete(unsigned* bar, unsigned x, unsigned& nloc, unsigned& nx) {
;     const unsigned G = gridDim.x * gridDim.y * gridDim.z;
;     unsigned sum, cnt, mine, sp = 0u;
;     for (;;) {
;         sum = 0u; cnt = 0u; mine = 0u;
; #pragma unroll
;         for (unsigned j = 0; j < 16; ++j) { const unsigned c = xb_ld(&bar[XB_XCNT(j)]); sum += c; cnt += (c > 0u) ? 1u : 0u; mine = (j == x) ? c : mine; }
; __device__ __forceinline__ void xcd_barrier(const XcdBarrier& b) {
;     asm volatile("s_waitcnt vmcnt(0)" ::: "memory");
;     __syncthreads();
;     if (threadIdx.x == 0) {
;         unsigned* bar = b.bar;
;         __builtin_amdgcn_s_waitcnt(0);
;         unsigned nloc = b.st[0], nx = b.st[1];
;         if (nloc == 0u) { xcd_barrier_complete(bar, b.x, nloc, nx); b.st[0] = nloc; b.st[1] = nx; }
;         const unsigned old = xb_add(&bar[XB_XSUB(b.x)], 1u);
;         const unsigned gen = old / nloc;
.LBB0_971:
	s_cselect_b32 s100, 1, 0
	s_cmp_ge_u32 s98, 1
	s_cbranch_scc1 .Lrerun_done_P10
	s_add_u32 s98, s98, 1
	s_waitcnt vmcnt(0) lgkmcnt(0)
	s_barrier
	v_readlane_b32 s0, v243, 0
	v_readlane_b32 s1, v243, 1
	v_readlane_b32 s2, v243, 2
	v_readlane_b32 s3, v243, 3
	v_readlane_b32 s4, v243, 4
	v_readlane_b32 s5, v243, 5
	v_readlane_b32 s6, v243, 6
	v_readlane_b32 s7, v243, 7
	v_readlane_b32 s8, v243, 8
	v_readlane_b32 s9, v243, 9
	v_readlane_b32 s10, v243, 10
	v_readlane_b32 s11, v243, 11
	v_readlane_b32 s12, v243, 12
	v_readlane_b32 s13, v243, 13
	v_readlane_b32 s14, v243, 14
	v_readlane_b32 s15, v243, 15
	v_readlane_b32 s16, v243, 16
	v_readlane_b32 s17, v243, 17
	v_readlane_b32 s18, v243, 18
	v_readlane_b32 s19, v243, 19
	v_readlane_b32 s20, v243, 20
	v_readlane_b32 s21, v243, 21
	v_readlane_b32 s22, v243, 22
	v_readlane_b32 s23, v243, 23
	v_readlane_b32 s24, v243, 24
	v_readlane_b32 s25, v243, 25
	v_readlane_b32 s26, v243, 26
	v_readlane_b32 s27, v243, 27
	v_readlane_b32 s28, v243, 28
	v_readlane_b32 s29, v243, 29
	v_readlane_b32 s30, v243, 30
	v_readlane_b32 s31, v243, 31
	v_readlane_b32 s32, v243, 32
	v_readlane_b32 s33, v243, 33
	v_readlane_b32 s34, v243, 34
	v_readlane_b32 s35, v243, 35
	v_readlane_b32 s36, v243, 36
	v_readlane_b32 s37, v243, 37
	v_readlane_b32 s38, v243, 38
	v_readlane_b32 s39, v243, 39
	v_readlane_b32 s40, v243, 40
	v_readlane_b32 s41, v243, 41
	v_readlane_b32 s42, v243, 42
	v_readlane_b32 s43, v243, 43
	v_readlane_b32 s44, v243, 44
	v_readlane_b32 s45, v243, 45
	v_readlane_b32 s46, v243, 46
	v_readlane_b32 s47, v243, 47
	v_readlane_b32 s48, v243, 48
	v_readlane_b32 s49, v243, 49
	v_readlane_b32 s50, v243, 50
	v_readlane_b32 s51, v243, 51
	v_readlane_b32 s52, v243, 52
	v_readlane_b32 s53, v243, 53
	v_readlane_b32 s54, v243, 54
	v_readlane_b32 s55, v243, 55
	v_readlane_b32 s56, v243, 56
	v_readlane_b32 s57, v243, 57
	v_readlane_b32 s58, v243, 58
	v_readlane_b32 s59, v243, 59
	v_readlane_b32 s60, v243, 60
	v_readlane_b32 s61, v243, 61
	v_readlane_b32 s62, v243, 62
	v_readlane_b32 s63, v243, 63
	v_readlane_b32 s64, v244, 0
	v_readlane_b32 s65, v244, 1
	v_readlane_b32 s66, v244, 2
	v_readlane_b32 s67, v244, 3
	v_readlane_b32 s68, v244, 4
	v_readlane_b32 s69, v244, 5
	v_readlane_b32 s70, v244, 6
	v_readlane_b32 s71, v244, 7
	v_readlane_b32 s72, v244, 8
	v_readlane_b32 s73, v244, 9
	v_readlane_b32 s74, v244, 10
	v_readlane_b32 s75, v244, 11
	v_readlane_b32 s76, v244, 12
	v_readlane_b32 s77, v244, 13
	v_readlane_b32 s78, v244, 14
	v_readlane_b32 s79, v244, 15
	v_readlane_b32 s80, v244, 16
	v_readlane_b32 s81, v244, 17
	v_readlane_b32 s82, v244, 18
	v_readlane_b32 s83, v244, 19
	v_readlane_b32 s84, v244, 20
	v_readlane_b32 s85, v244, 21
	v_readlane_b32 s86, v244, 22
	v_readlane_b32 s87, v244, 23
	v_readlane_b32 s88, v244, 24
	v_readlane_b32 s89, v244, 25
	v_readlane_b32 s90, v244, 26
	v_readlane_b32 s91, v244, 27
	v_readlane_b32 s92, v244, 28
	v_readlane_b32 s93, v244, 29
	v_readlane_b32 s94, v244, 30
	v_readlane_b32 s95, v244, 31
	v_readlane_b32 s96, v244, 32
	v_readlane_b32 s97, v244, 33
	v_readlane_b32 vcc_lo, v244, 34
	v_readlane_b32 vcc_hi, v244, 35
	v_mov_b32_e32 v14, v245
	v_mov_b32_e32 v242, v246
	s_nop 7
	s_cmp_lg_u32 s99, 0
	s_branch .Lrerun_P10
.Lrerun_done_P10:
	s_nop 0
	s_nop 0
	s_nop 0
	s_nop 0
	s_nop 0
	s_nop 0
	s_nop 0
	s_nop 0
	s_nop 0
	s_nop 0
	s_nop 0
	s_nop 0
	s_cmp_lg_u32 s100, 0
	s_waitcnt vmcnt(0)
	s_barrier
	s_and_saveexec_b64 s[4:5], s[42:43]
	s_cbranch_execz .LBB0_1024
	s_add_i32 s0, 0, 0x26820
	v_mov_b32_e32 v0, s0
	s_waitcnt vmcnt(0) expcnt(0) lgkmcnt(0)
	ds_read_b32 v2, v0
	s_add_i32 s0, 0, 0x26824
	v_mov_b32_e32 v0, s0
	ds_read_b32 v0, v0
	s_waitcnt lgkmcnt(1)
	v_cmp_ne_u32_e32 vcc, 0, v2
	s_cbranch_vccnz .LBB0_988
	s_add_u32 s6, s26, 0x780200
	s_addc_u32 s7, s27, 0
	s_add_u32 s8, s26, 0x780400
	s_addc_u32 s9, s27, 0
	s_add_u32 s10, s26, 0x780500
	s_addc_u32 s11, s27, 0
	s_add_u32 s12, s26, 0x780600
	s_addc_u32 s13, s27, 0
	s_add_u32 s14, s26, 0x780700
	s_addc_u32 s15, s27, 0
	s_add_u32 s16, s26, 0x780800
	s_addc_u32 s17, s27, 0
	s_add_u32 s18, s26, 0x780900
	s_addc_u32 s19, s27, 0
	s_add_u32 s20, s26, 0x780a00
	s_addc_u32 s21, s27, 0
	s_add_u32 s40, s26, 0x780b00
	s_addc_u32 s41, s27, 0
	s_add_u32 s44, s26, 0x780c00
	s_addc_u32 s45, s27, 0
	s_add_u32 s46, s26, 0x780d00
	s_addc_u32 s47, s27, 0
	s_add_u32 s52, s26, 0x780e00
	s_addc_u32 s53, s27, 0
	s_add_u32 s56, s26, 0x780f00
	s_addc_u32 s57, s27, 0
	s_add_u32 s58, s26, 0x781000
	s_addc_u32 s59, s27, 0
	s_add_u32 s60, s26, 0x781100
	v_readlane_b32 s0, v242, 0
	s_addc_u32 s61, s27, 0
	s_mul_i32 s2, s25, s0
	s_add_u32 s0, s26, 0x781200
	s_addc_u32 s1, s27, 0
	s_add_u32 s28, s26, 0x781300
	s_mul_i32 s2, s2, s24
	s_addc_u32 s29, s27, 0
	s_mov_b32 s3, 1
	v_mov_b32_e32 v16, 0
	s_branch .LBB0_976

;     __device__ bool next(int i, Unit& u) const { if (i >= n) return false; const int q = first + i; u.pm = rowbase + q % rows; u.pn = q / rows; return true; }
; #define PG8_WAIT_V(n) asm volatile("s_waitcnt vmcnt(" #n ")" ::: "memory")
; template <class Epi, class Sched, bool ALIGN_EPI = false, bool SP2 = false>
; __device__ __forceinline__ void gemm_phase(PG8_LAS unsigned char* lds, const Gemm g, const Sched& S, const Epi& E) {
;     ...
;         const bool has_next = S.next(ui + 1, nxt);
;         const char* nA = has_next ? (const char*)g.A + (size_t)nxt.pm * tstep : cA; const char* nB = has_next ? (const char*)g.Bt + (size_t)nxt.pn * tstep : cB;
;         constexpr int NSEG = Epi::HAS_MID ? 2 : 1; const int tseg = nt / NSEG;
; #pragma unroll
;         for (int seg = 0; seg < NSEG; ++seg) {
;         if constexpr (Epi::HAS_MID) { if (seg == 1) E.mid(acc, cur, wr, wc, fr, fq); }
;         for (int t = seg * tseg; t < (seg + 1) * tseg; t += 2) {
;             const bool last = (t == nt - 2);
;             const char* a1 = cA + (size_t)(t + 1) * kstep;
;             const char* a2 = last ? nA : cA + (size_t)(t + 2) * kstep; const char* b2 = last ? nB : cB + (size_t)(t + 2) * kstep;
;             const char* a3 = a2 + kstep; const char* b3 = b2 + kstep;
;             if (last && has_next) S.a_ready(nxt);
;             if constexpr (SP2) {
;             PG8_LDB(B0, 0, 0); PG8_LDB(B1, 0, 1); PG8_SCHED; PG8_LDA(At, 0, 0); PG8_STAGE(PG8_SA(1, 1), a1 + hstep, voffA);
;             PG8_WAIT_V(8); PG8_WAIT_L(0); PG8_BAR; PG8_MMA(0, 0, At, B0); PG8_MMA(0, 1, At, B1); PG8_BAR; PG8_SCHED;
;             PG8_LDA(At, 0, 1); PG8_STAGE(PG8_SB(0, 0), b2, voffB); PG8_STAGE(PG8_SB(0, 1), b2 + hstep, voffB); PG8_STAGE(PG8_SA(0, 0), a2, voffA);
;             PG8_WAIT_V(8); PG8_WAIT_L(0); PG8_BAR; PG8_MMA(1, 0, At, B0); PG8_MMA(1, 1, At, B1); PG8_BAR; PG8_SCHED;
;             PG8_LDB(B0, 1, 0); PG8_LDB(B1, 1, 1); PG8_SCHED; PG8_LDA(At, 1, 0); PG8_STAGE(PG8_SA(0, 1), a2 + hstep, voffA);
;             PG8_WAIT_V(8); PG8_WAIT_L(0); PG8_BAR; PG8_MMA(0, 0, At, B0); PG8_MMA(0, 1, At, B1); PG8_BAR; PG8_SCHED;
;             PG8_LDA(At, 1, 1); PG8_STAGE(PG8_SB(1, 0), b3, voffB); PG8_STAGE(PG8_SB(1, 1), b3 + hstep, voffB); PG8_STAGE(PG8_SA(1, 0), a3, voffA);
;             PG8_WAIT_V(8); PG8_WAIT_L(0); PG8_BAR; PG8_MMA(1, 0, At, B0); PG8_MMA(1, 1, At, B1); PG8_BAR; PG8_SCHED;
.LBB0_1100:
	s_add_u32 s0, s38, 0x100
	s_addc_u32 s1, s39, 0
	s_mov_b32 s59, -2
	ds_read_b128 v[120:123], v169
	ds_read_b128 v[124:127], v169 offset:1024
	ds_read_b128 v[128:131], v169 offset:2048
	ds_read_b128 v[132:135], v169 offset:3072
	ds_read_b128 v[160:163], v170
	ds_read_b128 v[172:175], v170 offset:1024
	ds_read_b128 v[176:179], v170 offset:2048
	ds_read_b128 v[180:183], v170 offset:3072
	s_add_u32 s38, s34, 0x100
	s_addc_u32 s39, s35, 0
	s_cmpk_eq_i32 s59, 0x54
	s_cselect_b32 s43, s5, s39
	s_cselect_b32 s42, s4, s38
	s_cselect_b32 s41, s21, s1
	s_cselect_b32 s40, s20, s0
	v_lshl_add_u64 v[164:165], s[34:35], 0, v[152:153]
	s_add_i32 m0, s28, 0xc000
	ds_read_b128 v[184:187], v171
	ds_read_b128 v[190:193], v171 offset:1024
	ds_read_b128 v[194:197], v171 offset:2048
	ds_read_b128 v[198:201], v171 offset:3072
	ds_read_b128 v[202:205], v171 offset:4096
	ds_read_b128 v[206:209], v171 offset:5120
	ds_read_b128 v[214:217], v171 offset:6144
	ds_read_b128 v[218:221], v171 offset:7168
	global_load_lds_dwordx4 v[164:165], off
	v_lshl_add_u64 v[164:165], s[34:35], 0, v[154:155]
	s_add_i32 m0, s28, 0xe000
	s_nop 0
	global_load_lds_dwordx4 v[164:165], off
	s_waitcnt vmcnt(8)
	s_waitcnt lgkmcnt(0)
	s_barrier
	s_waitcnt lgkmcnt(0)
	v_mfma_f32_16x16x32_bf16 v[140:143], v[120:123], v[184:187], 0
	v_mfma_f32_16x16x32_bf16 v[136:139], v[128:131], v[184:187], 0
	v_mfma_f32_16x16x32_bf16 v[116:119], v[120:123], v[194:197], 0
	v_mfma_f32_16x16x32_bf16 v[104:107], v[128:131], v[194:197], 0
	v_mfma_f32_16x16x32_bf16 v[100:103], v[120:123], v[202:205], 0
	v_mfma_f32_16x16x32_bf16 v[88:91], v[128:131], v[202:205], 0
	v_mfma_f32_16x16x32_bf16 v[84:87], v[120:123], v[214:217], 0
	v_mfma_f32_16x16x32_bf16 v[72:75], v[128:131], v[214:217], 0
	v_mfma_f32_16x16x32_bf16 v[140:143], v[124:127], v[190:193], v[140:143]
	v_mfma_f32_16x16x32_bf16 v[136:139], v[132:135], v[190:193], v[136:139]
	v_mfma_f32_16x16x32_bf16 v[116:119], v[124:127], v[198:201], v[116:119]
	v_mfma_f32_16x16x32_bf16 v[104:107], v[132:135], v[198:201], v[104:107]
	v_mfma_f32_16x16x32_bf16 v[100:103], v[124:127], v[206:209], v[100:103]
	v_mfma_f32_16x16x32_bf16 v[88:91], v[132:135], v[206:209], v[88:91]
	v_mfma_f32_16x16x32_bf16 v[84:87], v[124:127], v[218:221], v[84:87]
	v_mfma_f32_16x16x32_bf16 v[72:75], v[132:135], v[218:221], v[72:75]
	v_mfma_f32_16x16x32_bf16 v[112:115], v[160:163], v[184:187], 0
	v_mfma_f32_16x16x32_bf16 v[108:111], v[176:179], v[184:187], 0
	v_mfma_f32_16x16x32_bf16 v[96:99], v[160:163], v[194:197], 0
	v_mfma_f32_16x16x32_bf16 v[92:95], v[176:179], v[194:197], 0
	v_mfma_f32_16x16x32_bf16 v[80:83], v[160:163], v[202:205], 0
	v_mfma_f32_16x16x32_bf16 v[76:79], v[176:179], v[202:205], 0
	v_mfma_f32_16x16x32_bf16 v[68:71], v[160:163], v[214:217], 0
	v_mfma_f32_16x16x32_bf16 v[64:67], v[176:179], v[214:217], 0
	v_mfma_f32_16x16x32_bf16 v[112:115], v[172:175], v[190:193], v[112:115]
	v_mfma_f32_16x16x32_bf16 v[108:111], v[180:183], v[190:193], v[108:111]
	v_mfma_f32_16x16x32_bf16 v[96:99], v[172:175], v[198:201], v[96:99]
	v_mfma_f32_16x16x32_bf16 v[92:95], v[180:183], v[198:201], v[92:95]
	v_mfma_f32_16x16x32_bf16 v[80:83], v[172:175], v[206:209], v[80:83]
	v_mfma_f32_16x16x32_bf16 v[76:79], v[180:183], v[206:209], v[76:79]
	v_mfma_f32_16x16x32_bf16 v[68:71], v[172:175], v[218:221], v[68:71]
	v_mfma_f32_16x16x32_bf16 v[64:67], v[180:183], v[218:221], v[64:67]
	s_barrier
	s_add_i32 s22, s31, s23
	v_lshl_add_u64 v[164:165], s[40:41], 0, v[146:147]
	s_mov_b32 m0, s22
	ds_read_b128 v[184:187], v171 offset:16384
	ds_read_b128 v[190:193], v171 offset:17408
	ds_read_b128 v[194:197], v171 offset:18432
	ds_read_b128 v[198:201], v171 offset:19456
	ds_read_b128 v[202:205], v171 offset:20480
	ds_read_b128 v[206:209], v171 offset:21504
	ds_read_b128 v[214:217], v171 offset:22528
	ds_read_b128 v[218:221], v171 offset:23552
	global_load_lds_dwordx4 v[164:165], off
	s_add_i32 m0, s22, 0x2000
	s_add_u32 s34, s40, 0x160000
	v_lshl_add_u64 v[210:211], s[40:41], 0, v[150:151]
	s_addc_u32 s35, s41, 0
	s_add_i32 s22, s74, s23
	global_load_lds_dwordx4 v[210:211], off
	v_lshl_add_u64 v[222:223], s[34:35], 0, v[146:147]
	s_mov_b32 m0, s22
	v_lshl_add_u64 v[224:225], s[42:43], 0, v[148:149]
	global_load_lds_dwordx4 v[222:223], off
	v_lshl_add_u64 v[222:223], s[34:35], 0, v[150:151]
	s_add_i32 m0, s22, 0x2000
	s_nop 0
	global_load_lds_dwordx4 v[222:223], off
	v_lshl_add_u64 v[222:223], s[42:43], 0, v[144:145]
	s_mov_b32 m0, s28
	s_nop 0
	global_load_lds_dwordx4 v[222:223], off
	s_mov_b32 m0, s29
	s_nop 0
	global_load_lds_dwordx4 v[224:225], off
	s_waitcnt vmcnt(8)
	s_waitcnt lgkmcnt(0)
	s_barrier
; #define PG8_STAGE(bufoff, gbase, voff) do { _Pragma("unroll") for (int _i = 0; _i < 2; ++_i) \
;         __builtin_amdgcn_global_load_lds((const unsigned*)((const char*)(gbase) + (voff)[_i]), (PG8_LAS unsigned*)(lds + (bufoff) + ldsw + _i * 8192), 16, 0, 0); } while (0)
; #define PG8_LDA(dst, b, h) do { _Pragma("unroll") for (int m = 0; m < 4; ++m) _Pragma("unroll") for (int k = 0; k < 2; ++k) dst[m][k] = *(const PG8_LAS bf16x8*)(lds + PG8_SA(b, h) + aoff + m * 2048 + k * 1024); } while (0)
; #define PG8_WAIT_V(n) asm volatile("s_waitcnt vmcnt(" #n ")" ::: "memory")
; #define PG8_WAIT_L(n) asm volatile("s_waitcnt lgkmcnt(" #n ")" ::: "memory")
; #define PG8_BAR __builtin_amdgcn_s_barrier()
; template <class Epi, class Sched, bool ALIGN_EPI = false, bool SP2 = false>
; __device__ __forceinline__ void gemm_phase(PG8_LAS unsigned char* lds, const Gemm g, const Sched& S, const Epi& E) {
;     ...
;         for (int t = seg * tseg; t < (seg + 1) * tseg; t += 2) {
;             const bool last = (t == nt - 2);
;             const char* a1 = cA + (size_t)(t + 1) * kstep;
;             const char* a2 = last ? nA : cA + (size_t)(t + 2) * kstep; const char* b2 = last ? nB : cB + (size_t)(t + 2) * kstep;
;             const char* a3 = a2 + kstep; const char* b3 = b2 + kstep;
;             if (last && has_next) S.a_ready(nxt);
;             if constexpr (SP2) {
;             PG8_LDB(B0, 0, 0); PG8_LDB(B1, 0, 1); PG8_SCHED; PG8_LDA(At, 0, 0); PG8_STAGE(PG8_SA(1, 1), a1 + hstep, voffA);
;             PG8_WAIT_V(8); PG8_WAIT_L(0); PG8_BAR; PG8_MMA(0, 0, At, B0); PG8_MMA(0, 1, At, B1); PG8_BAR; PG8_SCHED;
;             PG8_LDA(At, 0, 1); PG8_STAGE(PG8_SB(0, 0), b2, voffB); PG8_STAGE(PG8_SB(0, 1), b2 + hstep, voffB); PG8_STAGE(PG8_SA(0, 0), a2, voffA);
;             PG8_WAIT_V(8); PG8_WAIT_L(0); PG8_BAR; PG8_MMA(1, 0, At, B0); PG8_MMA(1, 1, At, B1); PG8_BAR; PG8_SCHED;
;             PG8_LDB(B0, 1, 0); PG8_LDB(B1, 1, 1); PG8_SCHED; PG8_LDA(At, 1, 0); PG8_STAGE(PG8_SA(0, 1), a2 + hstep, voffA);
;             PG8_WAIT_V(8); PG8_WAIT_L(0); PG8_BAR; PG8_MMA(0, 0, At, B0); PG8_MMA(0, 1, At, B1); PG8_BAR; PG8_SCHED;
;             PG8_LDA(At, 1, 1); PG8_STAGE(PG8_SB(1, 0), b3, voffB); PG8_STAGE(PG8_SB(1, 1), b3 + hstep, voffB); PG8_STAGE(PG8_SA(1, 0), a3, voffA);
;             PG8_WAIT_V(8); PG8_WAIT_L(0); PG8_BAR; PG8_MMA(1, 0, At, B0); PG8_MMA(1, 1, At, B1); PG8_BAR; PG8_SCHED;
	s_waitcnt lgkmcnt(0)
	v_mfma_f32_16x16x32_bf16 v[60:63], v[120:123], v[184:187], 0
	v_mfma_f32_16x16x32_bf16 v[56:59], v[128:131], v[184:187], 0
	v_mfma_f32_16x16x32_bf16 v[52:55], v[120:123], v[194:197], 0
	v_mfma_f32_16x16x32_bf16 v[40:43], v[128:131], v[194:197], 0
	v_mfma_f32_16x16x32_bf16 v[36:39], v[120:123], v[202:205], 0
	v_mfma_f32_16x16x32_bf16 v[24:27], v[128:131], v[202:205], 0
	v_mfma_f32_16x16x32_bf16 v[20:23], v[120:123], v[214:217], 0
	v_mfma_f32_16x16x32_bf16 v[8:11], v[128:131], v[214:217], 0
	v_mfma_f32_16x16x32_bf16 v[60:63], v[124:127], v[190:193], v[60:63]
	v_mfma_f32_16x16x32_bf16 v[56:59], v[132:135], v[190:193], v[56:59]
	v_mfma_f32_16x16x32_bf16 v[52:55], v[124:127], v[198:201], v[52:55]
	v_mfma_f32_16x16x32_bf16 v[40:43], v[132:135], v[198:201], v[40:43]
	v_mfma_f32_16x16x32_bf16 v[36:39], v[124:127], v[206:209], v[36:39]
	v_mfma_f32_16x16x32_bf16 v[24:27], v[132:135], v[206:209], v[24:27]
	v_mfma_f32_16x16x32_bf16 v[20:23], v[124:127], v[218:221], v[20:23]
	v_mfma_f32_16x16x32_bf16 v[8:11], v[132:135], v[218:221], v[8:11]
	v_mfma_f32_16x16x32_bf16 v[48:51], v[160:163], v[184:187], 0
	v_mfma_f32_16x16x32_bf16 v[44:47], v[176:179], v[184:187], 0
	v_mfma_f32_16x16x32_bf16 v[32:35], v[160:163], v[194:197], 0
	v_mfma_f32_16x16x32_bf16 v[28:31], v[176:179], v[194:197], 0
	v_mfma_f32_16x16x32_bf16 v[16:19], v[160:163], v[202:205], 0
	v_mfma_f32_16x16x32_bf16 v[12:15], v[176:179], v[202:205], 0
	v_mfma_f32_16x16x32_bf16 v[4:7], v[160:163], v[214:217], 0
	v_mfma_f32_16x16x32_bf16 v[0:3], v[176:179], v[214:217], 0
	v_mfma_f32_16x16x32_bf16 v[48:51], v[172:175], v[190:193], v[48:51]
	v_mfma_f32_16x16x32_bf16 v[44:47], v[180:183], v[190:193], v[44:47]
	v_mfma_f32_16x16x32_bf16 v[32:35], v[172:175], v[198:201], v[32:35]
	v_mfma_f32_16x16x32_bf16 v[28:31], v[180:183], v[198:201], v[28:31]
	v_mfma_f32_16x16x32_bf16 v[16:19], v[172:175], v[206:209], v[16:19]
	v_mfma_f32_16x16x32_bf16 v[12:15], v[180:183], v[206:209], v[12:15]
	v_mfma_f32_16x16x32_bf16 v[4:7], v[172:175], v[218:221], v[4:7]
	v_mfma_f32_16x16x32_bf16 v[0:3], v[180:183], v[218:221], v[0:3]
	s_barrier
	v_add_u32_e32 v132, s75, v167
	v_add_u32_e32 v180, s84, v167
	ds_read_b128 v[120:123], v132
	ds_read_b128 v[124:127], v132 offset:1024
	ds_read_b128 v[128:131], v132 offset:2048
	ds_read_b128 v[132:135], v132 offset:3072
	ds_read_b128 v[160:163], v180
	ds_read_b128 v[172:175], v180 offset:1024
	ds_read_b128 v[176:179], v180 offset:2048
	ds_read_b128 v[180:183], v180 offset:3072
	s_add_u32 s34, s42, 0x160000
	s_addc_u32 s35, s43, 0
	s_mov_b32 m0, s30
	v_lshl_add_u64 v[226:227], s[34:35], 0, v[144:145]
	ds_read_b128 v[184:187], v171 offset:32768
	ds_read_b128 v[190:193], v171 offset:33792
	ds_read_b128 v[194:197], v171 offset:34816
	ds_read_b128 v[198:201], v171 offset:35840
	ds_read_b128 v[202:205], v171 offset:36864
	ds_read_b128 v[206:209], v171 offset:37888
	ds_read_b128 v[214:217], v171 offset:38912
	ds_read_b128 v[218:221], v171 offset:39936
	global_load_lds_dwordx4 v[226:227], off
	v_lshl_add_u64 v[226:227], s[34:35], 0, v[148:149]
	s_mov_b32 m0, s33
	s_nop 0
	global_load_lds_dwordx4 v[226:227], off
	s_waitcnt vmcnt(8)
	s_waitcnt lgkmcnt(0)
	s_barrier
	s_waitcnt lgkmcnt(0)
	v_mfma_f32_16x16x32_bf16 v[140:143], v[120:123], v[184:187], v[140:143]
	v_mfma_f32_16x16x32_bf16 v[136:139], v[128:131], v[184:187], v[136:139]
	v_mfma_f32_16x16x32_bf16 v[116:119], v[120:123], v[194:197], v[116:119]
	v_mfma_f32_16x16x32_bf16 v[104:107], v[128:131], v[194:197], v[104:107]
	v_mfma_f32_16x16x32_bf16 v[100:103], v[120:123], v[202:205], v[100:103]
	v_mfma_f32_16x16x32_bf16 v[88:91], v[128:131], v[202:205], v[88:91]
	v_mfma_f32_16x16x32_bf16 v[84:87], v[120:123], v[214:217], v[84:87]
	v_mfma_f32_16x16x32_bf16 v[72:75], v[128:131], v[214:217], v[72:75]
	v_mfma_f32_16x16x32_bf16 v[140:143], v[124:127], v[190:193], v[140:143]
	v_mfma_f32_16x16x32_bf16 v[136:139], v[132:135], v[190:193], v[136:139]
	v_mfma_f32_16x16x32_bf16 v[116:119], v[124:127], v[198:201], v[116:119]
	v_mfma_f32_16x16x32_bf16 v[104:107], v[132:135], v[198:201], v[104:107]
	v_mfma_f32_16x16x32_bf16 v[100:103], v[124:127], v[206:209], v[100:103]
	v_mfma_f32_16x16x32_bf16 v[88:91], v[132:135], v[206:209], v[88:91]
	v_mfma_f32_16x16x32_bf16 v[84:87], v[124:127], v[218:221], v[84:87]
	v_mfma_f32_16x16x32_bf16 v[72:75], v[132:135], v[218:221], v[72:75]
	v_mfma_f32_16x16x32_bf16 v[112:115], v[160:163], v[184:187], v[112:115]
	v_mfma_f32_16x16x32_bf16 v[108:111], v[176:179], v[184:187], v[108:111]
	v_mfma_f32_16x16x32_bf16 v[96:99], v[160:163], v[194:197], v[96:99]
	v_mfma_f32_16x16x32_bf16 v[92:95], v[176:179], v[194:197], v[92:95]
	v_mfma_f32_16x16x32_bf16 v[80:83], v[160:163], v[202:205], v[80:83]
	v_mfma_f32_16x16x32_bf16 v[76:79], v[176:179], v[202:205], v[76:79]
	v_mfma_f32_16x16x32_bf16 v[68:71], v[160:163], v[214:217], v[68:71]
	v_mfma_f32_16x16x32_bf16 v[64:67], v[176:179], v[214:217], v[64:67]
	v_mfma_f32_16x16x32_bf16 v[112:115], v[172:175], v[190:193], v[112:115]
	v_mfma_f32_16x16x32_bf16 v[108:111], v[180:183], v[190:193], v[108:111]
	v_mfma_f32_16x16x32_bf16 v[96:99], v[172:175], v[198:201], v[96:99]
	v_mfma_f32_16x16x32_bf16 v[92:95], v[180:183], v[198:201], v[92:95]
	v_mfma_f32_16x16x32_bf16 v[80:83], v[172:175], v[206:209], v[80:83]
	v_mfma_f32_16x16x32_bf16 v[76:79], v[180:183], v[206:209], v[76:79]
	v_mfma_f32_16x16x32_bf16 v[68:71], v[172:175], v[218:221], v[68:71]
	v_mfma_f32_16x16x32_bf16 v[64:67], v[180:183], v[218:221], v[64:67]
	s_barrier
; #define PG8_STAGE(bufoff, gbase, voff) do { _Pragma("unroll") for (int _i = 0; _i < 2; ++_i) \
;         __builtin_amdgcn_global_load_lds((const unsigned*)((const char*)(gbase) + (voff)[_i]), (PG8_LAS unsigned*)(lds + (bufoff) + ldsw + _i * 8192), 16, 0, 0); } while (0)
; #define PG8_LDA(dst, b, h) do { _Pragma("unroll") for (int m = 0; m < 4; ++m) _Pragma("unroll") for (int k = 0; k < 2; ++k) dst[m][k] = *(const PG8_LAS bf16x8*)(lds + PG8_SA(b, h) + aoff + m * 2048 + k * 1024); } while (0)
; #define PG8_WAIT_V(n) asm volatile("s_waitcnt vmcnt(" #n ")" ::: "memory")
; #define PG8_WAIT_L(n) asm volatile("s_waitcnt lgkmcnt(" #n ")" ::: "memory")
; #define PG8_BAR __builtin_amdgcn_s_barrier()
; template <class Epi, class Sched, bool ALIGN_EPI = false, bool SP2 = false>
; __device__ __forceinline__ void gemm_phase(PG8_LAS unsigned char* lds, const Gemm g, const Sched& S, const Epi& E) {
;     ...
;         for (int t = seg * tseg; t < (seg + 1) * tseg; t += 2) {
;             const bool last = (t == nt - 2);
;             const char* a1 = cA + (size_t)(t + 1) * kstep;
;             const char* a2 = last ? nA : cA + (size_t)(t + 2) * kstep; const char* b2 = last ? nB : cB + (size_t)(t + 2) * kstep;
;             const char* a3 = a2 + kstep; const char* b3 = b2 + kstep;
;             if (last && has_next) S.a_ready(nxt);
;             if constexpr (SP2) {
;             PG8_LDB(B0, 0, 0); PG8_LDB(B1, 0, 1); PG8_SCHED; PG8_LDA(At, 0, 0); PG8_STAGE(PG8_SA(1, 1), a1 + hstep, voffA);
;             PG8_WAIT_V(8); PG8_WAIT_L(0); PG8_BAR; PG8_MMA(0, 0, At, B0); PG8_MMA(0, 1, At, B1); PG8_BAR; PG8_SCHED;
;             PG8_LDA(At, 0, 1); PG8_STAGE(PG8_SB(0, 0), b2, voffB); PG8_STAGE(PG8_SB(0, 1), b2 + hstep, voffB); PG8_STAGE(PG8_SA(0, 0), a2, voffA);
;             PG8_WAIT_V(8); PG8_WAIT_L(0); PG8_BAR; PG8_MMA(1, 0, At, B0); PG8_MMA(1, 1, At, B1); PG8_BAR; PG8_SCHED;
;             PG8_LDB(B0, 1, 0); PG8_LDB(B1, 1, 1); PG8_SCHED; PG8_LDA(At, 1, 0); PG8_STAGE(PG8_SA(0, 1), a2 + hstep, voffA);
;             PG8_WAIT_V(8); PG8_WAIT_L(0); PG8_BAR; PG8_MMA(0, 0, At, B0); PG8_MMA(0, 1, At, B1); PG8_BAR; PG8_SCHED;
;             PG8_LDA(At, 1, 1); PG8_STAGE(PG8_SB(1, 0), b3, voffB); PG8_STAGE(PG8_SB(1, 1), b3 + hstep, voffB); PG8_STAGE(PG8_SA(1, 0), a3, voffA);
;             PG8_WAIT_V(8); PG8_WAIT_L(0); PG8_BAR; PG8_MMA(1, 0, At, B0); PG8_MMA(1, 1, At, B1); PG8_BAR; PG8_SCHED;
	s_add_i32 s22, s75, s23
	v_lshl_add_u64 v[164:165], v[164:165], 0, s[8:9]
	s_mov_b32 m0, s22
	ds_read_b128 v[184:187], v171 offset:49152
	ds_read_b128 v[190:193], v171 offset:50176
	ds_read_b128 v[194:197], v171 offset:51200
	ds_read_b128 v[198:201], v171 offset:52224
	ds_read_b128 v[202:205], v171 offset:53248
	ds_read_b128 v[206:209], v171 offset:54272
	ds_read_b128 v[214:217], v171 offset:55296
	ds_read_b128 v[218:221], v171 offset:56320
	global_load_lds_dwordx4 v[164:165], off
	s_add_i32 m0, s22, 0x2000
	s_add_u32 s34, s40, 0x160080
	v_lshl_add_u64 v[164:165], v[210:211], 0, s[8:9]
	s_addc_u32 s35, s41, 0
	s_add_i32 s22, s84, s23
	global_load_lds_dwordx4 v[164:165], off
	v_lshl_add_u64 v[164:165], s[34:35], 0, v[146:147]
	s_mov_b32 m0, s22
	s_nop 0
	global_load_lds_dwordx4 v[164:165], off
	v_lshl_add_u64 v[164:165], s[34:35], 0, v[150:151]
	s_add_i32 m0, s22, 0x2000
	s_nop 0
	global_load_lds_dwordx4 v[164:165], off
	v_lshl_add_u64 v[164:165], v[222:223], 0, s[8:9]
	s_mov_b32 m0, s47
	s_nop 0
	global_load_lds_dwordx4 v[164:165], off
	v_lshl_add_u64 v[164:165], v[224:225], 0, s[8:9]
	s_mov_b32 m0, s52
	s_nop 0
	global_load_lds_dwordx4 v[164:165], off
	s_waitcnt vmcnt(8)
	s_waitcnt lgkmcnt(0)
	s_barrier
	s_waitcnt lgkmcnt(0)
	v_mfma_f32_16x16x32_bf16 v[60:63], v[120:123], v[184:187], v[60:63]
	v_mfma_f32_16x16x32_bf16 v[56:59], v[128:131], v[184:187], v[56:59]
	v_mfma_f32_16x16x32_bf16 v[52:55], v[120:123], v[194:197], v[52:55]
	v_mfma_f32_16x16x32_bf16 v[40:43], v[128:131], v[194:197], v[40:43]
	v_mfma_f32_16x16x32_bf16 v[36:39], v[120:123], v[202:205], v[36:39]
	v_mfma_f32_16x16x32_bf16 v[24:27], v[128:131], v[202:205], v[24:27]
	v_mfma_f32_16x16x32_bf16 v[20:23], v[120:123], v[214:217], v[20:23]
	v_mfma_f32_16x16x32_bf16 v[8:11], v[128:131], v[214:217], v[8:11]
	v_mfma_f32_16x16x32_bf16 v[60:63], v[124:127], v[190:193], v[60:63]
	v_mfma_f32_16x16x32_bf16 v[56:59], v[132:135], v[190:193], v[56:59]
	v_mfma_f32_16x16x32_bf16 v[52:55], v[124:127], v[198:201], v[52:55]
	v_mfma_f32_16x16x32_bf16 v[40:43], v[132:135], v[198:201], v[40:43]
	v_mfma_f32_16x16x32_bf16 v[36:39], v[124:127], v[206:209], v[36:39]
	v_mfma_f32_16x16x32_bf16 v[24:27], v[132:135], v[206:209], v[24:27]
	v_mfma_f32_16x16x32_bf16 v[20:23], v[124:127], v[218:221], v[20:23]
	v_mfma_f32_16x16x32_bf16 v[8:11], v[132:135], v[218:221], v[8:11]
	v_mfma_f32_16x16x32_bf16 v[48:51], v[160:163], v[184:187], v[48:51]
	v_mfma_f32_16x16x32_bf16 v[44:47], v[176:179], v[184:187], v[44:47]
	v_mfma_f32_16x16x32_bf16 v[32:35], v[160:163], v[194:197], v[32:35]
	v_mfma_f32_16x16x32_bf16 v[28:31], v[176:179], v[194:197], v[28:31]
	v_mfma_f32_16x16x32_bf16 v[16:19], v[160:163], v[202:205], v[16:19]
	v_mfma_f32_16x16x32_bf16 v[12:15], v[176:179], v[202:205], v[12:15]
	v_mfma_f32_16x16x32_bf16 v[4:7], v[160:163], v[214:217], v[4:7]
	v_mfma_f32_16x16x32_bf16 v[0:3], v[176:179], v[214:217], v[0:3]
	v_mfma_f32_16x16x32_bf16 v[48:51], v[172:175], v[190:193], v[48:51]
	v_mfma_f32_16x16x32_bf16 v[44:47], v[180:183], v[190:193], v[44:47]
	v_mfma_f32_16x16x32_bf16 v[32:35], v[172:175], v[198:201], v[32:35]
	v_mfma_f32_16x16x32_bf16 v[28:31], v[180:183], v[198:201], v[28:31]
	v_mfma_f32_16x16x32_bf16 v[16:19], v[172:175], v[206:209], v[16:19]
	v_mfma_f32_16x16x32_bf16 v[12:15], v[180:183], v[206:209], v[12:15]
	v_mfma_f32_16x16x32_bf16 v[4:7], v[172:175], v[218:221], v[4:7]
	v_mfma_f32_16x16x32_bf16 v[0:3], v[180:183], v[218:221], v[0:3]
	s_barrier
	s_add_i32 s59, s59, 2
	s_add_u32 s0, s0, 0x100
	s_addc_u32 s1, s1, 0
	s_cmpk_gt_u32 s59, 0x55
	s_mov_b64 s[34:35], s[38:39]
.LBB0_1101:
	ds_read_b128 v[120:123], v169
	ds_read_b128 v[124:127], v169 offset:1024
	ds_read_b128 v[128:131], v169 offset:2048
	ds_read_b128 v[132:135], v169 offset:3072
	ds_read_b128 v[160:163], v170
	ds_read_b128 v[172:175], v170 offset:1024
	ds_read_b128 v[176:179], v170 offset:2048
	ds_read_b128 v[180:183], v170 offset:3072
	s_add_u32 s38, s34, 0x100
	s_addc_u32 s39, s35, 0
	s_cmpk_eq_i32 s59, 0x54
	s_cselect_b32 s43, s5, s39
	s_cselect_b32 s42, s4, s38
	s_cselect_b32 s41, s21, s1
	s_cselect_b32 s40, s20, s0
	v_lshl_add_u64 v[164:165], s[34:35], 0, v[152:153]
	s_add_i32 m0, s28, 0xc000
	ds_read_b128 v[184:187], v171
	ds_read_b128 v[190:193], v171 offset:1024
	ds_read_b128 v[194:197], v171 offset:2048
	ds_read_b128 v[198:201], v171 offset:3072
	ds_read_b128 v[202:205], v171 offset:4096
	ds_read_b128 v[206:209], v171 offset:5120
	ds_read_b128 v[214:217], v171 offset:6144
	ds_read_b128 v[218:221], v171 offset:7168
	global_load_lds_dwordx4 v[164:165], off
	v_lshl_add_u64 v[164:165], s[34:35], 0, v[154:155]
	s_add_i32 m0, s28, 0xe000
	s_nop 0
	global_load_lds_dwordx4 v[164:165], off
	s_waitcnt vmcnt(8)
	s_waitcnt lgkmcnt(0)
	s_barrier
; #define PG8_STAGE(bufoff, gbase, voff) do { _Pragma("unroll") for (int _i = 0; _i < 2; ++_i) \
;         __builtin_amdgcn_global_load_lds((const unsigned*)((const char*)(gbase) + (voff)[_i]), (PG8_LAS unsigned*)(lds + (bufoff) + ldsw + _i * 8192), 16, 0, 0); } while (0)
; #define PG8_LDA(dst, b, h) do { _Pragma("unroll") for (int m = 0; m < 4; ++m) _Pragma("unroll") for (int k = 0; k < 2; ++k) dst[m][k] = *(const PG8_LAS bf16x8*)(lds + PG8_SA(b, h) + aoff + m * 2048 + k * 1024); } while (0)
; #define PG8_WAIT_V(n) asm volatile("s_waitcnt vmcnt(" #n ")" ::: "memory")
; #define PG8_WAIT_L(n) asm volatile("s_waitcnt lgkmcnt(" #n ")" ::: "memory")
; #define PG8_BAR __builtin_amdgcn_s_barrier()
; template <class Epi, class Sched, bool ALIGN_EPI = false, bool SP2 = false>
; __device__ __forceinline__ void gemm_phase(PG8_LAS unsigned char* lds, const Gemm g, const Sched& S, const Epi& E) {
;     ...
;         for (int t = seg * tseg; t < (seg + 1) * tseg; t += 2) {
;             const bool last = (t == nt - 2);
;             const char* a1 = cA + (size_t)(t + 1) * kstep;
;             const char* a2 = last ? nA : cA + (size_t)(t + 2) * kstep; const char* b2 = last ? nB : cB + (size_t)(t + 2) * kstep;
;             const char* a3 = a2 + kstep; const char* b3 = b2 + kstep;
;             if (last && has_next) S.a_ready(nxt);
;             if constexpr (SP2) {
;             PG8_LDB(B0, 0, 0); PG8_LDB(B1, 0, 1); PG8_SCHED; PG8_LDA(At, 0, 0); PG8_STAGE(PG8_SA(1, 1), a1 + hstep, voffA);
;             PG8_WAIT_V(8); PG8_WAIT_L(0); PG8_BAR; PG8_MMA(0, 0, At, B0); PG8_MMA(0, 1, At, B1); PG8_BAR; PG8_SCHED;
;             PG8_LDA(At, 0, 1); PG8_STAGE(PG8_SB(0, 0), b2, voffB); PG8_STAGE(PG8_SB(0, 1), b2 + hstep, voffB); PG8_STAGE(PG8_SA(0, 0), a2, voffA);
;             PG8_WAIT_V(8); PG8_WAIT_L(0); PG8_BAR; PG8_MMA(1, 0, At, B0); PG8_MMA(1, 1, At, B1); PG8_BAR; PG8_SCHED;
;             PG8_LDB(B0, 1, 0); PG8_LDB(B1, 1, 1); PG8_SCHED; PG8_LDA(At, 1, 0); PG8_STAGE(PG8_SA(0, 1), a2 + hstep, voffA);
;             PG8_WAIT_V(8); PG8_WAIT_L(0); PG8_BAR; PG8_MMA(0, 0, At, B0); PG8_MMA(0, 1, At, B1); PG8_BAR; PG8_SCHED;
;             PG8_LDA(At, 1, 1); PG8_STAGE(PG8_SB(1, 0), b3, voffB); PG8_STAGE(PG8_SB(1, 1), b3 + hstep, voffB); PG8_STAGE(PG8_SA(1, 0), a3, voffA);
;             PG8_WAIT_V(8); PG8_WAIT_L(0); PG8_BAR; PG8_MMA(1, 0, At, B0); PG8_MMA(1, 1, At, B1); PG8_BAR; PG8_SCHED;
	s_waitcnt lgkmcnt(0)
	v_mfma_f32_16x16x32_bf16 v[140:143], v[120:123], v[184:187], v[140:143]
	v_mfma_f32_16x16x32_bf16 v[136:139], v[128:131], v[184:187], v[136:139]
	v_mfma_f32_16x16x32_bf16 v[116:119], v[120:123], v[194:197], v[116:119]
	v_mfma_f32_16x16x32_bf16 v[104:107], v[128:131], v[194:197], v[104:107]
	v_mfma_f32_16x16x32_bf16 v[100:103], v[120:123], v[202:205], v[100:103]
	v_mfma_f32_16x16x32_bf16 v[88:91], v[128:131], v[202:205], v[88:91]
	v_mfma_f32_16x16x32_bf16 v[84:87], v[120:123], v[214:217], v[84:87]
	v_mfma_f32_16x16x32_bf16 v[72:75], v[128:131], v[214:217], v[72:75]
	v_mfma_f32_16x16x32_bf16 v[140:143], v[124:127], v[190:193], v[140:143]
	v_mfma_f32_16x16x32_bf16 v[136:139], v[132:135], v[190:193], v[136:139]
	v_mfma_f32_16x16x32_bf16 v[116:119], v[124:127], v[198:201], v[116:119]
	v_mfma_f32_16x16x32_bf16 v[104:107], v[132:135], v[198:201], v[104:107]
	v_mfma_f32_16x16x32_bf16 v[100:103], v[124:127], v[206:209], v[100:103]
	v_mfma_f32_16x16x32_bf16 v[88:91], v[132:135], v[206:209], v[88:91]
	v_mfma_f32_16x16x32_bf16 v[84:87], v[124:127], v[218:221], v[84:87]
	v_mfma_f32_16x16x32_bf16 v[72:75], v[132:135], v[218:221], v[72:75]
	v_mfma_f32_16x16x32_bf16 v[112:115], v[160:163], v[184:187], v[112:115]
	v_mfma_f32_16x16x32_bf16 v[108:111], v[176:179], v[184:187], v[108:111]
	v_mfma_f32_16x16x32_bf16 v[96:99], v[160:163], v[194:197], v[96:99]
	v_mfma_f32_16x16x32_bf16 v[92:95], v[176:179], v[194:197], v[92:95]
	v_mfma_f32_16x16x32_bf16 v[80:83], v[160:163], v[202:205], v[80:83]
	v_mfma_f32_16x16x32_bf16 v[76:79], v[176:179], v[202:205], v[76:79]
	v_mfma_f32_16x16x32_bf16 v[68:71], v[160:163], v[214:217], v[68:71]
	v_mfma_f32_16x16x32_bf16 v[64:67], v[176:179], v[214:217], v[64:67]
	v_mfma_f32_16x16x32_bf16 v[112:115], v[172:175], v[190:193], v[112:115]
	v_mfma_f32_16x16x32_bf16 v[108:111], v[180:183], v[190:193], v[108:111]
	v_mfma_f32_16x16x32_bf16 v[96:99], v[172:175], v[198:201], v[96:99]
	v_mfma_f32_16x16x32_bf16 v[92:95], v[180:183], v[198:201], v[92:95]
	v_mfma_f32_16x16x32_bf16 v[80:83], v[172:175], v[206:209], v[80:83]
	v_mfma_f32_16x16x32_bf16 v[76:79], v[180:183], v[206:209], v[76:79]
	v_mfma_f32_16x16x32_bf16 v[68:71], v[172:175], v[218:221], v[68:71]
	v_mfma_f32_16x16x32_bf16 v[64:67], v[180:183], v[218:221], v[64:67]
	s_barrier
	s_add_i32 s22, s31, s23
	v_lshl_add_u64 v[164:165], s[40:41], 0, v[146:147]
	s_mov_b32 m0, s22
	ds_read_b128 v[184:187], v171 offset:16384
	ds_read_b128 v[190:193], v171 offset:17408
	ds_read_b128 v[194:197], v171 offset:18432
	ds_read_b128 v[198:201], v171 offset:19456
	ds_read_b128 v[202:205], v171 offset:20480
	ds_read_b128 v[206:209], v171 offset:21504
	ds_read_b128 v[214:217], v171 offset:22528
	ds_read_b128 v[218:221], v171 offset:23552
	global_load_lds_dwordx4 v[164:165], off
	s_add_i32 m0, s22, 0x2000
	s_add_u32 s34, s40, 0x160000
	v_lshl_add_u64 v[210:211], s[40:41], 0, v[150:151]
	s_addc_u32 s35, s41, 0
	s_add_i32 s22, s74, s23
	global_load_lds_dwordx4 v[210:211], off
	v_lshl_add_u64 v[222:223], s[34:35], 0, v[146:147]
	s_mov_b32 m0, s22
	v_lshl_add_u64 v[224:225], s[42:43], 0, v[148:149]
	global_load_lds_dwordx4 v[222:223], off
	v_lshl_add_u64 v[222:223], s[34:35], 0, v[150:151]
	s_add_i32 m0, s22, 0x2000
	s_nop 0
	global_load_lds_dwordx4 v[222:223], off
	v_lshl_add_u64 v[222:223], s[42:43], 0, v[144:145]
	s_mov_b32 m0, s28
	s_nop 0
	global_load_lds_dwordx4 v[222:223], off
	s_mov_b32 m0, s29
	s_nop 0
	global_load_lds_dwordx4 v[224:225], off
	s_waitcnt vmcnt(8)
	s_waitcnt lgkmcnt(0)
	s_barrier
	s_waitcnt lgkmcnt(0)
	v_mfma_f32_16x16x32_bf16 v[60:63], v[120:123], v[184:187], v[60:63]
	v_mfma_f32_16x16x32_bf16 v[56:59], v[128:131], v[184:187], v[56:59]
	v_mfma_f32_16x16x32_bf16 v[52:55], v[120:123], v[194:197], v[52:55]
	v_mfma_f32_16x16x32_bf16 v[40:43], v[128:131], v[194:197], v[40:43]
	v_mfma_f32_16x16x32_bf16 v[36:39], v[120:123], v[202:205], v[36:39]
	v_mfma_f32_16x16x32_bf16 v[24:27], v[128:131], v[202:205], v[24:27]
	v_mfma_f32_16x16x32_bf16 v[20:23], v[120:123], v[214:217], v[20:23]
	v_mfma_f32_16x16x32_bf16 v[8:11], v[128:131], v[214:217], v[8:11]
	v_mfma_f32_16x16x32_bf16 v[60:63], v[124:127], v[190:193], v[60:63]
	v_mfma_f32_16x16x32_bf16 v[56:59], v[132:135], v[190:193], v[56:59]
	v_mfma_f32_16x16x32_bf16 v[52:55], v[124:127], v[198:201], v[52:55]
	v_mfma_f32_16x16x32_bf16 v[40:43], v[132:135], v[198:201], v[40:43]
	v_mfma_f32_16x16x32_bf16 v[36:39], v[124:127], v[206:209], v[36:39]
	v_mfma_f32_16x16x32_bf16 v[24:27], v[132:135], v[206:209], v[24:27]
	v_mfma_f32_16x16x32_bf16 v[20:23], v[124:127], v[218:221], v[20:23]
	v_mfma_f32_16x16x32_bf16 v[8:11], v[132:135], v[218:221], v[8:11]
	v_mfma_f32_16x16x32_bf16 v[48:51], v[160:163], v[184:187], v[48:51]
	v_mfma_f32_16x16x32_bf16 v[44:47], v[176:179], v[184:187], v[44:47]
	v_mfma_f32_16x16x32_bf16 v[32:35], v[160:163], v[194:197], v[32:35]
	v_mfma_f32_16x16x32_bf16 v[28:31], v[176:179], v[194:197], v[28:31]
	v_mfma_f32_16x16x32_bf16 v[16:19], v[160:163], v[202:205], v[16:19]
	v_mfma_f32_16x16x32_bf16 v[12:15], v[176:179], v[202:205], v[12:15]
	v_mfma_f32_16x16x32_bf16 v[4:7], v[160:163], v[214:217], v[4:7]
	v_mfma_f32_16x16x32_bf16 v[0:3], v[176:179], v[214:217], v[0:3]
	v_mfma_f32_16x16x32_bf16 v[48:51], v[172:175], v[190:193], v[48:51]
	v_mfma_f32_16x16x32_bf16 v[44:47], v[180:183], v[190:193], v[44:47]
	v_mfma_f32_16x16x32_bf16 v[32:35], v[172:175], v[198:201], v[32:35]
	v_mfma_f32_16x16x32_bf16 v[28:31], v[180:183], v[198:201], v[28:31]
	v_mfma_f32_16x16x32_bf16 v[16:19], v[172:175], v[206:209], v[16:19]
	v_mfma_f32_16x16x32_bf16 v[12:15], v[180:183], v[206:209], v[12:15]
	v_mfma_f32_16x16x32_bf16 v[4:7], v[172:175], v[218:221], v[4:7]
	v_mfma_f32_16x16x32_bf16 v[0:3], v[180:183], v[218:221], v[0:3]
	s_barrier
; #define PG8_STAGE(bufoff, gbase, voff) do { _Pragma("unroll") for (int _i = 0; _i < 2; ++_i) \
;         __builtin_amdgcn_global_load_lds((const unsigned*)((const char*)(gbase) + (voff)[_i]), (PG8_LAS unsigned*)(lds + (bufoff) + ldsw + _i * 8192), 16, 0, 0); } while (0)
; #define PG8_LDA(dst, b, h) do { _Pragma("unroll") for (int m = 0; m < 4; ++m) _Pragma("unroll") for (int k = 0; k < 2; ++k) dst[m][k] = *(const PG8_LAS bf16x8*)(lds + PG8_SA(b, h) + aoff + m * 2048 + k * 1024); } while (0)
; #define PG8_WAIT_V(n) asm volatile("s_waitcnt vmcnt(" #n ")" ::: "memory")
; #define PG8_BAR __builtin_amdgcn_s_barrier()
; template <class Epi, class Sched, bool ALIGN_EPI = false, bool SP2 = false>
; __device__ __forceinline__ void gemm_phase(PG8_LAS unsigned char* lds, const Gemm g, const Sched& S, const Epi& E) {
;     ...
;         for (int t = seg * tseg; t < (seg + 1) * tseg; t += 2) {
;             const bool last = (t == nt - 2);
;             const char* a1 = cA + (size_t)(t + 1) * kstep;
;             const char* a2 = last ? nA : cA + (size_t)(t + 2) * kstep; const char* b2 = last ? nB : cB + (size_t)(t + 2) * kstep;
;             const char* a3 = a2 + kstep; const char* b3 = b2 + kstep;
;             if (last && has_next) S.a_ready(nxt);
;             if constexpr (SP2) {
;             PG8_LDB(B0, 0, 0); PG8_LDB(B1, 0, 1); PG8_SCHED; PG8_LDA(At, 0, 0); PG8_STAGE(PG8_SA(1, 1), a1 + hstep, voffA);
;             PG8_WAIT_V(8); PG8_WAIT_L(0); PG8_BAR; PG8_MMA(0, 0, At, B0); PG8_MMA(0, 1, At, B1); PG8_BAR; PG8_SCHED;
;             PG8_LDA(At, 0, 1); PG8_STAGE(PG8_SB(0, 0), b2, voffB); PG8_STAGE(PG8_SB(0, 1), b2 + hstep, voffB); PG8_STAGE(PG8_SA(0, 0), a2, voffA);
;             PG8_WAIT_V(8); PG8_WAIT_L(0); PG8_BAR; PG8_MMA(1, 0, At, B0); PG8_MMA(1, 1, At, B1); PG8_BAR; PG8_SCHED;
;             PG8_LDB(B0, 1, 0); PG8_LDB(B1, 1, 1); PG8_SCHED; PG8_LDA(At, 1, 0); PG8_STAGE(PG8_SA(0, 1), a2 + hstep, voffA);
;             PG8_WAIT_V(8); PG8_WAIT_L(0); PG8_BAR; PG8_MMA(0, 0, At, B0); PG8_MMA(0, 1, At, B1); PG8_BAR; PG8_SCHED;
;             PG8_LDA(At, 1, 1); PG8_STAGE(PG8_SB(1, 0), b3, voffB); PG8_STAGE(PG8_SB(1, 1), b3 + hstep, voffB); PG8_STAGE(PG8_SA(1, 0), a3, voffA);
;             PG8_WAIT_V(8); PG8_WAIT_L(0); PG8_BAR; PG8_MMA(1, 0, At, B0); PG8_MMA(1, 1, At, B1); PG8_BAR; PG8_SCHED;
;     ...
;         if constexpr (ALIGN_EPI) { if (wr == 0) PG8_BAR; }
	v_add_u32_e32 v132, s75, v167
	v_add_u32_e32 v180, s84, v167
	ds_read_b128 v[120:123], v132
	ds_read_b128 v[124:127], v132 offset:1024
	ds_read_b128 v[128:131], v132 offset:2048
	ds_read_b128 v[132:135], v132 offset:3072
	ds_read_b128 v[160:163], v180
	ds_read_b128 v[172:175], v180 offset:1024
	ds_read_b128 v[176:179], v180 offset:2048
	ds_read_b128 v[180:183], v180 offset:3072
	s_add_u32 s34, s42, 0x160000
	s_addc_u32 s35, s43, 0
	s_mov_b32 m0, s30
	v_lshl_add_u64 v[226:227], s[34:35], 0, v[144:145]
	ds_read_b128 v[184:187], v171 offset:32768
	ds_read_b128 v[190:193], v171 offset:33792
	ds_read_b128 v[194:197], v171 offset:34816
	ds_read_b128 v[198:201], v171 offset:35840
	ds_read_b128 v[202:205], v171 offset:36864
	ds_read_b128 v[206:209], v171 offset:37888
	ds_read_b128 v[214:217], v171 offset:38912
	ds_read_b128 v[218:221], v171 offset:39936
	global_load_lds_dwordx4 v[226:227], off
	v_lshl_add_u64 v[226:227], s[34:35], 0, v[148:149]
	s_mov_b32 m0, s33
	s_nop 0
	global_load_lds_dwordx4 v[226:227], off
	s_waitcnt vmcnt(8)
	s_waitcnt lgkmcnt(0)
	s_barrier
	s_waitcnt lgkmcnt(0)
	v_mfma_f32_16x16x32_bf16 v[140:143], v[120:123], v[184:187], v[140:143]
	v_mfma_f32_16x16x32_bf16 v[136:139], v[128:131], v[184:187], v[136:139]
	v_mfma_f32_16x16x32_bf16 v[116:119], v[120:123], v[194:197], v[116:119]
	v_mfma_f32_16x16x32_bf16 v[104:107], v[128:131], v[194:197], v[104:107]
	v_mfma_f32_16x16x32_bf16 v[100:103], v[120:123], v[202:205], v[100:103]
	v_mfma_f32_16x16x32_bf16 v[88:91], v[128:131], v[202:205], v[88:91]
	v_mfma_f32_16x16x32_bf16 v[84:87], v[120:123], v[214:217], v[84:87]
	v_mfma_f32_16x16x32_bf16 v[72:75], v[128:131], v[214:217], v[72:75]
	v_mfma_f32_16x16x32_bf16 v[140:143], v[124:127], v[190:193], v[140:143]
	v_mfma_f32_16x16x32_bf16 v[136:139], v[132:135], v[190:193], v[136:139]
	v_mfma_f32_16x16x32_bf16 v[116:119], v[124:127], v[198:201], v[116:119]
	v_mfma_f32_16x16x32_bf16 v[104:107], v[132:135], v[198:201], v[104:107]
	v_mfma_f32_16x16x32_bf16 v[100:103], v[124:127], v[206:209], v[100:103]
	v_mfma_f32_16x16x32_bf16 v[88:91], v[132:135], v[206:209], v[88:91]
	v_mfma_f32_16x16x32_bf16 v[84:87], v[124:127], v[218:221], v[84:87]
	v_mfma_f32_16x16x32_bf16 v[72:75], v[132:135], v[218:221], v[72:75]
	v_mfma_f32_16x16x32_bf16 v[112:115], v[160:163], v[184:187], v[112:115]
	v_mfma_f32_16x16x32_bf16 v[108:111], v[176:179], v[184:187], v[108:111]
	v_mfma_f32_16x16x32_bf16 v[96:99], v[160:163], v[194:197], v[96:99]
	v_mfma_f32_16x16x32_bf16 v[92:95], v[176:179], v[194:197], v[92:95]
	v_mfma_f32_16x16x32_bf16 v[80:83], v[160:163], v[202:205], v[80:83]
	v_mfma_f32_16x16x32_bf16 v[76:79], v[176:179], v[202:205], v[76:79]
	v_mfma_f32_16x16x32_bf16 v[68:71], v[160:163], v[214:217], v[68:71]
	v_mfma_f32_16x16x32_bf16 v[64:67], v[176:179], v[214:217], v[64:67]
	v_mfma_f32_16x16x32_bf16 v[112:115], v[172:175], v[190:193], v[112:115]
	v_mfma_f32_16x16x32_bf16 v[108:111], v[180:183], v[190:193], v[108:111]
	v_mfma_f32_16x16x32_bf16 v[96:99], v[172:175], v[198:201], v[96:99]
	v_mfma_f32_16x16x32_bf16 v[92:95], v[180:183], v[198:201], v[92:95]
	v_mfma_f32_16x16x32_bf16 v[80:83], v[172:175], v[206:209], v[80:83]
	v_mfma_f32_16x16x32_bf16 v[76:79], v[180:183], v[206:209], v[76:79]
	v_mfma_f32_16x16x32_bf16 v[68:71], v[172:175], v[218:221], v[68:71]
	v_mfma_f32_16x16x32_bf16 v[64:67], v[180:183], v[218:221], v[64:67]
	s_barrier
	s_add_i32 s22, s75, s23
	v_lshl_add_u64 v[164:165], v[164:165], 0, s[8:9]
	s_mov_b32 m0, s22
	ds_read_b128 v[184:187], v171 offset:49152
	ds_read_b128 v[190:193], v171 offset:50176
	ds_read_b128 v[194:197], v171 offset:51200
	ds_read_b128 v[198:201], v171 offset:52224
	ds_read_b128 v[202:205], v171 offset:53248
	ds_read_b128 v[206:209], v171 offset:54272
	ds_read_b128 v[214:217], v171 offset:55296
	ds_read_b128 v[218:221], v171 offset:56320
	global_load_lds_dwordx4 v[164:165], off
	s_add_i32 m0, s22, 0x2000
	s_add_u32 s34, s40, 0x160080
	v_lshl_add_u64 v[164:165], v[210:211], 0, s[8:9]
	s_addc_u32 s35, s41, 0
	s_add_i32 s22, s84, s23
	global_load_lds_dwordx4 v[164:165], off
	v_lshl_add_u64 v[164:165], s[34:35], 0, v[146:147]
	s_mov_b32 m0, s22
	s_nop 0
	global_load_lds_dwordx4 v[164:165], off
	v_lshl_add_u64 v[164:165], s[34:35], 0, v[150:151]
	s_add_i32 m0, s22, 0x2000
	s_nop 0
	global_load_lds_dwordx4 v[164:165], off
	v_lshl_add_u64 v[164:165], v[222:223], 0, s[8:9]
	s_mov_b32 m0, s47
	s_nop 0
	global_load_lds_dwordx4 v[164:165], off
	v_lshl_add_u64 v[164:165], v[224:225], 0, s[8:9]
	s_mov_b32 m0, s52
	s_nop 0
	global_load_lds_dwordx4 v[164:165], off
	s_waitcnt vmcnt(8)
	s_waitcnt lgkmcnt(0)
	s_barrier
	s_waitcnt lgkmcnt(0)
	v_mfma_f32_16x16x32_bf16 v[60:63], v[120:123], v[184:187], v[60:63]
	v_mfma_f32_16x16x32_bf16 v[56:59], v[128:131], v[184:187], v[56:59]
	v_mfma_f32_16x16x32_bf16 v[52:55], v[120:123], v[194:197], v[52:55]
	v_mfma_f32_16x16x32_bf16 v[40:43], v[128:131], v[194:197], v[40:43]
	v_mfma_f32_16x16x32_bf16 v[36:39], v[120:123], v[202:205], v[36:39]
	v_mfma_f32_16x16x32_bf16 v[24:27], v[128:131], v[202:205], v[24:27]
	v_mfma_f32_16x16x32_bf16 v[20:23], v[120:123], v[214:217], v[20:23]
	v_mfma_f32_16x16x32_bf16 v[8:11], v[128:131], v[214:217], v[8:11]
	v_mfma_f32_16x16x32_bf16 v[60:63], v[124:127], v[190:193], v[60:63]
	v_mfma_f32_16x16x32_bf16 v[56:59], v[132:135], v[190:193], v[56:59]
	v_mfma_f32_16x16x32_bf16 v[52:55], v[124:127], v[198:201], v[52:55]
	v_mfma_f32_16x16x32_bf16 v[40:43], v[132:135], v[198:201], v[40:43]
	v_mfma_f32_16x16x32_bf16 v[36:39], v[124:127], v[206:209], v[36:39]
	v_mfma_f32_16x16x32_bf16 v[24:27], v[132:135], v[206:209], v[24:27]
	v_mfma_f32_16x16x32_bf16 v[20:23], v[124:127], v[218:221], v[20:23]
	v_mfma_f32_16x16x32_bf16 v[8:11], v[132:135], v[218:221], v[8:11]
	v_mfma_f32_16x16x32_bf16 v[48:51], v[160:163], v[184:187], v[48:51]
	v_mfma_f32_16x16x32_bf16 v[44:47], v[176:179], v[184:187], v[44:47]
	v_mfma_f32_16x16x32_bf16 v[32:35], v[160:163], v[194:197], v[32:35]
	v_mfma_f32_16x16x32_bf16 v[28:31], v[176:179], v[194:197], v[28:31]
	v_mfma_f32_16x16x32_bf16 v[16:19], v[160:163], v[202:205], v[16:19]
	v_mfma_f32_16x16x32_bf16 v[12:15], v[176:179], v[202:205], v[12:15]
	v_mfma_f32_16x16x32_bf16 v[4:7], v[160:163], v[214:217], v[4:7]
	v_mfma_f32_16x16x32_bf16 v[0:3], v[176:179], v[214:217], v[0:3]
	v_mfma_f32_16x16x32_bf16 v[48:51], v[172:175], v[190:193], v[48:51]
	v_mfma_f32_16x16x32_bf16 v[44:47], v[180:183], v[190:193], v[44:47]
	v_mfma_f32_16x16x32_bf16 v[32:35], v[172:175], v[198:201], v[32:35]
	v_mfma_f32_16x16x32_bf16 v[28:31], v[180:183], v[198:201], v[28:31]
	v_mfma_f32_16x16x32_bf16 v[16:19], v[172:175], v[206:209], v[16:19]
	v_mfma_f32_16x16x32_bf16 v[12:15], v[180:183], v[206:209], v[12:15]
	v_mfma_f32_16x16x32_bf16 v[4:7], v[172:175], v[218:221], v[4:7]
	v_mfma_f32_16x16x32_bf16 v[0:3], v[180:183], v[218:221], v[0:3]
	s_barrier
	s_add_i32 s59, s59, 2
	s_add_u32 s0, s0, 0x100
	s_addc_u32 s1, s1, 0
	s_cmpk_gt_u32 s59, 0x55
	s_mov_b64 s[34:35], s[38:39]
	s_cbranch_scc0 .LBB0_1101
	s_and_b64 vcc, exec, s[10:11]
	s_cbranch_vccz .LBB0_1104
	s_barrier

; __global__ void __launch_bounds__(NTHR, 2) fwd_megakernel(Args A) {
	.amdhsa_kernel _Z14fwd_megakernel4Args
		.amdhsa_group_segment_fixed_size 0
		.amdhsa_private_segment_fixed_size 0
		.amdhsa_kernarg_size 456
		.amdhsa_user_sgpr_count 2
		.amdhsa_user_sgpr_dispatch_ptr 0
		.amdhsa_user_sgpr_queue_ptr 0
		.amdhsa_user_sgpr_kernarg_segment_ptr 1
		.amdhsa_user_sgpr_dispatch_id 0
		.amdhsa_user_sgpr_kernarg_preload_length 0
		.amdhsa_user_sgpr_kernarg_preload_offset 0
		.amdhsa_user_sgpr_private_segment_size 0
		.amdhsa_uses_dynamic_stack 0
		.amdhsa_enable_private_segment 0
		.amdhsa_system_sgpr_workgroup_id_x 1
		.amdhsa_system_sgpr_workgroup_id_y 0
		.amdhsa_system_sgpr_workgroup_id_z 0
		.amdhsa_system_sgpr_workgroup_info 0
		.amdhsa_system_vgpr_workitem_id 2
		.amdhsa_next_free_vgpr 256
		.amdhsa_next_free_sgpr 102
		.amdhsa_accum_offset 256
		.amdhsa_reserve_vcc 1
		.amdhsa_float_round_mode_32 0
		.amdhsa_float_round_mode_16_64 0
		.amdhsa_float_denorm_mode_32 3
		.amdhsa_float_denorm_mode_16_64 3
		.amdhsa_dx10_clamp 1
		.amdhsa_ieee_mode 1
		.amdhsa_fp16_overflow 0
		.amdhsa_tg_split 0
		.amdhsa_exception_fp_ieee_invalid_op 0
		.amdhsa_exception_fp_denorm_src 0
		.amdhsa_exception_fp_ieee_div_zero 0
		.amdhsa_exception_fp_ieee_overflow 0
		.amdhsa_exception_fp_ieee_underflow 0
		.amdhsa_exception_fp_ieee_inexact 0
		.amdhsa_exception_int_div_zero 0
	.end_amdhsa_kernel

amdhsa.kernels:
  - .agpr_count:     0
    .args:
      - .offset:         0
        .size:           200
        .value_kind:     by_value
      - .offset:         200
        .size:           4
        .value_kind:     hidden_block_count_x
      - .offset:         204
        .size:           4
        .value_kind:     hidden_block_count_y
      - .offset:         208
        .size:           4
        .value_kind:     hidden_block_count_z
      - .offset:         212
        .size:           2
        .value_kind:     hidden_group_size_x
      - .offset:         214
        .size:           2
        .value_kind:     hidden_group_size_y
      - .offset:         216
        .size:           2
        .value_kind:     hidden_group_size_z
      - .offset:         218
        .size:           2
        .value_kind:     hidden_remainder_x
      - .offset:         220
        .size:           2
        .value_kind:     hidden_remainder_y
      - .offset:         222
        .size:           2
        .value_kind:     hidden_remainder_z
      - .offset:         240
        .size:           8
        .value_kind:     hidden_global_offset_x
      - .offset:         248
        .size:           8
        .value_kind:     hidden_global_offset_y
      - .offset:         256
        .size:           8
        .value_kind:     hidden_global_offset_z
      - .offset:         264
        .size:           2
        .value_kind:     hidden_grid_dims
      - .offset:         288
        .size:           8
        .value_kind:     hidden_multigrid_sync_arg
      - .offset:         320
        .size:           4
        .value_kind:     hidden_dynamic_lds_size
    .group_segment_fixed_size: 0
    .kernarg_segment_align: 8
    .kernarg_segment_size: 456
    .language:       OpenCL C
    .language_version:
      - 2
      - 0
    .max_flat_workgroup_size: 512
    .name:           _Z14fwd_megakernel4Args
    .private_segment_fixed_size: 0
    .sgpr_count:     108
    .sgpr_spill_count: 46
    .symbol:         _Z14fwd_megakernel4Args.kd
    .uniform_work_group_size: 1
    .uses_dynamic_stack: false
    .vgpr_count:     256
    .vgpr_spill_count: 0
    .wavefront_size: 64
